# bf16 packs: integer round-to-nearest-even sequences replaced by v_cvt_pk_bf16_f32 (same rounding), on top of packed SwiGLU math
# speedup vs baseline: 1.0086x; 1.0020x over previous
; __device__ __forceinline__ bf16* lw(const Frame& F, int l, size_t off) { return (bf16*)(wsq(F.ws) + WS_W + (size_t)l * LW_SIZE + off); }
; __device__ __forceinline__ void p0_transpose_item(const float* W, int K, int ldw, int N, bf16* WT, int kind, LAS float* scr, int item, int lane) {
;     const int nblk = N / 32, kb = item / nblk, nb = item % nblk, k0 = 64 * kb, n0 = 32 * nb;
;     const int sc = srccol(kind, n0 + (lane & 31));
;     float t_[32];
; #pragma unroll
;     for (int i = 0; i < 32; ++i) t_[i] = W[(size_t)(k0 + 2 * i + (lane >> 5)) * ldw + sc];
; __device__ __forceinline__ void p0_prologue(Frame& F) {
;     ...
;             if (r < I_SQ) { p0_transpose_item(in_ptr(IN_WOUT) + (size_t)l * D * D, D, D, D, lw(F, l, LW_OUT), 0, scr, r, tc.lane); continue; } r -= I_SQ;
.LBB0_27:
	s_and_b64 vcc, exec, s[26:27]
	s_cbranch_vccz .LBB0_29
	s_mov_b64 s[26:27], s[0:1]
	s_load_dwordx2 s[26:27], s[26:27], 0x60
	s_mov_b64 s[28:29], s[46:47]
	s_waitcnt lgkmcnt(0)
	s_add_u32 s30, s26, s22
	s_addc_u32 s31, s27, s23
	s_add_u32 s26, s28, s78
	s_addc_u32 s27, s29, 0
	s_lshl_b32 s28, s77, 1
	s_lshl_b32 s4, s77, 5
	s_add_i32 s28, s28, 0x18e00
	s_and_b32 s4, s4, 0x3e0
	s_and_b32 s28, s28, 0x1ffc0
	v_or_b32_e32 v2, s4, v1
	v_add_u32_e32 v4, s28, v33
	v_lshlrev_b32_e32 v2, 2, v2
	v_ashrrev_i32_e32 v5, 31, v4
	v_lshl_add_u64 v[6:7], s[30:31], 0, v[2:3]
	v_lshlrev_b64 v[4:5], 12, v[4:5]
	v_lshl_add_u64 v[4:5], v[6:7], 0, v[4:5]
	v_add_co_u32_e32 v6, vcc, s41, v4
	s_lshl_b32 s28, s28, 1
	s_nop 0
	v_addc_co_u32_e32 v7, vcc, 0, v5, vcc
	v_add_co_u32_e32 v8, vcc, s42, v4
	s_add_u32 s26, s26, s28
	s_nop 0
	v_addc_co_u32_e32 v9, vcc, 0, v5, vcc
	v_add_co_u32_e32 v10, vcc, s43, v4
	s_addc_u32 s27, s27, 0
	s_nop 0
	v_addc_co_u32_e32 v11, vcc, 0, v5, vcc
	v_add_co_u32_e32 v12, vcc, s48, v4
	s_nop 1
	v_addc_co_u32_e32 v13, vcc, 0, v5, vcc
	v_add_co_u32_e32 v14, vcc, s49, v4
	s_nop 1
	v_addc_co_u32_e32 v15, vcc, 0, v5, vcc
	v_add_co_u32_e32 v16, vcc, s50, v4
	s_nop 1
	v_addc_co_u32_e32 v17, vcc, 0, v5, vcc
	v_add_co_u32_e32 v18, vcc, s37, v4
	s_nop 1
	v_addc_co_u32_e32 v19, vcc, 0, v5, vcc
	global_load_dword v2, v[4:5], off
	global_load_dword v22, v[6:7], off
	global_load_dword v23, v[8:9], off
	global_load_dword v24, v[10:11], off
	global_load_dword v25, v[12:13], off
	global_load_dword v26, v[14:15], off
	global_load_dword v27, v[16:17], off
	global_load_dword v28, v[18:19], off
	v_add_co_u32_e32 v6, vcc, s51, v4
	s_nop 1
	v_addc_co_u32_e32 v7, vcc, 0, v5, vcc
	v_add_co_u32_e32 v8, vcc, s52, v4
	s_nop 1
	v_addc_co_u32_e32 v9, vcc, 0, v5, vcc
	v_add_co_u32_e32 v10, vcc, s53, v4
	s_nop 1
	v_addc_co_u32_e32 v11, vcc, 0, v5, vcc
	v_add_co_u32_e32 v12, vcc, s54, v4
	s_nop 1
	v_addc_co_u32_e32 v13, vcc, 0, v5, vcc
	v_add_co_u32_e32 v14, vcc, s55, v4
	s_nop 1
	v_addc_co_u32_e32 v15, vcc, 0, v5, vcc
	v_add_co_u32_e32 v16, vcc, s56, v4
	s_nop 1
	v_addc_co_u32_e32 v17, vcc, 0, v5, vcc
	v_add_co_u32_e32 v18, vcc, s57, v4
	s_nop 1
	v_addc_co_u32_e32 v19, vcc, 0, v5, vcc
	v_add_co_u32_e32 v20, vcc, s58, v4
	s_nop 1
	v_addc_co_u32_e32 v21, vcc, 0, v5, vcc
	global_load_dword v29, v[6:7], off
	global_load_dword v30, v[8:9], off
	global_load_dword v31, v[10:11], off
	global_load_dword v34, v[12:13], off
	global_load_dword v35, v[14:15], off
	global_load_dword v36, v[16:17], off
	global_load_dword v37, v[18:19], off
	global_load_dword v38, v[20:21], off
	v_add_co_u32_e32 v6, vcc, s59, v4
	s_nop 1
	v_addc_co_u32_e32 v7, vcc, 0, v5, vcc
	v_add_co_u32_e32 v8, vcc, s60, v4
	s_nop 1
	v_addc_co_u32_e32 v9, vcc, 0, v5, vcc
	v_add_co_u32_e32 v10, vcc, s61, v4
	s_nop 1
	v_addc_co_u32_e32 v11, vcc, 0, v5, vcc
	v_add_co_u32_e32 v12, vcc, s62, v4
	s_nop 1
	v_addc_co_u32_e32 v13, vcc, 0, v5, vcc
	v_add_co_u32_e32 v14, vcc, s63, v4
	s_nop 1
	v_addc_co_u32_e32 v15, vcc, 0, v5, vcc
	v_add_co_u32_e32 v16, vcc, s64, v4
	s_nop 1
	v_addc_co_u32_e32 v17, vcc, 0, v5, vcc
	v_add_co_u32_e32 v18, vcc, s65, v4
	s_nop 1
	v_addc_co_u32_e32 v19, vcc, 0, v5, vcc
	v_add_co_u32_e32 v20, vcc, s66, v4
	s_nop 1
	v_addc_co_u32_e32 v21, vcc, 0, v5, vcc
	global_load_dword v39, v[6:7], off
	global_load_dword v40, v[8:9], off
	global_load_dword v42, v[10:11], off
	global_load_dword v44, v[12:13], off
	global_load_dword v46, v[14:15], off
	global_load_dword v48, v[16:17], off
	global_load_dword v50, v[18:19], off
	s_nop 0
	global_load_dword v20, v[20:21], off
	v_add_co_u32_e32 v6, vcc, s67, v4
	s_nop 1
	v_addc_co_u32_e32 v7, vcc, 0, v5, vcc
	v_add_co_u32_e32 v8, vcc, s68, v4
	s_nop 1
	v_addc_co_u32_e32 v9, vcc, 0, v5, vcc
	v_add_co_u32_e32 v10, vcc, s69, v4
	s_nop 1
	v_addc_co_u32_e32 v11, vcc, 0, v5, vcc
	v_add_co_u32_e32 v12, vcc, s70, v4
	s_nop 1
	v_addc_co_u32_e32 v13, vcc, 0, v5, vcc
	v_add_co_u32_e32 v14, vcc, s71, v4
	s_nop 1
	v_addc_co_u32_e32 v15, vcc, 0, v5, vcc
	v_add_co_u32_e32 v16, vcc, s72, v4
	s_nop 1
	v_addc_co_u32_e32 v17, vcc, 0, v5, vcc
	v_add_co_u32_e32 v18, vcc, s73, v4
	s_nop 1
	v_addc_co_u32_e32 v19, vcc, 0, v5, vcc
	v_add_co_u32_e32 v4, vcc, s74, v4
	s_nop 1
	v_addc_co_u32_e32 v5, vcc, 0, v5, vcc
	global_load_dword v6, v[6:7], off
	s_nop 0
	global_load_dword v7, v[8:9], off
	s_nop 0
	global_load_dword v8, v[10:11], off
	global_load_dword v9, v[12:13], off
	s_nop 0
	global_load_dword v10, v[14:15], off
	global_load_dword v11, v[16:17], off
	global_load_dword v12, v[18:19], off
	s_nop 0
	global_load_dword v4, v[4:5], off
	s_waitcnt vmcnt(30)
; #define GAS __attribute__((address_space(1)))
; #define LAS __attribute__((address_space(3)))
; __device__ __forceinline__ unsigned pk2(float lo, float hi) { return f2bf(lo) | (f2bf(hi) << 16); }
; __device__ __forceinline__ void p0_transpose_item(const float* W, int K, int ldw, int N, bf16* WT, int kind, LAS float* scr, int item, int lane) {
;     ...
; #pragma unroll
;     for (int i = 0; i < 32; ++i) scr[(2 * i + (lane >> 5)) * 33 + (lane & 31)] = t_[i];
;     asm volatile("s_waitcnt lgkmcnt(0)" ::: "memory");
;     const int c = lane & 7;
; #pragma unroll
;     for (int j = 0; j < 4; ++j) { const int n = (lane >> 3) + 8 * j; const LAS float* s = scr + (8 * c) * 33 + n;
;         v4u o; o.x = pk2(s[0 * 33], s[1 * 33]); o.y = pk2(s[2 * 33], s[3 * 33]); o.z = pk2(s[4 * 33], s[5 * 33]); o.w = pk2(s[6 * 33], s[7 * 33]);
;         *(GAS v4u*)(WT + (size_t)(n0 + n) * K + k0 + 8 * c) = o; }
;     asm volatile("s_waitcnt lgkmcnt(0)" ::: "memory");
	ds_write2_b32 v41, v2, v22 offset1:66
	s_waitcnt vmcnt(28)
	ds_write2_b32 v41, v23, v24 offset0:132 offset1:198
	v_add_u32_e32 v2, 0x400, v41
	s_waitcnt vmcnt(26)
	ds_write2_b32 v2, v25, v26 offset0:8 offset1:74
	s_waitcnt vmcnt(24)
	ds_write2_b32 v2, v27, v28 offset0:140 offset1:206
	v_add_u32_e32 v2, 0x800, v41
	s_waitcnt vmcnt(22)
	ds_write2_b32 v2, v29, v30 offset0:16 offset1:82
	s_waitcnt vmcnt(20)
	ds_write2_b32 v2, v31, v34 offset0:148 offset1:214
	v_add_u32_e32 v2, 0xc00, v41
	s_waitcnt vmcnt(18)
	ds_write2_b32 v2, v35, v36 offset0:24 offset1:90
	s_waitcnt vmcnt(16)
	ds_write2_b32 v2, v37, v38 offset0:156 offset1:222
	v_add_u32_e32 v2, 0x1000, v41
	s_waitcnt vmcnt(14)
	ds_write2_b32 v2, v39, v40 offset0:32 offset1:98
	s_waitcnt vmcnt(12)
	ds_write2_b32 v2, v42, v44 offset0:164 offset1:230
	v_add_u32_e32 v2, 0x1400, v41
	s_waitcnt vmcnt(10)
	ds_write2_b32 v2, v46, v48 offset0:40 offset1:106
	s_waitcnt vmcnt(8)
	ds_write2_b32 v2, v50, v20 offset0:172 offset1:238
	v_add_u32_e32 v2, 0x1800, v41
	s_waitcnt vmcnt(6)
	ds_write2_b32 v2, v6, v7 offset0:48 offset1:114
	s_waitcnt vmcnt(4)
	ds_write2_b32 v2, v8, v9 offset0:180 offset1:246
	v_add_u32_e32 v2, 0x1c00, v41
	s_waitcnt vmcnt(2)
	ds_write2_b32 v2, v10, v11 offset0:56 offset1:122
	s_waitcnt vmcnt(0)
	ds_write2_b32 v2, v12, v4 offset0:188 offset1:254
	s_waitcnt lgkmcnt(0)
	ds_read2_b32 v[8:9], v45 offset1:8
	ds_read2_b32 v[12:13], v45 offset0:33 offset1:41
	ds_read2_b32 v[14:15], v45 offset0:66 offset1:74
	v_lshlrev_b32_e32 v2, 1, v0
	ds_read2_b32 v[16:17], v45 offset0:99 offset1:107
	v_lshl_add_u64 v[4:5], s[26:27], 0, v[2:3]
	s_mov_b64 s[26:27], 0x99e40000
	s_waitcnt lgkmcnt(3)
	v_bfe_u32 v2, v8, 16, 1
	v_lshl_add_u64 v[10:11], v[4:5], 0, s[26:27]
	v_add3_u32 v2, v8, v2, s38
	s_waitcnt lgkmcnt(2)
	v_bfe_u32 v4, v12, 16, 1
	ds_read2_b32 v[18:19], v45 offset0:132 offset1:140
	v_lshrrev_b32_e32 v2, 16, v2
	v_add3_u32 v4, v12, v4, s38
	ds_read2_b32 v[20:21], v45 offset0:165 offset1:173
	v_and_or_b32 v4, v4, s39, v2
	s_waitcnt lgkmcnt(3)
	s_waitcnt lgkmcnt(2)
	ds_read2_b32 v[22:23], v45 offset0:198 offset1:206
	ds_read2_b32 v[24:25], v45 offset0:231 offset1:239
	v_cvt_pk_bf16_f32 v5, v14, v16
	s_waitcnt lgkmcnt(3)
	s_waitcnt lgkmcnt(2)
	v_cvt_pk_bf16_f32 v6, v18, v20
	s_waitcnt lgkmcnt(1)
	v_add_u32_e32 v26, s4, v43
	s_waitcnt lgkmcnt(0)
	v_ashrrev_i32_e32 v27, 31, v26
	v_lshlrev_b64 v[26:27], 11, v[26:27]
	v_cvt_pk_bf16_f32 v7, v22, v24
	v_lshl_add_u64 v[26:27], v[10:11], 0, v[26:27]
	v_bfe_u32 v2, v9, 16, 1
	global_store_dwordx4 v[26:27], v[4:7], off
	v_add3_u32 v2, v9, v2, s38
	v_lshrrev_b32_e32 v2, 16, v2
	v_bfe_u32 v4, v13, 16, 1
	v_add3_u32 v4, v13, v4, s38
	v_and_or_b32 v4, v4, s39, v2
	v_cvt_pk_bf16_f32 v5, v15, v17
	v_cvt_pk_bf16_f32 v6, v19, v21
	v_add_u32_e32 v8, s4, v47
	v_ashrrev_i32_e32 v9, 31, v8
	v_lshlrev_b64 v[8:9], 11, v[8:9]
	v_cvt_pk_bf16_f32 v7, v23, v25
	ds_read2_b32 v[12:13], v45 offset0:16 offset1:24
	v_lshl_add_u64 v[8:9], v[10:11], 0, v[8:9]
	global_store_dwordx4 v[8:9], v[4:7], off
	ds_read2_b32 v[8:9], v45 offset0:49 offset1:57
	ds_read2_b32 v[14:15], v45 offset0:82 offset1:90
	ds_read2_b32 v[16:17], v45 offset0:115 offset1:123
	s_waitcnt lgkmcnt(3)
	s_waitcnt lgkmcnt(2)
	ds_read2_b32 v[18:19], v45 offset0:148 offset1:156
	ds_read2_b32 v[20:21], v45 offset0:181 offset1:189
	v_cvt_pk_bf16_f32 v4, v12, v8
	s_waitcnt lgkmcnt(3)
	s_waitcnt lgkmcnt(2)
	ds_read2_b32 v[22:23], v45 offset0:214 offset1:222
	ds_read2_b32 v[24:25], v45 offset0:247 offset1:255
	v_cvt_pk_bf16_f32 v5, v14, v16
	s_waitcnt lgkmcnt(3)
	s_waitcnt lgkmcnt(2)
	v_cvt_pk_bf16_f32 v6, v18, v20
	s_waitcnt lgkmcnt(1)
	v_add_u32_e32 v26, s4, v49
	s_waitcnt lgkmcnt(0)
	v_ashrrev_i32_e32 v27, 31, v26
	v_lshlrev_b64 v[26:27], 11, v[26:27]
	v_cvt_pk_bf16_f32 v7, v22, v24
	v_lshl_add_u64 v[26:27], v[10:11], 0, v[26:27]
	v_bfe_u32 v2, v13, 16, 1
	global_store_dwordx4 v[26:27], v[4:7], off
	v_add3_u32 v2, v13, v2, s38
	v_lshrrev_b32_e32 v2, 16, v2
	v_bfe_u32 v4, v9, 16, 1
	v_add3_u32 v4, v9, v4, s38
	v_and_or_b32 v4, v4, s39, v2
	v_cvt_pk_bf16_f32 v5, v15, v17
	v_cvt_pk_bf16_f32 v6, v19, v21
	v_add_u32_e32 v8, s4, v51
	v_ashrrev_i32_e32 v9, 31, v8
	v_lshlrev_b64 v[8:9], 11, v[8:9]
	v_cvt_pk_bf16_f32 v7, v23, v25
	v_lshl_add_u64 v[8:9], v[10:11], 0, v[8:9]
	global_store_dwordx4 v[8:9], v[4:7], off
	s_waitcnt lgkmcnt(0)

; __device__ __forceinline__ bf16* lw(const Frame& F, int l, size_t off) { return (bf16*)(wsq(F.ws) + WS_W + (size_t)l * LW_SIZE + off); }
; __device__ __forceinline__ void p0_transpose_item(const float* W, int K, int ldw, int N, bf16* WT, int kind, LAS float* scr, int item, int lane) {
;     const int nblk = N / 32, kb = item / nblk, nb = item % nblk, k0 = 64 * kb, n0 = 32 * nb;
;     const int sc = srccol(kind, n0 + (lane & 31));
;     float t_[32];
; #pragma unroll
;     for (int i = 0; i < 32; ++i) t_[i] = W[(size_t)(k0 + 2 * i + (lane >> 5)) * ldw + sc];
; __device__ __forceinline__ void p0_prologue(Frame& F) {
;     ...
;             if (r < I_SQ) { p0_transpose_item(in_ptr(IN_WBR) + (size_t)(l * 3 + 1) * D * D, D, D, D, lw(F, l, LW_BR) + (size_t)D * D, 0, scr, r, tc.lane); continue; } r -= I_SQ;
.LBB0_30:
	s_andn2_b64 vcc, exec, s[26:27]
	s_cbranch_vccnz .LBB0_32
	s_mov_b64 s[26:27], s[0:1]
	s_load_dwordx2 s[26:27], s[26:27], 0x58
	s_lshl_b64 s[28:29], s[16:17], 2
	s_mov_b64 s[30:31], s[46:47]
	s_waitcnt lgkmcnt(0)
	s_add_u32 s84, s26, s28
	s_addc_u32 s85, s27, s29
	s_add_u32 s26, s30, s78
	s_addc_u32 s27, s31, 0
	s_lshl_b32 s28, s77, 1
	s_lshl_b32 s4, s77, 5
	s_add_i32 s28, s28, 0x19200
	s_and_b32 s4, s4, 0x3e0
	s_and_b32 s28, s28, 0x1ffc0
	v_or_b32_e32 v2, s4, v1
	v_add_u32_e32 v4, s28, v33
	v_lshlrev_b32_e32 v2, 2, v2
	v_ashrrev_i32_e32 v5, 31, v4
	v_lshl_add_u64 v[6:7], s[84:85], 0, v[2:3]
	v_lshlrev_b64 v[4:5], 12, v[4:5]
	v_lshl_add_u64 v[4:5], v[6:7], 0, v[4:5]
	s_mov_b32 s29, 0x400000
	v_add_co_u32_e32 v6, vcc, s29, v4
	s_mov_b32 s29, 0x402000
	s_nop 0
	v_addc_co_u32_e32 v7, vcc, 0, v5, vcc
	v_add_co_u32_e32 v8, vcc, s29, v4
	s_mov_b32 s29, 0x404000
	s_nop 0
	v_addc_co_u32_e32 v9, vcc, 0, v5, vcc
	v_add_co_u32_e32 v10, vcc, s29, v4
	s_mov_b32 s29, 0x406000
	s_nop 0
	v_addc_co_u32_e32 v11, vcc, 0, v5, vcc
	v_add_co_u32_e32 v12, vcc, s29, v4
	s_mov_b32 s29, 0x408000
	s_nop 0
	v_addc_co_u32_e32 v13, vcc, 0, v5, vcc
	v_add_co_u32_e32 v14, vcc, s29, v4
	s_mov_b32 s29, 0x40a000
	s_nop 0
	v_addc_co_u32_e32 v15, vcc, 0, v5, vcc
	v_add_co_u32_e32 v16, vcc, s29, v4
	s_mov_b32 s29, 0x40c000
	s_nop 0
	v_addc_co_u32_e32 v17, vcc, 0, v5, vcc
	v_add_co_u32_e32 v18, vcc, s29, v4
	s_mov_b32 s29, 0x40e000
	s_nop 0
	v_addc_co_u32_e32 v19, vcc, 0, v5, vcc
	v_add_co_u32_e32 v20, vcc, s29, v4
	s_mov_b32 s29, 0x410000
	s_nop 0
	v_addc_co_u32_e32 v21, vcc, 0, v5, vcc
	global_load_dword v2, v[6:7], off
	global_load_dword v22, v[8:9], off
	global_load_dword v23, v[10:11], off
	global_load_dword v24, v[12:13], off
	global_load_dword v25, v[14:15], off
	global_load_dword v26, v[16:17], off
	global_load_dword v27, v[18:19], off
	global_load_dword v28, v[20:21], off
	v_add_co_u32_e32 v6, vcc, s29, v4
	s_mov_b32 s29, 0x412000
	s_nop 0
	v_addc_co_u32_e32 v7, vcc, 0, v5, vcc
	v_add_co_u32_e32 v8, vcc, s29, v4
	s_mov_b32 s29, 0x414000
	s_nop 0
	v_addc_co_u32_e32 v9, vcc, 0, v5, vcc
	v_add_co_u32_e32 v10, vcc, s29, v4
	s_mov_b32 s29, 0x416000
	s_nop 0
	v_addc_co_u32_e32 v11, vcc, 0, v5, vcc
	v_add_co_u32_e32 v12, vcc, s29, v4
	s_mov_b32 s29, 0x418000
	s_nop 0
	v_addc_co_u32_e32 v13, vcc, 0, v5, vcc
	v_add_co_u32_e32 v14, vcc, s29, v4
	s_mov_b32 s29, 0x41a000
	s_nop 0
	v_addc_co_u32_e32 v15, vcc, 0, v5, vcc
	v_add_co_u32_e32 v16, vcc, s29, v4
	s_mov_b32 s29, 0x41c000
	s_nop 0
	v_addc_co_u32_e32 v17, vcc, 0, v5, vcc
	v_add_co_u32_e32 v18, vcc, s29, v4
	s_mov_b32 s29, 0x41e000
	s_nop 0
	v_addc_co_u32_e32 v19, vcc, 0, v5, vcc
	v_add_co_u32_e32 v20, vcc, s29, v4
	s_mov_b32 s29, 0x420000
	s_nop 0
	v_addc_co_u32_e32 v21, vcc, 0, v5, vcc
	global_load_dword v29, v[6:7], off
	global_load_dword v30, v[8:9], off
	global_load_dword v31, v[10:11], off
	global_load_dword v34, v[12:13], off
	global_load_dword v35, v[14:15], off
	global_load_dword v36, v[16:17], off
	global_load_dword v37, v[18:19], off
	global_load_dword v38, v[20:21], off
	v_add_co_u32_e32 v6, vcc, s29, v4
	s_mov_b32 s29, 0x422000
	s_nop 0
	v_addc_co_u32_e32 v7, vcc, 0, v5, vcc
	v_add_co_u32_e32 v8, vcc, s29, v4
	s_mov_b32 s29, 0x424000
	s_nop 0
	v_addc_co_u32_e32 v9, vcc, 0, v5, vcc
	v_add_co_u32_e32 v10, vcc, s29, v4
	s_mov_b32 s29, 0x426000
	s_nop 0
	v_addc_co_u32_e32 v11, vcc, 0, v5, vcc
	v_add_co_u32_e32 v12, vcc, s29, v4
	s_mov_b32 s29, 0x428000
	s_nop 0
	v_addc_co_u32_e32 v13, vcc, 0, v5, vcc
	v_add_co_u32_e32 v14, vcc, s29, v4
	s_mov_b32 s29, 0x42a000
	s_nop 0
	v_addc_co_u32_e32 v15, vcc, 0, v5, vcc
	v_add_co_u32_e32 v16, vcc, s29, v4
	s_mov_b32 s29, 0x42c000
	s_nop 0
	v_addc_co_u32_e32 v17, vcc, 0, v5, vcc
	v_add_co_u32_e32 v18, vcc, s29, v4
	s_mov_b32 s29, 0x42e000
	s_nop 0
	v_addc_co_u32_e32 v19, vcc, 0, v5, vcc
	v_add_co_u32_e32 v20, vcc, s29, v4
	s_mov_b32 s29, 0x430000
	s_nop 0
	v_addc_co_u32_e32 v21, vcc, 0, v5, vcc
	global_load_dword v39, v[6:7], off
	global_load_dword v40, v[8:9], off
	global_load_dword v42, v[10:11], off
	global_load_dword v44, v[12:13], off
	global_load_dword v46, v[14:15], off
	global_load_dword v48, v[16:17], off
	global_load_dword v50, v[18:19], off
	s_nop 0
	global_load_dword v20, v[20:21], off
	v_add_co_u32_e32 v6, vcc, s29, v4
	s_mov_b32 s29, 0x432000
	s_nop 0
	v_addc_co_u32_e32 v7, vcc, 0, v5, vcc
	v_add_co_u32_e32 v8, vcc, s29, v4
	s_mov_b32 s29, 0x434000
	s_nop 0
	v_addc_co_u32_e32 v9, vcc, 0, v5, vcc
	v_add_co_u32_e32 v10, vcc, s29, v4
	s_mov_b32 s29, 0x436000
	s_nop 0
	v_addc_co_u32_e32 v11, vcc, 0, v5, vcc
	v_add_co_u32_e32 v12, vcc, s29, v4
	s_mov_b32 s29, 0x438000
	s_nop 0
	v_addc_co_u32_e32 v13, vcc, 0, v5, vcc
	v_add_co_u32_e32 v14, vcc, s29, v4
	s_mov_b32 s29, 0x43a000
	s_nop 0
	v_addc_co_u32_e32 v15, vcc, 0, v5, vcc
	v_add_co_u32_e32 v16, vcc, s29, v4
	s_mov_b32 s29, 0x43c000
	s_nop 0
	v_addc_co_u32_e32 v17, vcc, 0, v5, vcc
	v_add_co_u32_e32 v18, vcc, s29, v4
	s_mov_b32 s29, 0x43e000
	s_nop 0
	v_addc_co_u32_e32 v19, vcc, 0, v5, vcc
	v_add_co_u32_e32 v4, vcc, s29, v4
	s_lshl_b32 s28, s28, 1
	s_nop 0
	v_addc_co_u32_e32 v5, vcc, 0, v5, vcc
	global_load_dword v6, v[6:7], off
	s_nop 0
	global_load_dword v7, v[8:9], off
	s_nop 0
	global_load_dword v8, v[10:11], off
	global_load_dword v9, v[12:13], off
	s_nop 0
	global_load_dword v10, v[14:15], off
	global_load_dword v11, v[16:17], off
	global_load_dword v12, v[18:19], off
	s_nop 0
	global_load_dword v4, v[4:5], off
	s_waitcnt vmcnt(30)
; #define GAS __attribute__((address_space(1)))
; #define LAS __attribute__((address_space(3)))
; __device__ __forceinline__ unsigned pk2(float lo, float hi) { return f2bf(lo) | (f2bf(hi) << 16); }
; __device__ __forceinline__ void p0_transpose_item(const float* W, int K, int ldw, int N, bf16* WT, int kind, LAS float* scr, int item, int lane) {
;     ...
; #pragma unroll
;     for (int i = 0; i < 32; ++i) scr[(2 * i + (lane >> 5)) * 33 + (lane & 31)] = t_[i];
;     asm volatile("s_waitcnt lgkmcnt(0)" ::: "memory");
;     const int c = lane & 7;
; #pragma unroll
;     for (int j = 0; j < 4; ++j) { const int n = (lane >> 3) + 8 * j; const LAS float* s = scr + (8 * c) * 33 + n;
;         v4u o; o.x = pk2(s[0 * 33], s[1 * 33]); o.y = pk2(s[2 * 33], s[3 * 33]); o.z = pk2(s[4 * 33], s[5 * 33]); o.w = pk2(s[6 * 33], s[7 * 33]);
;         *(GAS v4u*)(WT + (size_t)(n0 + n) * K + k0 + 8 * c) = o; }
;     asm volatile("s_waitcnt lgkmcnt(0)" ::: "memory");
	ds_write2_b32 v41, v2, v22 offset1:66
	s_waitcnt vmcnt(28)
	ds_write2_b32 v41, v23, v24 offset0:132 offset1:198
	v_add_u32_e32 v2, 0x400, v41
	s_waitcnt vmcnt(26)
	ds_write2_b32 v2, v25, v26 offset0:8 offset1:74
	s_waitcnt vmcnt(24)
	ds_write2_b32 v2, v27, v28 offset0:140 offset1:206
	v_add_u32_e32 v2, 0x800, v41
	s_waitcnt vmcnt(22)
	ds_write2_b32 v2, v29, v30 offset0:16 offset1:82
	s_waitcnt vmcnt(20)
	ds_write2_b32 v2, v31, v34 offset0:148 offset1:214
	v_add_u32_e32 v2, 0xc00, v41
	s_waitcnt vmcnt(18)
	ds_write2_b32 v2, v35, v36 offset0:24 offset1:90
	s_waitcnt vmcnt(16)
	ds_write2_b32 v2, v37, v38 offset0:156 offset1:222
	v_add_u32_e32 v2, 0x1000, v41
	s_waitcnt vmcnt(14)
	ds_write2_b32 v2, v39, v40 offset0:32 offset1:98
	s_waitcnt vmcnt(12)
	ds_write2_b32 v2, v42, v44 offset0:164 offset1:230
	v_add_u32_e32 v2, 0x1400, v41
	s_waitcnt vmcnt(10)
	ds_write2_b32 v2, v46, v48 offset0:40 offset1:106
	s_waitcnt vmcnt(8)
	ds_write2_b32 v2, v50, v20 offset0:172 offset1:238
	v_add_u32_e32 v2, 0x1800, v41
	s_waitcnt vmcnt(6)
	ds_write2_b32 v2, v6, v7 offset0:48 offset1:114
	s_waitcnt vmcnt(4)
	ds_write2_b32 v2, v8, v9 offset0:180 offset1:246
	v_add_u32_e32 v2, 0x1c00, v41
	s_waitcnt vmcnt(2)
	ds_write2_b32 v2, v10, v11 offset0:56 offset1:122
	s_waitcnt vmcnt(0)
	ds_write2_b32 v2, v12, v4 offset0:188 offset1:254
	s_waitcnt lgkmcnt(0)
	ds_read2_b32 v[8:9], v45 offset1:8
	ds_read2_b32 v[12:13], v45 offset0:33 offset1:41
	s_add_u32 s26, s26, s28
	ds_read2_b32 v[14:15], v45 offset0:66 offset1:74
	s_addc_u32 s27, s27, 0
	v_lshlrev_b32_e32 v2, 1, v0
	ds_read2_b32 v[16:17], v45 offset0:99 offset1:107
	v_lshl_add_u64 v[4:5], s[26:27], 0, v[2:3]
	s_mov_b64 s[26:27], 0x99a40000
	s_waitcnt lgkmcnt(3)
	v_bfe_u32 v2, v8, 16, 1
	v_lshl_add_u64 v[10:11], v[4:5], 0, s[26:27]
	v_add3_u32 v2, v8, v2, s38
	s_waitcnt lgkmcnt(2)
	v_bfe_u32 v4, v12, 16, 1
	ds_read2_b32 v[18:19], v45 offset0:132 offset1:140
	v_lshrrev_b32_e32 v2, 16, v2
	v_add3_u32 v4, v12, v4, s38
	ds_read2_b32 v[20:21], v45 offset0:165 offset1:173
	v_and_or_b32 v4, v4, s39, v2
	s_waitcnt lgkmcnt(3)
	s_waitcnt lgkmcnt(2)
	ds_read2_b32 v[22:23], v45 offset0:198 offset1:206
	ds_read2_b32 v[24:25], v45 offset0:231 offset1:239
	v_cvt_pk_bf16_f32 v5, v14, v16
	s_waitcnt lgkmcnt(3)
	s_waitcnt lgkmcnt(2)
	v_cvt_pk_bf16_f32 v6, v18, v20
	s_waitcnt lgkmcnt(1)
	v_add_u32_e32 v26, s4, v43
	s_waitcnt lgkmcnt(0)
	v_ashrrev_i32_e32 v27, 31, v26
	v_lshlrev_b64 v[26:27], 11, v[26:27]
	v_cvt_pk_bf16_f32 v7, v22, v24
	v_lshl_add_u64 v[26:27], v[10:11], 0, v[26:27]
	v_bfe_u32 v2, v9, 16, 1
	global_store_dwordx4 v[26:27], v[4:7], off
	v_add3_u32 v2, v9, v2, s38
	v_lshrrev_b32_e32 v2, 16, v2
	v_bfe_u32 v4, v13, 16, 1
	v_add3_u32 v4, v13, v4, s38
	v_and_or_b32 v4, v4, s39, v2
	v_cvt_pk_bf16_f32 v5, v15, v17
	v_cvt_pk_bf16_f32 v6, v19, v21
	v_add_u32_e32 v8, s4, v47
	v_ashrrev_i32_e32 v9, 31, v8
	v_lshlrev_b64 v[8:9], 11, v[8:9]
	v_cvt_pk_bf16_f32 v7, v23, v25
	ds_read2_b32 v[12:13], v45 offset0:16 offset1:24
	v_lshl_add_u64 v[8:9], v[10:11], 0, v[8:9]
	global_store_dwordx4 v[8:9], v[4:7], off
	ds_read2_b32 v[8:9], v45 offset0:49 offset1:57
	ds_read2_b32 v[14:15], v45 offset0:82 offset1:90
	ds_read2_b32 v[16:17], v45 offset0:115 offset1:123
	s_waitcnt lgkmcnt(3)
	s_waitcnt lgkmcnt(2)
	ds_read2_b32 v[18:19], v45 offset0:148 offset1:156
	ds_read2_b32 v[20:21], v45 offset0:181 offset1:189
	v_cvt_pk_bf16_f32 v4, v12, v8
	s_waitcnt lgkmcnt(3)
	s_waitcnt lgkmcnt(2)
	ds_read2_b32 v[22:23], v45 offset0:214 offset1:222
	ds_read2_b32 v[24:25], v45 offset0:247 offset1:255
	v_cvt_pk_bf16_f32 v5, v14, v16
	s_waitcnt lgkmcnt(3)
	s_waitcnt lgkmcnt(2)
	v_cvt_pk_bf16_f32 v6, v18, v20
	s_waitcnt lgkmcnt(1)
	v_add_u32_e32 v26, s4, v49
	s_waitcnt lgkmcnt(0)
	v_ashrrev_i32_e32 v27, 31, v26
	v_lshlrev_b64 v[26:27], 11, v[26:27]
	v_cvt_pk_bf16_f32 v7, v22, v24
	v_lshl_add_u64 v[26:27], v[10:11], 0, v[26:27]
	v_bfe_u32 v2, v13, 16, 1
	global_store_dwordx4 v[26:27], v[4:7], off
	v_add3_u32 v2, v13, v2, s38
	v_lshrrev_b32_e32 v2, 16, v2
	v_bfe_u32 v4, v9, 16, 1
	v_add3_u32 v4, v9, v4, s38
	v_and_or_b32 v4, v4, s39, v2
	v_cvt_pk_bf16_f32 v5, v15, v17
	v_cvt_pk_bf16_f32 v6, v19, v21
	v_add_u32_e32 v8, s4, v51
	v_ashrrev_i32_e32 v9, 31, v8
	v_lshlrev_b64 v[8:9], 11, v[8:9]
	v_cvt_pk_bf16_f32 v7, v23, v25
	v_lshl_add_u64 v[8:9], v[10:11], 0, v[8:9]
	global_store_dwordx4 v[8:9], v[4:7], off
	s_waitcnt lgkmcnt(0)

; __device__ __forceinline__ bf16* lw(const Frame& F, int l, size_t off) { return (bf16*)(wsq(F.ws) + WS_W + (size_t)l * LW_SIZE + off); }
; __device__ __forceinline__ void p0_transpose_item(const float* W, int K, int ldw, int N, bf16* WT, int kind, LAS float* scr, int item, int lane) {
;     const int nblk = N / 32, kb = item / nblk, nb = item % nblk, k0 = 64 * kb, n0 = 32 * nb;
;     const int sc = srccol(kind, n0 + (lane & 31));
;     float t_[32];
; #pragma unroll
;     for (int i = 0; i < 32; ++i) t_[i] = W[(size_t)(k0 + 2 * i + (lane >> 5)) * ldw + sc];
; __device__ __forceinline__ void p0_prologue(Frame& F) {
;     ...
;             if (r < I_SQ) { p0_transpose_item(in_ptr(IN_WBR) + (size_t)(l * 3 + 0) * D * D, D, D, D, lw(F, l, LW_BR), 0, scr, r, tc.lane); continue; } r -= I_SQ;
.LBB0_33:
	s_andn2_b64 vcc, exec, s[26:27]
	s_cbranch_vccnz .LBB0_35
	s_mov_b64 s[26:27], s[0:1]
	s_load_dwordx2 s[26:27], s[26:27], 0x58
	s_lshl_b64 s[28:29], s[16:17], 2
	s_mov_b64 s[30:31], s[46:47]
	s_waitcnt lgkmcnt(0)
	s_add_u32 s84, s26, s28
	s_addc_u32 s85, s27, s29
	s_add_u32 s26, s30, s78
	s_addc_u32 s27, s31, 0
	s_lshl_b32 s28, s77, 1
	s_lshl_b32 s4, s77, 5
	s_add_i32 s28, s28, 0x19600
	s_and_b32 s4, s4, 0x3e0
	s_and_b32 s28, s28, 0x1ffc0
	v_or_b32_e32 v2, s4, v1
	v_add_u32_e32 v4, s28, v33
	v_lshlrev_b32_e32 v2, 2, v2
	v_ashrrev_i32_e32 v5, 31, v4
	v_lshl_add_u64 v[6:7], s[84:85], 0, v[2:3]
	v_lshlrev_b64 v[4:5], 12, v[4:5]
	v_lshl_add_u64 v[4:5], v[6:7], 0, v[4:5]
	v_add_co_u32_e32 v6, vcc, s41, v4
	s_lshl_b32 s28, s28, 1
	s_nop 0
	v_addc_co_u32_e32 v7, vcc, 0, v5, vcc
	v_add_co_u32_e32 v8, vcc, s42, v4
	s_add_u32 s26, s26, s28
	s_nop 0
	v_addc_co_u32_e32 v9, vcc, 0, v5, vcc
	v_add_co_u32_e32 v10, vcc, s43, v4
	s_addc_u32 s27, s27, 0
	s_nop 0
	v_addc_co_u32_e32 v11, vcc, 0, v5, vcc
	v_add_co_u32_e32 v12, vcc, s48, v4
	s_nop 1
	v_addc_co_u32_e32 v13, vcc, 0, v5, vcc
	v_add_co_u32_e32 v14, vcc, s49, v4
	s_nop 1
	v_addc_co_u32_e32 v15, vcc, 0, v5, vcc
	v_add_co_u32_e32 v16, vcc, s50, v4
	s_nop 1
	v_addc_co_u32_e32 v17, vcc, 0, v5, vcc
	v_add_co_u32_e32 v18, vcc, s37, v4
	s_nop 1
	v_addc_co_u32_e32 v19, vcc, 0, v5, vcc
	global_load_dword v2, v[4:5], off
	global_load_dword v22, v[6:7], off
	global_load_dword v23, v[8:9], off
	global_load_dword v24, v[10:11], off
	global_load_dword v25, v[12:13], off
	global_load_dword v26, v[14:15], off
	global_load_dword v27, v[16:17], off
	global_load_dword v28, v[18:19], off
	v_add_co_u32_e32 v6, vcc, s51, v4
	s_nop 1
	v_addc_co_u32_e32 v7, vcc, 0, v5, vcc
	v_add_co_u32_e32 v8, vcc, s52, v4
	s_nop 1
	v_addc_co_u32_e32 v9, vcc, 0, v5, vcc
	v_add_co_u32_e32 v10, vcc, s53, v4
	s_nop 1
	v_addc_co_u32_e32 v11, vcc, 0, v5, vcc
	v_add_co_u32_e32 v12, vcc, s54, v4
	s_nop 1
	v_addc_co_u32_e32 v13, vcc, 0, v5, vcc
	v_add_co_u32_e32 v14, vcc, s55, v4
	s_nop 1
	v_addc_co_u32_e32 v15, vcc, 0, v5, vcc
	v_add_co_u32_e32 v16, vcc, s56, v4
	s_nop 1
	v_addc_co_u32_e32 v17, vcc, 0, v5, vcc
	v_add_co_u32_e32 v18, vcc, s57, v4
	s_nop 1
	v_addc_co_u32_e32 v19, vcc, 0, v5, vcc
	v_add_co_u32_e32 v20, vcc, s58, v4
	s_nop 1
	v_addc_co_u32_e32 v21, vcc, 0, v5, vcc
	global_load_dword v29, v[6:7], off
	global_load_dword v30, v[8:9], off
	global_load_dword v31, v[10:11], off
	global_load_dword v34, v[12:13], off
	global_load_dword v35, v[14:15], off
	global_load_dword v36, v[16:17], off
	global_load_dword v37, v[18:19], off
	global_load_dword v38, v[20:21], off
	v_add_co_u32_e32 v6, vcc, s59, v4
	s_nop 1
	v_addc_co_u32_e32 v7, vcc, 0, v5, vcc
	v_add_co_u32_e32 v8, vcc, s60, v4
	s_nop 1
	v_addc_co_u32_e32 v9, vcc, 0, v5, vcc
	v_add_co_u32_e32 v10, vcc, s61, v4
	s_nop 1
	v_addc_co_u32_e32 v11, vcc, 0, v5, vcc
	v_add_co_u32_e32 v12, vcc, s62, v4
	s_nop 1
	v_addc_co_u32_e32 v13, vcc, 0, v5, vcc
	v_add_co_u32_e32 v14, vcc, s63, v4
	s_nop 1
	v_addc_co_u32_e32 v15, vcc, 0, v5, vcc
	v_add_co_u32_e32 v16, vcc, s64, v4
	s_nop 1
	v_addc_co_u32_e32 v17, vcc, 0, v5, vcc
	v_add_co_u32_e32 v18, vcc, s65, v4
	s_nop 1
	v_addc_co_u32_e32 v19, vcc, 0, v5, vcc
	v_add_co_u32_e32 v20, vcc, s66, v4
	s_nop 1
	v_addc_co_u32_e32 v21, vcc, 0, v5, vcc
	global_load_dword v39, v[6:7], off
	global_load_dword v40, v[8:9], off
	global_load_dword v42, v[10:11], off
	global_load_dword v44, v[12:13], off
	global_load_dword v46, v[14:15], off
	global_load_dword v48, v[16:17], off
	global_load_dword v50, v[18:19], off
	s_nop 0
	global_load_dword v20, v[20:21], off
	v_add_co_u32_e32 v6, vcc, s67, v4
	s_nop 1
	v_addc_co_u32_e32 v7, vcc, 0, v5, vcc
	v_add_co_u32_e32 v8, vcc, s68, v4
	s_nop 1
	v_addc_co_u32_e32 v9, vcc, 0, v5, vcc
	v_add_co_u32_e32 v10, vcc, s69, v4
	s_nop 1
	v_addc_co_u32_e32 v11, vcc, 0, v5, vcc
	v_add_co_u32_e32 v12, vcc, s70, v4
	s_nop 1
	v_addc_co_u32_e32 v13, vcc, 0, v5, vcc
	v_add_co_u32_e32 v14, vcc, s71, v4
	s_nop 1
	v_addc_co_u32_e32 v15, vcc, 0, v5, vcc
	v_add_co_u32_e32 v16, vcc, s72, v4
	s_nop 1
	v_addc_co_u32_e32 v17, vcc, 0, v5, vcc
	v_add_co_u32_e32 v18, vcc, s73, v4
	s_nop 1
	v_addc_co_u32_e32 v19, vcc, 0, v5, vcc
	v_add_co_u32_e32 v4, vcc, s74, v4
	s_nop 1
	v_addc_co_u32_e32 v5, vcc, 0, v5, vcc
	global_load_dword v6, v[6:7], off
	s_nop 0
	global_load_dword v7, v[8:9], off
	s_nop 0
	global_load_dword v8, v[10:11], off
	global_load_dword v9, v[12:13], off
	s_nop 0
	global_load_dword v10, v[14:15], off
	global_load_dword v11, v[16:17], off
	global_load_dword v12, v[18:19], off
	s_nop 0
	global_load_dword v4, v[4:5], off
	s_waitcnt vmcnt(30)
; #define GAS __attribute__((address_space(1)))
; #define LAS __attribute__((address_space(3)))
; __device__ __forceinline__ unsigned pk2(float lo, float hi) { return f2bf(lo) | (f2bf(hi) << 16); }
; __device__ __forceinline__ void p0_transpose_item(const float* W, int K, int ldw, int N, bf16* WT, int kind, LAS float* scr, int item, int lane) {
;     ...
; #pragma unroll
;     for (int i = 0; i < 32; ++i) scr[(2 * i + (lane >> 5)) * 33 + (lane & 31)] = t_[i];
;     asm volatile("s_waitcnt lgkmcnt(0)" ::: "memory");
;     const int c = lane & 7;
; #pragma unroll
;     for (int j = 0; j < 4; ++j) { const int n = (lane >> 3) + 8 * j; const LAS float* s = scr + (8 * c) * 33 + n;
;         v4u o; o.x = pk2(s[0 * 33], s[1 * 33]); o.y = pk2(s[2 * 33], s[3 * 33]); o.z = pk2(s[4 * 33], s[5 * 33]); o.w = pk2(s[6 * 33], s[7 * 33]);
;         *(GAS v4u*)(WT + (size_t)(n0 + n) * K + k0 + 8 * c) = o; }
;     asm volatile("s_waitcnt lgkmcnt(0)" ::: "memory");
	ds_write2_b32 v41, v2, v22 offset1:66
	s_waitcnt vmcnt(28)
	ds_write2_b32 v41, v23, v24 offset0:132 offset1:198
	v_add_u32_e32 v2, 0x400, v41
	s_waitcnt vmcnt(26)
	ds_write2_b32 v2, v25, v26 offset0:8 offset1:74
	s_waitcnt vmcnt(24)
	ds_write2_b32 v2, v27, v28 offset0:140 offset1:206
	v_add_u32_e32 v2, 0x800, v41
	s_waitcnt vmcnt(22)
	ds_write2_b32 v2, v29, v30 offset0:16 offset1:82
	s_waitcnt vmcnt(20)
	ds_write2_b32 v2, v31, v34 offset0:148 offset1:214
	v_add_u32_e32 v2, 0xc00, v41
	s_waitcnt vmcnt(18)
	ds_write2_b32 v2, v35, v36 offset0:24 offset1:90
	s_waitcnt vmcnt(16)
	ds_write2_b32 v2, v37, v38 offset0:156 offset1:222
	v_add_u32_e32 v2, 0x1000, v41
	s_waitcnt vmcnt(14)
	ds_write2_b32 v2, v39, v40 offset0:32 offset1:98
	s_waitcnt vmcnt(12)
	ds_write2_b32 v2, v42, v44 offset0:164 offset1:230
	v_add_u32_e32 v2, 0x1400, v41
	s_waitcnt vmcnt(10)
	ds_write2_b32 v2, v46, v48 offset0:40 offset1:106
	s_waitcnt vmcnt(8)
	ds_write2_b32 v2, v50, v20 offset0:172 offset1:238
	v_add_u32_e32 v2, 0x1800, v41
	s_waitcnt vmcnt(6)
	ds_write2_b32 v2, v6, v7 offset0:48 offset1:114
	s_waitcnt vmcnt(4)
	ds_write2_b32 v2, v8, v9 offset0:180 offset1:246
	v_add_u32_e32 v2, 0x1c00, v41
	s_waitcnt vmcnt(2)
	ds_write2_b32 v2, v10, v11 offset0:56 offset1:122
	s_waitcnt vmcnt(0)
	ds_write2_b32 v2, v12, v4 offset0:188 offset1:254
	s_waitcnt lgkmcnt(0)
	ds_read2_b32 v[8:9], v45 offset1:8
	ds_read2_b32 v[12:13], v45 offset0:33 offset1:41
	ds_read2_b32 v[14:15], v45 offset0:66 offset1:74
	v_lshlrev_b32_e32 v2, 1, v0
	ds_read2_b32 v[16:17], v45 offset0:99 offset1:107
	v_lshl_add_u64 v[4:5], s[26:27], 0, v[2:3]
	s_mov_b64 s[26:27], 0x99840000
	s_waitcnt lgkmcnt(3)
	v_bfe_u32 v2, v8, 16, 1
	v_lshl_add_u64 v[10:11], v[4:5], 0, s[26:27]
	v_add3_u32 v2, v8, v2, s38
	s_waitcnt lgkmcnt(2)
	v_bfe_u32 v4, v12, 16, 1
	ds_read2_b32 v[18:19], v45 offset0:132 offset1:140
	v_lshrrev_b32_e32 v2, 16, v2
	v_add3_u32 v4, v12, v4, s38
	ds_read2_b32 v[20:21], v45 offset0:165 offset1:173
	v_and_or_b32 v4, v4, s39, v2
	s_waitcnt lgkmcnt(3)
	s_waitcnt lgkmcnt(2)
	ds_read2_b32 v[22:23], v45 offset0:198 offset1:206
	ds_read2_b32 v[24:25], v45 offset0:231 offset1:239
	v_cvt_pk_bf16_f32 v5, v14, v16
	s_waitcnt lgkmcnt(3)
	s_waitcnt lgkmcnt(2)
	v_cvt_pk_bf16_f32 v6, v18, v20
	s_waitcnt lgkmcnt(1)
	v_add_u32_e32 v26, s4, v43
	s_waitcnt lgkmcnt(0)
	v_ashrrev_i32_e32 v27, 31, v26
	v_lshlrev_b64 v[26:27], 11, v[26:27]
	v_cvt_pk_bf16_f32 v7, v22, v24
	v_lshl_add_u64 v[26:27], v[10:11], 0, v[26:27]
	v_bfe_u32 v2, v9, 16, 1
	global_store_dwordx4 v[26:27], v[4:7], off
	v_add3_u32 v2, v9, v2, s38
	v_lshrrev_b32_e32 v2, 16, v2
	v_bfe_u32 v4, v13, 16, 1
	v_add3_u32 v4, v13, v4, s38
	v_and_or_b32 v4, v4, s39, v2
	v_cvt_pk_bf16_f32 v5, v15, v17
	v_cvt_pk_bf16_f32 v6, v19, v21
	v_add_u32_e32 v8, s4, v47
	v_ashrrev_i32_e32 v9, 31, v8
	v_lshlrev_b64 v[8:9], 11, v[8:9]
	v_cvt_pk_bf16_f32 v7, v23, v25
	ds_read2_b32 v[12:13], v45 offset0:16 offset1:24
	v_lshl_add_u64 v[8:9], v[10:11], 0, v[8:9]
	global_store_dwordx4 v[8:9], v[4:7], off
	ds_read2_b32 v[8:9], v45 offset0:49 offset1:57
	ds_read2_b32 v[14:15], v45 offset0:82 offset1:90
	ds_read2_b32 v[16:17], v45 offset0:115 offset1:123
	s_waitcnt lgkmcnt(3)
	s_waitcnt lgkmcnt(2)
	ds_read2_b32 v[18:19], v45 offset0:148 offset1:156
	ds_read2_b32 v[20:21], v45 offset0:181 offset1:189
	v_cvt_pk_bf16_f32 v4, v12, v8
	s_waitcnt lgkmcnt(3)
	s_waitcnt lgkmcnt(2)
	ds_read2_b32 v[22:23], v45 offset0:214 offset1:222
	ds_read2_b32 v[24:25], v45 offset0:247 offset1:255
	v_cvt_pk_bf16_f32 v5, v14, v16
	s_waitcnt lgkmcnt(3)
	s_waitcnt lgkmcnt(2)
	v_cvt_pk_bf16_f32 v6, v18, v20
	s_waitcnt lgkmcnt(1)
	v_add_u32_e32 v26, s4, v49
	s_waitcnt lgkmcnt(0)
	v_ashrrev_i32_e32 v27, 31, v26
	v_lshlrev_b64 v[26:27], 11, v[26:27]
	v_cvt_pk_bf16_f32 v7, v22, v24
	v_lshl_add_u64 v[26:27], v[10:11], 0, v[26:27]
	v_bfe_u32 v2, v13, 16, 1
	global_store_dwordx4 v[26:27], v[4:7], off
	v_add3_u32 v2, v13, v2, s38
	v_lshrrev_b32_e32 v2, 16, v2
	v_bfe_u32 v4, v9, 16, 1
	v_add3_u32 v4, v9, v4, s38
	v_and_or_b32 v4, v4, s39, v2
	v_cvt_pk_bf16_f32 v5, v15, v17
	v_cvt_pk_bf16_f32 v6, v19, v21
	v_add_u32_e32 v8, s4, v51
	v_ashrrev_i32_e32 v9, 31, v8
	v_lshlrev_b64 v[8:9], 11, v[8:9]
	v_cvt_pk_bf16_f32 v7, v23, v25
	v_lshl_add_u64 v[8:9], v[10:11], 0, v[8:9]
	global_store_dwordx4 v[8:9], v[4:7], off
	s_waitcnt lgkmcnt(0)

; #define LAS __attribute__((address_space(3)))
; __device__ __forceinline__ bf16* lw(const Frame& F, int l, size_t off) { return (bf16*)(wsq(F.ws) + WS_W + (size_t)l * LW_SIZE + off); }
; __device__ __forceinline__ int srccol(int kind, int n) {
;     if (kind == 1) { const int pn = n >> 8, p = n & 255, bj = p >> 7, wc = (p >> 5) & 3, fq = (p >> 3) & 3, nn = (p >> 2) & 1, e = p & 3;
;         return (nn ? DFF : 0) + 128 * pn + 64 * bj + 16 * wc + 4 * fq + e; }
;     if (kind == 2 && n < 1024) { const int hb_ = n & ~127, p = n & 127, wc = p >> 5, fq = (p >> 3) & 3, nn = (p >> 2) & 1, e = p & 3;
;         return hb_ + 16 * wc + 4 * fq + e + 64 * nn; }
;     return n;
; }
; __device__ __forceinline__ void p0_transpose_item(const float* W, int K, int ldw, int N, bf16* WT, int kind, LAS float* scr, int item, int lane) {
;     const int nblk = N / 32, kb = item / nblk, nb = item % nblk, k0 = 64 * kb, n0 = 32 * nb;
;     const int sc = srccol(kind, n0 + (lane & 31));
;     float t_[32];
; #pragma unroll
;     for (int i = 0; i < 32; ++i) t_[i] = W[(size_t)(k0 + 2 * i + (lane >> 5)) * ldw + sc];
; __device__ __forceinline__ void p0_prologue(Frame& F) {
;     ...
;             if (r < I_IN) { p0_transpose_item(in_ptr(IN_WIN) + (size_t)l * D * DIN, D, DIN, DIN, lw(F, l, LW_IN), 2, scr, r, tc.lane); continue; } r -= I_IN;
.LBB0_36:
	s_andn2_b64 vcc, exec, s[26:27]
	s_cbranch_vccnz .LBB0_38
	s_mov_b64 s[26:27], s[0:1]
	s_load_dwordx2 s[26:27], s[26:27], 0x38
	s_mov_b64 s[28:29], s[46:47]
	s_waitcnt lgkmcnt(0)
	s_add_u32 s26, s26, s24
	s_addc_u32 s27, s27, s25
	s_add_u32 s28, s28, s78
	s_addc_u32 s29, s29, 0
	s_add_i32 s4, s77, 0xdf00
	s_and_b32 s30, s4, 0xffff
	s_mul_i32 s30, s30, 0xcccd
	s_lshr_b32 s30, s30, 24
	s_mul_i32 s31, s30, 0x140
	s_sub_i32 s4, s4, s31
	s_lshl_b32 s31, s4, 5
	s_and_b32 s84, s4, 0xffff
	s_and_b32 s4, s31, 0xffe0
	v_or_b32_e32 v2, s4, v1
	v_lshrrev_b32_e32 v4, 1, v2
	v_mov_b32_e32 v5, s4
	s_movk_i32 s31, 0x3f83
	s_cmp_lt_u32 s84, 32
	v_and_b32_e32 v4, 60, v4
	v_bitop3_b32 v5, v1, s31, v5 bitop3:0xc8
	v_or3_b32 v4, v5, v53, v4
	s_cselect_b64 vcc, -1, 0
	v_cndmask_b32_e32 v2, v2, v4, vcc
	v_lshl_add_u32 v22, s30, 6, v33
	v_lshlrev_b32_e32 v2, 2, v2
	v_lshl_add_u64 v[4:5], s[26:27], 0, v[2:3]
	v_add_u32_e32 v2, 2, v22
	v_mad_i64_i32 v[8:9], s[26:27], v2, s49, v[4:5]
	v_add_u32_e32 v2, 4, v22
	v_mad_i64_i32 v[10:11], s[26:27], v2, s49, v[4:5]
	v_add_u32_e32 v2, 6, v22
	v_mad_i64_i32 v[12:13], s[26:27], v2, s49, v[4:5]
	v_add_u32_e32 v2, 8, v22
	v_mad_i64_i32 v[14:15], s[26:27], v2, s49, v[4:5]
	v_add_u32_e32 v2, 10, v22
	v_mad_i64_i32 v[16:17], s[26:27], v2, s49, v[4:5]
	v_add_u32_e32 v2, 12, v22
	v_mad_i64_i32 v[18:19], s[26:27], v2, s49, v[4:5]
	v_add_u32_e32 v2, 14, v22
	v_mad_i64_i32 v[6:7], s[26:27], v22, s49, v[4:5]
	v_mad_i64_i32 v[20:21], s[26:27], v2, s49, v[4:5]
	global_load_dword v2, v[6:7], off
	global_load_dword v23, v[8:9], off
	global_load_dword v24, v[10:11], off
	global_load_dword v25, v[12:13], off
	global_load_dword v26, v[14:15], off
	global_load_dword v27, v[16:17], off
	global_load_dword v28, v[18:19], off
	global_load_dword v29, v[20:21], off
	v_add_u32_e32 v6, 16, v22
	v_add_u32_e32 v8, 18, v22
	v_add_u32_e32 v10, 20, v22
	v_add_u32_e32 v12, 22, v22
	v_add_u32_e32 v14, 24, v22
	v_add_u32_e32 v16, 26, v22
	v_add_u32_e32 v18, 28, v22
	v_add_u32_e32 v20, 30, v22
	v_mad_i64_i32 v[6:7], s[26:27], v6, s49, v[4:5]
	v_mad_i64_i32 v[8:9], s[26:27], v8, s49, v[4:5]
	v_mad_i64_i32 v[10:11], s[26:27], v10, s49, v[4:5]
	v_mad_i64_i32 v[12:13], s[26:27], v12, s49, v[4:5]
	v_mad_i64_i32 v[14:15], s[26:27], v14, s49, v[4:5]
	v_mad_i64_i32 v[16:17], s[26:27], v16, s49, v[4:5]
	v_mad_i64_i32 v[18:19], s[26:27], v18, s49, v[4:5]
	v_mad_i64_i32 v[20:21], s[26:27], v20, s49, v[4:5]
	global_load_dword v30, v[6:7], off
	global_load_dword v31, v[8:9], off
	global_load_dword v34, v[10:11], off
	global_load_dword v35, v[12:13], off
	global_load_dword v36, v[14:15], off
	global_load_dword v37, v[16:17], off
	global_load_dword v38, v[18:19], off
	global_load_dword v39, v[20:21], off
	v_add_u32_e32 v6, 32, v22
	v_add_u32_e32 v8, 34, v22
	v_add_u32_e32 v10, 36, v22
	v_add_u32_e32 v12, 38, v22
	v_add_u32_e32 v14, 40, v22
	v_add_u32_e32 v16, 42, v22
	v_add_u32_e32 v18, 44, v22
	v_add_u32_e32 v20, 46, v22
	v_mad_i64_i32 v[6:7], s[26:27], v6, s49, v[4:5]
	v_mad_i64_i32 v[8:9], s[26:27], v8, s49, v[4:5]
	v_mad_i64_i32 v[10:11], s[26:27], v10, s49, v[4:5]
	v_mad_i64_i32 v[12:13], s[26:27], v12, s49, v[4:5]
	v_mad_i64_i32 v[14:15], s[26:27], v14, s49, v[4:5]
	v_mad_i64_i32 v[16:17], s[26:27], v16, s49, v[4:5]
	v_mad_i64_i32 v[18:19], s[26:27], v18, s49, v[4:5]
	v_mad_i64_i32 v[20:21], s[26:27], v20, s49, v[4:5]
	global_load_dword v40, v[6:7], off
	global_load_dword v42, v[8:9], off
	global_load_dword v44, v[10:11], off
	global_load_dword v46, v[12:13], off
	global_load_dword v48, v[14:15], off
	global_load_dword v50, v[16:17], off
	global_load_dword v52, v[18:19], off
	s_nop 0
	global_load_dword v20, v[20:21], off
	v_add_u32_e32 v6, 48, v22
	v_add_u32_e32 v8, 50, v22
	v_add_u32_e32 v10, 52, v22
	v_add_u32_e32 v12, 54, v22
	v_add_u32_e32 v14, 56, v22
	v_add_u32_e32 v16, 58, v22
	v_add_u32_e32 v18, 60, v22
	v_add_u32_e32 v21, 62, v22
	v_mad_i64_i32 v[6:7], s[26:27], v6, s49, v[4:5]
	v_mad_i64_i32 v[8:9], s[26:27], v8, s49, v[4:5]
	v_mad_i64_i32 v[10:11], s[26:27], v10, s49, v[4:5]
	v_mad_i64_i32 v[12:13], s[26:27], v12, s49, v[4:5]
	v_mad_i64_i32 v[14:15], s[26:27], v14, s49, v[4:5]
	v_mad_i64_i32 v[16:17], s[26:27], v16, s49, v[4:5]
	v_mad_i64_i32 v[18:19], s[26:27], v18, s49, v[4:5]
	v_mad_i64_i32 v[4:5], s[26:27], v21, s49, v[4:5]
	global_load_dword v6, v[6:7], off
	s_nop 0
	global_load_dword v7, v[8:9], off
	s_nop 0
	global_load_dword v8, v[10:11], off
	global_load_dword v9, v[12:13], off
	s_nop 0
	global_load_dword v10, v[14:15], off
	global_load_dword v11, v[16:17], off
	global_load_dword v12, v[18:19], off
	s_nop 0
	global_load_dword v4, v[4:5], off
	s_waitcnt vmcnt(30)
; #define GAS __attribute__((address_space(1)))
; #define LAS __attribute__((address_space(3)))
; __device__ __forceinline__ unsigned pk2(float lo, float hi) { return f2bf(lo) | (f2bf(hi) << 16); }
; __device__ __forceinline__ void p0_transpose_item(const float* W, int K, int ldw, int N, bf16* WT, int kind, LAS float* scr, int item, int lane) {
;     ...
; #pragma unroll
;     for (int i = 0; i < 32; ++i) scr[(2 * i + (lane >> 5)) * 33 + (lane & 31)] = t_[i];
;     asm volatile("s_waitcnt lgkmcnt(0)" ::: "memory");
;     const int c = lane & 7;
; #pragma unroll
;     for (int j = 0; j < 4; ++j) { const int n = (lane >> 3) + 8 * j; const LAS float* s = scr + (8 * c) * 33 + n;
;         v4u o; o.x = pk2(s[0 * 33], s[1 * 33]); o.y = pk2(s[2 * 33], s[3 * 33]); o.z = pk2(s[4 * 33], s[5 * 33]); o.w = pk2(s[6 * 33], s[7 * 33]);
;         *(GAS v4u*)(WT + (size_t)(n0 + n) * K + k0 + 8 * c) = o; }
;     asm volatile("s_waitcnt lgkmcnt(0)" ::: "memory");
	ds_write2_b32 v41, v2, v23 offset1:66
	s_waitcnt vmcnt(28)
	ds_write2_b32 v41, v24, v25 offset0:132 offset1:198
	v_add_u32_e32 v2, 0x400, v41
	s_waitcnt vmcnt(26)
	ds_write2_b32 v2, v26, v27 offset0:8 offset1:74
	s_waitcnt vmcnt(24)
	ds_write2_b32 v2, v28, v29 offset0:140 offset1:206
	v_add_u32_e32 v2, 0x800, v41
	s_waitcnt vmcnt(22)
	ds_write2_b32 v2, v30, v31 offset0:16 offset1:82
	s_waitcnt vmcnt(20)
	ds_write2_b32 v2, v34, v35 offset0:148 offset1:214
	v_add_u32_e32 v2, 0xc00, v41
	s_waitcnt vmcnt(18)
	ds_write2_b32 v2, v36, v37 offset0:24 offset1:90
	s_waitcnt vmcnt(16)
	ds_write2_b32 v2, v38, v39 offset0:156 offset1:222
	v_add_u32_e32 v2, 0x1000, v41
	s_waitcnt vmcnt(14)
	ds_write2_b32 v2, v40, v42 offset0:32 offset1:98
	s_waitcnt vmcnt(12)
	ds_write2_b32 v2, v44, v46 offset0:164 offset1:230
	v_add_u32_e32 v2, 0x1400, v41
	s_waitcnt vmcnt(10)
	ds_write2_b32 v2, v48, v50 offset0:40 offset1:106
	s_waitcnt vmcnt(8)
	ds_write2_b32 v2, v52, v20 offset0:172 offset1:238
	v_add_u32_e32 v2, 0x1800, v41
	s_waitcnt vmcnt(6)
	ds_write2_b32 v2, v6, v7 offset0:48 offset1:114
	s_waitcnt vmcnt(4)
	ds_write2_b32 v2, v8, v9 offset0:180 offset1:246
	v_add_u32_e32 v2, 0x1c00, v41
	s_waitcnt vmcnt(2)
	ds_write2_b32 v2, v10, v11 offset0:56 offset1:122
	s_waitcnt vmcnt(0)
	ds_write2_b32 v2, v12, v4 offset0:188 offset1:254
	s_waitcnt lgkmcnt(0)
	ds_read2_b32 v[8:9], v45 offset1:8
	ds_read2_b32 v[12:13], v45 offset0:33 offset1:41
	s_lshl_b32 s26, s30, 7
	s_add_u32 s26, s28, s26
	ds_read2_b32 v[14:15], v45 offset0:66 offset1:74
	s_addc_u32 s27, s29, 0
	v_lshlrev_b32_e32 v2, 1, v0
	ds_read2_b32 v[16:17], v45 offset0:99 offset1:107
	v_lshl_add_u64 v[4:5], s[26:27], 0, v[2:3]
	s_mov_b64 s[26:27], 0x98440000
	s_waitcnt lgkmcnt(3)
	v_bfe_u32 v2, v8, 16, 1
	v_lshl_add_u64 v[10:11], v[4:5], 0, s[26:27]
	v_add3_u32 v2, v8, v2, s38
	s_waitcnt lgkmcnt(2)
	v_bfe_u32 v4, v12, 16, 1
	ds_read2_b32 v[18:19], v45 offset0:132 offset1:140
	v_lshrrev_b32_e32 v2, 16, v2
	v_add3_u32 v4, v12, v4, s38
	ds_read2_b32 v[20:21], v45 offset0:165 offset1:173
	v_and_or_b32 v4, v4, s39, v2
	s_waitcnt lgkmcnt(3)
	s_waitcnt lgkmcnt(2)
	ds_read2_b32 v[22:23], v45 offset0:198 offset1:206
	ds_read2_b32 v[24:25], v45 offset0:231 offset1:239
	v_cvt_pk_bf16_f32 v5, v14, v16
	s_waitcnt lgkmcnt(3)
	s_waitcnt lgkmcnt(2)
	v_cvt_pk_bf16_f32 v6, v18, v20
	s_waitcnt lgkmcnt(1)
	v_add_u32_e32 v26, s4, v43
	s_waitcnt lgkmcnt(0)
	v_ashrrev_i32_e32 v27, 31, v26
	v_lshlrev_b64 v[26:27], 11, v[26:27]
	v_cvt_pk_bf16_f32 v7, v22, v24
	v_lshl_add_u64 v[26:27], v[10:11], 0, v[26:27]
	v_bfe_u32 v2, v9, 16, 1
	global_store_dwordx4 v[26:27], v[4:7], off
	v_add3_u32 v2, v9, v2, s38
	v_lshrrev_b32_e32 v2, 16, v2
	v_bfe_u32 v4, v13, 16, 1
	v_add3_u32 v4, v13, v4, s38
	v_and_or_b32 v4, v4, s39, v2
	v_cvt_pk_bf16_f32 v5, v15, v17
	v_cvt_pk_bf16_f32 v6, v19, v21
	v_add_u32_e32 v8, s4, v47
	v_ashrrev_i32_e32 v9, 31, v8
	v_lshlrev_b64 v[8:9], 11, v[8:9]
	v_cvt_pk_bf16_f32 v7, v23, v25
	ds_read2_b32 v[12:13], v45 offset0:16 offset1:24
	v_lshl_add_u64 v[8:9], v[10:11], 0, v[8:9]
	global_store_dwordx4 v[8:9], v[4:7], off
	ds_read2_b32 v[8:9], v45 offset0:49 offset1:57
	ds_read2_b32 v[14:15], v45 offset0:82 offset1:90
	ds_read2_b32 v[16:17], v45 offset0:115 offset1:123
	s_waitcnt lgkmcnt(3)
	s_waitcnt lgkmcnt(2)
	ds_read2_b32 v[18:19], v45 offset0:148 offset1:156
	ds_read2_b32 v[20:21], v45 offset0:181 offset1:189
	v_cvt_pk_bf16_f32 v4, v12, v8
	s_waitcnt lgkmcnt(3)
	s_waitcnt lgkmcnt(2)
	ds_read2_b32 v[22:23], v45 offset0:214 offset1:222
	ds_read2_b32 v[24:25], v45 offset0:247 offset1:255
	v_cvt_pk_bf16_f32 v5, v14, v16
	s_waitcnt lgkmcnt(3)
	s_waitcnt lgkmcnt(2)
	v_cvt_pk_bf16_f32 v6, v18, v20
	s_waitcnt lgkmcnt(1)
	v_add_u32_e32 v26, s4, v49
	s_waitcnt lgkmcnt(0)
	v_ashrrev_i32_e32 v27, 31, v26
	v_lshlrev_b64 v[26:27], 11, v[26:27]
	v_cvt_pk_bf16_f32 v7, v22, v24
	v_lshl_add_u64 v[26:27], v[10:11], 0, v[26:27]
	v_bfe_u32 v2, v13, 16, 1
	global_store_dwordx4 v[26:27], v[4:7], off
	v_add3_u32 v2, v13, v2, s38
	v_lshrrev_b32_e32 v2, 16, v2
	v_bfe_u32 v4, v9, 16, 1
	v_add3_u32 v4, v9, v4, s38
	v_and_or_b32 v4, v4, s39, v2
	v_cvt_pk_bf16_f32 v5, v15, v17
	v_cvt_pk_bf16_f32 v6, v19, v21
	v_add_u32_e32 v8, s4, v51
	v_ashrrev_i32_e32 v9, 31, v8
	v_lshlrev_b64 v[8:9], 11, v[8:9]
	v_cvt_pk_bf16_f32 v7, v23, v25
	v_lshl_add_u64 v[8:9], v[10:11], 0, v[8:9]
	global_store_dwordx4 v[8:9], v[4:7], off
	s_waitcnt lgkmcnt(0)

; __device__ __forceinline__ bf16* lw(const Frame& F, int l, size_t off) { return (bf16*)(wsq(F.ws) + WS_W + (size_t)l * LW_SIZE + off); }
; __device__ __forceinline__ void p0_transpose_item(const float* W, int K, int ldw, int N, bf16* WT, int kind, LAS float* scr, int item, int lane) {
;     const int nblk = N / 32, kb = item / nblk, nb = item % nblk, k0 = 64 * kb, n0 = 32 * nb;
;     const int sc = srccol(kind, n0 + (lane & 31));
;     float t_[32];
; #pragma unroll
;     for (int i = 0; i < 32; ++i) t_[i] = W[(size_t)(k0 + 2 * i + (lane >> 5)) * ldw + sc];
; __device__ __forceinline__ void p0_prologue(Frame& F) {
;     ...
;             if (r < I_DN) { p0_transpose_item(in_ptr(IN_DN2) + (size_t)l * DFF * D, DFF, D, D, lw(F, l, LW_DN2), 0, scr, r, tc.lane); continue; } r -= I_DN;
.LBB0_39:
	s_andn2_b64 vcc, exec, s[26:27]
	s_cbranch_vccnz .LBB0_41
	s_mov_b64 s[26:27], s[0:1]
	s_load_dwordx2 s[26:27], s[26:27], 0x80
	s_lshl_b64 s[28:29], s[18:19], 2
	s_mov_b64 s[30:31], s[46:47]
	s_waitcnt lgkmcnt(0)
	s_add_u32 s84, s26, s28
	s_addc_u32 s85, s27, s29
	s_add_u32 s26, s30, s78
	s_addc_u32 s27, s31, 0
	s_lshl_b32 s28, s77, 1
	s_lshl_b32 s4, s77, 5
	s_add_i32 s28, s28, 0x1c900
	s_and_b32 s4, s4, 0x3e0
	s_and_b32 s28, s28, 0x1ffc0
	v_or_b32_e32 v2, s4, v1
	v_add_u32_e32 v4, s28, v33
	v_lshlrev_b32_e32 v2, 2, v2
	v_ashrrev_i32_e32 v5, 31, v4
	v_lshl_add_u64 v[6:7], s[84:85], 0, v[2:3]
	v_lshlrev_b64 v[4:5], 12, v[4:5]
	v_lshl_add_u64 v[4:5], v[6:7], 0, v[4:5]
	v_add_co_u32_e32 v6, vcc, s41, v4
	s_lshl_b32 s28, s28, 1
	s_nop 0
	v_addc_co_u32_e32 v7, vcc, 0, v5, vcc
	v_add_co_u32_e32 v8, vcc, s42, v4
	s_add_u32 s26, s26, s28
	s_nop 0
	v_addc_co_u32_e32 v9, vcc, 0, v5, vcc
	v_add_co_u32_e32 v10, vcc, s43, v4
	s_addc_u32 s27, s27, 0
	s_nop 0
	v_addc_co_u32_e32 v11, vcc, 0, v5, vcc
	v_add_co_u32_e32 v12, vcc, s48, v4
	s_nop 1
	v_addc_co_u32_e32 v13, vcc, 0, v5, vcc
	v_add_co_u32_e32 v14, vcc, s49, v4
	s_nop 1
	v_addc_co_u32_e32 v15, vcc, 0, v5, vcc
	v_add_co_u32_e32 v16, vcc, s50, v4
	s_nop 1
	v_addc_co_u32_e32 v17, vcc, 0, v5, vcc
	v_add_co_u32_e32 v18, vcc, s37, v4
	s_nop 1
	v_addc_co_u32_e32 v19, vcc, 0, v5, vcc
	global_load_dword v2, v[4:5], off
	global_load_dword v22, v[6:7], off
	global_load_dword v23, v[8:9], off
	global_load_dword v24, v[10:11], off
	global_load_dword v25, v[12:13], off
	global_load_dword v26, v[14:15], off
	global_load_dword v27, v[16:17], off
	global_load_dword v28, v[18:19], off
	v_add_co_u32_e32 v6, vcc, s51, v4
	s_nop 1
	v_addc_co_u32_e32 v7, vcc, 0, v5, vcc
	v_add_co_u32_e32 v8, vcc, s52, v4
	s_nop 1
	v_addc_co_u32_e32 v9, vcc, 0, v5, vcc
	v_add_co_u32_e32 v10, vcc, s53, v4
	s_nop 1
	v_addc_co_u32_e32 v11, vcc, 0, v5, vcc
	v_add_co_u32_e32 v12, vcc, s54, v4
	s_nop 1
	v_addc_co_u32_e32 v13, vcc, 0, v5, vcc
	v_add_co_u32_e32 v14, vcc, s55, v4
	s_nop 1
	v_addc_co_u32_e32 v15, vcc, 0, v5, vcc
	v_add_co_u32_e32 v16, vcc, s56, v4
	s_nop 1
	v_addc_co_u32_e32 v17, vcc, 0, v5, vcc
	v_add_co_u32_e32 v18, vcc, s57, v4
	s_nop 1
	v_addc_co_u32_e32 v19, vcc, 0, v5, vcc
	v_add_co_u32_e32 v20, vcc, s58, v4
	s_nop 1
	v_addc_co_u32_e32 v21, vcc, 0, v5, vcc
	global_load_dword v29, v[6:7], off
	global_load_dword v30, v[8:9], off
	global_load_dword v31, v[10:11], off
	global_load_dword v34, v[12:13], off
	global_load_dword v35, v[14:15], off
	global_load_dword v36, v[16:17], off
	global_load_dword v37, v[18:19], off
	global_load_dword v38, v[20:21], off
	v_add_co_u32_e32 v6, vcc, s59, v4
	s_nop 1
	v_addc_co_u32_e32 v7, vcc, 0, v5, vcc
	v_add_co_u32_e32 v8, vcc, s60, v4
	s_nop 1
	v_addc_co_u32_e32 v9, vcc, 0, v5, vcc
	v_add_co_u32_e32 v10, vcc, s61, v4
	s_nop 1
	v_addc_co_u32_e32 v11, vcc, 0, v5, vcc
	v_add_co_u32_e32 v12, vcc, s62, v4
	s_nop 1
	v_addc_co_u32_e32 v13, vcc, 0, v5, vcc
	v_add_co_u32_e32 v14, vcc, s63, v4
	s_nop 1
	v_addc_co_u32_e32 v15, vcc, 0, v5, vcc
	v_add_co_u32_e32 v16, vcc, s64, v4
	s_nop 1
	v_addc_co_u32_e32 v17, vcc, 0, v5, vcc
	v_add_co_u32_e32 v18, vcc, s65, v4
	s_nop 1
	v_addc_co_u32_e32 v19, vcc, 0, v5, vcc
	v_add_co_u32_e32 v20, vcc, s66, v4
	s_nop 1
	v_addc_co_u32_e32 v21, vcc, 0, v5, vcc
	global_load_dword v39, v[6:7], off
	global_load_dword v40, v[8:9], off
	global_load_dword v42, v[10:11], off
	global_load_dword v44, v[12:13], off
	global_load_dword v46, v[14:15], off
	global_load_dword v48, v[16:17], off
	global_load_dword v50, v[18:19], off
	s_nop 0
	global_load_dword v20, v[20:21], off
	v_add_co_u32_e32 v6, vcc, s67, v4
	s_nop 1
	v_addc_co_u32_e32 v7, vcc, 0, v5, vcc
	v_add_co_u32_e32 v8, vcc, s68, v4
	s_nop 1
	v_addc_co_u32_e32 v9, vcc, 0, v5, vcc
	v_add_co_u32_e32 v10, vcc, s69, v4
	s_nop 1
	v_addc_co_u32_e32 v11, vcc, 0, v5, vcc
	v_add_co_u32_e32 v12, vcc, s70, v4
	s_nop 1
	v_addc_co_u32_e32 v13, vcc, 0, v5, vcc
	v_add_co_u32_e32 v14, vcc, s71, v4
	s_nop 1
	v_addc_co_u32_e32 v15, vcc, 0, v5, vcc
	v_add_co_u32_e32 v16, vcc, s72, v4
	s_nop 1
	v_addc_co_u32_e32 v17, vcc, 0, v5, vcc
	v_add_co_u32_e32 v18, vcc, s73, v4
	s_nop 1
	v_addc_co_u32_e32 v19, vcc, 0, v5, vcc
	v_add_co_u32_e32 v4, vcc, s74, v4
	s_nop 1
	v_addc_co_u32_e32 v5, vcc, 0, v5, vcc
	global_load_dword v6, v[6:7], off
	s_nop 0
	global_load_dword v7, v[8:9], off
	s_nop 0
	global_load_dword v8, v[10:11], off
	global_load_dword v9, v[12:13], off
	s_nop 0
	global_load_dword v10, v[14:15], off
	global_load_dword v11, v[16:17], off
	global_load_dword v12, v[18:19], off
	s_nop 0
	global_load_dword v4, v[4:5], off
	s_waitcnt vmcnt(30)
; #define GAS __attribute__((address_space(1)))
; #define LAS __attribute__((address_space(3)))
; __device__ __forceinline__ unsigned pk2(float lo, float hi) { return f2bf(lo) | (f2bf(hi) << 16); }
; __device__ __forceinline__ void p0_transpose_item(const float* W, int K, int ldw, int N, bf16* WT, int kind, LAS float* scr, int item, int lane) {
;     ...
; #pragma unroll
;     for (int i = 0; i < 32; ++i) scr[(2 * i + (lane >> 5)) * 33 + (lane & 31)] = t_[i];
;     asm volatile("s_waitcnt lgkmcnt(0)" ::: "memory");
;     const int c = lane & 7;
; #pragma unroll
;     for (int j = 0; j < 4; ++j) { const int n = (lane >> 3) + 8 * j; const LAS float* s = scr + (8 * c) * 33 + n;
;         v4u o; o.x = pk2(s[0 * 33], s[1 * 33]); o.y = pk2(s[2 * 33], s[3 * 33]); o.z = pk2(s[4 * 33], s[5 * 33]); o.w = pk2(s[6 * 33], s[7 * 33]);
;         *(GAS v4u*)(WT + (size_t)(n0 + n) * K + k0 + 8 * c) = o; }
;     asm volatile("s_waitcnt lgkmcnt(0)" ::: "memory");
	ds_write2_b32 v41, v2, v22 offset1:66
	s_waitcnt vmcnt(28)
	ds_write2_b32 v41, v23, v24 offset0:132 offset1:198
	v_add_u32_e32 v2, 0x400, v41
	s_waitcnt vmcnt(26)
	ds_write2_b32 v2, v25, v26 offset0:8 offset1:74
	s_waitcnt vmcnt(24)
	ds_write2_b32 v2, v27, v28 offset0:140 offset1:206
	v_add_u32_e32 v2, 0x800, v41
	s_waitcnt vmcnt(22)
	ds_write2_b32 v2, v29, v30 offset0:16 offset1:82
	s_waitcnt vmcnt(20)
	ds_write2_b32 v2, v31, v34 offset0:148 offset1:214
	v_add_u32_e32 v2, 0xc00, v41
	s_waitcnt vmcnt(18)
	ds_write2_b32 v2, v35, v36 offset0:24 offset1:90
	s_waitcnt vmcnt(16)
	ds_write2_b32 v2, v37, v38 offset0:156 offset1:222
	v_add_u32_e32 v2, 0x1000, v41
	s_waitcnt vmcnt(14)
	ds_write2_b32 v2, v39, v40 offset0:32 offset1:98
	s_waitcnt vmcnt(12)
	ds_write2_b32 v2, v42, v44 offset0:164 offset1:230
	v_add_u32_e32 v2, 0x1400, v41
	s_waitcnt vmcnt(10)
	ds_write2_b32 v2, v46, v48 offset0:40 offset1:106
	s_waitcnt vmcnt(8)
	ds_write2_b32 v2, v50, v20 offset0:172 offset1:238
	v_add_u32_e32 v2, 0x1800, v41
	s_waitcnt vmcnt(6)
	ds_write2_b32 v2, v6, v7 offset0:48 offset1:114
	s_waitcnt vmcnt(4)
	ds_write2_b32 v2, v8, v9 offset0:180 offset1:246
	v_add_u32_e32 v2, 0x1c00, v41
	s_waitcnt vmcnt(2)
	ds_write2_b32 v2, v10, v11 offset0:56 offset1:122
	s_waitcnt vmcnt(0)
	ds_write2_b32 v2, v12, v4 offset0:188 offset1:254
	s_waitcnt lgkmcnt(0)
	ds_read2_b32 v[8:9], v45 offset1:8
	ds_read2_b32 v[12:13], v45 offset0:33 offset1:41
	ds_read2_b32 v[14:15], v45 offset0:66 offset1:74
	v_lshlrev_b32_e32 v2, 1, v0
	ds_read2_b32 v[16:17], v45 offset0:99 offset1:107
	v_lshl_add_u64 v[4:5], s[26:27], 0, v[2:3]
	s_mov_b64 s[26:27], 0x9ab40000
	s_waitcnt lgkmcnt(3)
	v_bfe_u32 v2, v8, 16, 1
	v_lshl_add_u64 v[10:11], v[4:5], 0, s[26:27]
	v_add3_u32 v2, v8, v2, s38
	s_waitcnt lgkmcnt(2)
	v_bfe_u32 v4, v12, 16, 1
	ds_read2_b32 v[18:19], v45 offset0:132 offset1:140
	v_lshrrev_b32_e32 v2, 16, v2
	v_add3_u32 v4, v12, v4, s38
	ds_read2_b32 v[20:21], v45 offset0:165 offset1:173
	v_and_or_b32 v4, v4, s39, v2
	s_waitcnt lgkmcnt(3)
	s_waitcnt lgkmcnt(2)
	ds_read2_b32 v[22:23], v45 offset0:198 offset1:206
	ds_read2_b32 v[24:25], v45 offset0:231 offset1:239
	v_cvt_pk_bf16_f32 v5, v14, v16
	s_waitcnt lgkmcnt(3)
	s_waitcnt lgkmcnt(2)
	v_cvt_pk_bf16_f32 v6, v18, v20
	s_waitcnt lgkmcnt(1)
	s_waitcnt lgkmcnt(0)
	v_cvt_pk_bf16_f32 v7, v22, v24
	v_add_u32_e32 v2, s4, v43
	v_mad_i64_i32 v[26:27], s[26:27], v2, s75, v[10:11]
	v_bfe_u32 v2, v9, 16, 1
	global_store_dwordx4 v[26:27], v[4:7], off
	v_add3_u32 v2, v9, v2, s38
	v_lshrrev_b32_e32 v2, 16, v2
	v_bfe_u32 v4, v13, 16, 1
	v_add3_u32 v4, v13, v4, s38
	v_and_or_b32 v4, v4, s39, v2
	v_cvt_pk_bf16_f32 v5, v15, v17
	v_cvt_pk_bf16_f32 v6, v19, v21
	v_cvt_pk_bf16_f32 v7, v23, v25
	v_add_u32_e32 v2, s4, v47
	ds_read2_b32 v[8:9], v45 offset0:16 offset1:24
	v_mad_i64_i32 v[12:13], s[26:27], v2, s75, v[10:11]
	global_store_dwordx4 v[12:13], v[4:7], off
	ds_read2_b32 v[12:13], v45 offset0:49 offset1:57
	ds_read2_b32 v[14:15], v45 offset0:82 offset1:90
	ds_read2_b32 v[16:17], v45 offset0:115 offset1:123
	s_waitcnt lgkmcnt(3)
	s_waitcnt lgkmcnt(2)
	ds_read2_b32 v[18:19], v45 offset0:148 offset1:156
	ds_read2_b32 v[20:21], v45 offset0:181 offset1:189
	v_cvt_pk_bf16_f32 v4, v8, v12
	s_waitcnt lgkmcnt(3)
	s_waitcnt lgkmcnt(2)
	ds_read2_b32 v[22:23], v45 offset0:214 offset1:222
	ds_read2_b32 v[24:25], v45 offset0:247 offset1:255
	v_cvt_pk_bf16_f32 v5, v14, v16
	s_waitcnt lgkmcnt(3)
	s_waitcnt lgkmcnt(2)
	v_cvt_pk_bf16_f32 v6, v18, v20
	s_waitcnt lgkmcnt(1)
	s_waitcnt lgkmcnt(0)
	v_cvt_pk_bf16_f32 v7, v22, v24
	v_add_u32_e32 v2, s4, v49
	v_mad_i64_i32 v[26:27], s[26:27], v2, s75, v[10:11]
	v_bfe_u32 v2, v9, 16, 1
	global_store_dwordx4 v[26:27], v[4:7], off
	v_add3_u32 v2, v9, v2, s38
	v_lshrrev_b32_e32 v2, 16, v2
	v_bfe_u32 v4, v13, 16, 1
	v_add3_u32 v4, v13, v4, s38
	v_and_or_b32 v4, v4, s39, v2
	v_cvt_pk_bf16_f32 v5, v15, v17
	v_cvt_pk_bf16_f32 v6, v19, v21
	v_cvt_pk_bf16_f32 v7, v23, v25
	v_add_u32_e32 v2, s4, v51
	v_mad_i64_i32 v[8:9], s[26:27], v2, s75, v[10:11]
	global_store_dwordx4 v[8:9], v[4:7], off
	s_waitcnt lgkmcnt(0)

; __device__ __forceinline__ bf16* lw(const Frame& F, int l, size_t off) { return (bf16*)(wsq(F.ws) + WS_W + (size_t)l * LW_SIZE + off); }
; __device__ __forceinline__ void p0_transpose_item(const float* W, int K, int ldw, int N, bf16* WT, int kind, LAS float* scr, int item, int lane) {
;     const int nblk = N / 32, kb = item / nblk, nb = item % nblk, k0 = 64 * kb, n0 = 32 * nb;
;     const int sc = srccol(kind, n0 + (lane & 31));
;     float t_[32];
; #pragma unroll
;     for (int i = 0; i < 32; ++i) t_[i] = W[(size_t)(k0 + 2 * i + (lane >> 5)) * ldw + sc];
; __device__ __forceinline__ void p0_prologue(Frame& F) {
;     ...
;             if (r < I_DN) { p0_transpose_item(in_ptr(IN_DN1) + (size_t)l * DFF * D, DFF, D, D, lw(F, l, LW_DN1), 0, scr, r, tc.lane); continue; } r -= I_DN;
.LBB0_42:
	s_andn2_b64 vcc, exec, s[26:27]
	s_cbranch_vccnz .LBB0_44
	s_mov_b64 s[26:27], s[0:1]
	s_load_dwordx2 s[26:27], s[26:27], 0x70
	s_lshl_b64 s[28:29], s[18:19], 2
	s_mov_b64 s[30:31], s[46:47]
	s_waitcnt lgkmcnt(0)
	s_add_u32 s84, s26, s28
	s_addc_u32 s85, s27, s29
	s_add_u32 s26, s30, s78
	s_addc_u32 s27, s31, 0
	s_lshl_b32 s28, s77, 1
	s_lshl_b32 s4, s77, 5
	s_add_i32 s28, s28, 0x1d400
	s_and_b32 s4, s4, 0x3e0
	s_and_b32 s28, s28, 0x1ffc0
	v_or_b32_e32 v2, s4, v1
	v_add_u32_e32 v4, s28, v33
	v_lshlrev_b32_e32 v2, 2, v2
	v_ashrrev_i32_e32 v5, 31, v4
	v_lshl_add_u64 v[6:7], s[84:85], 0, v[2:3]
	v_lshlrev_b64 v[4:5], 12, v[4:5]
	v_lshl_add_u64 v[4:5], v[6:7], 0, v[4:5]
	v_add_co_u32_e32 v6, vcc, s41, v4
	s_lshl_b32 s28, s28, 1
	s_nop 0
	v_addc_co_u32_e32 v7, vcc, 0, v5, vcc
	v_add_co_u32_e32 v8, vcc, s42, v4
	s_add_u32 s26, s26, s28
	s_nop 0
	v_addc_co_u32_e32 v9, vcc, 0, v5, vcc
	v_add_co_u32_e32 v10, vcc, s43, v4
	s_addc_u32 s27, s27, 0
	s_nop 0
	v_addc_co_u32_e32 v11, vcc, 0, v5, vcc
	v_add_co_u32_e32 v12, vcc, s48, v4
	s_nop 1
	v_addc_co_u32_e32 v13, vcc, 0, v5, vcc
	v_add_co_u32_e32 v14, vcc, s49, v4
	s_nop 1
	v_addc_co_u32_e32 v15, vcc, 0, v5, vcc
	v_add_co_u32_e32 v16, vcc, s50, v4
	s_nop 1
	v_addc_co_u32_e32 v17, vcc, 0, v5, vcc
	v_add_co_u32_e32 v18, vcc, s37, v4
	s_nop 1
	v_addc_co_u32_e32 v19, vcc, 0, v5, vcc
	global_load_dword v2, v[4:5], off
	global_load_dword v22, v[6:7], off
	global_load_dword v23, v[8:9], off
	global_load_dword v24, v[10:11], off
	global_load_dword v25, v[12:13], off
	global_load_dword v26, v[14:15], off
	global_load_dword v27, v[16:17], off
	global_load_dword v28, v[18:19], off
	v_add_co_u32_e32 v6, vcc, s51, v4
	s_nop 1
	v_addc_co_u32_e32 v7, vcc, 0, v5, vcc
	v_add_co_u32_e32 v8, vcc, s52, v4
	s_nop 1
	v_addc_co_u32_e32 v9, vcc, 0, v5, vcc
	v_add_co_u32_e32 v10, vcc, s53, v4
	s_nop 1
	v_addc_co_u32_e32 v11, vcc, 0, v5, vcc
	v_add_co_u32_e32 v12, vcc, s54, v4
	s_nop 1
	v_addc_co_u32_e32 v13, vcc, 0, v5, vcc
	v_add_co_u32_e32 v14, vcc, s55, v4
	s_nop 1
	v_addc_co_u32_e32 v15, vcc, 0, v5, vcc
	v_add_co_u32_e32 v16, vcc, s56, v4
	s_nop 1
	v_addc_co_u32_e32 v17, vcc, 0, v5, vcc
	v_add_co_u32_e32 v18, vcc, s57, v4
	s_nop 1
	v_addc_co_u32_e32 v19, vcc, 0, v5, vcc
	v_add_co_u32_e32 v20, vcc, s58, v4
	s_nop 1
	v_addc_co_u32_e32 v21, vcc, 0, v5, vcc
	global_load_dword v29, v[6:7], off
	global_load_dword v30, v[8:9], off
	global_load_dword v31, v[10:11], off
	global_load_dword v34, v[12:13], off
	global_load_dword v35, v[14:15], off
	global_load_dword v36, v[16:17], off
	global_load_dword v37, v[18:19], off
	global_load_dword v38, v[20:21], off
	v_add_co_u32_e32 v6, vcc, s59, v4
	s_nop 1
	v_addc_co_u32_e32 v7, vcc, 0, v5, vcc
	v_add_co_u32_e32 v8, vcc, s60, v4
	s_nop 1
	v_addc_co_u32_e32 v9, vcc, 0, v5, vcc
	v_add_co_u32_e32 v10, vcc, s61, v4
	s_nop 1
	v_addc_co_u32_e32 v11, vcc, 0, v5, vcc
	v_add_co_u32_e32 v12, vcc, s62, v4
	s_nop 1
	v_addc_co_u32_e32 v13, vcc, 0, v5, vcc
	v_add_co_u32_e32 v14, vcc, s63, v4
	s_nop 1
	v_addc_co_u32_e32 v15, vcc, 0, v5, vcc
	v_add_co_u32_e32 v16, vcc, s64, v4
	s_nop 1
	v_addc_co_u32_e32 v17, vcc, 0, v5, vcc
	v_add_co_u32_e32 v18, vcc, s65, v4
	s_nop 1
	v_addc_co_u32_e32 v19, vcc, 0, v5, vcc
	v_add_co_u32_e32 v20, vcc, s66, v4
	s_nop 1
	v_addc_co_u32_e32 v21, vcc, 0, v5, vcc
	global_load_dword v39, v[6:7], off
	global_load_dword v40, v[8:9], off
	global_load_dword v42, v[10:11], off
	global_load_dword v44, v[12:13], off
	global_load_dword v46, v[14:15], off
	global_load_dword v48, v[16:17], off
	global_load_dword v50, v[18:19], off
	s_nop 0
	global_load_dword v20, v[20:21], off
	v_add_co_u32_e32 v6, vcc, s67, v4
	s_nop 1
	v_addc_co_u32_e32 v7, vcc, 0, v5, vcc
	v_add_co_u32_e32 v8, vcc, s68, v4
	s_nop 1
	v_addc_co_u32_e32 v9, vcc, 0, v5, vcc
	v_add_co_u32_e32 v10, vcc, s69, v4
	s_nop 1
	v_addc_co_u32_e32 v11, vcc, 0, v5, vcc
	v_add_co_u32_e32 v12, vcc, s70, v4
	s_nop 1
	v_addc_co_u32_e32 v13, vcc, 0, v5, vcc
	v_add_co_u32_e32 v14, vcc, s71, v4
	s_nop 1
	v_addc_co_u32_e32 v15, vcc, 0, v5, vcc
	v_add_co_u32_e32 v16, vcc, s72, v4
	s_nop 1
	v_addc_co_u32_e32 v17, vcc, 0, v5, vcc
	v_add_co_u32_e32 v18, vcc, s73, v4
	s_nop 1
	v_addc_co_u32_e32 v19, vcc, 0, v5, vcc
	v_add_co_u32_e32 v4, vcc, s74, v4
	s_nop 1
	v_addc_co_u32_e32 v5, vcc, 0, v5, vcc
	global_load_dword v6, v[6:7], off
	s_nop 0
	global_load_dword v7, v[8:9], off
	s_nop 0
	global_load_dword v8, v[10:11], off
	global_load_dword v9, v[12:13], off
	s_nop 0
	global_load_dword v10, v[14:15], off
	global_load_dword v11, v[16:17], off
	global_load_dword v12, v[18:19], off
	s_nop 0
	global_load_dword v4, v[4:5], off
	s_waitcnt vmcnt(30)
; #define GAS __attribute__((address_space(1)))
; #define LAS __attribute__((address_space(3)))
; __device__ __forceinline__ unsigned pk2(float lo, float hi) { return f2bf(lo) | (f2bf(hi) << 16); }
; __device__ __forceinline__ void p0_transpose_item(const float* W, int K, int ldw, int N, bf16* WT, int kind, LAS float* scr, int item, int lane) {
;     ...
; #pragma unroll
;     for (int i = 0; i < 32; ++i) scr[(2 * i + (lane >> 5)) * 33 + (lane & 31)] = t_[i];
;     asm volatile("s_waitcnt lgkmcnt(0)" ::: "memory");
;     const int c = lane & 7;
; #pragma unroll
;     for (int j = 0; j < 4; ++j) { const int n = (lane >> 3) + 8 * j; const LAS float* s = scr + (8 * c) * 33 + n;
;         v4u o; o.x = pk2(s[0 * 33], s[1 * 33]); o.y = pk2(s[2 * 33], s[3 * 33]); o.z = pk2(s[4 * 33], s[5 * 33]); o.w = pk2(s[6 * 33], s[7 * 33]);
;         *(GAS v4u*)(WT + (size_t)(n0 + n) * K + k0 + 8 * c) = o; }
;     asm volatile("s_waitcnt lgkmcnt(0)" ::: "memory");
	ds_write2_b32 v41, v2, v22 offset1:66
	s_waitcnt vmcnt(28)
	ds_write2_b32 v41, v23, v24 offset0:132 offset1:198
	v_add_u32_e32 v2, 0x400, v41
	s_waitcnt vmcnt(26)
	ds_write2_b32 v2, v25, v26 offset0:8 offset1:74
	s_waitcnt vmcnt(24)
	ds_write2_b32 v2, v27, v28 offset0:140 offset1:206
	v_add_u32_e32 v2, 0x800, v41
	s_waitcnt vmcnt(22)
	ds_write2_b32 v2, v29, v30 offset0:16 offset1:82
	s_waitcnt vmcnt(20)
	ds_write2_b32 v2, v31, v34 offset0:148 offset1:214
	v_add_u32_e32 v2, 0xc00, v41
	s_waitcnt vmcnt(18)
	ds_write2_b32 v2, v35, v36 offset0:24 offset1:90
	s_waitcnt vmcnt(16)
	ds_write2_b32 v2, v37, v38 offset0:156 offset1:222
	v_add_u32_e32 v2, 0x1000, v41
	s_waitcnt vmcnt(14)
	ds_write2_b32 v2, v39, v40 offset0:32 offset1:98
	s_waitcnt vmcnt(12)
	ds_write2_b32 v2, v42, v44 offset0:164 offset1:230
	v_add_u32_e32 v2, 0x1400, v41
	s_waitcnt vmcnt(10)
	ds_write2_b32 v2, v46, v48 offset0:40 offset1:106
	s_waitcnt vmcnt(8)
	ds_write2_b32 v2, v50, v20 offset0:172 offset1:238
	v_add_u32_e32 v2, 0x1800, v41
	s_waitcnt vmcnt(6)
	ds_write2_b32 v2, v6, v7 offset0:48 offset1:114
	s_waitcnt vmcnt(4)
	ds_write2_b32 v2, v8, v9 offset0:180 offset1:246
	v_add_u32_e32 v2, 0x1c00, v41
	s_waitcnt vmcnt(2)
	ds_write2_b32 v2, v10, v11 offset0:56 offset1:122
	s_waitcnt vmcnt(0)
	ds_write2_b32 v2, v12, v4 offset0:188 offset1:254
	s_waitcnt lgkmcnt(0)
	ds_read2_b32 v[8:9], v45 offset1:8
	ds_read2_b32 v[12:13], v45 offset0:33 offset1:41
	ds_read2_b32 v[14:15], v45 offset0:66 offset1:74
	v_lshlrev_b32_e32 v2, 1, v0
	ds_read2_b32 v[16:17], v45 offset0:99 offset1:107
	v_lshl_add_u64 v[4:5], s[26:27], 0, v[2:3]
	s_mov_b64 s[26:27], 0x97ec0000
	s_waitcnt lgkmcnt(3)
	v_bfe_u32 v2, v8, 16, 1
	v_lshl_add_u64 v[10:11], v[4:5], 0, s[26:27]
	v_add3_u32 v2, v8, v2, s38
	s_waitcnt lgkmcnt(2)
	v_bfe_u32 v4, v12, 16, 1
	ds_read2_b32 v[18:19], v45 offset0:132 offset1:140
	v_lshrrev_b32_e32 v2, 16, v2
	v_add3_u32 v4, v12, v4, s38
	ds_read2_b32 v[20:21], v45 offset0:165 offset1:173
	v_and_or_b32 v4, v4, s39, v2
	s_waitcnt lgkmcnt(3)
	s_waitcnt lgkmcnt(2)
	ds_read2_b32 v[22:23], v45 offset0:198 offset1:206
	ds_read2_b32 v[24:25], v45 offset0:231 offset1:239
	v_cvt_pk_bf16_f32 v5, v14, v16
	s_waitcnt lgkmcnt(3)
	s_waitcnt lgkmcnt(2)
	v_cvt_pk_bf16_f32 v6, v18, v20
	s_waitcnt lgkmcnt(1)
	s_waitcnt lgkmcnt(0)
	v_cvt_pk_bf16_f32 v7, v22, v24
	v_add_u32_e32 v2, s4, v43
	v_mad_i64_i32 v[26:27], s[26:27], v2, s75, v[10:11]
	v_bfe_u32 v2, v9, 16, 1
	global_store_dwordx4 v[26:27], v[4:7], off
	v_add3_u32 v2, v9, v2, s38
	v_lshrrev_b32_e32 v2, 16, v2
	v_bfe_u32 v4, v13, 16, 1
	v_add3_u32 v4, v13, v4, s38
	v_and_or_b32 v4, v4, s39, v2
	v_cvt_pk_bf16_f32 v5, v15, v17
	v_cvt_pk_bf16_f32 v6, v19, v21
	v_cvt_pk_bf16_f32 v7, v23, v25
	v_add_u32_e32 v2, s4, v47
	ds_read2_b32 v[8:9], v45 offset0:16 offset1:24
	v_mad_i64_i32 v[12:13], s[26:27], v2, s75, v[10:11]
	global_store_dwordx4 v[12:13], v[4:7], off
	ds_read2_b32 v[12:13], v45 offset0:49 offset1:57
	ds_read2_b32 v[14:15], v45 offset0:82 offset1:90
	ds_read2_b32 v[16:17], v45 offset0:115 offset1:123
	s_waitcnt lgkmcnt(3)
	s_waitcnt lgkmcnt(2)
	ds_read2_b32 v[18:19], v45 offset0:148 offset1:156
	ds_read2_b32 v[20:21], v45 offset0:181 offset1:189
	v_cvt_pk_bf16_f32 v4, v8, v12
	s_waitcnt lgkmcnt(3)
	s_waitcnt lgkmcnt(2)
	ds_read2_b32 v[22:23], v45 offset0:214 offset1:222
	ds_read2_b32 v[24:25], v45 offset0:247 offset1:255
	v_cvt_pk_bf16_f32 v5, v14, v16
	s_waitcnt lgkmcnt(3)
	s_waitcnt lgkmcnt(2)
	v_cvt_pk_bf16_f32 v6, v18, v20
	s_waitcnt lgkmcnt(1)
	s_waitcnt lgkmcnt(0)
	v_cvt_pk_bf16_f32 v7, v22, v24
	v_add_u32_e32 v2, s4, v49
	v_mad_i64_i32 v[26:27], s[26:27], v2, s75, v[10:11]
	v_bfe_u32 v2, v9, 16, 1
	global_store_dwordx4 v[26:27], v[4:7], off
	v_add3_u32 v2, v9, v2, s38
	v_lshrrev_b32_e32 v2, 16, v2
	v_bfe_u32 v4, v13, 16, 1
	v_add3_u32 v4, v13, v4, s38
	v_and_or_b32 v4, v4, s39, v2
	v_cvt_pk_bf16_f32 v5, v15, v17
	v_cvt_pk_bf16_f32 v6, v19, v21
	v_cvt_pk_bf16_f32 v7, v23, v25
	v_add_u32_e32 v2, s4, v51
	v_mad_i64_i32 v[8:9], s[26:27], v2, s75, v[10:11]
	global_store_dwordx4 v[8:9], v[4:7], off
	s_waitcnt lgkmcnt(0)

; #define LAS __attribute__((address_space(3)))
; __device__ __forceinline__ bf16* lw(const Frame& F, int l, size_t off) { return (bf16*)(wsq(F.ws) + WS_W + (size_t)l * LW_SIZE + off); }
; __device__ __forceinline__ int srccol(int kind, int n) {
;     if (kind == 1) { const int pn = n >> 8, p = n & 255, bj = p >> 7, wc = (p >> 5) & 3, fq = (p >> 3) & 3, nn = (p >> 2) & 1, e = p & 3;
;         return (nn ? DFF : 0) + 128 * pn + 64 * bj + 16 * wc + 4 * fq + e; }
;     if (kind == 2 && n < 1024) { const int hb_ = n & ~127, p = n & 127, wc = p >> 5, fq = (p >> 3) & 3, nn = (p >> 2) & 1, e = p & 3;
;         return hb_ + 16 * wc + 4 * fq + e + 64 * nn; }
;     return n;
; }
; __device__ __forceinline__ void p0_transpose_item(const float* W, int K, int ldw, int N, bf16* WT, int kind, LAS float* scr, int item, int lane) {
;     const int nblk = N / 32, kb = item / nblk, nb = item % nblk, k0 = 64 * kb, n0 = 32 * nb;
;     const int sc = srccol(kind, n0 + (lane & 31));
;     float t_[32];
; #pragma unroll
;     for (int i = 0; i < 32; ++i) t_[i] = W[(size_t)(k0 + 2 * i + (lane >> 5)) * ldw + sc];
; __device__ __forceinline__ void p0_prologue(Frame& F) {
;     ...
;             if (r < I_UP) { p0_transpose_item(in_ptr(IN_UP2) + (size_t)l * D * 2 * DFF, D, 2 * DFF, 2 * DFF, lw(F, l, LW_UP2), 1, scr, r, tc.lane); continue; } r -= I_UP;
.LBB0_45:
	s_andn2_b64 vcc, exec, s[26:27]
	s_cbranch_vccnz .LBB0_47
	s_mov_b64 s[26:27], s[0:1]
	s_load_dwordx2 s[26:27], s[26:27], 0x78
	s_lshl_b64 s[28:29], s[20:21], 2
	s_mov_b64 s[30:31], s[46:47]
	s_waitcnt lgkmcnt(0)
	s_add_u32 s26, s26, s28
	s_addc_u32 s27, s27, s29
	s_add_u32 s28, s30, s78
	s_addc_u32 s29, s31, 0
	s_add_i32 s4, s77, 0xf500
	s_and_b32 s30, s4, 0xffff
	s_mul_i32 s30, s30, 0xba2f
	s_lshr_b32 s30, s30, 23
	s_mul_i32 s31, s30, 0xb0
	s_sub_i32 s4, s4, s31
	s_and_b32 s31, s4, 0xffff
	s_lshl_b32 s4, s31, 5
	v_or_b32_e32 v2, s4, v1
	s_lshl_b32 s31, s31, 4
	s_and_b32 s31, s31, 0xf80
	v_lshrrev_b32_e32 v2, 1, v2
	v_add_u32_e32 v4, s31, v55
	v_and_b32_e32 v2, 0x7c, v2
	v_or3_b32 v2, v2, v4, v54
	v_lshl_add_u32 v22, s30, 6, v33
	v_lshlrev_b32_e32 v2, 2, v2
	v_lshl_add_u64 v[4:5], s[26:27], 0, v[2:3]
	v_add_u32_e32 v2, 2, v22
	v_mad_i64_i32 v[8:9], s[26:27], v2, s76, v[4:5]
	v_add_u32_e32 v2, 4, v22
	v_mad_i64_i32 v[10:11], s[26:27], v2, s76, v[4:5]
	v_add_u32_e32 v2, 6, v22
	v_mad_i64_i32 v[12:13], s[26:27], v2, s76, v[4:5]
	v_add_u32_e32 v2, 8, v22
	v_mad_i64_i32 v[14:15], s[26:27], v2, s76, v[4:5]
	v_add_u32_e32 v2, 10, v22
	v_mad_i64_i32 v[16:17], s[26:27], v2, s76, v[4:5]
	v_add_u32_e32 v2, 12, v22
	v_mad_i64_i32 v[18:19], s[26:27], v2, s76, v[4:5]
	v_add_u32_e32 v2, 14, v22
	v_mad_i64_i32 v[6:7], s[26:27], v22, s76, v[4:5]
	v_mad_i64_i32 v[20:21], s[26:27], v2, s76, v[4:5]
	global_load_dword v2, v[6:7], off
	global_load_dword v23, v[8:9], off
	global_load_dword v24, v[10:11], off
	global_load_dword v25, v[12:13], off
	global_load_dword v26, v[14:15], off
	global_load_dword v27, v[16:17], off
	global_load_dword v28, v[18:19], off
	global_load_dword v29, v[20:21], off
	v_add_u32_e32 v6, 16, v22
	v_add_u32_e32 v8, 18, v22
	v_add_u32_e32 v10, 20, v22
	v_add_u32_e32 v12, 22, v22
	v_add_u32_e32 v14, 24, v22
	v_add_u32_e32 v16, 26, v22
	v_add_u32_e32 v18, 28, v22
	v_add_u32_e32 v20, 30, v22
	v_mad_i64_i32 v[6:7], s[26:27], v6, s76, v[4:5]
	v_mad_i64_i32 v[8:9], s[26:27], v8, s76, v[4:5]
	v_mad_i64_i32 v[10:11], s[26:27], v10, s76, v[4:5]
	v_mad_i64_i32 v[12:13], s[26:27], v12, s76, v[4:5]
	v_mad_i64_i32 v[14:15], s[26:27], v14, s76, v[4:5]
	v_mad_i64_i32 v[16:17], s[26:27], v16, s76, v[4:5]
	v_mad_i64_i32 v[18:19], s[26:27], v18, s76, v[4:5]
	v_mad_i64_i32 v[20:21], s[26:27], v20, s76, v[4:5]
	global_load_dword v30, v[6:7], off
	global_load_dword v31, v[8:9], off
	global_load_dword v34, v[10:11], off
	global_load_dword v35, v[12:13], off
	global_load_dword v36, v[14:15], off
	global_load_dword v37, v[16:17], off
	global_load_dword v38, v[18:19], off
	global_load_dword v39, v[20:21], off
	v_add_u32_e32 v6, 32, v22
	v_add_u32_e32 v8, 34, v22
	v_add_u32_e32 v10, 36, v22
	v_add_u32_e32 v12, 38, v22
	v_add_u32_e32 v14, 40, v22
	v_add_u32_e32 v16, 42, v22
	v_add_u32_e32 v18, 44, v22
	v_add_u32_e32 v20, 46, v22
	v_mad_i64_i32 v[6:7], s[26:27], v6, s76, v[4:5]
	v_mad_i64_i32 v[8:9], s[26:27], v8, s76, v[4:5]
	v_mad_i64_i32 v[10:11], s[26:27], v10, s76, v[4:5]
	v_mad_i64_i32 v[12:13], s[26:27], v12, s76, v[4:5]
	v_mad_i64_i32 v[14:15], s[26:27], v14, s76, v[4:5]
	v_mad_i64_i32 v[16:17], s[26:27], v16, s76, v[4:5]
	v_mad_i64_i32 v[18:19], s[26:27], v18, s76, v[4:5]
	v_mad_i64_i32 v[20:21], s[26:27], v20, s76, v[4:5]
	global_load_dword v40, v[6:7], off
	global_load_dword v42, v[8:9], off
	global_load_dword v44, v[10:11], off
	global_load_dword v46, v[12:13], off
	global_load_dword v48, v[14:15], off
	global_load_dword v50, v[16:17], off
	global_load_dword v52, v[18:19], off
	s_nop 0
	global_load_dword v20, v[20:21], off
	v_add_u32_e32 v6, 48, v22
	v_add_u32_e32 v8, 50, v22
	v_add_u32_e32 v10, 52, v22
	v_add_u32_e32 v12, 54, v22
	v_add_u32_e32 v14, 56, v22
	v_add_u32_e32 v16, 58, v22
	v_add_u32_e32 v18, 60, v22
	v_add_u32_e32 v21, 62, v22
	v_mad_i64_i32 v[6:7], s[26:27], v6, s76, v[4:5]
	v_mad_i64_i32 v[8:9], s[26:27], v8, s76, v[4:5]
	v_mad_i64_i32 v[10:11], s[26:27], v10, s76, v[4:5]
	v_mad_i64_i32 v[12:13], s[26:27], v12, s76, v[4:5]
	v_mad_i64_i32 v[14:15], s[26:27], v14, s76, v[4:5]
	v_mad_i64_i32 v[16:17], s[26:27], v16, s76, v[4:5]
	v_mad_i64_i32 v[18:19], s[26:27], v18, s76, v[4:5]
	v_mad_i64_i32 v[4:5], s[26:27], v21, s76, v[4:5]
	global_load_dword v6, v[6:7], off
	s_nop 0
	global_load_dword v7, v[8:9], off
	s_nop 0
	global_load_dword v8, v[10:11], off
	global_load_dword v9, v[12:13], off
	s_nop 0
	global_load_dword v10, v[14:15], off
	global_load_dword v11, v[16:17], off
	global_load_dword v12, v[18:19], off
	s_nop 0
	global_load_dword v4, v[4:5], off
	s_waitcnt vmcnt(30)
; #define GAS __attribute__((address_space(1)))
; #define LAS __attribute__((address_space(3)))
; __device__ __forceinline__ unsigned pk2(float lo, float hi) { return f2bf(lo) | (f2bf(hi) << 16); }
; __device__ __forceinline__ void p0_transpose_item(const float* W, int K, int ldw, int N, bf16* WT, int kind, LAS float* scr, int item, int lane) {
;     ...
; #pragma unroll
;     for (int i = 0; i < 32; ++i) scr[(2 * i + (lane >> 5)) * 33 + (lane & 31)] = t_[i];
;     asm volatile("s_waitcnt lgkmcnt(0)" ::: "memory");
;     const int c = lane & 7;
; #pragma unroll
;     for (int j = 0; j < 4; ++j) { const int n = (lane >> 3) + 8 * j; const LAS float* s = scr + (8 * c) * 33 + n;
;         v4u o; o.x = pk2(s[0 * 33], s[1 * 33]); o.y = pk2(s[2 * 33], s[3 * 33]); o.z = pk2(s[4 * 33], s[5 * 33]); o.w = pk2(s[6 * 33], s[7 * 33]);
;         *(GAS v4u*)(WT + (size_t)(n0 + n) * K + k0 + 8 * c) = o; }
;     asm volatile("s_waitcnt lgkmcnt(0)" ::: "memory");
	ds_write2_b32 v41, v2, v23 offset1:66
	s_waitcnt vmcnt(28)
	ds_write2_b32 v41, v24, v25 offset0:132 offset1:198
	v_add_u32_e32 v2, 0x400, v41
	s_waitcnt vmcnt(26)
	ds_write2_b32 v2, v26, v27 offset0:8 offset1:74
	s_waitcnt vmcnt(24)
	ds_write2_b32 v2, v28, v29 offset0:140 offset1:206
	v_add_u32_e32 v2, 0x800, v41
	s_waitcnt vmcnt(22)
	ds_write2_b32 v2, v30, v31 offset0:16 offset1:82
	s_waitcnt vmcnt(20)
	ds_write2_b32 v2, v34, v35 offset0:148 offset1:214
	v_add_u32_e32 v2, 0xc00, v41
	s_waitcnt vmcnt(18)
	ds_write2_b32 v2, v36, v37 offset0:24 offset1:90
	s_waitcnt vmcnt(16)
	ds_write2_b32 v2, v38, v39 offset0:156 offset1:222
	v_add_u32_e32 v2, 0x1000, v41
	s_waitcnt vmcnt(14)
	ds_write2_b32 v2, v40, v42 offset0:32 offset1:98
	s_waitcnt vmcnt(12)
	ds_write2_b32 v2, v44, v46 offset0:164 offset1:230
	v_add_u32_e32 v2, 0x1400, v41
	s_waitcnt vmcnt(10)
	ds_write2_b32 v2, v48, v50 offset0:40 offset1:106
	s_waitcnt vmcnt(8)
	ds_write2_b32 v2, v52, v20 offset0:172 offset1:238
	v_add_u32_e32 v2, 0x1800, v41
	s_waitcnt vmcnt(6)
	ds_write2_b32 v2, v6, v7 offset0:48 offset1:114
	s_waitcnt vmcnt(4)
	ds_write2_b32 v2, v8, v9 offset0:180 offset1:246
	v_add_u32_e32 v2, 0x1c00, v41
	s_waitcnt vmcnt(2)
	ds_write2_b32 v2, v10, v11 offset0:56 offset1:122
	s_waitcnt vmcnt(0)
	ds_write2_b32 v2, v12, v4 offset0:188 offset1:254
	s_waitcnt lgkmcnt(0)
	ds_read2_b32 v[8:9], v45 offset1:8
	ds_read2_b32 v[12:13], v45 offset0:33 offset1:41
	s_lshl_b32 s26, s30, 7
	s_add_u32 s26, s28, s26
	ds_read2_b32 v[14:15], v45 offset0:66 offset1:74
	s_addc_u32 s27, s29, 0
	v_lshlrev_b32_e32 v2, 1, v0
	ds_read2_b32 v[16:17], v45 offset0:99 offset1:107
	v_lshl_add_u64 v[4:5], s[26:27], 0, v[2:3]
	s_waitcnt lgkmcnt(3)
	v_bfe_u32 v2, v8, 16, 1
	v_lshl_add_u64 v[10:11], v[4:5], 0, s[8:9]
	v_add3_u32 v2, v8, v2, s38
	s_waitcnt lgkmcnt(2)
	v_bfe_u32 v4, v12, 16, 1
	ds_read2_b32 v[18:19], v45 offset0:132 offset1:140
	v_lshrrev_b32_e32 v2, 16, v2
	v_add3_u32 v4, v12, v4, s38
	ds_read2_b32 v[20:21], v45 offset0:165 offset1:173
	v_and_or_b32 v4, v4, s39, v2
	s_waitcnt lgkmcnt(3)
	s_waitcnt lgkmcnt(2)
	ds_read2_b32 v[22:23], v45 offset0:198 offset1:206
	ds_read2_b32 v[24:25], v45 offset0:231 offset1:239
	v_cvt_pk_bf16_f32 v5, v14, v16
	s_waitcnt lgkmcnt(3)
	s_waitcnt lgkmcnt(2)
	v_cvt_pk_bf16_f32 v6, v18, v20
	s_waitcnt lgkmcnt(1)
	v_add_u32_e32 v26, s4, v43
	s_waitcnt lgkmcnt(0)
	v_ashrrev_i32_e32 v27, 31, v26
	v_lshlrev_b64 v[26:27], 11, v[26:27]
	v_cvt_pk_bf16_f32 v7, v22, v24
	v_lshl_add_u64 v[26:27], v[10:11], 0, v[26:27]
	v_bfe_u32 v2, v9, 16, 1
	global_store_dwordx4 v[26:27], v[4:7], off
	v_add3_u32 v2, v9, v2, s38
	v_lshrrev_b32_e32 v2, 16, v2
	v_bfe_u32 v4, v13, 16, 1
	v_add3_u32 v4, v13, v4, s38
	v_and_or_b32 v4, v4, s39, v2
	v_cvt_pk_bf16_f32 v5, v15, v17
	v_cvt_pk_bf16_f32 v6, v19, v21
	v_add_u32_e32 v8, s4, v47
	v_ashrrev_i32_e32 v9, 31, v8
	v_lshlrev_b64 v[8:9], 11, v[8:9]
	v_cvt_pk_bf16_f32 v7, v23, v25
	ds_read2_b32 v[12:13], v45 offset0:16 offset1:24
	v_lshl_add_u64 v[8:9], v[10:11], 0, v[8:9]
	global_store_dwordx4 v[8:9], v[4:7], off
	ds_read2_b32 v[8:9], v45 offset0:49 offset1:57
	ds_read2_b32 v[14:15], v45 offset0:82 offset1:90
	ds_read2_b32 v[16:17], v45 offset0:115 offset1:123
	s_waitcnt lgkmcnt(3)
	s_waitcnt lgkmcnt(2)
	ds_read2_b32 v[18:19], v45 offset0:148 offset1:156
	ds_read2_b32 v[20:21], v45 offset0:181 offset1:189
	v_cvt_pk_bf16_f32 v4, v12, v8
	s_waitcnt lgkmcnt(3)
	s_waitcnt lgkmcnt(2)
	ds_read2_b32 v[22:23], v45 offset0:214 offset1:222
	ds_read2_b32 v[24:25], v45 offset0:247 offset1:255
	v_cvt_pk_bf16_f32 v5, v14, v16
	s_waitcnt lgkmcnt(3)
	s_waitcnt lgkmcnt(2)
	v_cvt_pk_bf16_f32 v6, v18, v20
	s_waitcnt lgkmcnt(1)
	v_add_u32_e32 v26, s4, v49
	s_waitcnt lgkmcnt(0)
	v_ashrrev_i32_e32 v27, 31, v26
	v_lshlrev_b64 v[26:27], 11, v[26:27]
	v_cvt_pk_bf16_f32 v7, v22, v24
	v_lshl_add_u64 v[26:27], v[10:11], 0, v[26:27]
	v_bfe_u32 v2, v13, 16, 1
	global_store_dwordx4 v[26:27], v[4:7], off
	v_add3_u32 v2, v13, v2, s38
	v_lshrrev_b32_e32 v2, 16, v2
	v_bfe_u32 v4, v9, 16, 1
	v_add3_u32 v4, v9, v4, s38
	v_and_or_b32 v4, v4, s39, v2
	v_cvt_pk_bf16_f32 v5, v15, v17
	v_cvt_pk_bf16_f32 v6, v19, v21
	v_add_u32_e32 v8, s4, v51
	v_ashrrev_i32_e32 v9, 31, v8
	v_lshlrev_b64 v[8:9], 11, v[8:9]
	v_cvt_pk_bf16_f32 v7, v23, v25
	v_lshl_add_u64 v[8:9], v[10:11], 0, v[8:9]
	global_store_dwordx4 v[8:9], v[4:7], off
	s_waitcnt lgkmcnt(0)

; #define LAS __attribute__((address_space(3)))
; __device__ __forceinline__ bf16* lw(const Frame& F, int l, size_t off) { return (bf16*)(wsq(F.ws) + WS_W + (size_t)l * LW_SIZE + off); }
; __device__ __forceinline__ int srccol(int kind, int n) {
;     if (kind == 1) { const int pn = n >> 8, p = n & 255, bj = p >> 7, wc = (p >> 5) & 3, fq = (p >> 3) & 3, nn = (p >> 2) & 1, e = p & 3;
;         return (nn ? DFF : 0) + 128 * pn + 64 * bj + 16 * wc + 4 * fq + e; }
;     if (kind == 2 && n < 1024) { const int hb_ = n & ~127, p = n & 127, wc = p >> 5, fq = (p >> 3) & 3, nn = (p >> 2) & 1, e = p & 3;
;         return hb_ + 16 * wc + 4 * fq + e + 64 * nn; }
;     return n;
; }
; __device__ __forceinline__ void p0_transpose_item(const float* W, int K, int ldw, int N, bf16* WT, int kind, LAS float* scr, int item, int lane) {
;     const int nblk = N / 32, kb = item / nblk, nb = item % nblk, k0 = 64 * kb, n0 = 32 * nb;
;     const int sc = srccol(kind, n0 + (lane & 31));
;     float t_[32];
; #pragma unroll
;     for (int i = 0; i < 32; ++i) t_[i] = W[(size_t)(k0 + 2 * i + (lane >> 5)) * ldw + sc];
; __device__ __forceinline__ void p0_prologue(Frame& F) {
;     ...
;             if (r < I_UP) { p0_transpose_item(in_ptr(IN_UP1) + (size_t)l * D * 2 * DFF, D, 2 * DFF, 2 * DFF, lw(F, l, LW_UP1), 1, scr, r, tc.lane); continue; } r -= I_UP;
.LBB0_48:
	s_andn2_b64 vcc, exec, s[26:27]
	s_cbranch_vccnz .LBB0_15
	s_mov_b64 s[26:27], s[0:1]
	s_load_dwordx2 s[26:27], s[26:27], 0x68
	s_lshl_b64 s[28:29], s[20:21], 2
	s_mov_b64 s[30:31], s[46:47]
	s_mul_hi_i32 s4, s77, 0x2e8ba2e9
	s_waitcnt lgkmcnt(0)
	s_add_u32 s28, s26, s28
	s_addc_u32 s29, s27, s29
	s_add_u32 s30, s30, s78
	s_addc_u32 s31, s31, 0
	s_lshr_b32 s26, s4, 31
	s_ashr_i32 s4, s4, 5
	s_add_i32 s26, s4, s26
	s_mul_i32 s4, s26, 0xb0
	s_sub_i32 s27, s77, s4
	s_lshl_b32 s4, s27, 5
	v_or_b32_e32 v2, s4, v1
	s_lshl_b32 s27, s27, 4
	s_and_b32 s27, s27, 0xffffff80
	v_lshrrev_b32_e32 v2, 1, v2
	v_add_u32_e32 v4, s27, v55
	v_and_b32_e32 v2, 0x7c, v2
	v_or3_b32 v4, v2, v4, v54
	s_lshl_b32 s26, s26, 6
	v_add_u32_e32 v2, s26, v33
	v_ashrrev_i32_e32 v5, 31, v4
	v_lshl_add_u64 v[4:5], v[4:5], 2, s[28:29]
	v_add_u32_e32 v8, 2, v2
	v_add_u32_e32 v10, 4, v2
	v_add_u32_e32 v12, 6, v2
	v_add_u32_e32 v14, 8, v2
	v_add_u32_e32 v16, 10, v2
	v_add_u32_e32 v18, 12, v2
	v_add_u32_e32 v20, 14, v2
	v_mad_i64_i32 v[6:7], s[28:29], v2, s76, v[4:5]
	v_mad_i64_i32 v[8:9], s[28:29], v8, s76, v[4:5]
	v_mad_i64_i32 v[10:11], s[28:29], v10, s76, v[4:5]
	v_mad_i64_i32 v[12:13], s[28:29], v12, s76, v[4:5]
	v_mad_i64_i32 v[14:15], s[28:29], v14, s76, v[4:5]
	v_mad_i64_i32 v[16:17], s[28:29], v16, s76, v[4:5]
	v_mad_i64_i32 v[18:19], s[28:29], v18, s76, v[4:5]
	v_mad_i64_i32 v[20:21], s[28:29], v20, s76, v[4:5]
	global_load_dword v22, v[6:7], off
	global_load_dword v23, v[8:9], off
	global_load_dword v24, v[10:11], off
	global_load_dword v25, v[12:13], off
	global_load_dword v26, v[14:15], off
	global_load_dword v27, v[16:17], off
	global_load_dword v28, v[18:19], off
	global_load_dword v29, v[20:21], off
	v_add_u32_e32 v6, 16, v2
	v_add_u32_e32 v8, 18, v2
	v_add_u32_e32 v10, 20, v2
	v_add_u32_e32 v12, 22, v2
	v_add_u32_e32 v14, 24, v2
	v_add_u32_e32 v16, 26, v2
	v_add_u32_e32 v18, 28, v2
	v_add_u32_e32 v20, 30, v2
	v_mad_i64_i32 v[6:7], s[28:29], v6, s76, v[4:5]
	v_mad_i64_i32 v[8:9], s[28:29], v8, s76, v[4:5]
	v_mad_i64_i32 v[10:11], s[28:29], v10, s76, v[4:5]
	v_mad_i64_i32 v[12:13], s[28:29], v12, s76, v[4:5]
	v_mad_i64_i32 v[14:15], s[28:29], v14, s76, v[4:5]
	v_mad_i64_i32 v[16:17], s[28:29], v16, s76, v[4:5]
	v_mad_i64_i32 v[18:19], s[28:29], v18, s76, v[4:5]
	v_mad_i64_i32 v[20:21], s[28:29], v20, s76, v[4:5]
	global_load_dword v30, v[6:7], off
	global_load_dword v31, v[8:9], off
	global_load_dword v34, v[10:11], off
	global_load_dword v35, v[12:13], off
	global_load_dword v36, v[14:15], off
	global_load_dword v37, v[16:17], off
	global_load_dword v38, v[18:19], off
	global_load_dword v39, v[20:21], off
	v_add_u32_e32 v6, 32, v2
	v_add_u32_e32 v8, 34, v2
	v_add_u32_e32 v10, 36, v2
	v_add_u32_e32 v12, 38, v2
	v_add_u32_e32 v14, 40, v2
	v_add_u32_e32 v16, 42, v2
	v_add_u32_e32 v18, 44, v2
	v_add_u32_e32 v20, 46, v2
	v_mad_i64_i32 v[6:7], s[28:29], v6, s76, v[4:5]
	v_mad_i64_i32 v[8:9], s[28:29], v8, s76, v[4:5]
	v_mad_i64_i32 v[10:11], s[28:29], v10, s76, v[4:5]
	v_mad_i64_i32 v[12:13], s[28:29], v12, s76, v[4:5]
	v_mad_i64_i32 v[14:15], s[28:29], v14, s76, v[4:5]
	v_mad_i64_i32 v[16:17], s[28:29], v16, s76, v[4:5]
	v_mad_i64_i32 v[18:19], s[28:29], v18, s76, v[4:5]
	v_mad_i64_i32 v[20:21], s[28:29], v20, s76, v[4:5]
	global_load_dword v40, v[6:7], off
	global_load_dword v42, v[8:9], off
	global_load_dword v44, v[10:11], off
	global_load_dword v46, v[12:13], off
	global_load_dword v48, v[14:15], off
	global_load_dword v50, v[16:17], off
	global_load_dword v52, v[18:19], off
	s_nop 0
	global_load_dword v20, v[20:21], off
	v_add_u32_e32 v6, 48, v2
	v_add_u32_e32 v8, 50, v2
	v_add_u32_e32 v10, 52, v2
	v_add_u32_e32 v12, 54, v2
	v_add_u32_e32 v14, 56, v2
	v_add_u32_e32 v16, 58, v2
	v_add_u32_e32 v18, 60, v2
	v_add_u32_e32 v2, 62, v2
	v_mad_i64_i32 v[6:7], s[28:29], v6, s76, v[4:5]
	v_mad_i64_i32 v[8:9], s[28:29], v8, s76, v[4:5]
	v_mad_i64_i32 v[10:11], s[28:29], v10, s76, v[4:5]
	v_mad_i64_i32 v[12:13], s[28:29], v12, s76, v[4:5]
	v_mad_i64_i32 v[14:15], s[28:29], v14, s76, v[4:5]
	v_mad_i64_i32 v[16:17], s[28:29], v16, s76, v[4:5]
	v_mad_i64_i32 v[18:19], s[28:29], v18, s76, v[4:5]
	v_mad_i64_i32 v[4:5], s[28:29], v2, s76, v[4:5]
	global_load_dword v2, v[6:7], off
	s_nop 0
	global_load_dword v6, v[8:9], off
	global_load_dword v7, v[10:11], off
	s_nop 0
	global_load_dword v8, v[12:13], off
	global_load_dword v9, v[14:15], off
	global_load_dword v10, v[16:17], off
	global_load_dword v11, v[18:19], off
	s_nop 0
	global_load_dword v4, v[4:5], off
	v_add_u32_e32 v5, 0x400, v41
	s_waitcnt vmcnt(30)
; #define GAS __attribute__((address_space(1)))
; #define LAS __attribute__((address_space(3)))
; __device__ __forceinline__ unsigned pk2(float lo, float hi) { return f2bf(lo) | (f2bf(hi) << 16); }
; __device__ __forceinline__ void p0_transpose_item(const float* W, int K, int ldw, int N, bf16* WT, int kind, LAS float* scr, int item, int lane) {
;     ...
; #pragma unroll
;     for (int i = 0; i < 32; ++i) scr[(2 * i + (lane >> 5)) * 33 + (lane & 31)] = t_[i];
;     asm volatile("s_waitcnt lgkmcnt(0)" ::: "memory");
;     const int c = lane & 7;
; #pragma unroll
;     for (int j = 0; j < 4; ++j) { const int n = (lane >> 3) + 8 * j; const LAS float* s = scr + (8 * c) * 33 + n;
;         v4u o; o.x = pk2(s[0 * 33], s[1 * 33]); o.y = pk2(s[2 * 33], s[3 * 33]); o.z = pk2(s[4 * 33], s[5 * 33]); o.w = pk2(s[6 * 33], s[7 * 33]);
;         *(GAS v4u*)(WT + (size_t)(n0 + n) * K + k0 + 8 * c) = o; }
;     asm volatile("s_waitcnt lgkmcnt(0)" ::: "memory");
	ds_write2_b32 v41, v22, v23 offset1:66
	s_waitcnt vmcnt(28)
	ds_write2_b32 v41, v24, v25 offset0:132 offset1:198
	s_waitcnt vmcnt(26)
	ds_write2_b32 v5, v26, v27 offset0:8 offset1:74
	s_waitcnt vmcnt(24)
	ds_write2_b32 v5, v28, v29 offset0:140 offset1:206
	v_add_u32_e32 v5, 0x800, v41
	s_waitcnt vmcnt(22)
	ds_write2_b32 v5, v30, v31 offset0:16 offset1:82
	s_waitcnt vmcnt(20)
	ds_write2_b32 v5, v34, v35 offset0:148 offset1:214
	v_add_u32_e32 v5, 0xc00, v41
	s_waitcnt vmcnt(18)
	ds_write2_b32 v5, v36, v37 offset0:24 offset1:90
	s_waitcnt vmcnt(16)
	ds_write2_b32 v5, v38, v39 offset0:156 offset1:222
	v_add_u32_e32 v5, 0x1000, v41
	s_waitcnt vmcnt(14)
	ds_write2_b32 v5, v40, v42 offset0:32 offset1:98
	s_waitcnt vmcnt(12)
	ds_write2_b32 v5, v44, v46 offset0:164 offset1:230
	v_add_u32_e32 v5, 0x1400, v41
	s_waitcnt vmcnt(10)
	ds_write2_b32 v5, v48, v50 offset0:40 offset1:106
	s_waitcnt vmcnt(8)
	ds_write2_b32 v5, v52, v20 offset0:172 offset1:238
	v_add_u32_e32 v5, 0x1800, v41
	s_waitcnt vmcnt(6)
	ds_write2_b32 v5, v2, v6 offset0:48 offset1:114
	s_waitcnt vmcnt(4)
	ds_write2_b32 v5, v7, v8 offset0:180 offset1:246
	v_add_u32_e32 v2, 0x1c00, v41
	s_waitcnt vmcnt(2)
	ds_write2_b32 v2, v9, v10 offset0:56 offset1:122
	s_waitcnt vmcnt(0)
	ds_write2_b32 v2, v11, v4 offset0:188 offset1:254
	s_waitcnt lgkmcnt(0)
	ds_read2_b32 v[8:9], v45 offset1:8
	s_ashr_i32 s27, s26, 31
	ds_read2_b32 v[12:13], v45 offset0:33 offset1:41
	s_lshl_b64 s[26:27], s[26:27], 1
	s_add_u32 s26, s30, s26
	ds_read2_b32 v[14:15], v45 offset0:66 offset1:74
	s_addc_u32 s27, s31, s27
	v_lshlrev_b32_e32 v2, 1, v0
	ds_read2_b32 v[16:17], v45 offset0:99 offset1:107
	v_lshl_add_u64 v[4:5], s[26:27], 0, v[2:3]
	s_waitcnt lgkmcnt(3)
	v_bfe_u32 v2, v8, 16, 1
	v_lshl_add_u64 v[10:11], v[4:5], 0, s[10:11]
	v_add3_u32 v2, v8, v2, s38
	s_waitcnt lgkmcnt(2)
	v_bfe_u32 v4, v12, 16, 1
	ds_read2_b32 v[18:19], v45 offset0:132 offset1:140
	v_lshrrev_b32_e32 v2, 16, v2
	v_add3_u32 v4, v12, v4, s38
	ds_read2_b32 v[20:21], v45 offset0:165 offset1:173
	v_and_or_b32 v4, v4, s39, v2
	s_waitcnt lgkmcnt(3)
	s_waitcnt lgkmcnt(2)
	ds_read2_b32 v[22:23], v45 offset0:198 offset1:206
	ds_read2_b32 v[24:25], v45 offset0:231 offset1:239
	v_cvt_pk_bf16_f32 v5, v14, v16
	s_waitcnt lgkmcnt(3)
	s_waitcnt lgkmcnt(2)
	v_cvt_pk_bf16_f32 v6, v18, v20
	s_waitcnt lgkmcnt(1)
	v_add_u32_e32 v26, s4, v43
	s_waitcnt lgkmcnt(0)
	v_ashrrev_i32_e32 v27, 31, v26
	v_lshlrev_b64 v[26:27], 11, v[26:27]
	v_cvt_pk_bf16_f32 v7, v22, v24
	v_lshl_add_u64 v[26:27], v[10:11], 0, v[26:27]
	v_bfe_u32 v2, v9, 16, 1
	global_store_dwordx4 v[26:27], v[4:7], off
	v_add3_u32 v2, v9, v2, s38
	v_lshrrev_b32_e32 v2, 16, v2
	v_bfe_u32 v4, v13, 16, 1
	v_add3_u32 v4, v13, v4, s38
	v_and_or_b32 v4, v4, s39, v2
	v_cvt_pk_bf16_f32 v5, v15, v17
	v_cvt_pk_bf16_f32 v6, v19, v21
	v_add_u32_e32 v8, s4, v47
	v_ashrrev_i32_e32 v9, 31, v8
	v_lshlrev_b64 v[8:9], 11, v[8:9]
	v_cvt_pk_bf16_f32 v7, v23, v25
	ds_read2_b32 v[12:13], v45 offset0:16 offset1:24
	v_lshl_add_u64 v[8:9], v[10:11], 0, v[8:9]
	global_store_dwordx4 v[8:9], v[4:7], off
	ds_read2_b32 v[8:9], v45 offset0:49 offset1:57
	ds_read2_b32 v[14:15], v45 offset0:82 offset1:90
	ds_read2_b32 v[16:17], v45 offset0:115 offset1:123
	s_waitcnt lgkmcnt(3)
	s_waitcnt lgkmcnt(2)
	ds_read2_b32 v[18:19], v45 offset0:148 offset1:156
	ds_read2_b32 v[20:21], v45 offset0:181 offset1:189
	v_cvt_pk_bf16_f32 v4, v12, v8
	s_waitcnt lgkmcnt(3)
	s_waitcnt lgkmcnt(2)
	ds_read2_b32 v[22:23], v45 offset0:214 offset1:222
	ds_read2_b32 v[24:25], v45 offset0:247 offset1:255
	v_cvt_pk_bf16_f32 v5, v14, v16
	s_waitcnt lgkmcnt(3)
	s_waitcnt lgkmcnt(2)
	v_cvt_pk_bf16_f32 v6, v18, v20
	s_waitcnt lgkmcnt(1)
	v_add_u32_e32 v26, s4, v49
	s_waitcnt lgkmcnt(0)
	v_ashrrev_i32_e32 v27, 31, v26
	v_lshlrev_b64 v[26:27], 11, v[26:27]
	v_cvt_pk_bf16_f32 v7, v22, v24
	v_lshl_add_u64 v[26:27], v[10:11], 0, v[26:27]
	v_bfe_u32 v2, v13, 16, 1
	global_store_dwordx4 v[26:27], v[4:7], off
	v_add3_u32 v2, v13, v2, s38
	v_lshrrev_b32_e32 v2, 16, v2
	v_bfe_u32 v4, v9, 16, 1
	v_add3_u32 v4, v9, v4, s38
	v_and_or_b32 v4, v4, s39, v2
	v_cvt_pk_bf16_f32 v5, v15, v17
	v_cvt_pk_bf16_f32 v6, v19, v21
	v_add_u32_e32 v8, s4, v51
	v_ashrrev_i32_e32 v9, 31, v8
	v_lshlrev_b64 v[8:9], 11, v[8:9]
	v_cvt_pk_bf16_f32 v7, v23, v25
	v_lshl_add_u64 v[8:9], v[10:11], 0, v[8:9]
	global_store_dwordx4 v[8:9], v[4:7], off
	s_waitcnt lgkmcnt(0)
	s_branch .LBB0_15

; #define GAS __attribute__((address_space(1)))
; __device__ __forceinline__ unsigned pk2(float lo, float hi) { return f2bf(lo) | (f2bf(hi) << 16); }
; #define WSB(F, off) ((bf16*)(wsq((F).ws) + (off)))
; __device__ __forceinline__ void p0_prologue(Frame& F) {
;     ...
; #pragma unroll
;         for (int r = 0; r < 2; ++r) { const int m = m0 + r * NGW;
;             if (m < M_PAD) { GAS v2u* o8 = (GAS v2u*)(WSB(F, WS_HB) + (size_t)m * D) + tc.lane;
; #pragma unroll
;                 for (int j = 0; j < 4; ++j) o8[64 * j] = (v2u){pk2(v[r][j].x, v[r][j].y), pk2(v[r][j].z, v[r][j].w)}; } }
.LBB0_87:
	s_waitcnt vmcnt(0)
	s_mov_b64 s[4:5], s[46:47]
	v_cvt_pk_bf16_f32 v4, v4, v5
	s_add_u32 s4, s4, s3
	s_addc_u32 s5, s5, s24
	v_lshl_add_u64 v[34:35], v[32:33], 3, s[4:5]
	v_cvt_pk_bf16_f32 v5, v6, v7
	global_store_dwordx2 v[34:35], v[4:5], off
	v_cvt_pk_bf16_f32 v0, v0, v1
	v_cvt_pk_bf16_f32 v1, v2, v3
	global_store_dwordx2 v[34:35], v[0:1], off offset:512
	v_cvt_pk_bf16_f32 v0, v12, v13
	v_cvt_pk_bf16_f32 v1, v14, v15
	global_store_dwordx2 v[34:35], v[0:1], off offset:1024
	v_cvt_pk_bf16_f32 v0, v8, v9
	v_cvt_pk_bf16_f32 v1, v10, v11
	s_andn2_b64 vcc, exec, s[20:21]
	global_store_dwordx2 v[34:35], v[0:1], off offset:1536
	s_cbranch_vccnz .LBB0_52
	s_mov_b64 s[4:5], s[46:47]
	s_ashr_i32 s19, s18, 31
	s_lshl_b64 s[18:19], s[18:19], 11
	s_add_u32 s4, s4, s18
	s_addc_u32 s5, s5, s19
	v_cvt_pk_bf16_f32 v4, v24, v25
	v_lshl_add_u64 v[0:1], v[32:33], 3, s[4:5]
	v_lshl_add_u64 v[2:3], v[0:1], 0, s[12:13]
	v_add_co_u32_e32 v0, vcc, s27, v0
	v_cvt_pk_bf16_f32 v5, v26, v27
	s_nop 0
	v_addc_co_u32_e32 v1, vcc, 0, v1, vcc
	global_store_dwordx2 v[0:1], v[4:5], off
	v_cvt_pk_bf16_f32 v0, v16, v17
	v_cvt_pk_bf16_f32 v1, v18, v19
	global_store_dwordx2 v[2:3], v[0:1], off offset:512
	v_cvt_pk_bf16_f32 v0, v28, v29
	v_cvt_pk_bf16_f32 v1, v30, v31
	global_store_dwordx2 v[2:3], v[0:1], off offset:1024
	v_cvt_pk_bf16_f32 v0, v20, v21
	v_cvt_pk_bf16_f32 v1, v22, v23
	global_store_dwordx2 v[2:3], v[0:1], off offset:1536
	s_branch .LBB0_52

; #define GAS __attribute__((address_space(1)))
; #define WSB(F, off) ((bf16*)(wsq((F).ws) + (off)))
; __device__ __forceinline__ void ln_rows(const Frame& F, int idx, bool final_out, int row_lo, int row_hi, int gw0, int NGW, bool comb = false) {
;     ...
;     for (int m0 = row_lo + gw; m0 < row_hi; m0 += 2 * NGW) {
;         v4u w[2][2]; const bool two = m0 + NGW < row_hi;
; #pragma unroll
;         for (int r = 0; r < 2; ++r) { const int m = (r == 0 || two) ? m0 + r * NGW : m0; const GAS v4u* yr = (const GAS v4u*)(WSB(F, comb ? WS_HB : WS_YB) + (size_t)m * D) + tc.lane; w[r][0] = yr[0]; w[r][1] = yr[64]; }
; #pragma unroll
;         for (int r = 0; r < 2; ++r) { const int m = m0 + r * NGW; if (r == 1 && !two) break;
;         f32x4 v[4]; float s = 0.f;
; #pragma unroll
;         for (int j = 0; j < 2; ++j) { const v4u x = w[r][j]; v[2 * j] = (f32x4){bflo(x.x), bfhi(x.x), bflo(x.y), bfhi(x.y)}; v[2 * j + 1] = (f32x4){bflo(x.z), bfhi(x.z), bflo(x.w), bfhi(x.w)}; }
;         if (comb) {
;             const GAS f32x4* pa = (const GAS f32x4*)((const float*)WSB(F, WS_ACT) + (size_t)(m - MP) * D) + 2 * tc.lane; const GAS f32x4* pb = pa + (size_t)512 * D / 4;
; #pragma unroll
;             for (int j = 0; j < 2; ++j) { v[2 * j] = v[2 * j] * ALPHA + (pa[128 * j] + pb[128 * j]) * 0.5f; v[2 * j + 1] = v[2 * j + 1] * ALPHA + (pa[128 * j + 1] + pb[128 * j + 1]) * 0.5f; } }
; #pragma unroll
;         for (int j = 0; j < 4; ++j) s += (v[j].x + v[j].y) + (v[j].z + v[j].w);
;         const float mean = wave_sum(s) * (1.f / D); float s2 = 0.f;
; #pragma unroll
;         for (int j = 0; j < 4; ++j) { v[j] = v[j] - mean; s2 += (v[j].x * v[j].x + v[j].y * v[j].y) + (v[j].z * v[j].z + v[j].w * v[j].w); }
;         const float rstd = 1.f / sqrtf(wave_sum(s2) * (1.f / D) + LN_EPS);
.LBB0_296:
	v_readlane_b32 s4, v253, 7
	s_add_i32 s4, s4, s10
	s_add_i32 s6, s4, 0xffffff80
	s_mov_b64 s[4:5], s[46:47]
	s_add_u32 s4, s4, s2
	s_addc_u32 s5, s5, s3
	v_lshlrev_b64 v[44:45], 4, v[42:43]
	v_lshl_add_u64 v[34:35], s[4:5], 0, v[44:45]
	s_mov_b32 s4, 0xf7f00000
	s_mov_b32 s5, -1
	v_lshl_add_u64 v[36:37], v[34:35], 0, s[4:5]
	s_mov_b32 s4, 0xf7f00000
	v_add_co_u32_e32 v34, vcc, s4, v34
	s_cmp_lt_i32 s6, 0x10000
	s_nop 0
	v_addc_co_u32_e32 v35, vcc, -1, v35, vcc
	global_load_dwordx4 v[60:63], v[34:35], off
	global_load_dwordx4 v[46:49], v[36:37], off offset:1024
	v_readlane_b32 s4, v253, 15
	s_cselect_b32 s4, s4, 0
	s_add_i32 s4, s4, s10
	s_ashr_i32 s5, s4, 31
	s_mov_b64 s[8:9], s[46:47]
	s_lshl_b64 s[4:5], s[4:5], 11
	s_add_u32 s4, s8, s4
	s_addc_u32 s5, s9, s5
	v_lshl_add_u64 v[34:35], s[4:5], 0, v[44:45]
	s_mov_b64 s[4:5], 0x100000
	v_lshl_add_u64 v[38:39], v[34:35], 0, s[4:5]
	s_mov_b32 s4, 0x100000
	v_add_co_u32_e32 v34, vcc, s4, v34
	s_mov_b64 s[4:5], s[46:47]
	s_nop 0
	v_addc_co_u32_e32 v35, vcc, 0, v35, vcc
	global_load_dwordx4 v[34:37], v[34:35], off
	s_nop 0
	global_load_dwordx4 v[38:41], v[38:39], off offset:1024
	s_add_u32 s8, s4, s2
	s_addc_u32 s9, s5, s3
	s_cmp_gt_i32 s6, 0xffff
	s_waitcnt vmcnt(0)
	v_lshlrev_b32_e32 v59, 16, v61
	v_lshlrev_b32_e32 v58, 16, v60
	v_and_b32_e32 v65, 0xffff0000, v61
	v_and_b32_e32 v64, 0xffff0000, v60
	v_pk_add_f32 v[60:61], v[58:59], v[64:65]
	v_lshlrev_b32_e32 v54, 16, v46
	v_add_f32_e32 v1, v60, v61
	v_lshlrev_b32_e32 v61, 16, v63
	v_lshlrev_b32_e32 v60, 16, v62
	v_and_b32_e32 v63, 0xffff0000, v63
	v_and_b32_e32 v62, 0xffff0000, v62
	v_and_b32_e32 v55, 0xffff0000, v46
	v_lshlrev_b32_e32 v56, 16, v47
	v_and_b32_e32 v57, 0xffff0000, v47
	v_pk_add_f32 v[66:67], v[60:61], v[62:63]
	v_lshlrev_b32_e32 v50, 16, v48
	v_and_b32_e32 v52, 0xffff0000, v48
	v_lshlrev_b32_e32 v46, 16, v49
	v_and_b32_e32 v48, 0xffff0000, v49
	v_add_f32_e32 v49, 0, v1
	v_pk_add_f32 v[66:67], v[66:67], v[66:67] op_sel_hi:[0,1]
	v_add_f32_e32 v51, v54, v55
	v_add_f32_e32 v53, v56, v57
	v_and_b32_e32 v1, 64, v239
	v_pk_add_f32 v[68:69], v[50:51], v[52:53]
	v_mov_b32_e32 v47, v67
	v_add_u32_e32 v51, 64, v1
	v_xor_b32_e32 v1, 1, v239
	v_pk_add_f32 v[66:67], v[46:47], v[48:49]
	v_cmp_lt_i32_e32 vcc, v1, v51
	v_pk_add_f32 v[66:67], v[68:69], v[66:67]
	s_nop 0
	v_cndmask_b32_e32 v1, v239, v1, vcc
	v_add_f32_e32 v47, v66, v67
	v_lshlrev_b32_e32 v1, 2, v1
	ds_bpermute_b32 v49, v1, v47
	s_waitcnt lgkmcnt(0)
	v_add_f32_e32 v47, v47, v49
	v_xor_b32_e32 v49, 2, v239
	v_cmp_lt_i32_e32 vcc, v49, v51
	s_nop 1
	v_cndmask_b32_e32 v49, v239, v49, vcc
	v_lshlrev_b32_e32 v49, 2, v49
	ds_bpermute_b32 v53, v49, v47
	s_waitcnt lgkmcnt(0)
	v_add_f32_e32 v47, v47, v53
	v_xor_b32_e32 v53, 4, v239
	v_cmp_lt_i32_e32 vcc, v53, v51
	s_nop 1
	v_cndmask_b32_e32 v53, v239, v53, vcc
	v_lshlrev_b32_e32 v53, 2, v53
	ds_bpermute_b32 v66, v53, v47
	s_waitcnt lgkmcnt(0)
	v_add_f32_e32 v47, v47, v66
	v_xor_b32_e32 v66, 8, v239
	v_cmp_lt_i32_e32 vcc, v66, v51
	s_nop 1
	v_cndmask_b32_e32 v66, v239, v66, vcc
	v_lshlrev_b32_e32 v70, 2, v66
	ds_bpermute_b32 v66, v70, v47
	s_waitcnt lgkmcnt(0)
	v_add_f32_e32 v47, v47, v66
	v_xor_b32_e32 v66, 16, v239
	v_cmp_lt_i32_e32 vcc, v66, v51
	s_nop 1
	v_cndmask_b32_e32 v66, v239, v66, vcc
	v_lshlrev_b32_e32 v71, 2, v66
	ds_bpermute_b32 v66, v71, v47
	s_waitcnt lgkmcnt(0)
	v_add_f32_e32 v47, v47, v66
	v_xor_b32_e32 v66, 32, v239
	v_cmp_lt_i32_e32 vcc, v66, v51
	s_nop 1
	v_cndmask_b32_e32 v51, v239, v66, vcc
	v_lshlrev_b32_e32 v72, 2, v51
	ds_bpermute_b32 v51, v72, v47
	s_waitcnt lgkmcnt(0)
	v_add_f32_e32 v47, v47, v51
	v_fmac_f32_e32 v64, 0xba800000, v47
	v_fmac_f32_e32 v65, 0xba800000, v47
	v_fmac_f32_e32 v59, 0xba800000, v47
	v_fmac_f32_e32 v58, 0xba800000, v47
	v_mov_b32_e32 v66, v59
	v_mov_b32_e32 v67, v65
	v_mov_b32_e32 v59, v64
	v_pk_mul_f32 v[68:69], v[66:67], v[66:67]
	v_pk_mul_f32 v[64:65], v[58:59], v[58:59]
	v_fmac_f32_e32 v62, 0xba800000, v47
	v_pk_mov_b32 v[74:75], v[64:65], v[68:69] op_sel:[1,0]
	v_mov_b32_e32 v65, v69
	v_pk_add_f32 v[64:65], v[74:75], v[64:65]
	v_fmac_f32_e32 v63, 0xba800000, v47
	v_fmac_f32_e32 v61, 0xba800000, v47
	v_pk_add_f32 v[68:69], v[64:65], v[64:65] op_sel_hi:[0,1]
	v_fmac_f32_e32 v60, 0xba800000, v47
	v_mov_b32_e32 v64, v61
	v_mov_b32_e32 v65, v63
	v_mov_b32_e32 v61, v62
	v_pk_mul_f32 v[74:75], v[64:65], v[64:65]
	v_pk_mul_f32 v[62:63], v[60:61], v[60:61]
	v_fmac_f32_e32 v54, 0xba800000, v47
	v_pk_mov_b32 v[76:77], v[62:63], v[74:75] op_sel:[1,0]
	v_mov_b32_e32 v63, v75
	v_pk_add_f32 v[62:63], v[76:77], v[62:63]
	v_fmac_f32_e32 v55, 0xba800000, v47
	v_pk_add_f32 v[62:63], v[62:63], v[62:63] op_sel_hi:[0,1]
	v_fmac_f32_e32 v56, 0xba800000, v47
	v_mul_f32_e32 v62, v54, v54
	v_fmac_f32_e32 v57, 0xba800000, v47
	v_pk_fma_f32 v[74:75], v[54:55], v[54:55], v[62:63] op_sel_hi:[1,1,0]
	v_mul_f32_e32 v62, v56, v56
	v_pk_fma_f32 v[76:77], v[56:57], v[56:57], v[62:63] op_sel_hi:[1,1,0]
	v_fmac_f32_e32 v48, 0xba800000, v47
	v_fmac_f32_e32 v46, 0xba800000, v47
	v_fmac_f32_e32 v52, 0xba800000, v47
	v_fmac_f32_e32 v50, 0xba800000, v47
	v_mul_f32_e32 v74, v50, v50
	v_mul_f32_e32 v76, v52, v52
	v_mul_f32_e32 v68, v46, v46
	v_mul_f32_e32 v62, v48, v48
	v_pk_add_f32 v[74:75], v[74:75], v[76:77]
	v_pk_add_f32 v[62:63], v[68:69], v[62:63]
	s_nop 0
	v_pk_add_f32 v[62:63], v[74:75], v[62:63]
	s_nop 0
	v_add_f32_e32 v47, v62, v63
	ds_bpermute_b32 v51, v1, v47
	s_waitcnt lgkmcnt(0)
	v_add_f32_e32 v47, v47, v51
	ds_bpermute_b32 v51, v49, v47
	s_waitcnt lgkmcnt(0)
	v_add_f32_e32 v47, v47, v51
	ds_bpermute_b32 v51, v53, v47
	s_waitcnt lgkmcnt(0)
	v_add_f32_e32 v47, v47, v51
	ds_bpermute_b32 v51, v70, v47
	s_waitcnt lgkmcnt(0)
; #define GAS __attribute__((address_space(1)))
; __device__ __forceinline__ unsigned pk2(float lo, float hi) { return f2bf(lo) | (f2bf(hi) << 16); }
; #define WSB(F, off) ((bf16*)(wsq((F).ws) + (off)))
; __device__ __forceinline__ void ln_rows(const Frame& F, int idx, bool final_out, int row_lo, int row_hi, int gw0, int NGW, bool comb = false) {
;     ...
;         const float mean = wave_sum(s) * (1.f / D); float s2 = 0.f;
; #pragma unroll
;         for (int j = 0; j < 4; ++j) { v[j] = v[j] - mean; s2 += (v[j].x * v[j].x + v[j].y * v[j].y) + (v[j].z * v[j].z + v[j].w * v[j].w); }
;         const float rstd = 1.f / sqrtf(wave_sum(s2) * (1.f / D) + LN_EPS);
; #pragma unroll
;         for (int j = 0; j < 4; ++j) v[j] = v[j] * rstd * gv[j] + bv[j];
;         if (!final_out) { GAS v4u* o = (GAS v4u*)(WSB(F, WS_HB) + (size_t)m * D) + tc.lane;
; #pragma unroll
;             for (int j = 0; j < 2; ++j) o[64 * j] = (v4u){pk2(v[2 * j].x, v[2 * j].y), pk2(v[2 * j].z, v[2 * j].w), pk2(v[2 * j + 1].x, v[2 * j + 1].y), pk2(v[2 * j + 1].z, v[2 * j + 1].w)}; }
	v_add_f32_e32 v47, v47, v51
	ds_bpermute_b32 v51, v71, v47
	s_waitcnt lgkmcnt(0)
	v_add_f32_e32 v47, v47, v51
	ds_bpermute_b32 v51, v72, v47
	s_waitcnt lgkmcnt(0)
	v_add_f32_e32 v47, v47, v51
	v_fmamk_f32 v47, v47, 0x3a800000, v235
	v_cmp_gt_f32_e32 vcc, s89, v47
	v_mul_f32_e32 v51, 0x4f800000, v47
	s_nop 0
	v_cndmask_b32_e32 v47, v47, v51, vcc
	v_sqrt_f32_e32 v51, v47
	s_nop 0
	v_add_u32_e32 v62, -1, v51
	v_fma_f32 v63, -v62, v51, v47
	v_cmp_ge_f32_e64 s[4:5], 0, v63
	v_add_u32_e32 v63, 1, v51
	s_nop 0
	v_cndmask_b32_e64 v62, v51, v62, s[4:5]
	v_fma_f32 v51, -v63, v51, v47
	v_cmp_lt_f32_e64 s[4:5], 0, v51
	s_nop 1
	v_cndmask_b32_e64 v51, v62, v63, s[4:5]
	v_mul_f32_e32 v62, 0x37800000, v51
	v_cndmask_b32_e32 v51, v51, v62, vcc
	v_cmp_class_f32_e32 vcc, v47, v236
	s_nop 1
	v_cndmask_b32_e32 v47, v51, v47, vcc
	v_div_scale_f32 v51, s[4:5], v47, v47, 1.0
	v_rcp_f32_e32 v62, v51
	s_nop 0
	v_fma_f32 v63, -v51, v62, 1.0
	v_fmac_f32_e32 v62, v63, v62
	v_div_scale_f32 v63, vcc, 1.0, v47, 1.0
	v_mul_f32_e32 v68, v63, v62
	v_fma_f32 v69, -v51, v68, v63
	v_fmac_f32_e32 v68, v69, v62
	v_fma_f32 v51, -v51, v68, v63
	v_div_fmas_f32 v51, v51, v62, v68
	v_div_fixup_f32 v68, v51, v47, 1.0
	v_pk_mul_f32 v[58:59], v[58:59], v[68:69] op_sel_hi:[1,0]
	v_mov_b32_e32 v47, v48
	v_pk_mul_f32 v[62:63], v[66:67], v[68:69] op_sel_hi:[1,0]
	v_pk_mul_f32 v[60:61], v[60:61], v[68:69] op_sel_hi:[1,0]
	v_pk_mul_f32 v[46:47], v[46:47], v[68:69] op_sel_hi:[1,0]
	v_pk_fma_f32 v[58:59], v[6:7], v[58:59], v[14:15]
	v_pk_fma_f32 v[66:67], v[20:21], v[46:47], v[28:29]
	v_pk_fma_f32 v[46:47], v[2:3], v[60:61], v[10:11]
	v_pk_fma_f32 v[60:61], v[8:9], v[62:63], v[16:17]
	v_lshl_add_u64 v[62:63], s[8:9], 0, v[44:45]
	v_cvt_pk_bf16_f32 v44, v58, v59
	v_cvt_pk_bf16_f32 v45, v60, v61
	v_pk_mul_f32 v[64:65], v[64:65], v[68:69] op_sel_hi:[1,0]
	v_pk_fma_f32 v[64:65], v[4:5], v[64:65], v[12:13]
	v_cvt_pk_bf16_f32 v46, v46, v47
	v_pk_mul_f32 v[54:55], v[54:55], v[68:69] op_sel_hi:[1,0]
	v_pk_fma_f32 v[54:55], v[22:23], v[54:55], v[30:31]
	v_cvt_pk_bf16_f32 v47, v64, v65
	global_store_dwordx4 v[62:63], v[44:47], off
	v_pk_mul_f32 v[56:57], v[56:57], v[68:69] op_sel_hi:[1,0]
	v_mov_b32_e32 v51, v52
	v_pk_fma_f32 v[56:57], v[24:25], v[56:57], v[32:33]
	v_cvt_pk_bf16_f32 v44, v54, v55
	v_pk_mul_f32 v[50:51], v[50:51], v[68:69] op_sel_hi:[1,0]
	v_pk_fma_f32 v[50:51], v[18:19], v[50:51], v[26:27]
	v_cvt_pk_bf16_f32 v45, v56, v57
	v_cvt_pk_bf16_f32 v46, v50, v51
	v_cvt_pk_bf16_f32 v47, v66, v67
	global_store_dwordx4 v[62:63], v[44:47], off offset:1024
	s_cbranch_scc1 .LBB0_295
; #define GAS __attribute__((address_space(1)))
; __device__ __forceinline__ unsigned pk2(float lo, float hi) { return f2bf(lo) | (f2bf(hi) << 16); }
; #define WSB(F, off) ((bf16*)(wsq((F).ws) + (off)))
; __device__ __forceinline__ void ln_rows(const Frame& F, int idx, bool final_out, int row_lo, int row_hi, int gw0, int NGW, bool comb = false) {
;     ...
;         for (int r = 0; r < 2; ++r) { const int m = m0 + r * NGW; if (r == 1 && !two) break;
;         f32x4 v[4]; float s = 0.f;
; #pragma unroll
;         for (int j = 0; j < 2; ++j) { const v4u x = w[r][j]; v[2 * j] = (f32x4){bflo(x.x), bfhi(x.x), bflo(x.y), bfhi(x.y)}; v[2 * j + 1] = (f32x4){bflo(x.z), bfhi(x.z), bflo(x.w), bfhi(x.w)}; }
;         if (comb) {
;             const GAS f32x4* pa = (const GAS f32x4*)((const float*)WSB(F, WS_ACT) + (size_t)(m - MP) * D) + 2 * tc.lane; const GAS f32x4* pb = pa + (size_t)512 * D / 4;
; #pragma unroll
;             for (int j = 0; j < 2; ++j) { v[2 * j] = v[2 * j] * ALPHA + (pa[128 * j] + pb[128 * j]) * 0.5f; v[2 * j + 1] = v[2 * j + 1] * ALPHA + (pa[128 * j + 1] + pb[128 * j + 1]) * 0.5f; } }
; #pragma unroll
;         for (int j = 0; j < 4; ++j) s += (v[j].x + v[j].y) + (v[j].z + v[j].w);
;         const float mean = wave_sum(s) * (1.f / D); float s2 = 0.f;
; #pragma unroll
;         for (int j = 0; j < 4; ++j) { v[j] = v[j] - mean; s2 += (v[j].x * v[j].x + v[j].y * v[j].y) + (v[j].z * v[j].z + v[j].w * v[j].w); }
;         const float rstd = 1.f / sqrtf(wave_sum(s2) * (1.f / D) + LN_EPS);
; #pragma unroll
;         for (int j = 0; j < 4; ++j) v[j] = v[j] * rstd * gv[j] + bv[j];
;         if (!final_out) { GAS v4u* o = (GAS v4u*)(WSB(F, WS_HB) + (size_t)m * D) + tc.lane;
; #pragma unroll
;             for (int j = 0; j < 2; ++j) o[64 * j] = (v4u){pk2(v[2 * j].x, v[2 * j].y), pk2(v[2 * j].z, v[2 * j].w), pk2(v[2 * j + 1].x, v[2 * j + 1].y), pk2(v[2 * j + 1].z, v[2 * j + 1].w)}; }
	v_lshlrev_b32_e32 v57, 16, v35
	v_lshlrev_b32_e32 v56, 16, v34
	v_and_b32_e32 v35, 0xffff0000, v35
	v_and_b32_e32 v34, 0xffff0000, v34
	v_pk_add_f32 v[58:59], v[56:57], v[34:35]
	v_lshlrev_b32_e32 v50, 16, v41
	v_and_b32_e32 v54, 0xffff0000, v41
	v_add_f32_e32 v41, v58, v59
	v_lshlrev_b32_e32 v59, 16, v37
	v_lshlrev_b32_e32 v58, 16, v36
	v_and_b32_e32 v37, 0xffff0000, v37
	v_and_b32_e32 v36, 0xffff0000, v36
	v_pk_add_f32 v[60:61], v[58:59], v[36:37]
	v_lshlrev_b32_e32 v44, 16, v38
	v_and_b32_e32 v45, 0xffff0000, v38
	v_lshlrev_b32_e32 v38, 16, v39
	v_and_b32_e32 v39, 0xffff0000, v39
	v_pk_add_f32 v[60:61], v[60:61], v[60:61] op_sel_hi:[0,1]
	v_lshlrev_b32_e32 v46, 16, v40
	v_and_b32_e32 v40, 0xffff0000, v40
	v_add_f32_e32 v55, 0, v41
	v_add_f32_e32 v47, v44, v45
	v_add_f32_e32 v41, v38, v39
	v_mov_b32_e32 v51, v61
	v_pk_add_f32 v[62:63], v[46:47], v[40:41]
	v_pk_add_f32 v[60:61], v[50:51], v[54:55]
	s_ashr_i32 s7, s6, 31
	v_pk_add_f32 v[60:61], v[62:63], v[60:61]
	s_lshl_b64 s[6:7], s[6:7], 11
	v_add_f32_e32 v41, v60, v61
	ds_bpermute_b32 v47, v1, v41
	s_waitcnt lgkmcnt(0)
	v_add_f32_e32 v41, v41, v47
	ds_bpermute_b32 v47, v49, v41
	s_waitcnt lgkmcnt(0)
	v_add_f32_e32 v41, v41, v47
	ds_bpermute_b32 v47, v53, v41
	s_waitcnt lgkmcnt(0)
	v_add_f32_e32 v41, v41, v47
	ds_bpermute_b32 v47, v70, v41
	s_waitcnt lgkmcnt(0)
	v_add_f32_e32 v41, v41, v47
	ds_bpermute_b32 v47, v71, v41
	s_waitcnt lgkmcnt(0)
	v_add_f32_e32 v41, v41, v47
	ds_bpermute_b32 v47, v72, v41
	s_waitcnt lgkmcnt(0)
	v_add_f32_e32 v41, v41, v47
	v_fmac_f32_e32 v34, 0xba800000, v41
	v_fmac_f32_e32 v35, 0xba800000, v41
	v_fmac_f32_e32 v57, 0xba800000, v41
	v_fmac_f32_e32 v56, 0xba800000, v41
	v_mov_b32_e32 v60, v57
	v_mov_b32_e32 v61, v35
	v_mov_b32_e32 v57, v34
	v_pk_mul_f32 v[62:63], v[60:61], v[60:61]
	v_pk_mul_f32 v[34:35], v[56:57], v[56:57]
	v_fmac_f32_e32 v36, 0xba800000, v41
	v_pk_mov_b32 v[64:65], v[34:35], v[62:63] op_sel:[1,0]
	v_mov_b32_e32 v35, v63
	v_fmac_f32_e32 v37, 0xba800000, v41
	v_fmac_f32_e32 v59, 0xba800000, v41
	v_pk_add_f32 v[34:35], v[64:65], v[34:35]
	v_fmac_f32_e32 v58, 0xba800000, v41
	v_mov_b32_e32 v62, v59
	v_mov_b32_e32 v63, v37
	v_mov_b32_e32 v59, v36
	v_pk_add_f32 v[34:35], v[34:35], v[34:35] op_sel_hi:[0,1]
	v_pk_mul_f32 v[64:65], v[62:63], v[62:63]
	v_pk_mul_f32 v[36:37], v[58:59], v[58:59]
	v_fmac_f32_e32 v44, 0xba800000, v41
	v_pk_mov_b32 v[66:67], v[36:37], v[64:65] op_sel:[1,0]
	v_mov_b32_e32 v37, v65
	v_fmac_f32_e32 v45, 0xba800000, v41
	v_fmac_f32_e32 v38, 0xba800000, v41
	v_mul_f32_e32 v34, v44, v44
	v_pk_add_f32 v[36:37], v[66:67], v[36:37]
	v_fmac_f32_e32 v39, 0xba800000, v41
	v_pk_fma_f32 v[64:65], v[44:45], v[44:45], v[34:35] op_sel_hi:[1,1,0]
	v_mul_f32_e32 v34, v38, v38
	v_pk_add_f32 v[36:37], v[36:37], v[36:37] op_sel_hi:[0,1]
	v_pk_fma_f32 v[66:67], v[38:39], v[38:39], v[34:35] op_sel_hi:[1,1,0]
	v_fmac_f32_e32 v54, 0xba800000, v41
	v_fmac_f32_e32 v50, 0xba800000, v41
	v_fmac_f32_e32 v40, 0xba800000, v41
	v_fmac_f32_e32 v46, 0xba800000, v41
	v_mul_f32_e32 v64, v46, v46
	v_mul_f32_e32 v66, v40, v40
	v_mul_f32_e32 v34, v50, v50
	v_mul_f32_e32 v36, v54, v54
	v_pk_add_f32 v[64:65], v[64:65], v[66:67]
	v_pk_add_f32 v[34:35], v[34:35], v[36:37]
	v_mov_b32_e32 v47, v40
	v_pk_add_f32 v[34:35], v[64:65], v[34:35]
	v_mov_b32_e32 v51, v54
	v_add_f32_e32 v34, v34, v35
	ds_bpermute_b32 v1, v1, v34
	s_waitcnt lgkmcnt(0)
	v_add_f32_e32 v1, v34, v1
	ds_bpermute_b32 v34, v49, v1
	s_waitcnt lgkmcnt(0)
	v_add_f32_e32 v1, v1, v34
	ds_bpermute_b32 v34, v53, v1
	s_waitcnt lgkmcnt(0)
	v_add_f32_e32 v1, v1, v34
	ds_bpermute_b32 v34, v70, v1
	s_waitcnt lgkmcnt(0)
	v_add_f32_e32 v1, v1, v34
	ds_bpermute_b32 v34, v71, v1
	s_waitcnt lgkmcnt(0)
	v_add_f32_e32 v1, v1, v34
	ds_bpermute_b32 v34, v72, v1
	s_waitcnt lgkmcnt(0)
	v_add_f32_e32 v1, v1, v34
	v_fmamk_f32 v1, v1, 0x3a800000, v235
	v_mul_f32_e32 v34, 0x4f800000, v1
	v_cmp_gt_f32_e32 vcc, s89, v1
	s_nop 1
	v_cndmask_b32_e32 v1, v1, v34, vcc
	v_sqrt_f32_e32 v34, v1
	s_nop 0
	v_add_u32_e32 v35, -1, v34
	v_fma_f32 v36, -v35, v34, v1
	v_cmp_ge_f32_e64 s[4:5], 0, v36
	v_add_u32_e32 v36, 1, v34
	s_nop 0
	v_cndmask_b32_e64 v35, v34, v35, s[4:5]
	v_fma_f32 v34, -v36, v34, v1
	v_cmp_lt_f32_e64 s[4:5], 0, v34
	s_nop 1
	v_cndmask_b32_e64 v34, v35, v36, s[4:5]
	v_mul_f32_e32 v35, 0x37800000, v34
	v_cndmask_b32_e32 v34, v34, v35, vcc
	v_cmp_class_f32_e32 vcc, v1, v236
	s_nop 1
	v_cndmask_b32_e32 v1, v34, v1, vcc
	v_div_scale_f32 v34, s[4:5], v1, v1, 1.0
	v_rcp_f32_e32 v35, v34
	s_mov_b64 s[4:5], s[46:47]
	s_add_u32 s4, s4, s6
	v_fma_f32 v36, -v34, v35, 1.0
	v_fmac_f32_e32 v35, v36, v35
	v_div_scale_f32 v36, vcc, 1.0, v1, 1.0
	v_mul_f32_e32 v37, v36, v35
	v_fma_f32 v41, -v34, v37, v36
	v_fmac_f32_e32 v37, v41, v35
	v_fma_f32 v34, -v34, v37, v36
	v_div_fmas_f32 v34, v34, v35, v37
	v_div_fixup_f32 v34, v34, v1, 1.0
	v_pk_mul_f32 v[36:37], v[56:57], v[34:35] op_sel_hi:[1,0]
	v_pk_mul_f32 v[48:49], v[60:61], v[34:35] op_sel_hi:[1,0]
	v_pk_mul_f32 v[52:53], v[58:59], v[34:35] op_sel_hi:[1,0]
	v_pk_mul_f32 v[56:57], v[62:63], v[34:35] op_sel_hi:[1,0]
	v_pk_mul_f32 v[44:45], v[44:45], v[34:35] op_sel_hi:[1,0]
	v_pk_mul_f32 v[38:39], v[38:39], v[34:35] op_sel_hi:[1,0]
	v_pk_mul_f32 v[40:41], v[46:47], v[34:35] op_sel_hi:[1,0]
	v_pk_mul_f32 v[34:35], v[50:51], v[34:35] op_sel_hi:[1,0]
	v_pk_fma_f32 v[48:49], v[8:9], v[48:49], v[16:17]
	v_pk_fma_f32 v[46:47], v[20:21], v[34:35], v[28:29]
	v_pk_fma_f32 v[34:35], v[6:7], v[36:37], v[14:15]
	v_pk_fma_f32 v[52:53], v[2:3], v[52:53], v[10:11]
	v_cvt_pk_bf16_f32 v34, v34, v35
	v_cvt_pk_bf16_f32 v35, v48, v49
	v_pk_fma_f32 v[50:51], v[4:5], v[56:57], v[12:13]
	s_addc_u32 s5, s5, s7
	v_lshl_add_u64 v[54:55], v[42:43], 4, s[4:5]
	s_mov_b64 s[4:5], 0x8200000
	v_cvt_pk_bf16_f32 v36, v52, v53
	v_lshl_add_u64 v[56:57], v[54:55], 0, s[4:5]
	s_mov_b32 s4, 0x8200000
	v_pk_fma_f32 v[44:45], v[22:23], v[44:45], v[30:31]
	v_add_co_u32_e32 v48, vcc, s4, v54
	v_cvt_pk_bf16_f32 v37, v50, v51
	s_nop 0
	v_addc_co_u32_e32 v49, vcc, 0, v55, vcc
	v_bfe_u32 v1, v44, 16, 1
	global_store_dwordx4 v[48:49], v[34:37], off
	v_add3_u32 v1, v44, v1, s72
	v_pk_fma_f32 v[38:39], v[24:25], v[38:39], v[32:33]
	v_bfe_u32 v34, v45, 16, 1
	v_lshrrev_b32_e32 v1, 16, v1
	v_add3_u32 v34, v45, v34, s72
	v_and_or_b32 v34, v34, s88, v1
	v_pk_fma_f32 v[40:41], v[18:19], v[40:41], v[26:27]
	v_cvt_pk_bf16_f32 v35, v38, v39
	v_cvt_pk_bf16_f32 v36, v40, v41
	v_cvt_pk_bf16_f32 v37, v46, v47
	global_store_dwordx4 v[56:57], v[34:37], off offset:1024
	s_branch .LBB0_295

; #define GAS __attribute__((address_space(1)))
; #define WSB(F, off) ((bf16*)(wsq((F).ws) + (off)))
; __device__ __forceinline__ void ln_rows(const Frame& F, int idx, bool final_out, int row_lo, int row_hi, int gw0, int NGW, bool comb = false) {
;     ...
;     for (int m0 = row_lo + gw; m0 < row_hi; m0 += 2 * NGW) {
;         v4u w[2][2]; const bool two = m0 + NGW < row_hi;
; #pragma unroll
;         for (int r = 0; r < 2; ++r) { const int m = (r == 0 || two) ? m0 + r * NGW : m0; const GAS v4u* yr = (const GAS v4u*)(WSB(F, comb ? WS_HB : WS_YB) + (size_t)m * D) + tc.lane; w[r][0] = yr[0]; w[r][1] = yr[64]; }
; #pragma unroll
;         for (int r = 0; r < 2; ++r) { const int m = m0 + r * NGW; if (r == 1 && !two) break;
;         f32x4 v[4]; float s = 0.f;
; #pragma unroll
;         for (int j = 0; j < 2; ++j) { const v4u x = w[r][j]; v[2 * j] = (f32x4){bflo(x.x), bfhi(x.x), bflo(x.y), bfhi(x.y)}; v[2 * j + 1] = (f32x4){bflo(x.z), bfhi(x.z), bflo(x.w), bfhi(x.w)}; }
;         if (comb) {
;             const GAS f32x4* pa = (const GAS f32x4*)((const float*)WSB(F, WS_ACT) + (size_t)(m - MP) * D) + 2 * tc.lane; const GAS f32x4* pb = pa + (size_t)512 * D / 4;
; #pragma unroll
;             for (int j = 0; j < 2; ++j) { v[2 * j] = v[2 * j] * ALPHA + (pa[128 * j] + pb[128 * j]) * 0.5f; v[2 * j + 1] = v[2 * j + 1] * ALPHA + (pa[128 * j + 1] + pb[128 * j + 1]) * 0.5f; } }
; #pragma unroll
;         for (int j = 0; j < 4; ++j) s += (v[j].x + v[j].y) + (v[j].z + v[j].w);
;         const float mean = wave_sum(s) * (1.f / D); float s2 = 0.f;
.LBB0_361:
	v_readlane_b32 s5, v253, 7
	s_mov_b64 s[6:7], s[46:47]
	s_add_i32 s4, s5, s8
	s_add_u32 s6, s6, s2
	s_addc_u32 s7, s7, s3
	s_cmp_lt_i32 s4, 0x10200
	v_lshlrev_b64 v[46:47], 4, v[42:43]
	s_cselect_b32 s5, s5, 0
	v_lshl_add_u64 v[34:35], s[6:7], 0, v[46:47]
	s_add_i32 s6, s5, s8
	s_ashr_i32 s7, s6, 31
	s_mov_b64 s[10:11], s[46:47]
	s_lshl_b64 s[6:7], s[6:7], 11
	global_load_dwordx4 v[48:51], v[34:35], off
	global_load_dwordx4 v[52:55], v[34:35], off offset:1024
	s_add_u32 s6, s10, s6
	s_addc_u32 s7, s11, s7
	v_lshl_add_u64 v[34:35], s[6:7], 0, v[46:47]
	s_mov_b64 s[6:7], 0x8200000
	s_mov_b32 s5, 0x8200000
	v_lshl_add_u64 v[36:37], v[34:35], 0, s[6:7]
	v_add_co_u32_e32 v34, vcc, s5, v34
	s_add_i32 s10, s8, 0xffff0000
	s_nop 0
	v_addc_co_u32_e32 v35, vcc, 0, v35, vcc
	s_mov_b64 s[6:7], s[46:47]
	s_ashr_i32 s11, s10, 31
	global_load_dwordx4 v[38:41], v[34:35], off
	s_nop 0
	global_load_dwordx4 v[34:37], v[36:37], off offset:1024
	s_lshl_b64 s[10:11], s[10:11], 12
	s_add_u32 s6, s6, s10
	s_addc_u32 s7, s7, s11
	v_lshl_add_u64 v[84:85], v[44:45], 4, s[6:7]
	s_mov_b32 s5, 0x10300000
	s_mov_b64 s[6:7], 0x10300000
	v_add_co_u32_e32 v56, vcc, s5, v84
	v_lshl_add_u64 v[76:77], v[84:85], 0, s[6:7]
	s_mov_b64 s[6:7], 0x10500000
	v_addc_co_u32_e32 v57, vcc, 0, v85, vcc
	s_mov_b32 s5, 0x10500000
	v_lshl_add_u64 v[72:73], v[84:85], 0, s[6:7]
	v_add_co_u32_e32 v80, vcc, s5, v84
	s_mov_b64 s[6:7], 0x10500800
	s_nop 0
	v_addc_co_u32_e32 v81, vcc, 0, v85, vcc
	v_lshl_add_u64 v[84:85], v[84:85], 0, s[6:7]
	global_load_dwordx4 v[56:59], v[56:57], off
	s_nop 0
	global_load_dwordx4 v[60:63], v[80:81], off
	global_load_dwordx4 v[64:67], v[76:77], off offset:16
	global_load_dwordx4 v[68:71], v[76:77], off offset:2048
	s_nop 0
	global_load_dwordx4 v[72:75], v[72:73], off offset:16
	s_nop 0
	global_load_dwordx4 v[76:79], v[76:77], off offset:2064
	s_nop 0
	global_load_dwordx4 v[80:83], v[80:81], off offset:2048
	s_mov_b64 s[10:11], s[46:47]
	global_load_dwordx4 v[84:87], v[84:85], off offset:16
	s_waitcnt vmcnt(0)
	v_lshlrev_b32_e32 v88, 16, v48
	v_and_b32_e32 v89, 0xffff0000, v48
	v_lshlrev_b32_e32 v48, 16, v49
	v_and_b32_e32 v49, 0xffff0000, v49
	v_lshlrev_b32_e32 v90, 16, v50
	v_and_b32_e32 v91, 0xffff0000, v50
	v_lshlrev_b32_e32 v50, 16, v51
	v_and_b32_e32 v51, 0xffff0000, v51
	v_lshlrev_b32_e32 v92, 16, v52
	v_and_b32_e32 v93, 0xffff0000, v52
	v_lshlrev_b32_e32 v52, 16, v53
	v_and_b32_e32 v53, 0xffff0000, v53
	v_lshlrev_b32_e32 v94, 16, v54
	v_and_b32_e32 v95, 0xffff0000, v54
	v_lshlrev_b32_e32 v54, 16, v55
	v_and_b32_e32 v55, 0xffff0000, v55
	v_pk_add_f32 v[58:59], v[58:59], v[62:63]
	v_pk_add_f32 v[56:57], v[56:57], v[60:61]
	v_pk_mul_f32 v[58:59], v[58:59], 0.5 op_sel_hi:[1,0]
	v_pk_add_f32 v[60:61], v[66:67], v[74:75]
	v_pk_add_f32 v[62:63], v[64:65], v[72:73]
	v_pk_add_f32 v[64:65], v[70:71], v[82:83]
	v_pk_add_f32 v[66:67], v[68:69], v[80:81]
	v_pk_add_f32 v[68:69], v[78:79], v[86:87]
	v_pk_mul_f32 v[56:57], v[56:57], 0.5 op_sel_hi:[1,0]
	v_pk_mul_f32 v[60:61], v[60:61], 0.5 op_sel_hi:[1,0]
	v_pk_mul_f32 v[62:63], v[62:63], 0.5 op_sel_hi:[1,0]
	v_pk_mul_f32 v[64:65], v[64:65], 0.5 op_sel_hi:[1,0]
	v_pk_mul_f32 v[68:69], v[68:69], 0.5 op_sel_hi:[1,0]
	v_pk_fma_f32 v[48:49], v[48:49], s[96:97], v[58:59] op_sel_hi:[1,0,1]
	v_pk_fma_f32 v[72:73], v[88:89], s[96:97], v[56:57] op_sel_hi:[1,0,1]
	v_pk_fma_f32 v[62:63], v[90:91], s[96:97], v[62:63] op_sel_hi:[1,0,1]
	v_pk_fma_f32 v[50:51], v[50:51], s[96:97], v[60:61] op_sel_hi:[1,0,1]
	v_pk_add_f32 v[70:71], v[76:77], v[84:85]
	v_pk_fma_f32 v[52:53], v[52:53], s[96:97], v[64:65] op_sel_hi:[1,0,1]
	v_pk_fma_f32 v[64:65], v[54:55], s[96:97], v[68:69] op_sel_hi:[1,0,1]
	v_pk_mov_b32 v[54:55], v[72:73], v[48:49] op_sel:[1,0]
	v_mov_b32_e32 v56, v72
	v_mov_b32_e32 v57, v49
	v_pk_mov_b32 v[58:59], v[62:63], v[50:51] op_sel:[1,0]
	v_mov_b32_e32 v68, v62
	v_mov_b32_e32 v69, v51
	v_pk_mul_f32 v[66:67], v[66:67], 0.5 op_sel_hi:[1,0]
	v_pk_mul_f32 v[70:71], v[70:71], 0.5 op_sel_hi:[1,0]
	v_pk_add_f32 v[54:55], v[54:55], v[56:57]
	v_pk_add_f32 v[56:57], v[58:59], v[68:69]
	v_pk_fma_f32 v[60:61], v[92:93], s[96:97], v[66:67] op_sel_hi:[1,0,1]
	v_pk_fma_f32 v[66:67], v[94:95], s[96:97], v[70:71] op_sel_hi:[1,0,1]
	v_add_f32_e32 v1, v54, v55
	v_pk_add_f32 v[54:55], v[56:57], v[56:57] op_sel:[0,1] op_sel_hi:[1,0]
	v_add_f32_e32 v70, v60, v61
	v_add_f32_e32 v56, 0, v1
	v_add_f32_e32 v58, v52, v53
	v_mov_b32_e32 v57, v66
	v_mov_b32_e32 v55, v67
	v_mov_b32_e32 v71, v64
	v_mov_b32_e32 v59, v65
	v_and_b32_e32 v1, 64, v239
	v_pk_add_f32 v[54:55], v[56:57], v[54:55]
	v_pk_add_f32 v[56:57], v[70:71], v[58:59]
	v_add_u32_e32 v58, 64, v1
	v_xor_b32_e32 v1, 1, v239
	v_cmp_lt_i32_e32 vcc, v1, v58
	v_pk_add_f32 v[54:55], v[54:55], v[56:57]
	s_nop 0
	v_cndmask_b32_e32 v1, v239, v1, vcc
	v_add_f32_e32 v54, v54, v55
	v_lshlrev_b32_e32 v1, 2, v1
	ds_bpermute_b32 v55, v1, v54
	s_waitcnt lgkmcnt(0)
	v_add_f32_e32 v55, v54, v55
	v_xor_b32_e32 v54, 2, v239
	v_cmp_lt_i32_e32 vcc, v54, v58
	s_nop 1
	v_cndmask_b32_e32 v54, v239, v54, vcc
	v_lshlrev_b32_e32 v54, 2, v54
	ds_bpermute_b32 v56, v54, v55
	s_waitcnt lgkmcnt(0)
	v_add_f32_e32 v56, v55, v56
	v_xor_b32_e32 v55, 4, v239
	v_cmp_lt_i32_e32 vcc, v55, v58
	s_nop 1
	v_cndmask_b32_e32 v55, v239, v55, vcc
	v_lshlrev_b32_e32 v55, 2, v55
	ds_bpermute_b32 v57, v55, v56
	s_waitcnt lgkmcnt(0)
	v_add_f32_e32 v57, v56, v57
	v_xor_b32_e32 v56, 8, v239
	v_cmp_lt_i32_e32 vcc, v56, v58
	s_nop 1
	v_cndmask_b32_e32 v56, v239, v56, vcc
	v_lshlrev_b32_e32 v56, 2, v56
	ds_bpermute_b32 v59, v56, v57
	s_waitcnt lgkmcnt(0)
; #define GAS __attribute__((address_space(1)))
; __device__ __forceinline__ unsigned pk2(float lo, float hi) { return f2bf(lo) | (f2bf(hi) << 16); }
; #define WSB(F, off) ((bf16*)(wsq((F).ws) + (off)))
; __device__ __forceinline__ void ln_rows(const Frame& F, int idx, bool final_out, int row_lo, int row_hi, int gw0, int NGW, bool comb = false) {
;     ...
;         const float mean = wave_sum(s) * (1.f / D); float s2 = 0.f;
; #pragma unroll
;         for (int j = 0; j < 4; ++j) { v[j] = v[j] - mean; s2 += (v[j].x * v[j].x + v[j].y * v[j].y) + (v[j].z * v[j].z + v[j].w * v[j].w); }
;         const float rstd = 1.f / sqrtf(wave_sum(s2) * (1.f / D) + LN_EPS);
; #pragma unroll
;         for (int j = 0; j < 4; ++j) v[j] = v[j] * rstd * gv[j] + bv[j];
;         if (!final_out) { GAS v4u* o = (GAS v4u*)(WSB(F, WS_HB) + (size_t)m * D) + tc.lane;
; #pragma unroll
;             for (int j = 0; j < 2; ++j) o[64 * j] = (v4u){pk2(v[2 * j].x, v[2 * j].y), pk2(v[2 * j].z, v[2 * j].w), pk2(v[2 * j + 1].x, v[2 * j + 1].y), pk2(v[2 * j + 1].z, v[2 * j + 1].w)}; }
	v_add_f32_e32 v59, v57, v59
	v_xor_b32_e32 v57, 16, v239
	v_cmp_lt_i32_e32 vcc, v57, v58
	s_nop 1
	v_cndmask_b32_e32 v57, v239, v57, vcc
	v_lshlrev_b32_e32 v57, 2, v57
	ds_bpermute_b32 v68, v57, v59
	s_waitcnt lgkmcnt(0)
	v_add_f32_e32 v59, v59, v68
	v_xor_b32_e32 v68, 32, v239
	v_cmp_lt_i32_e32 vcc, v68, v58
	s_nop 1
	v_cndmask_b32_e32 v58, v239, v68, vcc
	v_lshlrev_b32_e32 v58, 2, v58
	ds_bpermute_b32 v68, v58, v59
	s_waitcnt lgkmcnt(0)
	v_add_f32_e32 v59, v59, v68
	v_fmamk_f32 v73, v59, 0xba800000, v73
	v_fmac_f32_e32 v72, 0xba800000, v59
	v_fmamk_f32 v49, v59, 0xba800000, v49
	v_fmac_f32_e32 v48, 0xba800000, v59
	v_pk_mul_f32 v[68:69], v[48:49], v[48:49]
	v_pk_mul_f32 v[70:71], v[72:73], v[72:73]
	v_fmamk_f32 v63, v59, 0xba800000, v63
	v_pk_mov_b32 v[74:75], v[70:71], v[68:69] op_sel:[1,0]
	v_mov_b32_e32 v71, v69
	v_pk_add_f32 v[68:69], v[74:75], v[70:71]
	v_fmac_f32_e32 v62, 0xba800000, v59
	v_fmamk_f32 v51, v59, 0xba800000, v51
	v_fmac_f32_e32 v50, 0xba800000, v59
	v_pk_add_f32 v[68:69], v[68:69], v[68:69] op_sel_hi:[0,1]
	v_pk_mul_f32 v[70:71], v[50:51], v[50:51]
	v_pk_mul_f32 v[74:75], v[62:63], v[62:63]
	v_fmac_f32_e32 v60, 0xba800000, v59
	v_pk_mov_b32 v[76:77], v[74:75], v[70:71] op_sel:[1,0]
	v_mov_b32_e32 v75, v71
	v_fmamk_f32 v61, v59, 0xba800000, v61
	v_fmac_f32_e32 v52, 0xba800000, v59
	v_mul_f32_e32 v68, v60, v60
	v_pk_add_f32 v[70:71], v[76:77], v[74:75]
	v_fmamk_f32 v53, v59, 0xba800000, v53
	v_pk_fma_f32 v[74:75], v[60:61], v[60:61], v[68:69] op_sel_hi:[1,1,0]
	v_mul_f32_e32 v68, v52, v52
	v_pk_add_f32 v[70:71], v[70:71], v[70:71] op_sel_hi:[0,1]
	v_pk_fma_f32 v[76:77], v[52:53], v[52:53], v[68:69] op_sel_hi:[1,1,0]
	v_fmamk_f32 v65, v59, 0xba800000, v65
	v_fmac_f32_e32 v64, 0xba800000, v59
	v_fmamk_f32 v67, v59, 0xba800000, v67
	v_fmac_f32_e32 v66, 0xba800000, v59
	v_mul_f32_e32 v74, v66, v66
	v_mul_f32_e32 v76, v67, v67
	v_mul_f32_e32 v68, v64, v64
	v_mul_f32_e32 v70, v65, v65
	v_pk_add_f32 v[74:75], v[74:75], v[76:77]
	v_pk_add_f32 v[68:69], v[68:69], v[70:71]
	s_nop 0
	v_pk_add_f32 v[68:69], v[74:75], v[68:69]
	s_nop 0
	v_add_f32_e32 v59, v68, v69
	ds_bpermute_b32 v68, v1, v59
	s_waitcnt lgkmcnt(0)
	v_add_f32_e32 v59, v59, v68
	ds_bpermute_b32 v68, v54, v59
	s_waitcnt lgkmcnt(0)
	v_add_f32_e32 v59, v59, v68
	ds_bpermute_b32 v68, v55, v59
	s_waitcnt lgkmcnt(0)
	v_add_f32_e32 v59, v59, v68
	ds_bpermute_b32 v68, v56, v59
	s_waitcnt lgkmcnt(0)
	v_add_f32_e32 v59, v59, v68
	ds_bpermute_b32 v68, v57, v59
	s_waitcnt lgkmcnt(0)
	v_add_f32_e32 v59, v59, v68
	ds_bpermute_b32 v68, v58, v59
	s_waitcnt lgkmcnt(0)
	v_add_f32_e32 v59, v59, v68
	v_fmamk_f32 v59, v59, 0x3a800000, v235
	v_mul_f32_e32 v68, 0x4f800000, v59
	v_cmp_gt_f32_e32 vcc, s89, v59
	s_nop 1
	v_cndmask_b32_e32 v59, v59, v68, vcc
	v_sqrt_f32_e32 v68, v59
	s_nop 0
	v_add_u32_e32 v69, -1, v68
	v_fma_f32 v70, -v69, v68, v59
	v_cmp_ge_f32_e64 s[6:7], 0, v70
	v_add_u32_e32 v70, 1, v68
	s_nop 0
	v_cndmask_b32_e64 v69, v68, v69, s[6:7]
	v_fma_f32 v68, -v70, v68, v59
	v_cmp_lt_f32_e64 s[6:7], 0, v68
	s_nop 1
	v_cndmask_b32_e64 v68, v69, v70, s[6:7]
	v_mul_f32_e32 v69, 0x37800000, v68
	v_cndmask_b32_e32 v68, v68, v69, vcc
	v_cmp_class_f32_e32 vcc, v59, v236
	s_nop 1
	v_cndmask_b32_e32 v59, v68, v59, vcc
	v_div_scale_f32 v68, s[6:7], v59, v59, 1.0
	v_rcp_f32_e32 v69, v68
	s_add_u32 s6, s10, s2
	s_addc_u32 s7, s11, s3
	s_cmp_gt_i32 s4, 0x101ff
	v_fma_f32 v70, -v68, v69, 1.0
	v_fmac_f32_e32 v69, v70, v69
	v_div_scale_f32 v70, vcc, 1.0, v59, 1.0
	v_mul_f32_e32 v71, v70, v69
	v_fma_f32 v74, -v68, v71, v70
	v_fmac_f32_e32 v71, v74, v69
	v_fma_f32 v68, -v68, v71, v70
	v_div_fmas_f32 v68, v68, v69, v71
	v_div_fixup_f32 v68, v68, v59, 1.0
	v_pk_mul_f32 v[70:71], v[72:73], v[68:69] op_sel_hi:[1,0]
	v_pk_mul_f32 v[48:49], v[48:49], v[68:69] op_sel_hi:[1,0]
	v_pk_mul_f32 v[62:63], v[62:63], v[68:69] op_sel_hi:[1,0]
	v_pk_mul_f32 v[50:51], v[50:51], v[68:69] op_sel_hi:[1,0]
	v_pk_mul_f32 v[60:61], v[60:61], v[68:69] op_sel_hi:[1,0]
	v_pk_mul_f32 v[52:53], v[52:53], v[68:69] op_sel_hi:[1,0]
	v_pk_mul_f32 v[66:67], v[66:67], v[68:69] op_sel_hi:[1,0]
	v_pk_mul_f32 v[64:65], v[64:65], v[68:69] op_sel_hi:[1,0]
	v_pk_fma_f32 v[68:69], v[6:7], v[70:71], v[14:15]
	v_lshl_add_u64 v[70:71], s[6:7], 0, v[46:47]
	v_pk_fma_f32 v[48:49], v[8:9], v[48:49], v[16:17]
	v_cvt_pk_bf16_f32 v46, v68, v69
	v_pk_fma_f32 v[62:63], v[2:3], v[62:63], v[10:11]
	v_cvt_pk_bf16_f32 v47, v48, v49
	v_pk_fma_f32 v[50:51], v[4:5], v[50:51], v[12:13]
	v_cvt_pk_bf16_f32 v48, v62, v63
	v_pk_fma_f32 v[60:61], v[22:23], v[60:61], v[30:31]
	v_cvt_pk_bf16_f32 v49, v50, v51
	global_store_dwordx4 v[70:71], v[46:49], off
	v_pk_fma_f32 v[52:53], v[24:25], v[52:53], v[32:33]
	v_pk_fma_f32 v[66:67], v[18:19], v[66:67], v[26:27]
	v_cvt_pk_bf16_f32 v46, v60, v61
	v_cvt_pk_bf16_f32 v47, v52, v53
	v_pk_fma_f32 v[64:65], v[20:21], v[64:65], v[28:29]
	v_cvt_pk_bf16_f32 v48, v66, v67
	v_cvt_pk_bf16_f32 v49, v64, v65
	global_store_dwordx4 v[70:71], v[46:49], off offset:1024
	s_cbranch_scc1 .LBB0_360
; #define GAS __attribute__((address_space(1)))
; #define WSB(F, off) ((bf16*)(wsq((F).ws) + (off)))
; __device__ __forceinline__ void ln_rows(const Frame& F, int idx, bool final_out, int row_lo, int row_hi, int gw0, int NGW, bool comb = false) {
;     ...
;         for (int r = 0; r < 2; ++r) { const int m = (r == 0 || two) ? m0 + r * NGW : m0; const GAS v4u* yr = (const GAS v4u*)(WSB(F, comb ? WS_HB : WS_YB) + (size_t)m * D) + tc.lane; w[r][0] = yr[0]; w[r][1] = yr[64]; }
; #pragma unroll
;         for (int r = 0; r < 2; ++r) { const int m = m0 + r * NGW; if (r == 1 && !two) break;
;         f32x4 v[4]; float s = 0.f;
; #pragma unroll
;         for (int j = 0; j < 2; ++j) { const v4u x = w[r][j]; v[2 * j] = (f32x4){bflo(x.x), bfhi(x.x), bflo(x.y), bfhi(x.y)}; v[2 * j + 1] = (f32x4){bflo(x.z), bfhi(x.z), bflo(x.w), bfhi(x.w)}; }
;         if (comb) {
;             const GAS f32x4* pa = (const GAS f32x4*)((const float*)WSB(F, WS_ACT) + (size_t)(m - MP) * D) + 2 * tc.lane; const GAS f32x4* pb = pa + (size_t)512 * D / 4;
; #pragma unroll
;             for (int j = 0; j < 2; ++j) { v[2 * j] = v[2 * j] * ALPHA + (pa[128 * j] + pb[128 * j]) * 0.5f; v[2 * j + 1] = v[2 * j + 1] * ALPHA + (pa[128 * j + 1] + pb[128 * j + 1]) * 0.5f; } }
; #pragma unroll
;         for (int j = 0; j < 4; ++j) s += (v[j].x + v[j].y) + (v[j].z + v[j].w);
;         const float mean = wave_sum(s) * (1.f / D); float s2 = 0.f;
	s_add_i32 s10, s4, 0xffff0000
	s_mov_b64 s[6:7], s[46:47]
	s_ashr_i32 s11, s10, 31
	s_lshl_b64 s[10:11], s[10:11], 12
	s_add_u32 s6, s6, s10
	s_addc_u32 s7, s7, s11
	v_lshl_add_u64 v[76:77], v[44:45], 4, s[6:7]
	s_mov_b32 s5, 0x10300000
	v_lshlrev_b32_e32 v72, 16, v34
	v_and_b32_e32 v73, 0xffff0000, v34
	v_add_co_u32_e32 v34, vcc, s5, v76
	v_lshlrev_b32_e32 v74, 16, v35
	v_and_b32_e32 v75, 0xffff0000, v35
	s_mov_b64 s[6:7], 0x10300000
	v_addc_co_u32_e32 v35, vcc, 0, v77, vcc
	s_mov_b32 s5, 0x10500000
	v_lshl_add_u64 v[78:79], v[76:77], 0, s[6:7]
	s_mov_b64 s[6:7], 0x10500000
	v_add_co_u32_e32 v80, vcc, s5, v76
	v_lshl_add_u64 v[60:61], v[76:77], 0, s[6:7]
	s_nop 0
	v_addc_co_u32_e32 v81, vcc, 0, v77, vcc
	v_lshlrev_b32_e32 v64, 16, v38
	v_and_b32_e32 v65, 0xffff0000, v38
	v_lshlrev_b32_e32 v66, 16, v39
	v_and_b32_e32 v67, 0xffff0000, v39
	v_lshlrev_b32_e32 v68, 16, v40
	v_and_b32_e32 v69, 0xffff0000, v40
	v_lshlrev_b32_e32 v70, 16, v41
	v_and_b32_e32 v71, 0xffff0000, v41
	v_lshlrev_b32_e32 v50, 16, v36
	v_and_b32_e32 v51, 0xffff0000, v36
	v_lshlrev_b32_e32 v52, 16, v37
	v_and_b32_e32 v53, 0xffff0000, v37
	global_load_dwordx4 v[34:37], v[34:35], off
	s_nop 0
	global_load_dwordx4 v[38:41], v[78:79], off offset:16
	global_load_dwordx4 v[46:49], v[80:81], off
	s_nop 0
	global_load_dwordx4 v[60:63], v[60:61], off offset:16
	s_mov_b64 s[6:7], 0x10500800
	s_ashr_i32 s5, s4, 31
	s_lshl_b64 s[4:5], s[4:5], 11
	s_waitcnt vmcnt(1)
	v_pk_add_f32 v[36:37], v[36:37], v[48:49]
	v_pk_add_f32 v[34:35], v[34:35], v[46:47]
	v_pk_mul_f32 v[36:37], v[36:37], 0.5 op_sel_hi:[1,0]
	v_pk_mul_f32 v[46:47], v[34:35], 0.5 op_sel_hi:[1,0]
	s_waitcnt vmcnt(0)
	v_pk_add_f32 v[40:41], v[40:41], v[62:63]
	v_pk_add_f32 v[38:39], v[38:39], v[60:61]
	v_pk_fma_f32 v[34:35], v[66:67], s[96:97], v[36:37] op_sel_hi:[1,0,1]
	v_pk_fma_f32 v[36:37], v[64:65], s[96:97], v[46:47] op_sel_hi:[1,0,1]
	v_pk_mul_f32 v[40:41], v[40:41], 0.5 op_sel_hi:[1,0]
	v_pk_mul_f32 v[46:47], v[38:39], 0.5 op_sel_hi:[1,0]
	v_pk_fma_f32 v[38:39], v[70:71], s[96:97], v[40:41] op_sel_hi:[1,0,1]
	v_pk_fma_f32 v[40:41], v[68:69], s[96:97], v[46:47] op_sel_hi:[1,0,1]
	v_lshl_add_u64 v[68:69], v[76:77], 0, s[6:7]
	global_load_dwordx4 v[60:63], v[78:79], off offset:2064
	global_load_dwordx4 v[46:49], v[78:79], off offset:2048
	global_load_dwordx4 v[64:67], v[80:81], off offset:2048
	s_nop 0
	global_load_dwordx4 v[68:71], v[68:69], off offset:16
	s_waitcnt vmcnt(1)
	v_pk_add_f32 v[48:49], v[48:49], v[66:67]
	s_waitcnt vmcnt(0)
	v_pk_add_f32 v[62:63], v[62:63], v[70:71]
	v_pk_add_f32 v[60:61], v[60:61], v[68:69]
	v_pk_add_f32 v[46:47], v[46:47], v[64:65]
	v_pk_mul_f32 v[62:63], v[62:63], 0.5 op_sel_hi:[1,0]
	v_pk_mul_f32 v[60:61], v[60:61], 0.5 op_sel_hi:[1,0]
	v_pk_mul_f32 v[48:49], v[48:49], 0.5 op_sel_hi:[1,0]
	v_pk_mul_f32 v[64:65], v[46:47], 0.5 op_sel_hi:[1,0]
	v_pk_fma_f32 v[52:53], v[52:53], s[96:97], v[62:63] op_sel_hi:[1,0,1]
	v_pk_fma_f32 v[50:51], v[50:51], s[96:97], v[60:61] op_sel_hi:[1,0,1]
	v_pk_mov_b32 v[60:61], v[36:37], v[34:35] op_sel:[1,0]
	v_mov_b32_e32 v62, v36
	v_mov_b32_e32 v63, v35
	v_pk_fma_f32 v[46:47], v[74:75], s[96:97], v[48:49] op_sel_hi:[1,0,1]
	v_pk_fma_f32 v[48:49], v[72:73], s[96:97], v[64:65] op_sel_hi:[1,0,1]
	v_pk_add_f32 v[60:61], v[60:61], v[62:63]
	v_pk_mov_b32 v[62:63], v[40:41], v[38:39] op_sel:[1,0]
	v_mov_b32_e32 v64, v40
	v_mov_b32_e32 v65, v39
	v_pk_add_f32 v[62:63], v[62:63], v[64:65]
	v_add_f32_e32 v59, v60, v61
	v_pk_add_f32 v[62:63], v[62:63], v[62:63] op_sel:[0,1] op_sel_hi:[1,0]
	v_add_f32_e32 v60, 0, v59
	v_add_f32_e32 v64, v48, v49
	v_add_f32_e32 v66, v46, v47
	v_mov_b32_e32 v61, v50
	v_mov_b32_e32 v63, v51
	v_mov_b32_e32 v65, v52
	v_mov_b32_e32 v67, v53
	v_pk_add_f32 v[60:61], v[60:61], v[62:63]
	v_pk_add_f32 v[62:63], v[64:65], v[66:67]
	s_nop 0
	v_pk_add_f32 v[60:61], v[60:61], v[62:63]
	s_nop 0
	v_add_f32_e32 v59, v60, v61
	ds_bpermute_b32 v60, v1, v59
	s_waitcnt lgkmcnt(0)
	v_add_f32_e32 v59, v59, v60
	ds_bpermute_b32 v60, v54, v59
	s_waitcnt lgkmcnt(0)
	v_add_f32_e32 v59, v59, v60
	ds_bpermute_b32 v60, v55, v59
	s_waitcnt lgkmcnt(0)
	v_add_f32_e32 v59, v59, v60
	ds_bpermute_b32 v60, v56, v59
	s_waitcnt lgkmcnt(0)
	v_add_f32_e32 v59, v59, v60
	ds_bpermute_b32 v60, v57, v59
	s_waitcnt lgkmcnt(0)
	v_add_f32_e32 v59, v59, v60
	ds_bpermute_b32 v60, v58, v59
	s_waitcnt lgkmcnt(0)
; #define GAS __attribute__((address_space(1)))
; __device__ __forceinline__ unsigned pk2(float lo, float hi) { return f2bf(lo) | (f2bf(hi) << 16); }
; #define WSB(F, off) ((bf16*)(wsq((F).ws) + (off)))
; __device__ __forceinline__ void ln_rows(const Frame& F, int idx, bool final_out, int row_lo, int row_hi, int gw0, int NGW, bool comb = false) {
;     ...
;         const float mean = wave_sum(s) * (1.f / D); float s2 = 0.f;
; #pragma unroll
;         for (int j = 0; j < 4; ++j) { v[j] = v[j] - mean; s2 += (v[j].x * v[j].x + v[j].y * v[j].y) + (v[j].z * v[j].z + v[j].w * v[j].w); }
;         const float rstd = 1.f / sqrtf(wave_sum(s2) * (1.f / D) + LN_EPS);
; #pragma unroll
;         for (int j = 0; j < 4; ++j) v[j] = v[j] * rstd * gv[j] + bv[j];
;         if (!final_out) { GAS v4u* o = (GAS v4u*)(WSB(F, WS_HB) + (size_t)m * D) + tc.lane;
; #pragma unroll
;             for (int j = 0; j < 2; ++j) o[64 * j] = (v4u){pk2(v[2 * j].x, v[2 * j].y), pk2(v[2 * j].z, v[2 * j].w), pk2(v[2 * j + 1].x, v[2 * j + 1].y), pk2(v[2 * j + 1].z, v[2 * j + 1].w)}; }
	v_add_f32_e32 v59, v59, v60
	v_fmamk_f32 v37, v59, 0xba800000, v37
	v_fmac_f32_e32 v36, 0xba800000, v59
	v_fmamk_f32 v35, v59, 0xba800000, v35
	v_fmac_f32_e32 v34, 0xba800000, v59
	v_pk_mul_f32 v[60:61], v[34:35], v[34:35]
	v_pk_mul_f32 v[62:63], v[36:37], v[36:37]
	v_fmamk_f32 v41, v59, 0xba800000, v41
	v_pk_mov_b32 v[64:65], v[62:63], v[60:61] op_sel:[1,0]
	v_mov_b32_e32 v63, v61
	v_pk_add_f32 v[60:61], v[64:65], v[62:63]
	v_fmac_f32_e32 v40, 0xba800000, v59
	v_fmamk_f32 v39, v59, 0xba800000, v39
	v_fmac_f32_e32 v38, 0xba800000, v59
	v_pk_add_f32 v[60:61], v[60:61], v[60:61] op_sel_hi:[0,1]
	v_pk_mul_f32 v[62:63], v[38:39], v[38:39]
	v_pk_mul_f32 v[64:65], v[40:41], v[40:41]
	v_fmac_f32_e32 v48, 0xba800000, v59
	v_pk_mov_b32 v[66:67], v[64:65], v[62:63] op_sel:[1,0]
	v_mov_b32_e32 v65, v63
	v_fmamk_f32 v49, v59, 0xba800000, v49
	v_fmac_f32_e32 v46, 0xba800000, v59
	v_mul_f32_e32 v60, v48, v48
	v_pk_add_f32 v[62:63], v[66:67], v[64:65]
	v_fmamk_f32 v47, v59, 0xba800000, v47
	v_pk_fma_f32 v[64:65], v[48:49], v[48:49], v[60:61] op_sel_hi:[1,1,0]
	v_mul_f32_e32 v60, v46, v46
	v_pk_add_f32 v[62:63], v[62:63], v[62:63] op_sel_hi:[0,1]
	v_pk_fma_f32 v[66:67], v[46:47], v[46:47], v[60:61] op_sel_hi:[1,1,0]
	v_fmamk_f32 v53, v59, 0xba800000, v53
	v_fmac_f32_e32 v52, 0xba800000, v59
	v_fmamk_f32 v51, v59, 0xba800000, v51
	v_fmac_f32_e32 v50, 0xba800000, v59
	v_mul_f32_e32 v64, v50, v50
	v_mul_f32_e32 v66, v51, v51
	v_mul_f32_e32 v60, v52, v52
	v_mul_f32_e32 v62, v53, v53
	v_pk_add_f32 v[64:65], v[64:65], v[66:67]
	v_pk_add_f32 v[60:61], v[60:61], v[62:63]
	s_nop 0
	v_pk_add_f32 v[60:61], v[64:65], v[60:61]
	s_nop 0
	v_add_f32_e32 v59, v60, v61
	ds_bpermute_b32 v1, v1, v59
	s_waitcnt lgkmcnt(0)
	v_add_f32_e32 v1, v59, v1
	ds_bpermute_b32 v54, v54, v1
	s_waitcnt lgkmcnt(0)
	v_add_f32_e32 v1, v1, v54
	ds_bpermute_b32 v54, v55, v1
	s_waitcnt lgkmcnt(0)
	v_add_f32_e32 v1, v1, v54
	ds_bpermute_b32 v54, v56, v1
	s_waitcnt lgkmcnt(0)
	v_add_f32_e32 v1, v1, v54
	ds_bpermute_b32 v54, v57, v1
	s_waitcnt lgkmcnt(0)
	v_add_f32_e32 v1, v1, v54
	ds_bpermute_b32 v54, v58, v1
	s_waitcnt lgkmcnt(0)
	v_add_f32_e32 v1, v1, v54
	v_fmamk_f32 v1, v1, 0x3a800000, v235
	v_cmp_gt_f32_e32 vcc, s89, v1
	v_mul_f32_e32 v54, 0x4f800000, v1
	s_nop 0
	v_cndmask_b32_e32 v1, v1, v54, vcc
	v_sqrt_f32_e32 v54, v1
	s_nop 0
	v_add_u32_e32 v55, -1, v54
	v_fma_f32 v56, -v55, v54, v1
	v_cmp_ge_f32_e64 s[6:7], 0, v56
	v_add_u32_e32 v56, 1, v54
	s_nop 0
	v_cndmask_b32_e64 v55, v54, v55, s[6:7]
	v_fma_f32 v54, -v56, v54, v1
	v_cmp_lt_f32_e64 s[6:7], 0, v54
	s_nop 1
	v_cndmask_b32_e64 v54, v55, v56, s[6:7]
	v_mul_f32_e32 v55, 0x37800000, v54
	v_cndmask_b32_e32 v54, v54, v55, vcc
	v_cmp_class_f32_e32 vcc, v1, v236
	s_nop 1
	v_cndmask_b32_e32 v1, v54, v1, vcc
	v_div_scale_f32 v54, s[6:7], v1, v1, 1.0
	v_rcp_f32_e32 v55, v54
	s_mov_b64 s[6:7], s[46:47]
	s_add_u32 s4, s6, s4
	v_fma_f32 v56, -v54, v55, 1.0
	v_fmac_f32_e32 v55, v56, v55
	v_div_scale_f32 v56, vcc, 1.0, v1, 1.0
	v_mul_f32_e32 v57, v56, v55
	v_fma_f32 v58, -v54, v57, v56
	v_fmac_f32_e32 v57, v58, v55
	v_fma_f32 v54, -v54, v57, v56
	v_div_fmas_f32 v54, v54, v55, v57
	v_div_fixup_f32 v54, v54, v1, 1.0
	v_pk_mul_f32 v[56:57], v[36:37], v[54:55] op_sel_hi:[1,0]
	v_pk_mul_f32 v[58:59], v[34:35], v[54:55] op_sel_hi:[1,0]
	v_pk_mul_f32 v[34:35], v[52:53], v[54:55] op_sel_hi:[1,0]
	v_pk_fma_f32 v[52:53], v[6:7], v[56:57], v[14:15]
	v_pk_mul_f32 v[36:37], v[50:51], v[54:55] op_sel_hi:[1,0]
	v_pk_fma_f32 v[50:51], v[8:9], v[58:59], v[16:17]
	v_cvt_pk_bf16_f32 v52, v52, v53
	v_pk_mul_f32 v[60:61], v[40:41], v[54:55] op_sel_hi:[1,0]
	v_pk_mul_f32 v[40:41], v[48:49], v[54:55] op_sel_hi:[1,0]
	v_pk_fma_f32 v[48:49], v[2:3], v[60:61], v[10:11]
	v_cvt_pk_bf16_f32 v53, v50, v51
	v_pk_mul_f32 v[62:63], v[38:39], v[54:55] op_sel_hi:[1,0]
	v_pk_mul_f32 v[38:39], v[46:47], v[54:55] op_sel_hi:[1,0]
	v_pk_fma_f32 v[46:47], v[4:5], v[62:63], v[12:13]
	v_cvt_pk_bf16_f32 v54, v48, v49
	s_addc_u32 s5, s7, s5
	v_pk_fma_f32 v[40:41], v[22:23], v[40:41], v[30:31]
	v_lshl_add_u64 v[56:57], v[42:43], 4, s[4:5]
	s_mov_b64 s[4:5], 0x8200000
	v_lshl_add_u64 v[58:59], v[56:57], 0, s[4:5]
	v_cvt_pk_bf16_f32 v55, v46, v47
	s_mov_b32 s4, 0x8200000
	v_add_co_u32_e32 v46, vcc, s4, v56
	v_pk_fma_f32 v[38:39], v[24:25], v[38:39], v[32:33]
	v_addc_co_u32_e32 v47, vcc, 0, v57, vcc
	global_store_dwordx4 v[46:47], v[52:55], off
	v_cvt_pk_bf16_f32 v46, v40, v41
	v_pk_fma_f32 v[36:37], v[18:19], v[36:37], v[26:27]
	v_cvt_pk_bf16_f32 v47, v38, v39
	v_pk_fma_f32 v[34:35], v[20:21], v[34:35], v[28:29]
	v_cvt_pk_bf16_f32 v48, v36, v37
	v_cvt_pk_bf16_f32 v49, v34, v35
	global_store_dwordx4 v[58:59], v[46:49], off offset:1024
	s_branch .LBB0_360

; #define GAS __attribute__((address_space(1)))
; __device__ __forceinline__ unsigned pk2(float lo, float hi) { return f2bf(lo) | (f2bf(hi) << 16); }
; #define WSB(F, off) ((bf16*)(wsq((F).ws) + (off)))
; __device__ __forceinline__ void pool_row(const Frame& F, int layer, int stream, int b, int rowbase, int tp, int ch, float (&v)[8]) {
;     if (tp >= 0 || stream == 0) { const size_t row = tp >= 0 ? (size_t)(rowbase + tp) : (size_t)(ROW_M + NMETA + tp);
;         const v4u x = *(const GAS v4u*)(WSB(F, WS_U) + row * D + ch * 8);
;         v[0] = bflo(x.x); v[1] = bfhi(x.x); v[2] = bflo(x.y); v[3] = bfhi(x.y); v[4] = bflo(x.z); v[5] = bfhi(x.z); v[6] = bflo(x.w); v[7] = bfhi(x.w); }
;     else if (stream == 1) { const float* sp = in_ptr(IN_SPOOL) + (((size_t)layer * SBATCH + b) * PBUF + (PBUF + tp)) * D + ch * 8;
;         const f32x4 a = *(const GAS f32x4*)sp, c = *(const GAS f32x4*)(sp + 4);
;         v[0] = a[0]; v[1] = a[1]; v[2] = a[2]; v[3] = a[3]; v[4] = c[0]; v[5] = c[1]; v[6] = c[2]; v[7] = c[3]; }
; __device__ __forceinline__ void pool_unit(const Frame& F, int layer, int uid) {
;     ...
;     for (int tt = 0; tt < 16; ++tt) {
;         const int t = ts + tt;
;         float vn[8], vo[8]; pool_row(F, layer, stream, b, rowbase, t, ch, vn);
;         if (tt > 0) pool_row(F, layer, stream, b, rowbase, t - win, ch, vo);
; #pragma unroll
;         for (int e = 0; e < 8; ++e) acc[e] += vn[e] - (tt > 0 ? vo[e] : 0.f);
;         const int have = (stream == 2) ? (t + 1 < win ? t + 1 : win) : win;
;         const float inv = 1.0f / (float)have;
;         float y[8];
; #pragma unroll
;         for (int e = 0; e < 8; ++e) y[e] = acc[e] * inv - vn[e];
;         *(GAS v4u*)(WSB(F, WS_BR) + (size_t)2 * M_PAD * D + (size_t)(rowbase + t) * D + ch * 8) = (v4u){pk2(y[0], y[1]), pk2(y[2], y[3]), pk2(y[4], y[5]), pk2(y[6], y[7])};
.LBB0_1327:
	s_or_b64 exec, exec, s[24:25]
	v_add_u32_e32 v6, 2, v48
	v_min_i32_e32 v6, v6, v19
	v_cndmask_b32_e64 v6, v19, v6, s[18:19]
	v_cvt_f32_i32_e32 v21, v6
	s_waitcnt vmcnt(0)
	v_sub_f32_e32 v7, v5, v17
	v_sub_f32_e32 v6, v4, v15
	v_sub_f32_e32 v14, v42, v14
	v_div_scale_f32 v17, s[10:11], v21, v21, 1.0
	v_rcp_f32_e32 v22, v17
	v_div_scale_f32 v15, vcc, 1.0, v21, 1.0
	v_sub_f32_e32 v10, v2, v10
	v_fma_f32 v23, -v17, v22, 1.0
	v_fmac_f32_e32 v22, v23, v22
	v_mul_f32_e32 v23, v15, v22
	v_fma_f32 v24, -v17, v23, v15
	v_fmac_f32_e32 v23, v24, v22
	v_fma_f32 v15, -v17, v23, v15
	v_div_fmas_f32 v15, v15, v22, v23
	v_div_fixup_f32 v50, v15, v21, 1.0
	v_sub_f32_e32 v15, v43, v16
	v_sub_f32_e32 v17, v9, v13
	v_sub_f32_e32 v16, v8, v11
	v_sub_f32_e32 v11, v3, v12
	v_pk_add_f32 v[24:25], v[28:29], v[16:17]
	v_pk_add_f32 v[22:23], v[26:27], v[10:11]
	v_pk_fma_f32 v[8:9], v[50:51], v[24:25], v[8:9] op_sel_hi:[0,1,1] neg_lo:[0,0,1] neg_hi:[0,0,1]
	v_pk_add_f32 v[26:27], v[38:39], v[14:15]
	v_pk_add_f32 v[28:29], v[40:41], v[6:7]
	v_pk_fma_f32 v[6:7], v[50:51], v[26:27], v[42:43] op_sel_hi:[0,1,1] neg_lo:[0,0,1] neg_hi:[0,0,1]
	v_bfe_u32 v12, v9, 16, 1
	v_pk_fma_f32 v[4:5], v[50:51], v[28:29], v[4:5] op_sel_hi:[0,1,1] neg_lo:[0,0,1] neg_hi:[0,0,1]
	v_bfe_u32 v13, v8, 16, 1
	v_add3_u32 v9, v9, v12, s72
	v_add3_u32 v8, v8, v13, s72
	v_cvt_pk_bf16_f32 v4, v6, v4
	v_add_u32_e32 v6, 1, v36
	v_cvt_pk_bf16_f32 v5, v7, v5
	v_ashrrev_i32_e32 v7, 31, v6
	v_pk_fma_f32 v[2:3], v[50:51], v[22:23], v[2:3] op_sel_hi:[0,1,1] neg_lo:[0,0,1] neg_hi:[0,0,1]
	s_mov_b64 s[10:11], s[46:47]
	v_lshlrev_b64 v[6:7], 11, v[6:7]
	v_bfe_u32 v10, v2, 16, 1
	v_bfe_u32 v11, v3, 16, 1
	v_mov_b32_e32 v21, v0
	v_lshl_add_u64 v[6:7], s[10:11], 0, v[6:7]
	v_add3_u32 v3, v3, v11, s72
	v_add3_u32 v2, v2, v10, s72
	v_lshl_add_u64 v[6:7], v[6:7], 0, v[20:21]
	v_lshrrev_b32_e32 v2, 16, v2
	v_lshrrev_b32_e32 v3, 16, v3
	v_add_co_u32_e32 v6, vcc, 0x871c0000, v6
	v_and_or_b32 v3, v9, s88, v3
	v_and_or_b32 v2, v8, s88, v2
	v_addc_co_u32_e32 v7, vcc, 0, v7, vcc
	global_store_dwordx4 v[6:7], v[2:5], off
	s_and_saveexec_b64 s[10:11], s[12:13]
	s_xor_b64 s[10:11], exec, s[10:11]
	s_cbranch_execz .LBB0_1330
	v_mov_b32_e32 v5, 0
	s_and_b64 vcc, exec, s[8:9]
	v_mov_b32_e32 v41, 0
	v_mov_b32_e32 v4, 0
	v_mov_b32_e32 v40, 0
	v_mov_b32_e32 v9, 0
	v_mov_b32_e32 v3, 0
	v_mov_b32_e32 v8, 0
	v_mov_b32_e32 v2, 0
	s_cbranch_vccnz .LBB0_1330
	s_mov_b64 s[24:25], s[0:1]
	s_load_dwordx2 s[24:25], s[24:25], 0x28
	s_waitcnt lgkmcnt(0)
	v_lshl_add_u64 v[2:3], s[24:25], 0, v[30:31]
	v_lshl_add_u64 v[6:7], v[2:3], 0, v[32:33]
	s_mov_b64 s[24:25], 0x1000
	v_lshl_add_u64 v[2:3], v[6:7], 0, s[24:25]
	v_add_co_u32_e32 v6, vcc, 0x1000, v6
	global_load_dwordx4 v[2:5], v[2:3], off offset:16
	s_nop 0
	v_addc_co_u32_e32 v7, vcc, 0, v7, vcc
	global_load_dwordx4 v[6:9], v[6:7], off
	s_waitcnt vmcnt(1)
	v_mov_b32_e32 v41, v4
	v_mov_b32_e32 v4, v3
	v_mov_b32_e32 v40, v2
	s_waitcnt vmcnt(0)
	v_mov_b32_e32 v3, v8
	v_mov_b32_e32 v8, v7
	v_mov_b32_e32 v2, v6

; #define GAS __attribute__((address_space(1)))
; __device__ __forceinline__ unsigned pk2(float lo, float hi) { return f2bf(lo) | (f2bf(hi) << 16); }
; #define WSB(F, off) ((bf16*)(wsq((F).ws) + (off)))
; __device__ __forceinline__ void pool_row(const Frame& F, int layer, int stream, int b, int rowbase, int tp, int ch, float (&v)[8]) {
;     if (tp >= 0 || stream == 0) { const size_t row = tp >= 0 ? (size_t)(rowbase + tp) : (size_t)(ROW_M + NMETA + tp);
;         const v4u x = *(const GAS v4u*)(WSB(F, WS_U) + row * D + ch * 8);
;         v[0] = bflo(x.x); v[1] = bfhi(x.x); v[2] = bflo(x.y); v[3] = bfhi(x.y); v[4] = bflo(x.z); v[5] = bfhi(x.z); v[6] = bflo(x.w); v[7] = bfhi(x.w); }
;     else if (stream == 1) { const float* sp = in_ptr(IN_SPOOL) + (((size_t)layer * SBATCH + b) * PBUF + (PBUF + tp)) * D + ch * 8;
;         const f32x4 a = *(const GAS f32x4*)sp, c = *(const GAS f32x4*)(sp + 4);
;         v[0] = a[0]; v[1] = a[1]; v[2] = a[2]; v[3] = a[3]; v[4] = c[0]; v[5] = c[1]; v[6] = c[2]; v[7] = c[3]; }
; __device__ __forceinline__ void pool_unit(const Frame& F, int layer, int uid) {
;     ...
;     for (int tt = 0; tt < 16; ++tt) {
;         const int t = ts + tt;
;         float vn[8], vo[8]; pool_row(F, layer, stream, b, rowbase, t, ch, vn);
;         if (tt > 0) pool_row(F, layer, stream, b, rowbase, t - win, ch, vo);
; #pragma unroll
;         for (int e = 0; e < 8; ++e) acc[e] += vn[e] - (tt > 0 ? vo[e] : 0.f);
;         const int have = (stream == 2) ? (t + 1 < win ? t + 1 : win) : win;
;         const float inv = 1.0f / (float)have;
;         float y[8];
; #pragma unroll
;         for (int e = 0; e < 8; ++e) y[e] = acc[e] * inv - vn[e];
;         *(GAS v4u*)(WSB(F, WS_BR) + (size_t)2 * M_PAD * D + (size_t)(rowbase + t) * D + ch * 8) = (v4u){pk2(y[0], y[1]), pk2(y[2], y[3]), pk2(y[4], y[5]), pk2(y[6], y[7])};
.LBB0_1337:
	s_or_b64 exec, exec, s[24:25]
	v_add_u32_e32 v6, 3, v48
	v_min_i32_e32 v6, v6, v19
	v_cndmask_b32_e64 v6, v19, v6, s[18:19]
	v_cvt_f32_i32_e32 v21, v6
	s_waitcnt vmcnt(0)
	v_sub_f32_e32 v7, v5, v17
	v_sub_f32_e32 v6, v4, v15
	v_sub_f32_e32 v10, v2, v10
	v_div_scale_f32 v17, s[10:11], v21, v21, 1.0
	v_rcp_f32_e32 v37, v17
	v_div_scale_f32 v15, vcc, 1.0, v21, 1.0
	v_sub_f32_e32 v14, v40, v14
	v_fma_f32 v38, -v17, v37, 1.0
	v_fmac_f32_e32 v37, v38, v37
	v_mul_f32_e32 v38, v15, v37
	v_fma_f32 v39, -v17, v38, v15
	v_fmac_f32_e32 v38, v39, v37
	v_fma_f32 v15, -v17, v38, v15
	v_div_fmas_f32 v15, v15, v37, v38
	v_sub_f32_e32 v39, v9, v13
	v_sub_f32_e32 v38, v8, v11
	v_sub_f32_e32 v11, v3, v12
	v_div_fixup_f32 v42, v15, v21, 1.0
	v_sub_f32_e32 v15, v41, v16
	v_pk_add_f32 v[16:17], v[22:23], v[10:11]
	v_pk_add_f32 v[22:23], v[24:25], v[38:39]
	v_pk_add_f32 v[24:25], v[26:27], v[14:15]
	v_pk_fma_f32 v[8:9], v[42:43], v[22:23], v[8:9] op_sel_hi:[0,1,1] neg_lo:[0,0,1] neg_hi:[0,0,1]
	v_pk_add_f32 v[38:39], v[28:29], v[6:7]
	v_pk_fma_f32 v[6:7], v[42:43], v[24:25], v[40:41] op_sel_hi:[0,1,1] neg_lo:[0,0,1] neg_hi:[0,0,1]
	v_bfe_u32 v12, v9, 16, 1
	v_pk_fma_f32 v[4:5], v[42:43], v[38:39], v[4:5] op_sel_hi:[0,1,1] neg_lo:[0,0,1] neg_hi:[0,0,1]
	v_bfe_u32 v13, v8, 16, 1
	v_add3_u32 v9, v9, v12, s72
	v_add3_u32 v8, v8, v13, s72
	v_cvt_pk_bf16_f32 v4, v6, v4
	v_add_u32_e32 v6, 2, v36
	v_cvt_pk_bf16_f32 v5, v7, v5
	v_ashrrev_i32_e32 v7, 31, v6
	v_pk_fma_f32 v[2:3], v[42:43], v[16:17], v[2:3] op_sel_hi:[0,1,1] neg_lo:[0,0,1] neg_hi:[0,0,1]
	s_mov_b64 s[10:11], s[46:47]
	v_lshlrev_b64 v[6:7], 11, v[6:7]
	v_bfe_u32 v10, v2, 16, 1
	v_bfe_u32 v11, v3, 16, 1
	v_mov_b32_e32 v21, v0
	v_lshl_add_u64 v[6:7], s[10:11], 0, v[6:7]
	v_add3_u32 v3, v3, v11, s72
	v_add3_u32 v2, v2, v10, s72
	v_lshl_add_u64 v[6:7], v[6:7], 0, v[20:21]
	v_lshrrev_b32_e32 v2, 16, v2
	v_lshrrev_b32_e32 v3, 16, v3
	v_add_co_u32_e32 v6, vcc, 0x871c0000, v6
	v_and_or_b32 v3, v9, s88, v3
	v_and_or_b32 v2, v8, s88, v2
	v_addc_co_u32_e32 v7, vcc, 0, v7, vcc
	global_store_dwordx4 v[6:7], v[2:5], off
	s_and_saveexec_b64 s[10:11], s[12:13]
	s_xor_b64 s[10:11], exec, s[10:11]
	s_cbranch_execz .LBB0_1340
	v_mov_b32_e32 v11, 0
	s_and_b64 vcc, exec, s[8:9]
	v_mov_b32_e32 v41, 0
	v_mov_b32_e32 v10, 0
	v_mov_b32_e32 v40, 0
	v_mov_b32_e32 v15, 0
	v_mov_b32_e32 v43, 0
	v_mov_b32_e32 v14, 0
	v_mov_b32_e32 v42, 0
	s_cbranch_vccnz .LBB0_1340
	s_mov_b64 s[24:25], s[0:1]
	s_load_dwordx2 s[24:25], s[24:25], 0x28
	s_waitcnt lgkmcnt(0)
	v_lshl_add_u64 v[2:3], s[24:25], 0, v[30:31]
	v_lshl_add_u64 v[2:3], v[2:3], 0, v[32:33]
	s_mov_b64 s[24:25], 0x2000
	v_lshl_add_u64 v[4:5], v[2:3], 0, s[24:25]
	v_add_co_u32_e32 v2, vcc, 0x2000, v2
	global_load_dwordx4 v[8:11], v[4:5], off offset:16
	s_nop 0
	v_addc_co_u32_e32 v3, vcc, 0, v3, vcc
	global_load_dwordx4 v[12:15], v[2:3], off
	s_waitcnt vmcnt(1)
	v_mov_b32_e32 v41, v10
	v_mov_b32_e32 v10, v9
	v_mov_b32_e32 v40, v8
	s_waitcnt vmcnt(0)
	v_mov_b32_e32 v43, v14
	v_mov_b32_e32 v14, v13
	v_mov_b32_e32 v42, v12

; __device__ __forceinline__ unsigned cvt_pk_bf16(float lo, float hi) { unsigned r; asm volatile("v_cvt_pk_bf16_f32 %0, %1, %2" : "=v"(r) : "v"(lo), "v"(hi)); return r; }
; __device__ __forceinline__ void ret_unit(const Frame& F, int layer, int uid) {
;     ...
;             *(LAS v2u*)(F.lds + RT_A + (16 * nt + l15) * RT_AS + (16 * mt + 4 * g) * 2) = (v2u){pg8::cvt_pk_bf16(a4[0], a4[1]), pg8::cvt_pk_bf16(a4[2], a4[3])}; }
;         __syncthreads();
;         f32x4 accO[4][2];
; #pragma unroll
;         for (int m = 0; m < 4; ++m)
; #pragma unroll
;             for (int n = 0; n < 2; ++n) accO[m][n] = (f32x4){0.f, 0.f, 0.f, 0.f};
; #pragma unroll
;         for (int ks = 0; ks < 4; ++ks) {
;             bf16x8 Sf[2];
; #pragma unroll
;             for (int n = 0; n < 2; ++n) Sf[n] = __builtin_bit_cast(bf16x8, (v4u){pg8::cvt_pk_bf16(accS[2 * ks][n][0], accS[2 * ks][n][1]), pg8::cvt_pk_bf16(accS[2 * ks][n][2], accS[2 * ks][n][3]),
;                                                                                pg8::cvt_pk_bf16(accS[2 * ks + 1][n][0], accS[2 * ks + 1][n][1]), pg8::cvt_pk_bf16(accS[2 * ks + 1][n][2], accS[2 * ks + 1][n][3])});
; #pragma unroll
;             for (int m = 0; m < 4; ++m) { const v2u lo = *(const LAS v2u*)(Ql + (16 * m + l15) * RT_QS + (32 * ks + 4 * g) * 2), hi = *(const LAS v2u*)(Ql + (16 * m + l15) * RT_QS + (32 * ks + 16 + 4 * g) * 2);
;                 const bf16x8 A = __builtin_bit_cast(bf16x8, (v4u){lo.x, lo.y, hi.x, hi.y});
; #pragma unroll
;                 for (int n = 0; n < 2; ++n) accO[m][n] = MFMA16(A, Sf[n], accO[m][n]); }
;         }
;         bf16x8 Bv[2][2];
; #pragma unroll
;         for (int k2 = 0; k2 < 2; ++k2)
; #pragma unroll
;             for (int n = 0; n < 2; ++n) { const s16x4 lo = tr16(Vl + (32 * k2 + 8 * g + q4) * RT_VS + (32 * w + 16 * n + 4 * p4) * 2), hi = tr16(Vl + (32 * k2 + 8 * g + 4 + q4) * RT_VS + (32 * w + 16 * n + 4 * p4) * 2);
;                 Bv[k2][n] = __builtin_shufflevector(lo, hi, 0, 1, 2, 3, 4, 5, 6, 7); }
; #pragma unroll
;         for (int k2 = 0; k2 < 2; ++k2)
; #pragma unroll
;             for (int m = 0; m < 4; ++m) { const bf16x8 A = *(const LAS bf16x8*)(Al + (16 * m + l15) * RT_AS + (32 * k2 + 8 * g) * 2);
; #pragma unroll
;                 for (int n = 0; n < 2; ++n) accO[m][n] = MFMA16(A, Bv[k2][n], accO[m][n]); }
; #pragma unroll
;         for (int m = 0; m < 8; ++m)
; #pragma unroll
.LBB0_1413:
	v_cvt_pk_bf16_f32 v102, v1, v3
	v_cvt_pk_bf16_f32 v103, v100, v101
	v_add_u32_e32 v1, v189, v186
	ds_write_b64 v215, v[102:103]
	s_waitcnt lgkmcnt(0)
	s_barrier
	v_cvt_pk_bf16_f32 v100, v84, v85
	v_cvt_pk_bf16_f32 v101, v86, v87
	v_cvt_pk_bf16_f32 v102, v88, v89
	v_cvt_pk_bf16_f32 v103, v90, v91
	v_cvt_pk_bf16_f32 v104, v92, v93
	v_cvt_pk_bf16_f32 v105, v94, v95
	v_cvt_pk_bf16_f32 v106, v96, v97
	v_cvt_pk_bf16_f32 v107, v98, v99
	ds_read_b64 v[108:109], v1
	ds_read_b64 v[110:111], v216
	ds_read_b64 v[116:117], v1 offset:4352
	ds_read_b64 v[118:119], v216 offset:4352
	ds_read_b64 v[124:125], v1 offset:8704
	ds_read_b64 v[126:127], v216 offset:8704
	ds_read_b64 v[132:133], v1 offset:13056
	ds_read_b64 v[134:135], v216 offset:13056
	s_waitcnt lgkmcnt(6)
	v_mfma_f32_16x16x32_bf16 v[112:115], v[108:111], v[100:103], 0
	v_add_u32_e32 v1, v190, v188
	s_and_b64 vcc, exec, s[38:39]
	v_mfma_f32_16x16x32_bf16 v[108:111], v[108:111], v[104:107], 0
	s_waitcnt lgkmcnt(4)
	v_mfma_f32_16x16x32_bf16 v[120:123], v[116:119], v[100:103], 0
	v_mfma_f32_16x16x32_bf16 v[116:119], v[116:119], v[104:107], 0
	s_waitcnt lgkmcnt(2)
	v_mfma_f32_16x16x32_bf16 v[128:131], v[124:127], v[100:103], 0
	v_mfma_f32_16x16x32_bf16 v[124:127], v[124:127], v[104:107], 0
	s_waitcnt lgkmcnt(0)
	v_mfma_f32_16x16x32_bf16 v[100:103], v[132:135], v[100:103], 0
	v_mfma_f32_16x16x32_bf16 v[104:107], v[132:135], v[104:107], 0
	v_cvt_pk_bf16_f32 v132, v76, v77
	v_cvt_pk_bf16_f32 v133, v78, v79
	v_cvt_pk_bf16_f32 v134, v68, v69
	v_cvt_pk_bf16_f32 v135, v70, v71
	v_cvt_pk_bf16_f32 v136, v80, v81
	v_cvt_pk_bf16_f32 v137, v82, v83
	v_cvt_pk_bf16_f32 v138, v72, v73
	v_cvt_pk_bf16_f32 v139, v74, v75
	ds_read_b64 v[140:141], v217
	ds_read_b64 v[142:143], v218
	s_waitcnt lgkmcnt(0)
	v_mfma_f32_16x16x32_bf16 v[112:115], v[140:143], v[132:135], v[112:115]
	v_mfma_f32_16x16x32_bf16 v[108:111], v[140:143], v[136:139], v[108:111]
	ds_read_b64 v[140:141], v217 offset:4352
	ds_read_b64 v[142:143], v218 offset:4352
	s_waitcnt lgkmcnt(0)
	v_mfma_f32_16x16x32_bf16 v[120:123], v[140:143], v[132:135], v[120:123]
	v_mfma_f32_16x16x32_bf16 v[116:119], v[140:143], v[136:139], v[116:119]
	ds_read_b64 v[140:141], v217 offset:8704
	ds_read_b64 v[142:143], v218 offset:8704
	s_waitcnt lgkmcnt(0)
	v_mfma_f32_16x16x32_bf16 v[128:131], v[140:143], v[132:135], v[128:131]
	v_mfma_f32_16x16x32_bf16 v[124:127], v[140:143], v[136:139], v[124:127]
	ds_read_b64 v[140:141], v217 offset:13056
	ds_read_b64 v[142:143], v218 offset:13056
	s_waitcnt lgkmcnt(0)
	v_mfma_f32_16x16x32_bf16 v[100:103], v[140:143], v[132:135], v[100:103]
	v_cvt_pk_bf16_f32 v132, v52, v53
	v_cvt_pk_bf16_f32 v133, v54, v55
	v_cvt_pk_bf16_f32 v134, v40, v41
	v_mfma_f32_16x16x32_bf16 v[104:107], v[140:143], v[136:139], v[104:107]
	v_cvt_pk_bf16_f32 v135, v42, v43
	v_cvt_pk_bf16_f32 v136, v64, v65
	v_cvt_pk_bf16_f32 v137, v66, v67
	v_cvt_pk_bf16_f32 v138, v56, v57
	v_cvt_pk_bf16_f32 v139, v58, v59
	ds_read_b64 v[140:141], v219
	ds_read_b64 v[142:143], v220
	s_waitcnt lgkmcnt(0)
	v_mfma_f32_16x16x32_bf16 v[112:115], v[140:143], v[132:135], v[112:115]
	v_mfma_f32_16x16x32_bf16 v[108:111], v[140:143], v[136:139], v[108:111]
	ds_read_b64 v[140:141], v219 offset:4352
	ds_read_b64 v[142:143], v220 offset:4352
	s_waitcnt lgkmcnt(0)
	v_mfma_f32_16x16x32_bf16 v[120:123], v[140:143], v[132:135], v[120:123]
	v_mfma_f32_16x16x32_bf16 v[116:119], v[140:143], v[136:139], v[116:119]
	ds_read_b64 v[140:141], v219 offset:8704
	ds_read_b64 v[142:143], v220 offset:8704
	s_waitcnt lgkmcnt(0)
	v_mfma_f32_16x16x32_bf16 v[128:131], v[140:143], v[132:135], v[128:131]
	v_mfma_f32_16x16x32_bf16 v[124:127], v[140:143], v[136:139], v[124:127]
	ds_read_b64 v[140:141], v219 offset:13056
	ds_read_b64 v[142:143], v220 offset:13056
	s_waitcnt lgkmcnt(0)
	v_mfma_f32_16x16x32_bf16 v[100:103], v[140:143], v[132:135], v[100:103]
	v_cvt_pk_bf16_f32 v132, v44, v45
	v_cvt_pk_bf16_f32 v133, v46, v47
	v_cvt_pk_bf16_f32 v134, v36, v37
	v_mfma_f32_16x16x32_bf16 v[104:107], v[140:143], v[136:139], v[104:107]
	v_cvt_pk_bf16_f32 v135, v38, v39
	v_cvt_pk_bf16_f32 v136, v60, v61
	v_cvt_pk_bf16_f32 v137, v62, v63
	v_cvt_pk_bf16_f32 v138, v48, v49
	v_cvt_pk_bf16_f32 v139, v50, v51
	ds_read_b64 v[140:141], v221
	ds_read_b64 v[142:143], v222
	s_waitcnt lgkmcnt(0)
	v_mfma_f32_16x16x32_bf16 v[112:115], v[140:143], v[132:135], v[112:115]
	v_mfma_f32_16x16x32_bf16 v[108:111], v[140:143], v[136:139], v[108:111]
	ds_read_b64 v[140:141], v221 offset:4352
	ds_read_b64 v[142:143], v222 offset:4352
	s_waitcnt lgkmcnt(0)
	v_mfma_f32_16x16x32_bf16 v[120:123], v[140:143], v[132:135], v[120:123]
	v_mfma_f32_16x16x32_bf16 v[116:119], v[140:143], v[136:139], v[116:119]
	ds_read_b64 v[140:141], v221 offset:8704
	ds_read_b64 v[142:143], v222 offset:8704
	s_waitcnt lgkmcnt(0)
	v_mfma_f32_16x16x32_bf16 v[144:147], v[140:143], v[132:135], v[128:131]
	v_mfma_f32_16x16x32_bf16 v[140:143], v[140:143], v[136:139], v[124:127]
	s_nop 2
	ds_read_b64 v[124:125], v221 offset:13056
	ds_read_b64 v[126:127], v222 offset:13056
	s_waitcnt lgkmcnt(0)
	v_mfma_f32_16x16x32_bf16 v[100:103], v[124:127], v[132:135], v[100:103]
	ds_read_b128 v[132:135], v224
	v_mfma_f32_16x16x32_bf16 v[104:107], v[124:127], v[136:139], v[104:107]
	ds_read_b64_tr_b16 v[126:127], v1 offset:36928
	ds_read_b64_tr_b16 v[124:125], v1 offset:34816
	ds_read_b64_tr_b16 v[128:129], v1 offset:34848
	ds_read_b64_tr_b16 v[130:131], v1 offset:36960
	v_add_u32_e32 v1, v191, v187
	s_waitcnt lgkmcnt(2)
	v_mfma_f32_16x16x32_bf16 v[136:139], v[132:135], v[124:127], v[112:115]
	s_waitcnt lgkmcnt(0)
	v_mfma_f32_16x16x32_bf16 v[132:135], v[132:135], v[128:131], v[108:111]
	s_nop 2
	ds_read_b128 v[108:111], v224 offset:2304
	s_waitcnt lgkmcnt(0)
; #define LAS __attribute__((address_space(3)))
; #define MFMA16(a, b, c) __builtin_amdgcn_mfma_f32_16x16x32_bf16((a), (b), (c), 0, 0, 0)
; __device__ __forceinline__ s16x4 tr16(const LAS unsigned char* p) { typedef short v4i16_t __attribute__((ext_vector_type(4))); return __builtin_bit_cast(s16x4, __builtin_amdgcn_ds_read_tr16_b64_v4i16((LAS v4i16_t*)p)); }
; __device__ __forceinline__ void ret_unit(const Frame& F, int layer, int uid) {
;     ...
;         bf16x8 Bv[2][2];
; #pragma unroll
;         for (int k2 = 0; k2 < 2; ++k2)
; #pragma unroll
;             for (int n = 0; n < 2; ++n) { const s16x4 lo = tr16(Vl + (32 * k2 + 8 * g + q4) * RT_VS + (32 * w + 16 * n + 4 * p4) * 2), hi = tr16(Vl + (32 * k2 + 8 * g + 4 + q4) * RT_VS + (32 * w + 16 * n + 4 * p4) * 2);
;                 Bv[k2][n] = __builtin_shufflevector(lo, hi, 0, 1, 2, 3, 4, 5, 6, 7); }
; #pragma unroll
;         for (int k2 = 0; k2 < 2; ++k2)
; #pragma unroll
;             for (int m = 0; m < 4; ++m) { const bf16x8 A = *(const LAS bf16x8*)(Al + (16 * m + l15) * RT_AS + (32 * k2 + 8 * g) * 2);
; #pragma unroll
;                 for (int n = 0; n < 2; ++n) accO[m][n] = MFMA16(A, Bv[k2][n], accO[m][n]); }
; #pragma unroll
;         for (int m = 0; m < 8; ++m)
; #pragma unroll
;             for (int k2 = 0; k2 < 2; ++k2) { const s16x4 lo = tr16(Kl + (32 * k2 + 8 * g + q4) * RT_QS + (16 * m + 4 * p4) * 2), hi = tr16(Kl + (32 * k2 + 8 * g + 4 + q4) * RT_QS + (16 * m + 4 * p4) * 2);
;                 const bf16x8 A = __builtin_shufflevector(lo, hi, 0, 1, 2, 3, 4, 5, 6, 7);
; #pragma unroll
;                 for (int n = 0; n < 2; ++n) accS[m][n] = MFMA16(A, Bv[k2][n], accS[m][n]); }
	v_mfma_f32_16x16x32_bf16 v[120:123], v[108:111], v[124:127], v[120:123]
	v_mfma_f32_16x16x32_bf16 v[246:249], v[108:111], v[128:131], v[116:119]
	ds_read_b128 v[108:111], v224 offset:4608
	s_waitcnt lgkmcnt(0)
	v_mfma_f32_16x16x32_bf16 v[144:147], v[108:111], v[124:127], v[144:147]
	v_mfma_f32_16x16x32_bf16 v[140:143], v[108:111], v[128:131], v[140:143]
	ds_read_b128 v[108:111], v224 offset:6912
	ds_read_b128 v[116:119], v224 offset:64
	ds_read_b64_tr_b16 v[114:115], v223 offset:36928
	s_waitcnt lgkmcnt(2)
	v_mfma_f32_16x16x32_bf16 v[194:197], v[108:111], v[124:127], v[100:103]
	v_mfma_f32_16x16x32_bf16 v[202:205], v[108:111], v[128:131], v[104:107]
	ds_read_b64_tr_b16 v[112:113], v223 offset:34816
	ds_read_b64_tr_b16 v[108:109], v223 offset:34848
	ds_read_b64_tr_b16 v[110:111], v223 offset:36960
	s_waitcnt lgkmcnt(2)
	v_mfma_f32_16x16x32_bf16 v[100:103], v[116:119], v[112:115], v[136:139]
	s_nop 2
	ds_read_b128 v[136:139], v224 offset:4672
	s_waitcnt lgkmcnt(1)
	v_mfma_f32_16x16x32_bf16 v[104:107], v[116:119], v[108:111], v[132:135]
	s_nop 2
	ds_read_b128 v[132:135], v224 offset:2368
	s_waitcnt lgkmcnt(0)
	v_mfma_f32_16x16x32_bf16 v[116:119], v[132:135], v[112:115], v[120:123]
	v_mfma_f32_16x16x32_bf16 v[120:123], v[132:135], v[108:111], v[246:249]
	v_mfma_f32_16x16x32_bf16 v[132:135], v[136:139], v[112:115], v[144:147]
	s_nop 2
	ds_read_b128 v[144:147], v224 offset:6976
	v_mfma_f32_16x16x32_bf16 v[136:139], v[136:139], v[108:111], v[140:143]
	s_waitcnt lgkmcnt(0)
	v_mfma_f32_16x16x32_bf16 v[140:143], v[144:147], v[112:115], v[194:197]
	s_nop 2
	ds_read_b64_tr_b16 v[196:197], v1 offset:18496
	ds_read_b64_tr_b16 v[194:195], v1 offset:17408
	s_waitcnt lgkmcnt(0)
	v_mfma_f32_16x16x32_bf16 v[84:87], v[194:197], v[124:127], v[84:87]
	v_mfma_f32_16x16x32_bf16 v[92:95], v[194:197], v[128:131], v[92:95]
	ds_read_b64_tr_b16 v[196:197], v225 offset:18496
	ds_read_b64_tr_b16 v[194:195], v225 offset:17408
	v_mfma_f32_16x16x32_bf16 v[144:147], v[144:147], v[108:111], v[202:205]
	s_nop 2
	ds_read_b64_tr_b16 v[202:203], v1 offset:17440
	ds_read_b64_tr_b16 v[204:205], v1 offset:18528
	s_waitcnt lgkmcnt(2)
	v_mfma_f32_16x16x32_bf16 v[84:87], v[194:197], v[112:115], v[84:87]
	v_mfma_f32_16x16x32_bf16 v[92:95], v[194:197], v[108:111], v[92:95]
	ds_read_b64_tr_b16 v[194:195], v225 offset:17440
	ds_read_b64_tr_b16 v[196:197], v225 offset:18528
	s_waitcnt lgkmcnt(2)
	v_mfma_f32_16x16x32_bf16 v[88:91], v[202:205], v[124:127], v[88:91]
	v_mfma_f32_16x16x32_bf16 v[96:99], v[202:205], v[128:131], v[96:99]
	s_waitcnt lgkmcnt(0)
	v_mfma_f32_16x16x32_bf16 v[88:91], v[194:197], v[112:115], v[88:91]
	v_mfma_f32_16x16x32_bf16 v[96:99], v[194:197], v[108:111], v[96:99]
	ds_read_b64_tr_b16 v[194:195], v1 offset:17472
	ds_read_b64_tr_b16 v[196:197], v1 offset:18560
	s_waitcnt lgkmcnt(0)
	v_mfma_f32_16x16x32_bf16 v[76:79], v[194:197], v[124:127], v[76:79]
	v_mfma_f32_16x16x32_bf16 v[80:83], v[194:197], v[128:131], v[80:83]
	ds_read_b64_tr_b16 v[194:195], v225 offset:17472
	ds_read_b64_tr_b16 v[196:197], v225 offset:18560
	s_waitcnt lgkmcnt(0)
	v_mfma_f32_16x16x32_bf16 v[76:79], v[194:197], v[112:115], v[76:79]
	v_mfma_f32_16x16x32_bf16 v[80:83], v[194:197], v[108:111], v[80:83]
	ds_read_b64_tr_b16 v[194:195], v1 offset:17504
	ds_read_b64_tr_b16 v[196:197], v1 offset:18592
	s_waitcnt lgkmcnt(0)
	v_mfma_f32_16x16x32_bf16 v[68:71], v[194:197], v[124:127], v[68:71]
	v_mfma_f32_16x16x32_bf16 v[72:75], v[194:197], v[128:131], v[72:75]
	ds_read_b64_tr_b16 v[194:195], v225 offset:17504
	ds_read_b64_tr_b16 v[196:197], v225 offset:18592
	s_waitcnt lgkmcnt(0)
	v_mfma_f32_16x16x32_bf16 v[68:71], v[194:197], v[112:115], v[68:71]
	v_mfma_f32_16x16x32_bf16 v[72:75], v[194:197], v[108:111], v[72:75]
	ds_read_b64_tr_b16 v[194:195], v1 offset:17536
	ds_read_b64_tr_b16 v[196:197], v1 offset:18624
	s_waitcnt lgkmcnt(0)
	v_mfma_f32_16x16x32_bf16 v[52:55], v[194:197], v[124:127], v[52:55]
	v_mfma_f32_16x16x32_bf16 v[64:67], v[194:197], v[128:131], v[64:67]
	ds_read_b64_tr_b16 v[194:195], v225 offset:17536
	ds_read_b64_tr_b16 v[196:197], v225 offset:18624
	s_waitcnt lgkmcnt(0)
	v_mfma_f32_16x16x32_bf16 v[52:55], v[194:197], v[112:115], v[52:55]
	v_mfma_f32_16x16x32_bf16 v[64:67], v[194:197], v[108:111], v[64:67]
	ds_read_b64_tr_b16 v[194:195], v1 offset:17568
	ds_read_b64_tr_b16 v[196:197], v1 offset:18656
	s_waitcnt lgkmcnt(0)
	v_mfma_f32_16x16x32_bf16 v[40:43], v[194:197], v[124:127], v[40:43]
	v_mfma_f32_16x16x32_bf16 v[56:59], v[194:197], v[128:131], v[56:59]
	ds_read_b64_tr_b16 v[194:195], v225 offset:17568
	ds_read_b64_tr_b16 v[196:197], v225 offset:18656
	s_waitcnt lgkmcnt(0)
	v_mfma_f32_16x16x32_bf16 v[40:43], v[194:197], v[112:115], v[40:43]
	v_mfma_f32_16x16x32_bf16 v[56:59], v[194:197], v[108:111], v[56:59]
	ds_read_b64_tr_b16 v[194:195], v1 offset:17600
	ds_read_b64_tr_b16 v[196:197], v1 offset:18688
	s_waitcnt lgkmcnt(0)
	v_mfma_f32_16x16x32_bf16 v[44:47], v[194:197], v[124:127], v[44:47]
	v_mfma_f32_16x16x32_bf16 v[60:63], v[194:197], v[128:131], v[60:63]
	ds_read_b64_tr_b16 v[194:195], v225 offset:17600
	ds_read_b64_tr_b16 v[196:197], v225 offset:18688
	s_waitcnt lgkmcnt(0)
	v_mfma_f32_16x16x32_bf16 v[44:47], v[194:197], v[112:115], v[44:47]
	v_mfma_f32_16x16x32_bf16 v[60:63], v[194:197], v[108:111], v[60:63]
	ds_read_b64_tr_b16 v[194:195], v1 offset:17632
	ds_read_b64_tr_b16 v[196:197], v1 offset:18720
	s_waitcnt lgkmcnt(0)
	v_mfma_f32_16x16x32_bf16 v[36:39], v[194:197], v[124:127], v[36:39]
	ds_read_b64_tr_b16 v[124:125], v225 offset:17632
	ds_read_b64_tr_b16 v[126:127], v225 offset:18720
	v_mfma_f32_16x16x32_bf16 v[48:51], v[194:197], v[128:131], v[48:51]
	s_waitcnt lgkmcnt(0)
	v_mfma_f32_16x16x32_bf16 v[36:39], v[124:127], v[112:115], v[36:39]
	v_mfma_f32_16x16x32_bf16 v[48:51], v[124:127], v[108:111], v[48:51]
	s_cbranch_vccnz .LBB0_1380
; #define GAS __attribute__((address_space(1)))
; #define LAS __attribute__((address_space(3)))
; __device__ __forceinline__ void ret_unit(const Frame& F, int layer, int uid) {
;     ...
;         if (write_out) {
;             __syncthreads();
;             LAS float* oL = (LAS float*)F.lds;
; #pragma unroll
;             for (int m = 0; m < 4; ++m)
; #pragma unroll
;                 for (int n = 0; n < 2; ++n)
; #pragma unroll
;                     for (int r = 0; r < 4; ++r) oL[(16 * m + 4 * g + r) * 256 + 32 * w + 16 * n + l15] = accO[m][n][r];
;             __syncthreads();
;             const f32x4 gn = *(const GAS f32x4*)(in_ptr(IN_RETG) + ((size_t)layer * HRET + h) * DVR + lane * 4);
; #pragma unroll
;             for (int hb2 = 0; hb2 < 2; ++hb2) {
;             f32x4 x[4]; v2u gr[4]; float s1[4], s2[4];
; #pragma unroll
;             for (int tt = 0; tt < 4; ++tt) { const int t = w * 8 + hb2 * 4 + tt; x[tt] = *(const LAS f32x4*)(oL + t * 256 + lane * 4); gr[tt] = grp[hb2][tt];
;                 s1[tt] = (x[tt][0] + x[tt][1]) + (x[tt][2] + x[tt][3]); }
; #pragma unroll
;             for (int o = 1; o < 64; o <<= 1)
; #pragma unroll
;                 for (int tt = 0; tt < 4; ++tt) s1[tt] += __shfl_xor(s1[tt], o);
	v_add_u32_e32 v1, 0x400, v226
	s_barrier
	ds_write2_b32 v1, v101, v105 offset1:16
	v_add_u32_e32 v1, 0x800, v226
	ds_write2_b32 v1, v102, v106 offset1:16
	v_add_u32_e32 v1, 0xc00, v226
	ds_write2_b32 v226, v100, v104 offset1:16
	ds_write2_b32 v1, v103, v107 offset1:16
	ds_write2_b32 v227, v116, v120 offset1:16
	v_add_u32_e32 v1, 0x4400, v226
	ds_write2_b32 v1, v117, v121 offset1:16
	v_add_u32_e32 v1, 0x4800, v226
	ds_write2_b32 v1, v118, v122 offset1:16
	v_add_u32_e32 v1, 0x4c00, v226
	ds_write2_b32 v1, v119, v123 offset1:16
	ds_write2_b32 v228, v132, v136 offset1:16
	v_add_u32_e32 v1, 0x8400, v226
	ds_write2_b32 v1, v133, v137 offset1:16
	v_add_u32_e32 v1, 0x8800, v226
	ds_write2_b32 v1, v134, v138 offset1:16
	v_add_u32_e32 v1, 0x8c00, v226
	ds_write2_b32 v1, v135, v139 offset1:16
	ds_write2_b32 v229, v140, v144 offset1:16
	v_add_u32_e32 v1, 0xc400, v226
	ds_write2_b32 v1, v141, v145 offset1:16
	v_add_u32_e32 v1, 0xc800, v226
	ds_write2_b32 v1, v142, v146 offset1:16
	v_add_u32_e32 v1, 0xcc00, v226
	s_mov_b64 s[38:39], s[0:1]
	ds_write2_b32 v1, v143, v147 offset1:16
	s_waitcnt lgkmcnt(0)
	s_barrier
	s_load_dwordx2 s[38:39], s[38:39], 0x40
	v_and_b32_e32 v1, 64, v239
	v_add_u32_e32 v124, 64, v1
	s_waitcnt lgkmcnt(0)
	s_add_u32 s38, s38, s68
	s_addc_u32 s39, s39, s69
	v_lshl_add_u64 v[100:101], v[166:167], 2, s[38:39]
	v_readlane_b32 s38, v253, 33
	global_load_dwordx4 v[100:103], v[100:101], off
	s_cmp_ge_u32 s70, s67
	v_add_u32_e32 v1, s38, v192
	ds_read_b128 v[116:119], v1
	v_readlane_b32 s38, v253, 45
	s_waitcnt lgkmcnt(0)
	v_mov_b32_e32 v104, v117
	v_add_u32_e32 v1, s38, v192
	ds_read_b128 v[112:115], v1
	v_readlane_b32 s38, v253, 47
	v_mov_b32_e32 v105, v118
	v_mov_b32_e32 v106, v116
	v_add_u32_e32 v1, s38, v192
	ds_read_b128 v[108:111], v1
	v_mov_b32_e32 v107, v119
	v_pk_add_f32 v[104:105], v[104:105], v[106:107]
	s_waitcnt lgkmcnt(1)
	v_mov_b32_e32 v106, v112
	v_add_f32_e32 v3, v104, v105
	v_mov_b32_e32 v104, v113
	v_mov_b32_e32 v105, v114
	v_mov_b32_e32 v107, v115
	v_pk_add_f32 v[104:105], v[104:105], v[106:107]
	s_waitcnt lgkmcnt(0)
	v_mov_b32_e32 v106, v108
	v_add_f32_e32 v125, v104, v105
	v_mov_b32_e32 v104, v109
	v_mov_b32_e32 v105, v110
	v_mov_b32_e32 v107, v111
	v_readlane_b32 s38, v253, 48
	v_pk_add_f32 v[104:105], v[104:105], v[106:107]
	s_nop 0
	v_add_u32_e32 v1, s38, v192
	v_add_f32_e32 v126, v104, v105
	ds_read_b128 v[104:107], v1
	v_xor_b32_e32 v1, 1, v239
	v_cmp_lt_i32_e32 vcc, v1, v124
	s_waitcnt lgkmcnt(0)
	v_mov_b32_e32 v120, v105
	v_mov_b32_e32 v121, v106
	v_mov_b32_e32 v122, v104
	v_mov_b32_e32 v123, v107
	v_cndmask_b32_e32 v1, v239, v1, vcc
	v_pk_add_f32 v[120:121], v[120:121], v[122:123]
	v_lshlrev_b32_e32 v1, 2, v1
	v_add_f32_e32 v120, v120, v121
	ds_bpermute_b32 v194, v1, v3
	ds_bpermute_b32 v195, v1, v125
	ds_bpermute_b32 v196, v1, v126
	ds_bpermute_b32 v197, v1, v120
	s_waitcnt lgkmcnt(3)
	v_add_f32_e32 v121, v3, v194
	s_waitcnt lgkmcnt(2)
	v_add_f32_e32 v122, v125, v195
	s_waitcnt lgkmcnt(1)
	v_add_f32_e32 v123, v126, v196
	s_waitcnt lgkmcnt(0)
	v_add_f32_e32 v120, v120, v197
	v_xor_b32_e32 v3, 2, v239
	v_cmp_lt_i32_e32 vcc, v3, v124
	s_nop 1
	v_cndmask_b32_e32 v3, v239, v3, vcc
	v_lshlrev_b32_e32 v3, 2, v3
	ds_bpermute_b32 v194, v3, v121
	ds_bpermute_b32 v195, v3, v122
	ds_bpermute_b32 v196, v3, v123
	ds_bpermute_b32 v197, v3, v120
	s_waitcnt lgkmcnt(3)
	v_add_f32_e32 v121, v121, v194
	s_waitcnt lgkmcnt(2)
	v_add_f32_e32 v122, v122, v195
	s_waitcnt lgkmcnt(1)
	v_add_f32_e32 v123, v123, v196
	s_waitcnt lgkmcnt(0)
	v_add_f32_e32 v125, v120, v197
	v_xor_b32_e32 v120, 4, v239
	v_cmp_lt_i32_e32 vcc, v120, v124
	s_nop 1
	v_cndmask_b32_e32 v120, v239, v120, vcc
	v_lshlrev_b32_e32 v120, 2, v120
	ds_bpermute_b32 v194, v120, v121
	ds_bpermute_b32 v195, v120, v122
	ds_bpermute_b32 v196, v120, v123
	ds_bpermute_b32 v197, v120, v125
	s_waitcnt lgkmcnt(3)
	v_add_f32_e32 v126, v121, v194
	s_waitcnt lgkmcnt(2)
	v_add_f32_e32 v122, v122, v195
	s_waitcnt lgkmcnt(1)
	v_add_f32_e32 v123, v123, v196
	s_waitcnt lgkmcnt(0)
	v_add_f32_e32 v125, v125, v197
	v_xor_b32_e32 v121, 8, v239
	v_cmp_lt_i32_e32 vcc, v121, v124
	s_nop 1
	v_cndmask_b32_e32 v121, v239, v121, vcc
	v_lshlrev_b32_e32 v121, 2, v121
	ds_bpermute_b32 v194, v121, v126
	ds_bpermute_b32 v195, v121, v122
	ds_bpermute_b32 v196, v121, v123
	ds_bpermute_b32 v197, v121, v125
	s_waitcnt lgkmcnt(3)
	v_add_f32_e32 v126, v126, v194
	s_waitcnt lgkmcnt(2)
	v_add_f32_e32 v127, v122, v195
	s_waitcnt lgkmcnt(1)
	v_add_f32_e32 v123, v123, v196
	s_waitcnt lgkmcnt(0)
	v_add_f32_e32 v125, v125, v197
	v_xor_b32_e32 v122, 16, v239
	v_cmp_lt_i32_e32 vcc, v122, v124
	s_nop 1
	v_cndmask_b32_e32 v122, v239, v122, vcc
	v_lshlrev_b32_e32 v122, 2, v122
	ds_bpermute_b32 v194, v122, v126
	ds_bpermute_b32 v195, v122, v127
	ds_bpermute_b32 v196, v122, v123
	ds_bpermute_b32 v197, v122, v125
	s_waitcnt lgkmcnt(3)
	v_add_f32_e32 v126, v126, v194
	s_waitcnt lgkmcnt(2)
	v_add_f32_e32 v127, v127, v195
	s_waitcnt lgkmcnt(1)
	v_add_f32_e32 v128, v123, v196
	s_waitcnt lgkmcnt(0)
	v_add_f32_e32 v125, v125, v197
	v_xor_b32_e32 v123, 32, v239
	v_cmp_lt_i32_e32 vcc, v123, v124
	s_nop 1
	v_cndmask_b32_e32 v123, v239, v123, vcc
	v_lshlrev_b32_e32 v123, 2, v123
	ds_bpermute_b32 v124, v123, v126
	s_waitcnt lgkmcnt(0)
	v_add_f32_e32 v124, v126, v124
	ds_bpermute_b32 v126, v123, v127
	v_fmamk_f32 v119, v124, 0xbb800000, v119
	v_fmamk_f32 v117, v124, 0xbb800000, v117
	v_fmamk_f32 v118, v124, 0xbb800000, v118
	v_fmac_f32_e32 v116, 0xbb800000, v124
	s_waitcnt lgkmcnt(0)
	v_add_f32_e32 v126, v127, v126
	ds_bpermute_b32 v127, v123, v128
	v_mul_f32_e32 v124, v117, v117
	v_fmac_f32_e32 v124, v116, v116
	v_fmamk_f32 v115, v126, 0xbb800000, v115
	v_fmamk_f32 v113, v126, 0xbb800000, v113
	s_waitcnt lgkmcnt(0)
; #define GAS __attribute__((address_space(1)))
; __device__ __forceinline__ unsigned pk2(float lo, float hi) { return f2bf(lo) | (f2bf(hi) << 16); }
; #define WSB(F, off) ((bf16*)(wsq((F).ws) + (off)))
; __device__ __forceinline__ void ret_unit(const Frame& F, int layer, int uid) {
;     ...
;                 for (int tt = 0; tt < 4; ++tt) s1[tt] += __shfl_xor(s1[tt], o);
; #pragma unroll
;             for (int tt = 0; tt < 4; ++tt) { x[tt] = x[tt] - s1[tt] * (1.f / 256.f); s2[tt] = (x[tt][0] * x[tt][0] + x[tt][1] * x[tt][1]) + (x[tt][2] * x[tt][2] + x[tt][3] * x[tt][3]); }
; #pragma unroll
;             for (int o = 1; o < 64; o <<= 1)
; #pragma unroll
;                 for (int tt = 0; tt < 4; ++tt) s2[tt] += __shfl_xor(s2[tt], o);
; #pragma unroll
;             for (int tt = 0; tt < 4; ++tt) { const int t = w * 8 + hb2 * 4 + tt; const float rstd = 1.f / sqrtf(s2[tt] * (1.f / 256.f) + LN_EPS);
;                 const f32x4 y = x[tt] * rstd * gn * (f32x4){bflo(gr[tt].x), bfhi(gr[tt].x), bflo(gr[tt].y), bfhi(gr[tt].y)};
;                 if (t < valid) *(GAS v2u*)(WSB(F, WS_BR) + (size_t)(rowbase + t) * D + h * 256 + lane * 4) = (v2u){pk2(y[0], y[1]), pk2(y[2], y[3])}; }
	v_add_f32_e32 v127, v128, v127
	ds_bpermute_b32 v128, v123, v125
	v_fmamk_f32 v114, v126, 0xbb800000, v114
	v_fmac_f32_e32 v112, 0xbb800000, v126
	v_mul_f32_e32 v126, v113, v113
	v_fmac_f32_e32 v126, v112, v112
	s_waitcnt lgkmcnt(0)
	v_add_f32_e32 v125, v125, v128
	v_mul_f32_e32 v128, v119, v119
	v_fmac_f32_e32 v128, v118, v118
	v_add_f32_e32 v124, v124, v128
	v_mul_f32_e32 v128, v115, v115
	v_fmac_f32_e32 v128, v114, v114
	v_fmamk_f32 v111, v127, 0xbb800000, v111
	v_fmamk_f32 v109, v127, 0xbb800000, v109
	v_add_f32_e32 v126, v126, v128
	v_fmamk_f32 v110, v127, 0xbb800000, v110
	v_fmac_f32_e32 v108, 0xbb800000, v127
	v_mul_f32_e32 v127, v109, v109
	v_mul_f32_e32 v128, v111, v111
	v_fmac_f32_e32 v127, v108, v108
	v_fmac_f32_e32 v128, v110, v110
	v_fmamk_f32 v107, v125, 0xbb800000, v107
	v_fmamk_f32 v105, v125, 0xbb800000, v105
	v_add_f32_e32 v127, v127, v128
	v_fmamk_f32 v106, v125, 0xbb800000, v106
	v_fmac_f32_e32 v104, 0xbb800000, v125
	v_mul_f32_e32 v125, v105, v105
	v_mul_f32_e32 v128, v107, v107
	v_fmac_f32_e32 v125, v104, v104
	v_fmac_f32_e32 v128, v106, v106
	v_add_f32_e32 v125, v125, v128
	ds_bpermute_b32 v194, v1, v124
	ds_bpermute_b32 v195, v1, v126
	ds_bpermute_b32 v196, v1, v127
	ds_bpermute_b32 v197, v1, v125
	s_waitcnt lgkmcnt(3)
	v_add_f32_e32 v124, v124, v194
	s_waitcnt lgkmcnt(2)
	v_add_f32_e32 v126, v126, v195
	s_waitcnt lgkmcnt(1)
	v_add_f32_e32 v127, v127, v196
	s_waitcnt lgkmcnt(0)
	v_add_f32_e32 v125, v125, v197
	ds_bpermute_b32 v194, v3, v124
	ds_bpermute_b32 v195, v3, v126
	ds_bpermute_b32 v196, v3, v127
	ds_bpermute_b32 v197, v3, v125
	s_waitcnt lgkmcnt(3)
	v_add_f32_e32 v124, v124, v194
	s_waitcnt lgkmcnt(2)
	v_add_f32_e32 v126, v126, v195
	s_waitcnt lgkmcnt(1)
	v_add_f32_e32 v127, v127, v196
	s_waitcnt lgkmcnt(0)
	v_add_f32_e32 v125, v125, v197
	ds_bpermute_b32 v194, v120, v124
	ds_bpermute_b32 v195, v120, v126
	ds_bpermute_b32 v196, v120, v127
	ds_bpermute_b32 v197, v120, v125
	s_waitcnt lgkmcnt(3)
	v_add_f32_e32 v124, v124, v194
	s_waitcnt lgkmcnt(2)
	v_add_f32_e32 v126, v126, v195
	s_waitcnt lgkmcnt(1)
	v_add_f32_e32 v127, v127, v196
	s_waitcnt lgkmcnt(0)
	v_add_f32_e32 v125, v125, v197
	ds_bpermute_b32 v194, v121, v124
	ds_bpermute_b32 v195, v121, v126
	ds_bpermute_b32 v196, v121, v127
	ds_bpermute_b32 v197, v121, v125
	s_waitcnt lgkmcnt(3)
	v_add_f32_e32 v124, v124, v194
	s_waitcnt lgkmcnt(2)
	v_add_f32_e32 v126, v126, v195
	s_waitcnt lgkmcnt(1)
	v_add_f32_e32 v127, v127, v196
	s_waitcnt lgkmcnt(0)
	v_add_f32_e32 v125, v125, v197
	ds_bpermute_b32 v128, v122, v124
	s_waitcnt lgkmcnt(0)
	v_add_f32_e32 v130, v124, v128
	ds_bpermute_b32 v124, v122, v126
	ds_bpermute_b32 v131, v123, v130
	s_waitcnt lgkmcnt(1)
	v_add_f32_e32 v128, v126, v124
	ds_bpermute_b32 v124, v122, v127
	ds_bpermute_b32 v129, v123, v128
	s_waitcnt lgkmcnt(1)
	v_add_f32_e32 v126, v127, v124
	ds_bpermute_b32 v124, v122, v125
	ds_bpermute_b32 v127, v123, v126
	s_waitcnt lgkmcnt(1)
	v_add_f32_e32 v124, v125, v124
	ds_bpermute_b32 v125, v123, v124
	s_waitcnt vmcnt(0)
	s_cbranch_scc1 .LBB0_1416
	v_add_f32_e32 v130, v130, v131
	v_fmamk_f32 v130, v130, 0x3b800000, v235
	v_mul_f32_e32 v131, 0x4f800000, v130
	v_cmp_gt_f32_e32 vcc, s89, v130
	s_ashr_i32 s43, s42, 31
	s_lshl_b64 s[42:43], s[42:43], 11
	v_cndmask_b32_e32 v130, v130, v131, vcc
	v_sqrt_f32_e32 v132, v130
	s_nop 0
	v_and_b32_e32 v131, 0xffff0000, v185
	v_add_u32_e32 v133, -1, v132
	v_fma_f32 v134, -v133, v132, v130
	v_cmp_ge_f32_e64 s[38:39], 0, v134
	v_add_u32_e32 v134, 1, v132
	s_nop 0
	v_cndmask_b32_e64 v133, v132, v133, s[38:39]
	v_fma_f32 v132, -v134, v132, v130
	v_cmp_lt_f32_e64 s[38:39], 0, v132
	s_nop 1
	v_cndmask_b32_e64 v132, v133, v134, s[38:39]
	v_mul_f32_e32 v133, 0x37800000, v132
	v_cndmask_b32_e32 v132, v132, v133, vcc
	v_cmp_class_f32_e32 vcc, v130, v236
	v_and_b32_e32 v133, 0xffff0000, v184
	s_nop 0
	v_cndmask_b32_e32 v134, v132, v130, vcc
	v_div_scale_f32 v135, s[38:39], v134, v134, 1.0
	v_rcp_f32_e32 v136, v135
	v_lshlrev_b32_e32 v132, 16, v184
	v_lshlrev_b32_e32 v130, 16, v185
	s_mov_b64 s[38:39], s[46:47]
	v_fma_f32 v137, -v135, v136, 1.0
	v_fmac_f32_e32 v136, v137, v136
	v_div_scale_f32 v137, vcc, 1.0, v134, 1.0
	v_mul_f32_e32 v138, v137, v136
	v_fma_f32 v139, -v135, v138, v137
	v_fmac_f32_e32 v138, v139, v136
	v_fma_f32 v135, -v135, v138, v137
	v_div_fmas_f32 v135, v135, v136, v138
	v_div_fixup_f32 v134, v135, v134, 1.0
	v_pk_mul_f32 v[116:117], v[116:117], v[134:135] op_sel_hi:[1,0]
	v_pk_mul_f32 v[118:119], v[118:119], v[134:135] op_sel_hi:[1,0]
	s_nop 0
	v_pk_mul_f32 v[116:117], v[100:101], v[116:117]
	v_pk_mul_f32 v[118:119], v[102:103], v[118:119]
	v_pk_mul_f32 v[116:117], v[116:117], v[132:133]
	v_pk_mul_f32 v[118:119], v[118:119], v[130:131]
	s_add_u32 s38, s38, s42
	v_cvt_pk_bf16_f32 v116, v116, v117
	s_addc_u32 s39, s39, s43
	s_lshl_b32 s42, s52, 1
	s_add_u32 s38, s38, s42
	s_addc_u32 s39, s39, 0
	v_cvt_pk_bf16_f32 v117, v118, v119
	v_lshl_add_u64 v[118:119], v[166:167], 1, s[38:39]
	v_add_co_u32_e32 v118, vcc, 0x76fc0000, v118
	s_nop 1
	v_addc_co_u32_e32 v119, vcc, 0, v119, vcc
	global_store_dwordx2 v[118:119], v[116:117], off
; #define GAS __attribute__((address_space(1)))
; __device__ __forceinline__ unsigned pk2(float lo, float hi) { return f2bf(lo) | (f2bf(hi) << 16); }
; #define WSB(F, off) ((bf16*)(wsq((F).ws) + (off)))
; __device__ __forceinline__ void ret_unit(const Frame& F, int layer, int uid) {
;     ...
;             for (int tt = 0; tt < 4; ++tt) { const int t = w * 8 + hb2 * 4 + tt; const float rstd = 1.f / sqrtf(s2[tt] * (1.f / 256.f) + LN_EPS);
;                 const f32x4 y = x[tt] * rstd * gn * (f32x4){bflo(gr[tt].x), bfhi(gr[tt].x), bflo(gr[tt].y), bfhi(gr[tt].y)};
;                 if (t < valid) *(GAS v2u*)(WSB(F, WS_BR) + (size_t)(rowbase + t) * D + h * 256 + lane * 4) = (v2u){pk2(y[0], y[1]), pk2(y[2], y[3])}; }
.LBB0_1416:
	v_readlane_b32 s38, v253, 44
	s_cmp_ge_u32 s38, s67
	s_cbranch_scc1 .LBB0_1418
	v_add_f32_e32 v116, v128, v129
	v_fmamk_f32 v116, v116, 0x3b800000, v235
	v_mul_f32_e32 v117, 0x4f800000, v116
	v_cmp_gt_f32_e32 vcc, s89, v116
	v_readlane_b32 s42, v253, 44
	s_add_i32 s42, s78, s42
	v_cndmask_b32_e32 v116, v116, v117, vcc
	v_sqrt_f32_e32 v118, v116
	s_nop 0
	v_and_b32_e32 v117, 0xffff0000, v181
	s_ashr_i32 s43, s42, 31
	s_lshl_b64 s[42:43], s[42:43], 11
	v_add_u32_e32 v119, -1, v118
	v_fma_f32 v128, -v119, v118, v116
	v_cmp_ge_f32_e64 s[38:39], 0, v128
	v_add_u32_e32 v128, 1, v118
	s_nop 0
	v_cndmask_b32_e64 v119, v118, v119, s[38:39]
	v_fma_f32 v118, -v128, v118, v116
	v_cmp_lt_f32_e64 s[38:39], 0, v118
	s_nop 1
	v_cndmask_b32_e64 v118, v119, v128, s[38:39]
	v_mul_f32_e32 v119, 0x37800000, v118
	v_cndmask_b32_e32 v118, v118, v119, vcc
	v_cmp_class_f32_e32 vcc, v116, v236
	v_and_b32_e32 v119, 0xffff0000, v180
	s_nop 0
	v_cndmask_b32_e32 v128, v118, v116, vcc
	v_div_scale_f32 v129, s[38:39], v128, v128, 1.0
	v_rcp_f32_e32 v130, v129
	v_lshlrev_b32_e32 v118, 16, v180
	v_lshlrev_b32_e32 v116, 16, v181
	s_mov_b64 s[38:39], s[46:47]
	v_fma_f32 v131, -v129, v130, 1.0
	v_fmac_f32_e32 v130, v131, v130
	v_div_scale_f32 v131, vcc, 1.0, v128, 1.0
	v_mul_f32_e32 v132, v131, v130
	v_fma_f32 v133, -v129, v132, v131
	v_fmac_f32_e32 v132, v133, v130
	v_fma_f32 v129, -v129, v132, v131
	v_div_fmas_f32 v129, v129, v130, v132
	v_div_fixup_f32 v128, v129, v128, 1.0
	v_pk_mul_f32 v[112:113], v[112:113], v[128:129] op_sel_hi:[1,0]
	v_pk_mul_f32 v[114:115], v[114:115], v[128:129] op_sel_hi:[1,0]
	s_nop 0
	v_pk_mul_f32 v[112:113], v[100:101], v[112:113]
	v_pk_mul_f32 v[114:115], v[102:103], v[114:115]
	v_pk_mul_f32 v[112:113], v[112:113], v[118:119]
	v_pk_mul_f32 v[114:115], v[114:115], v[116:117]
	s_add_u32 s38, s38, s42
	v_cvt_pk_bf16_f32 v112, v112, v113
	s_addc_u32 s39, s39, s43
	s_lshl_b32 s42, s52, 1
	s_add_u32 s38, s38, s42
	s_addc_u32 s39, s39, 0
	v_cvt_pk_bf16_f32 v113, v114, v115
	v_lshl_add_u64 v[114:115], v[166:167], 1, s[38:39]
	v_add_co_u32_e32 v114, vcc, 0x76fc0000, v114
	s_nop 1
	v_addc_co_u32_e32 v115, vcc, 0, v115, vcc
	global_store_dwordx2 v[114:115], v[112:113], off
.LBB0_1418:
	v_readlane_b32 s38, v253, 46
	s_cmp_ge_u32 s38, s67
	s_cbranch_scc1 .LBB0_1420
	s_waitcnt lgkmcnt(1)
	v_add_f32_e32 v112, v126, v127
	v_fmamk_f32 v112, v112, 0x3b800000, v235
	v_mul_f32_e32 v113, 0x4f800000, v112
	v_cmp_gt_f32_e32 vcc, s89, v112
	v_readlane_b32 s42, v253, 46
	s_add_i32 s42, s78, s42
	v_cndmask_b32_e32 v112, v112, v113, vcc
	v_sqrt_f32_e32 v114, v112
	s_nop 0
	v_and_b32_e32 v113, 0xffff0000, v177
	s_ashr_i32 s43, s42, 31
	s_lshl_b64 s[42:43], s[42:43], 11
	v_add_u32_e32 v115, -1, v114
	v_fma_f32 v116, -v115, v114, v112
	v_cmp_ge_f32_e64 s[38:39], 0, v116
	v_add_u32_e32 v116, 1, v114
	s_nop 0
	v_cndmask_b32_e64 v115, v114, v115, s[38:39]
	v_fma_f32 v114, -v116, v114, v112
	v_cmp_lt_f32_e64 s[38:39], 0, v114
	s_nop 1
	v_cndmask_b32_e64 v114, v115, v116, s[38:39]
	v_mul_f32_e32 v115, 0x37800000, v114
	v_cndmask_b32_e32 v114, v114, v115, vcc
	v_cmp_class_f32_e32 vcc, v112, v236
	v_and_b32_e32 v115, 0xffff0000, v176
	s_nop 0
	v_cndmask_b32_e32 v116, v114, v112, vcc
	v_div_scale_f32 v117, s[38:39], v116, v116, 1.0
	v_rcp_f32_e32 v118, v117
	v_lshlrev_b32_e32 v114, 16, v176
	v_lshlrev_b32_e32 v112, 16, v177
	s_mov_b64 s[38:39], s[46:47]
	v_fma_f32 v119, -v117, v118, 1.0
	v_fmac_f32_e32 v118, v119, v118
	v_div_scale_f32 v119, vcc, 1.0, v116, 1.0
	v_mul_f32_e32 v126, v119, v118
	v_fma_f32 v127, -v117, v126, v119
	v_fmac_f32_e32 v126, v127, v118
	v_fma_f32 v117, -v117, v126, v119
	v_div_fmas_f32 v117, v117, v118, v126
	v_div_fixup_f32 v116, v117, v116, 1.0
	v_pk_mul_f32 v[108:109], v[108:109], v[116:117] op_sel_hi:[1,0]
	v_pk_mul_f32 v[110:111], v[110:111], v[116:117] op_sel_hi:[1,0]
	s_nop 0
	v_pk_mul_f32 v[108:109], v[100:101], v[108:109]
	v_pk_mul_f32 v[110:111], v[102:103], v[110:111]
	v_pk_mul_f32 v[108:109], v[108:109], v[114:115]
	v_pk_mul_f32 v[110:111], v[110:111], v[112:113]
	s_add_u32 s38, s38, s42
	v_cvt_pk_bf16_f32 v108, v108, v109
	s_addc_u32 s39, s39, s43
	s_lshl_b32 s42, s52, 1
	s_add_u32 s38, s38, s42
	s_addc_u32 s39, s39, 0
	v_cvt_pk_bf16_f32 v109, v110, v111
	v_lshl_add_u64 v[110:111], v[166:167], 1, s[38:39]
	v_add_co_u32_e32 v110, vcc, 0x76fc0000, v110
	s_nop 1
	v_addc_co_u32_e32 v111, vcc, 0, v111, vcc
	global_store_dwordx2 v[110:111], v[108:109], off
.LBB0_1420:
	s_cmp_ge_u32 s66, s67
	s_cbranch_scc1 .LBB0_1422
	s_waitcnt lgkmcnt(0)
	v_add_f32_e32 v108, v124, v125
	v_fmamk_f32 v108, v108, 0x3b800000, v235
	v_mul_f32_e32 v109, 0x4f800000, v108
	v_cmp_gt_f32_e32 vcc, s89, v108
	s_add_i32 s42, s78, s66
	s_ashr_i32 s43, s42, 31
	v_cndmask_b32_e32 v108, v108, v109, vcc
	v_sqrt_f32_e32 v110, v108
	s_nop 0
	v_and_b32_e32 v109, 0xffff0000, v179
	s_lshl_b64 s[42:43], s[42:43], 11
	v_add_u32_e32 v111, -1, v110
	v_fma_f32 v112, -v111, v110, v108
	v_cmp_ge_f32_e64 s[38:39], 0, v112
	v_add_u32_e32 v112, 1, v110
	s_nop 0
	v_cndmask_b32_e64 v111, v110, v111, s[38:39]
	v_fma_f32 v110, -v112, v110, v108
	v_cmp_lt_f32_e64 s[38:39], 0, v110
	s_nop 1
	v_cndmask_b32_e64 v110, v111, v112, s[38:39]
	v_mul_f32_e32 v111, 0x37800000, v110
	v_cndmask_b32_e32 v110, v110, v111, vcc
	v_cmp_class_f32_e32 vcc, v108, v236
	v_and_b32_e32 v111, 0xffff0000, v178
	s_nop 0
	v_cndmask_b32_e32 v112, v110, v108, vcc
	v_div_scale_f32 v113, s[38:39], v112, v112, 1.0
	v_rcp_f32_e32 v114, v113
	v_lshlrev_b32_e32 v110, 16, v178
	v_lshlrev_b32_e32 v108, 16, v179
	s_mov_b64 s[38:39], s[46:47]
	v_fma_f32 v115, -v113, v114, 1.0
	v_fmac_f32_e32 v114, v115, v114
	v_div_scale_f32 v115, vcc, 1.0, v112, 1.0
	v_mul_f32_e32 v116, v115, v114
	v_fma_f32 v117, -v113, v116, v115
	v_fmac_f32_e32 v116, v117, v114
	v_fma_f32 v113, -v113, v116, v115
	v_div_fmas_f32 v113, v113, v114, v116
	v_div_fixup_f32 v112, v113, v112, 1.0
	v_pk_mul_f32 v[104:105], v[104:105], v[112:113] op_sel_hi:[1,0]
	v_pk_mul_f32 v[106:107], v[106:107], v[112:113] op_sel_hi:[1,0]
	s_nop 0
	v_pk_mul_f32 v[104:105], v[100:101], v[104:105]
	v_pk_mul_f32 v[106:107], v[102:103], v[106:107]
	v_pk_mul_f32 v[104:105], v[104:105], v[110:111]
	v_pk_mul_f32 v[106:107], v[106:107], v[108:109]
	s_add_u32 s38, s38, s42
	v_cvt_pk_bf16_f32 v104, v104, v105
	s_addc_u32 s39, s39, s43
	s_lshl_b32 s42, s52, 1
	s_add_u32 s38, s38, s42
	s_addc_u32 s39, s39, 0
	v_cvt_pk_bf16_f32 v105, v106, v107
	v_lshl_add_u64 v[106:107], v[166:167], 1, s[38:39]
	v_add_co_u32_e32 v106, vcc, 0x76fc0000, v106
	s_nop 1
	v_addc_co_u32_e32 v107, vcc, 0, v107, vcc
	global_store_dwordx2 v[106:107], v[104:105], off
; #define LAS __attribute__((address_space(3)))
; __device__ __forceinline__ void ret_unit(const Frame& F, int layer, int uid) {
;     ...
;             for (int hb2 = 0; hb2 < 2; ++hb2) {
;             f32x4 x[4]; v2u gr[4]; float s1[4], s2[4];
; #pragma unroll
;             for (int tt = 0; tt < 4; ++tt) { const int t = w * 8 + hb2 * 4 + tt; x[tt] = *(const LAS f32x4*)(oL + t * 256 + lane * 4); gr[tt] = grp[hb2][tt];
;                 s1[tt] = (x[tt][0] + x[tt][1]) + (x[tt][2] + x[tt][3]); }
; #pragma unroll
;             for (int o = 1; o < 64; o <<= 1)
; #pragma unroll
;                 for (int tt = 0; tt < 4; ++tt) s1[tt] += __shfl_xor(s1[tt], o);
; #pragma unroll
;             for (int tt = 0; tt < 4; ++tt) { x[tt] = x[tt] - s1[tt] * (1.f / 256.f); s2[tt] = (x[tt][0] * x[tt][0] + x[tt][1] * x[tt][1]) + (x[tt][2] * x[tt][2] + x[tt][3] * x[tt][3]); }
; #pragma unroll
;             for (int o = 1; o < 64; o <<= 1)
; #pragma unroll
;                 for (int tt = 0; tt < 4; ++tt) s2[tt] += __shfl_xor(s2[tt], o);
.LBB0_1422:
	v_readlane_b32 s38, v253, 49
	s_cmp_ge_u32 s33, s67
	s_nop 0
	v_add_u32_e32 v104, s38, v192
	ds_read_b128 v[116:119], v104
	v_readlane_b32 s38, v253, 50
	s_waitcnt lgkmcnt(0)
	v_mov_b32_e32 v105, v118
	v_add_u32_e32 v104, s38, v192
	ds_read_b128 v[112:115], v104
	v_readlane_b32 s38, v253, 51
	v_mov_b32_e32 v106, v116
	v_mov_b32_e32 v107, v119
	v_add_u32_e32 v108, s38, v192
	ds_read_b128 v[108:111], v108
	v_mov_b32_e32 v104, v117
	v_pk_add_f32 v[104:105], v[104:105], v[106:107]
	s_waitcnt lgkmcnt(1)
	v_mov_b32_e32 v106, v112
	v_add_f32_e32 v128, v104, v105
	v_mov_b32_e32 v104, v113
	v_mov_b32_e32 v105, v114
	v_mov_b32_e32 v107, v115
	v_pk_add_f32 v[104:105], v[104:105], v[106:107]
	v_readlane_b32 s38, v253, 52
	v_add_f32_e32 v129, v104, v105
	s_waitcnt lgkmcnt(0)
	v_mov_b32_e32 v124, v109
	v_add_u32_e32 v104, s38, v192
	ds_read_b128 v[104:107], v104
	v_mov_b32_e32 v125, v110
	v_mov_b32_e32 v126, v108
	v_mov_b32_e32 v127, v111
	v_pk_add_f32 v[124:125], v[124:125], v[126:127]
	s_waitcnt lgkmcnt(0)
	v_mov_b32_e32 v126, v104
	v_add_f32_e32 v130, v124, v125
	v_mov_b32_e32 v124, v105
	v_mov_b32_e32 v125, v106
	v_mov_b32_e32 v127, v107
	v_pk_add_f32 v[124:125], v[124:125], v[126:127]
	ds_bpermute_b32 v126, v1, v129
	v_add_f32_e32 v124, v124, v125
	ds_bpermute_b32 v125, v1, v128
	ds_bpermute_b32 v127, v1, v130
	ds_bpermute_b32 v131, v1, v124
	s_waitcnt lgkmcnt(3)
	v_add_f32_e32 v126, v129, v126
	ds_bpermute_b32 v129, v3, v126
	s_waitcnt lgkmcnt(3)
	v_add_f32_e32 v125, v128, v125
	ds_bpermute_b32 v128, v3, v125
	s_waitcnt lgkmcnt(3)
	v_add_f32_e32 v127, v130, v127
	ds_bpermute_b32 v130, v3, v127
	s_waitcnt lgkmcnt(3)
	v_add_f32_e32 v124, v124, v131
	ds_bpermute_b32 v131, v3, v124
	s_waitcnt lgkmcnt(2)
	v_add_f32_e32 v125, v125, v128
	ds_bpermute_b32 v128, v120, v125
	v_add_f32_e32 v126, v126, v129
	ds_bpermute_b32 v129, v120, v126
	s_waitcnt lgkmcnt(3)
	v_add_f32_e32 v127, v127, v130
	ds_bpermute_b32 v130, v120, v127
	s_waitcnt lgkmcnt(3)
	v_add_f32_e32 v124, v124, v131
	s_waitcnt lgkmcnt(2)
	v_add_f32_e32 v125, v125, v128
	ds_bpermute_b32 v131, v120, v124
	ds_bpermute_b32 v128, v121, v125
	s_waitcnt lgkmcnt(3)
	v_add_f32_e32 v126, v126, v129
	ds_bpermute_b32 v129, v121, v126
	s_waitcnt lgkmcnt(3)
	v_add_f32_e32 v127, v127, v130
	ds_bpermute_b32 v130, v121, v127
	s_waitcnt lgkmcnt(3)
	v_add_f32_e32 v124, v124, v131
	s_waitcnt lgkmcnt(2)
	v_add_f32_e32 v125, v125, v128
	ds_bpermute_b32 v131, v121, v124
	ds_bpermute_b32 v128, v122, v125
	s_waitcnt lgkmcnt(3)
	v_add_f32_e32 v126, v126, v129
	ds_bpermute_b32 v129, v122, v126
	s_waitcnt lgkmcnt(3)
	v_add_f32_e32 v127, v127, v130
	ds_bpermute_b32 v130, v122, v127
	s_waitcnt lgkmcnt(3)
	v_add_f32_e32 v124, v124, v131
	s_waitcnt lgkmcnt(2)
	v_add_f32_e32 v125, v125, v128
	ds_bpermute_b32 v131, v122, v124
	ds_bpermute_b32 v128, v123, v125
	s_waitcnt lgkmcnt(3)
	v_add_f32_e32 v126, v126, v129
	ds_bpermute_b32 v129, v123, v126
	s_waitcnt lgkmcnt(3)
	v_add_f32_e32 v127, v127, v130
	ds_bpermute_b32 v130, v123, v127
	s_waitcnt lgkmcnt(3)
	v_add_f32_e32 v124, v124, v131
	s_waitcnt lgkmcnt(2)
	v_add_f32_e32 v125, v125, v128
	ds_bpermute_b32 v131, v123, v124
	v_fmamk_f32 v119, v125, 0xbb800000, v119
	v_fmamk_f32 v117, v125, 0xbb800000, v117
	s_waitcnt lgkmcnt(2)
	v_add_f32_e32 v126, v126, v129
	v_fmamk_f32 v118, v125, 0xbb800000, v118
	v_fmac_f32_e32 v116, 0xbb800000, v125
	v_mul_f32_e32 v125, v117, v117
	v_mul_f32_e32 v128, v119, v119
	v_fmac_f32_e32 v125, v116, v116
	v_fmac_f32_e32 v128, v118, v118
	v_fmamk_f32 v115, v126, 0xbb800000, v115
	v_fmamk_f32 v113, v126, 0xbb800000, v113
	s_waitcnt lgkmcnt(1)
	v_add_f32_e32 v127, v127, v130
	v_add_f32_e32 v125, v125, v128
	v_fmamk_f32 v114, v126, 0xbb800000, v114
	v_fmac_f32_e32 v112, 0xbb800000, v126
	v_mul_f32_e32 v126, v113, v113
	v_mul_f32_e32 v128, v115, v115
	v_fmac_f32_e32 v126, v112, v112
	v_fmac_f32_e32 v128, v114, v114
	v_fmamk_f32 v111, v127, 0xbb800000, v111
	v_fmamk_f32 v109, v127, 0xbb800000, v109
	s_waitcnt lgkmcnt(0)
	v_add_f32_e32 v124, v124, v131
	v_add_f32_e32 v126, v126, v128
	v_fmamk_f32 v110, v127, 0xbb800000, v110
	v_fmac_f32_e32 v108, 0xbb800000, v127
	v_mul_f32_e32 v127, v109, v109
	v_mul_f32_e32 v128, v111, v111
	v_fmac_f32_e32 v127, v108, v108
	v_fmac_f32_e32 v128, v110, v110
	v_fmamk_f32 v107, v124, 0xbb800000, v107
	v_fmamk_f32 v105, v124, 0xbb800000, v105
	v_add_f32_e32 v127, v127, v128
	v_fmamk_f32 v106, v124, 0xbb800000, v106
	v_fmac_f32_e32 v104, 0xbb800000, v124
	v_mul_f32_e32 v124, v105, v105
	v_mul_f32_e32 v128, v107, v107
	v_fmac_f32_e32 v124, v104, v104
	v_fmac_f32_e32 v128, v106, v106
	v_add_f32_e32 v124, v124, v128
	ds_bpermute_b32 v128, v1, v125
	ds_bpermute_b32 v129, v1, v126
	ds_bpermute_b32 v130, v1, v127
	ds_bpermute_b32 v1, v1, v124
	s_waitcnt lgkmcnt(3)
	v_add_f32_e32 v125, v125, v128
	s_waitcnt lgkmcnt(2)
	v_add_f32_e32 v126, v126, v129
	s_waitcnt lgkmcnt(1)
	v_add_f32_e32 v127, v127, v130
	s_waitcnt lgkmcnt(0)
	v_add_f32_e32 v1, v124, v1
	ds_bpermute_b32 v124, v3, v125
	ds_bpermute_b32 v128, v3, v126
	ds_bpermute_b32 v129, v3, v127
	ds_bpermute_b32 v3, v3, v1
	s_waitcnt lgkmcnt(3)
	v_add_f32_e32 v124, v125, v124
	s_waitcnt lgkmcnt(2)
	v_add_f32_e32 v125, v126, v128
	s_waitcnt lgkmcnt(1)
	v_add_f32_e32 v126, v127, v129
	s_waitcnt lgkmcnt(0)
	v_add_f32_e32 v1, v1, v3
	ds_bpermute_b32 v3, v120, v124
	ds_bpermute_b32 v127, v120, v125
	ds_bpermute_b32 v128, v120, v126
	ds_bpermute_b32 v120, v120, v1
	s_waitcnt lgkmcnt(3)
	v_add_f32_e32 v3, v124, v3
	s_waitcnt lgkmcnt(2)
	v_add_f32_e32 v124, v125, v127
	s_waitcnt lgkmcnt(1)
	v_add_f32_e32 v125, v126, v128
	s_waitcnt lgkmcnt(0)
	v_add_f32_e32 v1, v1, v120
	ds_bpermute_b32 v120, v121, v3
	ds_bpermute_b32 v126, v121, v124
	ds_bpermute_b32 v127, v121, v125
	ds_bpermute_b32 v121, v121, v1
	s_waitcnt lgkmcnt(3)
	v_add_f32_e32 v3, v3, v120
	s_waitcnt lgkmcnt(2)
	v_add_f32_e32 v120, v124, v126
	s_waitcnt lgkmcnt(1)
	v_add_f32_e32 v124, v125, v127
	s_waitcnt lgkmcnt(0)
	v_add_f32_e32 v1, v1, v121
	ds_bpermute_b32 v121, v122, v3
	ds_bpermute_b32 v126, v122, v120
	ds_bpermute_b32 v127, v122, v124
	ds_bpermute_b32 v128, v122, v1
	s_waitcnt lgkmcnt(3)
	v_add_f32_e32 v125, v3, v121
	s_waitcnt lgkmcnt(2)
	v_add_f32_e32 v122, v120, v126
	s_waitcnt lgkmcnt(1)
	v_add_f32_e32 v120, v124, v127
	s_waitcnt lgkmcnt(0)
	v_add_f32_e32 v1, v1, v128
	ds_bpermute_b32 v126, v123, v125
	ds_bpermute_b32 v124, v123, v122
	ds_bpermute_b32 v121, v123, v120
	ds_bpermute_b32 v3, v123, v1
	s_cbranch_scc1 .LBB0_1428
; #define GAS __attribute__((address_space(1)))
; __device__ __forceinline__ unsigned pk2(float lo, float hi) { return f2bf(lo) | (f2bf(hi) << 16); }
; #define WSB(F, off) ((bf16*)(wsq((F).ws) + (off)))
; __device__ __forceinline__ void ret_unit(const Frame& F, int layer, int uid) {
;     ...
;             for (int tt = 0; tt < 4; ++tt) { const int t = w * 8 + hb2 * 4 + tt; const float rstd = 1.f / sqrtf(s2[tt] * (1.f / 256.f) + LN_EPS);
;                 const f32x4 y = x[tt] * rstd * gn * (f32x4){bflo(gr[tt].x), bfhi(gr[tt].x), bflo(gr[tt].y), bfhi(gr[tt].y)};
;                 if (t < valid) *(GAS v2u*)(WSB(F, WS_BR) + (size_t)(rowbase + t) * D + h * 256 + lane * 4) = (v2u){pk2(y[0], y[1]), pk2(y[2], y[3])}; }
	s_waitcnt lgkmcnt(3)
	v_add_f32_e32 v123, v125, v126
	v_fmamk_f32 v123, v123, 0x3b800000, v235
	v_mul_f32_e32 v125, 0x4f800000, v123
	v_cmp_gt_f32_e32 vcc, s89, v123
	s_nop 0
	v_and_b32_e32 v129, 0xffff0000, v174
	s_add_i32 s42, s78, s33
	v_cndmask_b32_e32 v123, v123, v125, vcc
	v_sqrt_f32_e32 v125, v123
	s_ashr_i32 s43, s42, 31
	v_and_b32_e32 v127, 0xffff0000, v175
	s_lshl_b64 s[42:43], s[42:43], 11
	v_add_u32_e32 v126, -1, v125
	v_fma_f32 v128, -v126, v125, v123
	v_cmp_ge_f32_e64 s[38:39], 0, v128
	v_add_u32_e32 v128, 1, v125
	s_nop 0
	v_cndmask_b32_e64 v126, v125, v126, s[38:39]
	v_fma_f32 v125, -v128, v125, v123
	v_cmp_lt_f32_e64 s[38:39], 0, v125
	s_nop 1
	v_cndmask_b32_e64 v125, v126, v128, s[38:39]
	v_mul_f32_e32 v126, 0x37800000, v125
	v_cndmask_b32_e32 v125, v125, v126, vcc
	v_cmp_class_f32_e32 vcc, v123, v236
	v_lshlrev_b32_e32 v128, 16, v174
	v_lshlrev_b32_e32 v126, 16, v175
	v_cndmask_b32_e32 v123, v125, v123, vcc
	v_div_scale_f32 v125, s[38:39], v123, v123, 1.0
	v_rcp_f32_e32 v130, v125
	s_mov_b64 s[38:39], s[46:47]
	s_add_u32 s38, s38, s42
	v_fma_f32 v131, -v125, v130, 1.0
	v_fmac_f32_e32 v130, v131, v130
	v_div_scale_f32 v131, vcc, 1.0, v123, 1.0
	v_mul_f32_e32 v132, v131, v130
	v_fma_f32 v133, -v125, v132, v131
	v_fmac_f32_e32 v132, v133, v130
	v_fma_f32 v125, -v125, v132, v131
	v_div_fmas_f32 v125, v125, v130, v132
	v_div_fixup_f32 v130, v125, v123, 1.0
	v_pk_mul_f32 v[116:117], v[116:117], v[130:131] op_sel_hi:[1,0]
	v_pk_mul_f32 v[118:119], v[118:119], v[130:131] op_sel_hi:[1,0]
	s_nop 0
	v_pk_mul_f32 v[116:117], v[100:101], v[116:117]
	v_pk_mul_f32 v[118:119], v[102:103], v[118:119]
	v_pk_mul_f32 v[116:117], v[116:117], v[128:129]
	v_pk_mul_f32 v[118:119], v[118:119], v[126:127]
	v_cvt_pk_bf16_f32 v116, v116, v117
	s_addc_u32 s39, s39, s43
	s_lshl_b32 s42, s52, 1
	s_add_u32 s38, s38, s42
	s_addc_u32 s39, s39, 0
	v_cvt_pk_bf16_f32 v117, v118, v119
	v_lshl_add_u64 v[118:119], v[166:167], 1, s[38:39]
	v_add_co_u32_e32 v118, vcc, 0x76fc0000, v118
	s_nop 1
	v_addc_co_u32_e32 v119, vcc, 0, v119, vcc
	global_store_dwordx2 v[118:119], v[116:117], off
	s_cmp_ge_u32 s84, s67
	s_cbranch_scc0 .LBB0_1429

; #define GAS __attribute__((address_space(1)))
; __device__ __forceinline__ unsigned pk2(float lo, float hi) { return f2bf(lo) | (f2bf(hi) << 16); }
; #define WSB(F, off) ((bf16*)(wsq((F).ws) + (off)))
; __device__ __forceinline__ void ret_unit(const Frame& F, int layer, int uid) {
;     ...
;             for (int tt = 0; tt < 4; ++tt) { const int t = w * 8 + hb2 * 4 + tt; const float rstd = 1.f / sqrtf(s2[tt] * (1.f / 256.f) + LN_EPS);
;                 const f32x4 y = x[tt] * rstd * gn * (f32x4){bflo(gr[tt].x), bfhi(gr[tt].x), bflo(gr[tt].y), bfhi(gr[tt].y)};
;                 if (t < valid) *(GAS v2u*)(WSB(F, WS_BR) + (size_t)(rowbase + t) * D + h * 256 + lane * 4) = (v2u){pk2(y[0], y[1]), pk2(y[2], y[3])}; }
.LBB0_1425:
	s_waitcnt lgkmcnt(1)
	v_add_f32_e32 v112, v120, v121
	v_fmamk_f32 v112, v112, 0x3b800000, v235
	v_mul_f32_e32 v113, 0x4f800000, v112
	v_cmp_gt_f32_e32 vcc, s89, v112
	s_add_i32 s42, s78, s77
	s_ashr_i32 s43, s42, 31
	v_cndmask_b32_e32 v112, v112, v113, vcc
	v_sqrt_f32_e32 v114, v112
	s_nop 0
	v_and_b32_e32 v113, 0xffff0000, v171
	s_lshl_b64 s[42:43], s[42:43], 11
	v_add_u32_e32 v115, -1, v114
	v_fma_f32 v116, -v115, v114, v112
	v_cmp_ge_f32_e64 s[38:39], 0, v116
	v_add_u32_e32 v116, 1, v114
	s_nop 0
	v_cndmask_b32_e64 v115, v114, v115, s[38:39]
	v_fma_f32 v114, -v116, v114, v112
	v_cmp_lt_f32_e64 s[38:39], 0, v114
	s_nop 1
	v_cndmask_b32_e64 v114, v115, v116, s[38:39]
	v_mul_f32_e32 v115, 0x37800000, v114
	v_cndmask_b32_e32 v114, v114, v115, vcc
	v_cmp_class_f32_e32 vcc, v112, v236
	v_and_b32_e32 v115, 0xffff0000, v170
	s_nop 0
	v_cndmask_b32_e32 v116, v114, v112, vcc
	v_div_scale_f32 v117, s[38:39], v116, v116, 1.0
	v_rcp_f32_e32 v118, v117
	v_lshlrev_b32_e32 v114, 16, v170
	v_lshlrev_b32_e32 v112, 16, v171
	s_mov_b64 s[38:39], s[46:47]
	v_fma_f32 v119, -v117, v118, 1.0
	v_fmac_f32_e32 v118, v119, v118
	v_div_scale_f32 v119, vcc, 1.0, v116, 1.0
	v_mul_f32_e32 v120, v119, v118
	v_fma_f32 v121, -v117, v120, v119
	v_fmac_f32_e32 v120, v121, v118
	v_fma_f32 v117, -v117, v120, v119
	v_div_fmas_f32 v117, v117, v118, v120
	v_div_fixup_f32 v116, v117, v116, 1.0
	v_pk_mul_f32 v[108:109], v[108:109], v[116:117] op_sel_hi:[1,0]
	v_pk_mul_f32 v[110:111], v[110:111], v[116:117] op_sel_hi:[1,0]
	s_nop 0
	v_pk_mul_f32 v[108:109], v[100:101], v[108:109]
	v_pk_mul_f32 v[110:111], v[102:103], v[110:111]
	v_pk_mul_f32 v[108:109], v[108:109], v[114:115]
	v_pk_mul_f32 v[110:111], v[110:111], v[112:113]
	s_add_u32 s38, s38, s42
	v_cvt_pk_bf16_f32 v108, v108, v109
	s_addc_u32 s39, s39, s43
	s_lshl_b32 s42, s52, 1
	s_add_u32 s38, s38, s42
	s_addc_u32 s39, s39, 0
	v_cvt_pk_bf16_f32 v109, v110, v111
	v_lshl_add_u64 v[110:111], v[166:167], 1, s[38:39]
	v_add_co_u32_e32 v110, vcc, 0x76fc0000, v110
	s_nop 1
	v_addc_co_u32_e32 v111, vcc, 0, v111, vcc
	global_store_dwordx2 v[110:111], v[108:109], off
	s_cmp_ge_u32 s71, s67
	s_cbranch_scc1 .LBB0_1380
	s_branch .LBB0_1431

; #define GAS __attribute__((address_space(1)))
; __device__ __forceinline__ unsigned pk2(float lo, float hi) { return f2bf(lo) | (f2bf(hi) << 16); }
; #define WSB(F, off) ((bf16*)(wsq((F).ws) + (off)))
; __device__ __forceinline__ void ret_unit(const Frame& F, int layer, int uid) {
;     ...
;             for (int tt = 0; tt < 4; ++tt) { const int t = w * 8 + hb2 * 4 + tt; const float rstd = 1.f / sqrtf(s2[tt] * (1.f / 256.f) + LN_EPS);
;                 const f32x4 y = x[tt] * rstd * gn * (f32x4){bflo(gr[tt].x), bfhi(gr[tt].x), bflo(gr[tt].y), bfhi(gr[tt].y)};
;                 if (t < valid) *(GAS v2u*)(WSB(F, WS_BR) + (size_t)(rowbase + t) * D + h * 256 + lane * 4) = (v2u){pk2(y[0], y[1]), pk2(y[2], y[3])}; }
.LBB0_1429:
	s_waitcnt lgkmcnt(2)
	v_add_f32_e32 v116, v122, v124
	v_fmamk_f32 v116, v116, 0x3b800000, v235
	v_mul_f32_e32 v117, 0x4f800000, v116
	v_cmp_gt_f32_e32 vcc, s89, v116
	s_add_i32 s42, s78, s84
	s_ashr_i32 s43, s42, 31
	v_cndmask_b32_e32 v116, v116, v117, vcc
	v_sqrt_f32_e32 v118, v116
	s_nop 0
	v_and_b32_e32 v117, 0xffff0000, v173
	s_lshl_b64 s[42:43], s[42:43], 11
	v_add_u32_e32 v119, -1, v118
	v_fma_f32 v122, -v119, v118, v116
	v_cmp_ge_f32_e64 s[38:39], 0, v122
	v_add_u32_e32 v122, 1, v118
	s_nop 0
	v_cndmask_b32_e64 v119, v118, v119, s[38:39]
	v_fma_f32 v118, -v122, v118, v116
	v_cmp_lt_f32_e64 s[38:39], 0, v118
	s_nop 1
	v_cndmask_b32_e64 v118, v119, v122, s[38:39]
	v_mul_f32_e32 v119, 0x37800000, v118
	v_cndmask_b32_e32 v118, v118, v119, vcc
	v_cmp_class_f32_e32 vcc, v116, v236
	v_and_b32_e32 v119, 0xffff0000, v172
	s_nop 0
	v_cndmask_b32_e32 v122, v118, v116, vcc
	v_div_scale_f32 v123, s[38:39], v122, v122, 1.0
	v_rcp_f32_e32 v124, v123
	v_lshlrev_b32_e32 v118, 16, v172
	v_lshlrev_b32_e32 v116, 16, v173
	s_mov_b64 s[38:39], s[46:47]
	v_fma_f32 v125, -v123, v124, 1.0
	v_fmac_f32_e32 v124, v125, v124
	v_div_scale_f32 v125, vcc, 1.0, v122, 1.0
	v_mul_f32_e32 v126, v125, v124
	v_fma_f32 v127, -v123, v126, v125
	v_fmac_f32_e32 v126, v127, v124
	v_fma_f32 v123, -v123, v126, v125
	v_div_fmas_f32 v123, v123, v124, v126
	v_div_fixup_f32 v122, v123, v122, 1.0
	v_pk_mul_f32 v[112:113], v[112:113], v[122:123] op_sel_hi:[1,0]
	v_pk_mul_f32 v[114:115], v[114:115], v[122:123] op_sel_hi:[1,0]
	s_nop 0
	v_pk_mul_f32 v[112:113], v[100:101], v[112:113]
	v_pk_mul_f32 v[114:115], v[102:103], v[114:115]
	v_pk_mul_f32 v[112:113], v[112:113], v[118:119]
	v_pk_mul_f32 v[114:115], v[114:115], v[116:117]
	s_add_u32 s38, s38, s42
	v_cvt_pk_bf16_f32 v112, v112, v113
	s_addc_u32 s39, s39, s43
	s_lshl_b32 s42, s52, 1
	s_add_u32 s38, s38, s42
	s_addc_u32 s39, s39, 0
	v_cvt_pk_bf16_f32 v113, v114, v115
	v_lshl_add_u64 v[114:115], v[166:167], 1, s[38:39]
	v_add_co_u32_e32 v114, vcc, 0x76fc0000, v114
	s_nop 1
	v_addc_co_u32_e32 v115, vcc, 0, v115, vcc
	global_store_dwordx2 v[114:115], v[112:113], off
	s_cmp_ge_u32 s77, s67
	s_cbranch_scc0 .LBB0_1425

; #define GAS __attribute__((address_space(1)))
; __device__ __forceinline__ unsigned pk2(float lo, float hi) { return f2bf(lo) | (f2bf(hi) << 16); }
; #define WSB(F, off) ((bf16*)(wsq((F).ws) + (off)))
; __device__ __forceinline__ void ret_unit(const Frame& F, int layer, int uid) {
;     ...
;             for (int tt = 0; tt < 4; ++tt) { const int t = w * 8 + hb2 * 4 + tt; const float rstd = 1.f / sqrtf(s2[tt] * (1.f / 256.f) + LN_EPS);
;                 const f32x4 y = x[tt] * rstd * gn * (f32x4){bflo(gr[tt].x), bfhi(gr[tt].x), bflo(gr[tt].y), bfhi(gr[tt].y)};
;                 if (t < valid) *(GAS v2u*)(WSB(F, WS_BR) + (size_t)(rowbase + t) * D + h * 256 + lane * 4) = (v2u){pk2(y[0], y[1]), pk2(y[2], y[3])}; }
.LBB0_1431:
	s_waitcnt lgkmcnt(0)
	v_add_f32_e32 v1, v1, v3
	v_fmamk_f32 v1, v1, 0x3b800000, v235
	v_mul_f32_e32 v3, 0x4f800000, v1
	v_cmp_gt_f32_e32 vcc, s89, v1
	s_add_i32 s42, s78, s71
	s_nop 0
	v_and_b32_e32 v111, 0xffff0000, v168
	v_cndmask_b32_e32 v1, v1, v3, vcc
	v_sqrt_f32_e32 v3, v1
	s_ashr_i32 s43, s42, 31
	s_lshl_b64 s[42:43], s[42:43], 11
	v_and_b32_e32 v109, 0xffff0000, v169
	v_add_u32_e32 v108, -1, v3
	v_fma_f32 v110, -v108, v3, v1
	v_cmp_ge_f32_e64 s[38:39], 0, v110
	v_add_u32_e32 v110, 1, v3
	s_nop 0
	v_cndmask_b32_e64 v108, v3, v108, s[38:39]
	v_fma_f32 v3, -v110, v3, v1
	v_cmp_lt_f32_e64 s[38:39], 0, v3
	s_nop 1
	v_cndmask_b32_e64 v3, v108, v110, s[38:39]
	v_mul_f32_e32 v108, 0x37800000, v3
	v_cndmask_b32_e32 v3, v3, v108, vcc
	v_cmp_class_f32_e32 vcc, v1, v236
	v_lshlrev_b32_e32 v110, 16, v168
	v_lshlrev_b32_e32 v108, 16, v169
	v_cndmask_b32_e32 v1, v3, v1, vcc
	v_div_scale_f32 v3, s[38:39], v1, v1, 1.0
	v_rcp_f32_e32 v112, v3
	s_mov_b64 s[38:39], s[46:47]
	s_add_u32 s38, s38, s42
	v_fma_f32 v113, -v3, v112, 1.0
	v_fmac_f32_e32 v112, v113, v112
	v_div_scale_f32 v113, vcc, 1.0, v1, 1.0
	v_mul_f32_e32 v114, v113, v112
	v_fma_f32 v115, -v3, v114, v113
	v_fmac_f32_e32 v114, v115, v112
	v_fma_f32 v3, -v3, v114, v113
	v_div_fmas_f32 v3, v3, v112, v114
	v_div_fixup_f32 v112, v3, v1, 1.0
	v_pk_mul_f32 v[104:105], v[104:105], v[112:113] op_sel_hi:[1,0]
	v_pk_mul_f32 v[106:107], v[106:107], v[112:113] op_sel_hi:[1,0]
	s_nop 0
	v_pk_mul_f32 v[100:101], v[100:101], v[104:105]
	v_pk_mul_f32 v[102:103], v[102:103], v[106:107]
	v_pk_mul_f32 v[100:101], v[100:101], v[110:111]
	s_addc_u32 s39, s39, s43
	s_lshl_b32 s42, s52, 1
	v_pk_mul_f32 v[102:103], v[102:103], v[108:109]
	s_add_u32 s38, s38, s42
	v_cvt_pk_bf16_f32 v100, v100, v101
	v_bfe_u32 v1, v102, 16, 1
	v_bfe_u32 v3, v103, 16, 1
	s_addc_u32 s39, s39, 0
	v_add3_u32 v1, v102, v1, s72
	v_add3_u32 v3, v103, v3, s72
	v_lshl_add_u64 v[102:103], v[166:167], 1, s[38:39]
	v_lshrrev_b32_e32 v1, 16, v1
	v_add_co_u32_e32 v102, vcc, 0x76fc0000, v102
	v_and_or_b32 v101, v3, s88, v1
	s_nop 0
	v_addc_co_u32_e32 v103, vcc, 0, v103, vcc
	global_store_dwordx2 v[102:103], v[100:101], off
	s_branch .LBB0_1380

; #define GAS __attribute__((address_space(1)))
; #define WSB(F, off) ((bf16*)(wsq((F).ws) + (off)))
; __device__ __forceinline__ void ln_rows(const Frame& F, int idx, bool final_out, int row_lo, int row_hi, int gw0, int NGW, bool comb = false) {
;     ...
;     for (int m0 = row_lo + gw; m0 < row_hi; m0 += 2 * NGW) {
;         v4u w[2][2]; const bool two = m0 + NGW < row_hi;
; #pragma unroll
;         for (int r = 0; r < 2; ++r) { const int m = (r == 0 || two) ? m0 + r * NGW : m0; const GAS v4u* yr = (const GAS v4u*)(WSB(F, comb ? WS_HB : WS_YB) + (size_t)m * D) + tc.lane; w[r][0] = yr[0]; w[r][1] = yr[64]; }
; #pragma unroll
;         for (int r = 0; r < 2; ++r) { const int m = m0 + r * NGW; if (r == 1 && !two) break;
;         f32x4 v[4]; float s = 0.f;
; #pragma unroll
;         for (int j = 0; j < 2; ++j) { const v4u x = w[r][j]; v[2 * j] = (f32x4){bflo(x.x), bfhi(x.x), bflo(x.y), bfhi(x.y)}; v[2 * j + 1] = (f32x4){bflo(x.z), bfhi(x.z), bflo(x.w), bfhi(x.w)}; }
;         if (comb) {
;             const GAS f32x4* pa = (const GAS f32x4*)((const float*)WSB(F, WS_ACT) + (size_t)(m - MP) * D) + 2 * tc.lane; const GAS f32x4* pb = pa + (size_t)512 * D / 4;
; #pragma unroll
;             for (int j = 0; j < 2; ++j) { v[2 * j] = v[2 * j] * ALPHA + (pa[128 * j] + pb[128 * j]) * 0.5f; v[2 * j + 1] = v[2 * j + 1] * ALPHA + (pa[128 * j + 1] + pb[128 * j + 1]) * 0.5f; } }
; #pragma unroll
;         for (int j = 0; j < 4; ++j) s += (v[j].x + v[j].y) + (v[j].z + v[j].w);
;         const float mean = wave_sum(s) * (1.f / D); float s2 = 0.f;
; #pragma unroll
;         for (int j = 0; j < 4; ++j) { v[j] = v[j] - mean; s2 += (v[j].x * v[j].x + v[j].y * v[j].y) + (v[j].z * v[j].z + v[j].w * v[j].w); }
;         const float rstd = 1.f / sqrtf(wave_sum(s2) * (1.f / D) + LN_EPS);
.LBB0_1467:
	s_mov_b64 s[8:9], s[46:47]
	s_add_i32 s12, s10, 8
	s_add_u32 s8, s8, s11
	s_addc_u32 s9, s9, s18
	v_lshlrev_b64 v[44:45], 4, v[42:43]
	s_waitcnt vmcnt(3)
	v_lshl_add_u64 v[34:35], s[8:9], 0, v[44:45]
	s_mov_b32 s8, 0xf7f00000
	s_mov_b32 s9, -1
	v_lshl_add_u64 v[36:37], v[34:35], 0, s[8:9]
	v_add_co_u32_e32 v34, vcc, 0xf7f00000, v34
	s_cmp_lt_i32 s12, s2
	s_nop 0
	v_addc_co_u32_e32 v35, vcc, -1, v35, vcc
	global_load_dwordx4 v[60:63], v[34:35], off
	global_load_dwordx4 v[46:49], v[36:37], off offset:1024
	s_cselect_b32 s8, 8, 0
	s_add_i32 s8, s8, s10
	s_ashr_i32 s9, s8, 31
	s_mov_b64 s[16:17], s[46:47]
	s_lshl_b64 s[8:9], s[8:9], 11
	s_add_u32 s8, s16, s8
	s_addc_u32 s9, s17, s9
	v_lshl_add_u64 v[34:35], s[8:9], 0, v[44:45]
	s_mov_b64 s[8:9], 0x100000
	s_waitcnt vmcnt(4)
	v_lshl_add_u64 v[38:39], v[34:35], 0, s[8:9]
	s_mov_b32 s8, 0x100000
	v_add_co_u32_e32 v34, vcc, s8, v34
	s_mov_b64 s[8:9], s[46:47]
	s_nop 0
	v_addc_co_u32_e32 v35, vcc, 0, v35, vcc
	global_load_dwordx4 v[34:37], v[34:35], off
	s_nop 0
	global_load_dwordx4 v[38:41], v[38:39], off offset:1024
	s_add_u32 s16, s8, s11
	s_addc_u32 s17, s9, s18
	s_cmp_ge_i32 s12, s2
	s_waitcnt vmcnt(3)
	v_lshlrev_b32_e32 v59, 16, v61
	v_lshlrev_b32_e32 v58, 16, v60
	v_and_b32_e32 v65, 0xffff0000, v61
	v_and_b32_e32 v64, 0xffff0000, v60
	v_pk_add_f32 v[60:61], v[58:59], v[64:65]
	s_waitcnt vmcnt(2)
	v_lshlrev_b32_e32 v54, 16, v46
	v_add_f32_e32 v1, v60, v61
	v_lshlrev_b32_e32 v61, 16, v63
	v_lshlrev_b32_e32 v60, 16, v62
	v_and_b32_e32 v63, 0xffff0000, v63
	v_and_b32_e32 v62, 0xffff0000, v62
	v_and_b32_e32 v55, 0xffff0000, v46
	v_lshlrev_b32_e32 v56, 16, v47
	v_and_b32_e32 v57, 0xffff0000, v47
	v_pk_add_f32 v[66:67], v[60:61], v[62:63]
	v_lshlrev_b32_e32 v50, 16, v48
	v_and_b32_e32 v52, 0xffff0000, v48
	v_lshlrev_b32_e32 v46, 16, v49
	v_and_b32_e32 v48, 0xffff0000, v49
	v_add_f32_e32 v49, 0, v1
	v_pk_add_f32 v[66:67], v[66:67], v[66:67] op_sel_hi:[0,1]
	v_add_f32_e32 v51, v54, v55
	v_add_f32_e32 v53, v56, v57
	v_and_b32_e32 v1, 64, v239
	v_pk_add_f32 v[68:69], v[50:51], v[52:53]
	v_mov_b32_e32 v47, v67
	v_add_u32_e32 v51, 64, v1
	v_xor_b32_e32 v1, 1, v239
	v_pk_add_f32 v[66:67], v[46:47], v[48:49]
	v_cmp_lt_i32_e32 vcc, v1, v51
	v_pk_add_f32 v[66:67], v[68:69], v[66:67]
	s_nop 0
	v_cndmask_b32_e32 v1, v239, v1, vcc
	v_add_f32_e32 v47, v66, v67
	v_lshlrev_b32_e32 v1, 2, v1
	ds_bpermute_b32 v49, v1, v47
	s_waitcnt lgkmcnt(0)
	v_add_f32_e32 v47, v47, v49
	v_xor_b32_e32 v49, 2, v239
	v_cmp_lt_i32_e32 vcc, v49, v51
	s_nop 1
	v_cndmask_b32_e32 v49, v239, v49, vcc
	v_lshlrev_b32_e32 v49, 2, v49
	ds_bpermute_b32 v53, v49, v47
	s_waitcnt lgkmcnt(0)
	v_add_f32_e32 v47, v47, v53
	v_xor_b32_e32 v53, 4, v239
	v_cmp_lt_i32_e32 vcc, v53, v51
	s_nop 1
	v_cndmask_b32_e32 v53, v239, v53, vcc
	v_lshlrev_b32_e32 v53, 2, v53
	ds_bpermute_b32 v66, v53, v47
	s_waitcnt lgkmcnt(0)
	v_add_f32_e32 v47, v47, v66
	v_xor_b32_e32 v66, 8, v239
	v_cmp_lt_i32_e32 vcc, v66, v51
	s_nop 1
	v_cndmask_b32_e32 v66, v239, v66, vcc
	v_lshlrev_b32_e32 v70, 2, v66
	ds_bpermute_b32 v66, v70, v47
	s_waitcnt lgkmcnt(0)
	v_add_f32_e32 v47, v47, v66
	v_xor_b32_e32 v66, 16, v239
	v_cmp_lt_i32_e32 vcc, v66, v51
	s_nop 1
	v_cndmask_b32_e32 v66, v239, v66, vcc
	v_lshlrev_b32_e32 v71, 2, v66
	ds_bpermute_b32 v66, v71, v47
	s_waitcnt lgkmcnt(0)
	v_add_f32_e32 v47, v47, v66
	v_xor_b32_e32 v66, 32, v239
	v_cmp_lt_i32_e32 vcc, v66, v51
	s_nop 1
	v_cndmask_b32_e32 v51, v239, v66, vcc
	v_lshlrev_b32_e32 v72, 2, v51
	ds_bpermute_b32 v51, v72, v47
	s_waitcnt lgkmcnt(0)
	v_add_f32_e32 v47, v47, v51
	v_fmac_f32_e32 v64, 0xba800000, v47
	v_fmac_f32_e32 v65, 0xba800000, v47
	v_fmac_f32_e32 v59, 0xba800000, v47
	v_fmac_f32_e32 v58, 0xba800000, v47
	v_mov_b32_e32 v66, v59
	v_mov_b32_e32 v67, v65
	v_mov_b32_e32 v59, v64
	v_pk_mul_f32 v[68:69], v[66:67], v[66:67]
	v_pk_mul_f32 v[64:65], v[58:59], v[58:59]
	v_fmac_f32_e32 v62, 0xba800000, v47
	v_pk_mov_b32 v[74:75], v[64:65], v[68:69] op_sel:[1,0]
	v_mov_b32_e32 v65, v69
	v_pk_add_f32 v[64:65], v[74:75], v[64:65]
	v_fmac_f32_e32 v63, 0xba800000, v47
	v_fmac_f32_e32 v61, 0xba800000, v47
	v_pk_add_f32 v[68:69], v[64:65], v[64:65] op_sel_hi:[0,1]
	v_fmac_f32_e32 v60, 0xba800000, v47
	v_mov_b32_e32 v64, v61
	v_mov_b32_e32 v65, v63
	v_mov_b32_e32 v61, v62
	v_pk_mul_f32 v[74:75], v[64:65], v[64:65]
	v_pk_mul_f32 v[62:63], v[60:61], v[60:61]
	v_fmac_f32_e32 v54, 0xba800000, v47
	v_pk_mov_b32 v[76:77], v[62:63], v[74:75] op_sel:[1,0]
	v_mov_b32_e32 v63, v75
	v_pk_add_f32 v[62:63], v[76:77], v[62:63]
	v_fmac_f32_e32 v55, 0xba800000, v47
	v_pk_add_f32 v[62:63], v[62:63], v[62:63] op_sel_hi:[0,1]
	v_fmac_f32_e32 v56, 0xba800000, v47
	v_mul_f32_e32 v62, v54, v54
	v_fmac_f32_e32 v57, 0xba800000, v47
	v_pk_fma_f32 v[74:75], v[54:55], v[54:55], v[62:63] op_sel_hi:[1,1,0]
	v_mul_f32_e32 v62, v56, v56
	v_pk_fma_f32 v[76:77], v[56:57], v[56:57], v[62:63] op_sel_hi:[1,1,0]
	v_fmac_f32_e32 v48, 0xba800000, v47
	v_fmac_f32_e32 v46, 0xba800000, v47
	v_fmac_f32_e32 v52, 0xba800000, v47
	v_fmac_f32_e32 v50, 0xba800000, v47
	v_mul_f32_e32 v74, v50, v50
	v_mul_f32_e32 v76, v52, v52
	v_mul_f32_e32 v68, v46, v46
	v_mul_f32_e32 v62, v48, v48
	v_pk_add_f32 v[74:75], v[74:75], v[76:77]
	v_pk_add_f32 v[62:63], v[68:69], v[62:63]
	s_nop 0
	v_pk_add_f32 v[62:63], v[74:75], v[62:63]
	s_nop 0
	v_add_f32_e32 v47, v62, v63
	ds_bpermute_b32 v51, v1, v47
	s_waitcnt lgkmcnt(0)
	v_add_f32_e32 v47, v47, v51
	ds_bpermute_b32 v51, v49, v47
	s_waitcnt lgkmcnt(0)
	v_add_f32_e32 v47, v47, v51
	ds_bpermute_b32 v51, v53, v47
	s_waitcnt lgkmcnt(0)
	v_add_f32_e32 v47, v47, v51
	ds_bpermute_b32 v51, v70, v47
	s_waitcnt lgkmcnt(0)
; #define GAS __attribute__((address_space(1)))
; __device__ __forceinline__ unsigned pk2(float lo, float hi) { return f2bf(lo) | (f2bf(hi) << 16); }
; #define WSB(F, off) ((bf16*)(wsq((F).ws) + (off)))
; __device__ __forceinline__ void ln_rows(const Frame& F, int idx, bool final_out, int row_lo, int row_hi, int gw0, int NGW, bool comb = false) {
;     ...
;         const float mean = wave_sum(s) * (1.f / D); float s2 = 0.f;
; #pragma unroll
;         for (int j = 0; j < 4; ++j) { v[j] = v[j] - mean; s2 += (v[j].x * v[j].x + v[j].y * v[j].y) + (v[j].z * v[j].z + v[j].w * v[j].w); }
;         const float rstd = 1.f / sqrtf(wave_sum(s2) * (1.f / D) + LN_EPS);
; #pragma unroll
;         for (int j = 0; j < 4; ++j) v[j] = v[j] * rstd * gv[j] + bv[j];
;         if (!final_out) { GAS v4u* o = (GAS v4u*)(WSB(F, WS_HB) + (size_t)m * D) + tc.lane;
; #pragma unroll
;             for (int j = 0; j < 2; ++j) o[64 * j] = (v4u){pk2(v[2 * j].x, v[2 * j].y), pk2(v[2 * j].z, v[2 * j].w), pk2(v[2 * j + 1].x, v[2 * j + 1].y), pk2(v[2 * j + 1].z, v[2 * j + 1].w)}; }
	v_add_f32_e32 v47, v47, v51
	ds_bpermute_b32 v51, v71, v47
	s_waitcnt lgkmcnt(0)
	v_add_f32_e32 v47, v47, v51
	ds_bpermute_b32 v51, v72, v47
	s_waitcnt lgkmcnt(0)
	v_add_f32_e32 v47, v47, v51
	v_fmamk_f32 v47, v47, 0x3a800000, v235
	v_cmp_gt_f32_e32 vcc, s89, v47
	v_mul_f32_e32 v51, 0x4f800000, v47
	s_nop 0
	v_cndmask_b32_e32 v47, v47, v51, vcc
	v_sqrt_f32_e32 v51, v47
	s_nop 0
	v_add_u32_e32 v62, -1, v51
	v_fma_f32 v63, -v62, v51, v47
	v_cmp_ge_f32_e64 s[8:9], 0, v63
	v_add_u32_e32 v63, 1, v51
	s_nop 0
	v_cndmask_b32_e64 v62, v51, v62, s[8:9]
	v_fma_f32 v51, -v63, v51, v47
	v_cmp_lt_f32_e64 s[8:9], 0, v51
	s_nop 1
	v_cndmask_b32_e64 v51, v62, v63, s[8:9]
	v_mul_f32_e32 v62, 0x37800000, v51
	v_cndmask_b32_e32 v51, v51, v62, vcc
	v_cmp_class_f32_e32 vcc, v47, v236
	s_nop 1
	v_cndmask_b32_e32 v47, v51, v47, vcc
	v_div_scale_f32 v51, s[8:9], v47, v47, 1.0
	v_rcp_f32_e32 v62, v51
	s_nop 0
	v_fma_f32 v63, -v51, v62, 1.0
	v_fmac_f32_e32 v62, v63, v62
	v_div_scale_f32 v63, vcc, 1.0, v47, 1.0
	v_mul_f32_e32 v68, v63, v62
	v_fma_f32 v69, -v51, v68, v63
	v_fmac_f32_e32 v68, v69, v62
	v_fma_f32 v51, -v51, v68, v63
	v_div_fmas_f32 v51, v51, v62, v68
	v_div_fixup_f32 v68, v51, v47, 1.0
	v_pk_mul_f32 v[58:59], v[58:59], v[68:69] op_sel_hi:[1,0]
	v_mov_b32_e32 v47, v48
	v_pk_mul_f32 v[62:63], v[66:67], v[68:69] op_sel_hi:[1,0]
	v_pk_mul_f32 v[60:61], v[60:61], v[68:69] op_sel_hi:[1,0]
	v_pk_mul_f32 v[46:47], v[46:47], v[68:69] op_sel_hi:[1,0]
	v_pk_fma_f32 v[58:59], v[6:7], v[58:59], v[14:15]
	v_pk_fma_f32 v[66:67], v[20:21], v[46:47], v[28:29]
	v_pk_fma_f32 v[46:47], v[2:3], v[60:61], v[10:11]
	v_pk_fma_f32 v[60:61], v[8:9], v[62:63], v[16:17]
	v_lshl_add_u64 v[62:63], s[16:17], 0, v[44:45]
	v_cvt_pk_bf16_f32 v44, v58, v59
	v_cvt_pk_bf16_f32 v45, v60, v61
	v_pk_mul_f32 v[64:65], v[64:65], v[68:69] op_sel_hi:[1,0]
	v_pk_fma_f32 v[64:65], v[4:5], v[64:65], v[12:13]
	v_cvt_pk_bf16_f32 v46, v46, v47
	v_pk_mul_f32 v[54:55], v[54:55], v[68:69] op_sel_hi:[1,0]
	v_pk_fma_f32 v[54:55], v[22:23], v[54:55], v[30:31]
	v_cvt_pk_bf16_f32 v47, v64, v65
	global_store_dwordx4 v[62:63], v[44:47], off
	v_pk_mul_f32 v[56:57], v[56:57], v[68:69] op_sel_hi:[1,0]
	v_mov_b32_e32 v51, v52
	v_pk_fma_f32 v[56:57], v[24:25], v[56:57], v[32:33]
	v_cvt_pk_bf16_f32 v44, v54, v55
	v_pk_mul_f32 v[50:51], v[50:51], v[68:69] op_sel_hi:[1,0]
	v_pk_fma_f32 v[50:51], v[18:19], v[50:51], v[26:27]
	v_cvt_pk_bf16_f32 v45, v56, v57
	v_cvt_pk_bf16_f32 v46, v50, v51
	v_cvt_pk_bf16_f32 v47, v66, v67
	global_store_dwordx4 v[62:63], v[44:47], off offset:1024
	s_cbranch_scc1 .LBB0_1466
; #define GAS __attribute__((address_space(1)))
; __device__ __forceinline__ unsigned pk2(float lo, float hi) { return f2bf(lo) | (f2bf(hi) << 16); }
; #define WSB(F, off) ((bf16*)(wsq((F).ws) + (off)))
; __device__ __forceinline__ void ln_rows(const Frame& F, int idx, bool final_out, int row_lo, int row_hi, int gw0, int NGW, bool comb = false) {
;     ...
;         for (int r = 0; r < 2; ++r) { const int m = m0 + r * NGW; if (r == 1 && !two) break;
;         f32x4 v[4]; float s = 0.f;
; #pragma unroll
;         for (int j = 0; j < 2; ++j) { const v4u x = w[r][j]; v[2 * j] = (f32x4){bflo(x.x), bfhi(x.x), bflo(x.y), bfhi(x.y)}; v[2 * j + 1] = (f32x4){bflo(x.z), bfhi(x.z), bflo(x.w), bfhi(x.w)}; }
;         if (comb) {
;             const GAS f32x4* pa = (const GAS f32x4*)((const float*)WSB(F, WS_ACT) + (size_t)(m - MP) * D) + 2 * tc.lane; const GAS f32x4* pb = pa + (size_t)512 * D / 4;
; #pragma unroll
;             for (int j = 0; j < 2; ++j) { v[2 * j] = v[2 * j] * ALPHA + (pa[128 * j] + pb[128 * j]) * 0.5f; v[2 * j + 1] = v[2 * j + 1] * ALPHA + (pa[128 * j + 1] + pb[128 * j + 1]) * 0.5f; } }
; #pragma unroll
;         for (int j = 0; j < 4; ++j) s += (v[j].x + v[j].y) + (v[j].z + v[j].w);
;         const float mean = wave_sum(s) * (1.f / D); float s2 = 0.f;
; #pragma unroll
;         for (int j = 0; j < 4; ++j) { v[j] = v[j] - mean; s2 += (v[j].x * v[j].x + v[j].y * v[j].y) + (v[j].z * v[j].z + v[j].w * v[j].w); }
;         const float rstd = 1.f / sqrtf(wave_sum(s2) * (1.f / D) + LN_EPS);
; #pragma unroll
;         for (int j = 0; j < 4; ++j) v[j] = v[j] * rstd * gv[j] + bv[j];
;         if (!final_out) { GAS v4u* o = (GAS v4u*)(WSB(F, WS_HB) + (size_t)m * D) + tc.lane;
; #pragma unroll
;             for (int j = 0; j < 2; ++j) o[64 * j] = (v4u){pk2(v[2 * j].x, v[2 * j].y), pk2(v[2 * j].z, v[2 * j].w), pk2(v[2 * j + 1].x, v[2 * j + 1].y), pk2(v[2 * j + 1].z, v[2 * j + 1].w)}; }
	s_waitcnt vmcnt(3)
	v_lshlrev_b32_e32 v57, 16, v35
	v_lshlrev_b32_e32 v56, 16, v34
	v_and_b32_e32 v35, 0xffff0000, v35
	v_and_b32_e32 v34, 0xffff0000, v34
	v_pk_add_f32 v[58:59], v[56:57], v[34:35]
	s_waitcnt vmcnt(2)
	v_lshlrev_b32_e32 v50, 16, v41
	v_and_b32_e32 v54, 0xffff0000, v41
	v_add_f32_e32 v41, v58, v59
	v_lshlrev_b32_e32 v59, 16, v37
	v_lshlrev_b32_e32 v58, 16, v36
	v_and_b32_e32 v37, 0xffff0000, v37
	v_and_b32_e32 v36, 0xffff0000, v36
	v_pk_add_f32 v[60:61], v[58:59], v[36:37]
	v_lshlrev_b32_e32 v44, 16, v38
	v_and_b32_e32 v45, 0xffff0000, v38
	v_lshlrev_b32_e32 v38, 16, v39
	v_and_b32_e32 v39, 0xffff0000, v39
	v_pk_add_f32 v[60:61], v[60:61], v[60:61] op_sel_hi:[0,1]
	v_lshlrev_b32_e32 v46, 16, v40
	v_and_b32_e32 v40, 0xffff0000, v40
	v_add_f32_e32 v55, 0, v41
	v_add_f32_e32 v47, v44, v45
	v_add_f32_e32 v41, v38, v39
	v_mov_b32_e32 v51, v61
	v_pk_add_f32 v[62:63], v[46:47], v[40:41]
	v_pk_add_f32 v[60:61], v[50:51], v[54:55]
	s_ashr_i32 s13, s12, 31
	v_pk_add_f32 v[60:61], v[62:63], v[60:61]
	s_lshl_b64 s[12:13], s[12:13], 11
	v_add_f32_e32 v41, v60, v61
	ds_bpermute_b32 v47, v1, v41
	s_waitcnt lgkmcnt(0)
	v_add_f32_e32 v41, v41, v47
	ds_bpermute_b32 v47, v49, v41
	s_waitcnt lgkmcnt(0)
	v_add_f32_e32 v41, v41, v47
	ds_bpermute_b32 v47, v53, v41
	s_waitcnt lgkmcnt(0)
	v_add_f32_e32 v41, v41, v47
	ds_bpermute_b32 v47, v70, v41
	s_waitcnt lgkmcnt(0)
	v_add_f32_e32 v41, v41, v47
	ds_bpermute_b32 v47, v71, v41
	s_waitcnt lgkmcnt(0)
	v_add_f32_e32 v41, v41, v47
	ds_bpermute_b32 v47, v72, v41
	s_waitcnt lgkmcnt(0)
	v_add_f32_e32 v41, v41, v47
	v_fmac_f32_e32 v34, 0xba800000, v41
	v_fmac_f32_e32 v35, 0xba800000, v41
	v_fmac_f32_e32 v57, 0xba800000, v41
	v_fmac_f32_e32 v56, 0xba800000, v41
	v_mov_b32_e32 v60, v57
	v_mov_b32_e32 v61, v35
	v_mov_b32_e32 v57, v34
	v_pk_mul_f32 v[62:63], v[60:61], v[60:61]
	v_pk_mul_f32 v[34:35], v[56:57], v[56:57]
	v_fmac_f32_e32 v36, 0xba800000, v41
	v_pk_mov_b32 v[64:65], v[34:35], v[62:63] op_sel:[1,0]
	v_mov_b32_e32 v35, v63
	v_fmac_f32_e32 v37, 0xba800000, v41
	v_fmac_f32_e32 v59, 0xba800000, v41
	v_pk_add_f32 v[34:35], v[64:65], v[34:35]
	v_fmac_f32_e32 v58, 0xba800000, v41
	v_mov_b32_e32 v62, v59
	v_mov_b32_e32 v63, v37
	v_mov_b32_e32 v59, v36
	v_pk_add_f32 v[34:35], v[34:35], v[34:35] op_sel_hi:[0,1]
	v_pk_mul_f32 v[64:65], v[62:63], v[62:63]
	v_pk_mul_f32 v[36:37], v[58:59], v[58:59]
	v_fmac_f32_e32 v44, 0xba800000, v41
	v_pk_mov_b32 v[66:67], v[36:37], v[64:65] op_sel:[1,0]
	v_mov_b32_e32 v37, v65
	v_fmac_f32_e32 v45, 0xba800000, v41
	v_fmac_f32_e32 v38, 0xba800000, v41
	v_mul_f32_e32 v34, v44, v44
	v_pk_add_f32 v[36:37], v[66:67], v[36:37]
	v_fmac_f32_e32 v39, 0xba800000, v41
	v_pk_fma_f32 v[64:65], v[44:45], v[44:45], v[34:35] op_sel_hi:[1,1,0]
	v_mul_f32_e32 v34, v38, v38
	v_pk_add_f32 v[36:37], v[36:37], v[36:37] op_sel_hi:[0,1]
	v_pk_fma_f32 v[66:67], v[38:39], v[38:39], v[34:35] op_sel_hi:[1,1,0]
	v_fmac_f32_e32 v54, 0xba800000, v41
	v_fmac_f32_e32 v50, 0xba800000, v41
	v_fmac_f32_e32 v40, 0xba800000, v41
	v_fmac_f32_e32 v46, 0xba800000, v41
	v_mul_f32_e32 v64, v46, v46
	v_mul_f32_e32 v66, v40, v40
	v_mul_f32_e32 v34, v50, v50
	v_mul_f32_e32 v36, v54, v54
	v_pk_add_f32 v[64:65], v[64:65], v[66:67]
	v_pk_add_f32 v[34:35], v[34:35], v[36:37]
	v_mov_b32_e32 v47, v40
	v_pk_add_f32 v[34:35], v[64:65], v[34:35]
	v_mov_b32_e32 v51, v54
	v_add_f32_e32 v34, v34, v35
	ds_bpermute_b32 v1, v1, v34
	s_waitcnt lgkmcnt(0)
	v_add_f32_e32 v1, v34, v1
	ds_bpermute_b32 v34, v49, v1
	s_waitcnt lgkmcnt(0)
	v_add_f32_e32 v1, v1, v34
	ds_bpermute_b32 v34, v53, v1
	s_waitcnt lgkmcnt(0)
	v_add_f32_e32 v1, v1, v34
	ds_bpermute_b32 v34, v70, v1
	s_waitcnt lgkmcnt(0)
	v_add_f32_e32 v1, v1, v34
	ds_bpermute_b32 v34, v71, v1
	s_waitcnt lgkmcnt(0)
	v_add_f32_e32 v1, v1, v34
	ds_bpermute_b32 v34, v72, v1
	s_waitcnt lgkmcnt(0)
	v_add_f32_e32 v1, v1, v34
	v_fmamk_f32 v1, v1, 0x3a800000, v235
	v_mul_f32_e32 v34, 0x4f800000, v1
	v_cmp_gt_f32_e32 vcc, s89, v1
	s_nop 1
	v_cndmask_b32_e32 v1, v1, v34, vcc
	v_sqrt_f32_e32 v34, v1
	s_nop 0
	v_add_u32_e32 v35, -1, v34
	v_fma_f32 v36, -v35, v34, v1
	v_cmp_ge_f32_e64 s[8:9], 0, v36
	v_add_u32_e32 v36, 1, v34
	s_nop 0
	v_cndmask_b32_e64 v35, v34, v35, s[8:9]
	v_fma_f32 v34, -v36, v34, v1
	v_cmp_lt_f32_e64 s[8:9], 0, v34
	s_nop 1
	v_cndmask_b32_e64 v34, v35, v36, s[8:9]
	v_mul_f32_e32 v35, 0x37800000, v34
	v_cndmask_b32_e32 v34, v34, v35, vcc
	v_cmp_class_f32_e32 vcc, v1, v236
	s_nop 1
	v_cndmask_b32_e32 v1, v34, v1, vcc
	v_div_scale_f32 v34, s[8:9], v1, v1, 1.0
	v_rcp_f32_e32 v35, v34
	s_mov_b64 s[8:9], s[46:47]
	s_add_u32 s8, s8, s12
	v_fma_f32 v36, -v34, v35, 1.0
	v_fmac_f32_e32 v35, v36, v35
	v_div_scale_f32 v36, vcc, 1.0, v1, 1.0
	v_mul_f32_e32 v37, v36, v35
	v_fma_f32 v41, -v34, v37, v36
	v_fmac_f32_e32 v37, v41, v35
	v_fma_f32 v34, -v34, v37, v36
	v_div_fmas_f32 v34, v34, v35, v37
	v_div_fixup_f32 v34, v34, v1, 1.0
	v_pk_mul_f32 v[36:37], v[56:57], v[34:35] op_sel_hi:[1,0]
	v_pk_mul_f32 v[48:49], v[60:61], v[34:35] op_sel_hi:[1,0]
	v_pk_mul_f32 v[52:53], v[58:59], v[34:35] op_sel_hi:[1,0]
	v_pk_mul_f32 v[56:57], v[62:63], v[34:35] op_sel_hi:[1,0]
	v_pk_mul_f32 v[44:45], v[44:45], v[34:35] op_sel_hi:[1,0]
	v_pk_mul_f32 v[38:39], v[38:39], v[34:35] op_sel_hi:[1,0]
	v_pk_mul_f32 v[40:41], v[46:47], v[34:35] op_sel_hi:[1,0]
	v_pk_mul_f32 v[34:35], v[50:51], v[34:35] op_sel_hi:[1,0]
	v_pk_fma_f32 v[48:49], v[8:9], v[48:49], v[16:17]
	v_pk_fma_f32 v[46:47], v[20:21], v[34:35], v[28:29]
	v_pk_fma_f32 v[34:35], v[6:7], v[36:37], v[14:15]
	v_pk_fma_f32 v[52:53], v[2:3], v[52:53], v[10:11]
	v_cvt_pk_bf16_f32 v34, v34, v35
	v_cvt_pk_bf16_f32 v35, v48, v49
	v_pk_fma_f32 v[50:51], v[4:5], v[56:57], v[12:13]
	s_addc_u32 s9, s9, s13
	v_lshl_add_u64 v[54:55], v[42:43], 4, s[8:9]
	s_mov_b64 s[8:9], 0x8200000
	v_cvt_pk_bf16_f32 v36, v52, v53
	v_lshl_add_u64 v[56:57], v[54:55], 0, s[8:9]
	s_mov_b32 s8, 0x8200000
	v_pk_fma_f32 v[44:45], v[22:23], v[44:45], v[30:31]
	v_add_co_u32_e32 v48, vcc, s8, v54
	v_cvt_pk_bf16_f32 v37, v50, v51
	s_nop 0
	v_addc_co_u32_e32 v49, vcc, 0, v55, vcc
	v_bfe_u32 v1, v44, 16, 1
	global_store_dwordx4 v[48:49], v[34:37], off
	v_add3_u32 v1, v44, v1, s72
	v_pk_fma_f32 v[38:39], v[24:25], v[38:39], v[32:33]
	v_bfe_u32 v34, v45, 16, 1
	v_lshrrev_b32_e32 v1, 16, v1
	v_add3_u32 v34, v45, v34, s72
	v_and_or_b32 v34, v34, s88, v1
	v_pk_fma_f32 v[40:41], v[18:19], v[40:41], v[26:27]
	v_cvt_pk_bf16_f32 v35, v38, v39
	v_cvt_pk_bf16_f32 v36, v40, v41
	v_cvt_pk_bf16_f32 v37, v46, v47
	global_store_dwordx4 v[56:57], v[34:37], off offset:1024
	s_branch .LBB0_1466

; #define GAS __attribute__((address_space(1)))
; #define WSB(F, off) ((bf16*)(wsq((F).ws) + (off)))
; __device__ __forceinline__ void ln_rows(const Frame& F, int idx, bool final_out, int row_lo, int row_hi, int gw0, int NGW, bool comb = false) {
;     ...
;     for (int m0 = row_lo + gw; m0 < row_hi; m0 += 2 * NGW) {
;         v4u w[2][2]; const bool two = m0 + NGW < row_hi;
; #pragma unroll
;         for (int r = 0; r < 2; ++r) { const int m = (r == 0 || two) ? m0 + r * NGW : m0; const GAS v4u* yr = (const GAS v4u*)(WSB(F, comb ? WS_HB : WS_YB) + (size_t)m * D) + tc.lane; w[r][0] = yr[0]; w[r][1] = yr[64]; }
; #pragma unroll
;         for (int r = 0; r < 2; ++r) { const int m = m0 + r * NGW; if (r == 1 && !two) break;
;         f32x4 v[4]; float s = 0.f;
; #pragma unroll
;         for (int j = 0; j < 2; ++j) { const v4u x = w[r][j]; v[2 * j] = (f32x4){bflo(x.x), bfhi(x.x), bflo(x.y), bfhi(x.y)}; v[2 * j + 1] = (f32x4){bflo(x.z), bfhi(x.z), bflo(x.w), bfhi(x.w)}; }
;         if (comb) {
;             const GAS f32x4* pa = (const GAS f32x4*)((const float*)WSB(F, WS_ACT) + (size_t)(m - MP) * D) + 2 * tc.lane; const GAS f32x4* pb = pa + (size_t)512 * D / 4;
; #pragma unroll
;             for (int j = 0; j < 2; ++j) { v[2 * j] = v[2 * j] * ALPHA + (pa[128 * j] + pb[128 * j]) * 0.5f; v[2 * j + 1] = v[2 * j + 1] * ALPHA + (pa[128 * j + 1] + pb[128 * j + 1]) * 0.5f; } }
; #pragma unroll
;         for (int j = 0; j < 4; ++j) s += (v[j].x + v[j].y) + (v[j].z + v[j].w);
;         const float mean = wave_sum(s) * (1.f / D); float s2 = 0.f;
; #pragma unroll
;         for (int j = 0; j < 4; ++j) { v[j] = v[j] - mean; s2 += (v[j].x * v[j].x + v[j].y * v[j].y) + (v[j].z * v[j].z + v[j].w * v[j].w); }
;         const float rstd = 1.f / sqrtf(wave_sum(s2) * (1.f / D) + LN_EPS);
.LBB0_1882:
	v_readlane_b32 s4, v253, 7
	s_add_i32 s4, s4, s10
	s_mov_b64 s[6:7], s[46:47]
	s_addk_i32 s4, 0xfea0
	s_add_u32 s6, s6, s2
	s_addc_u32 s7, s7, s3
	v_lshlrev_b64 v[44:45], 4, v[42:43]
	v_lshl_add_u64 v[34:35], s[6:7], 0, v[44:45]
	s_mov_b32 s6, 0xf7f00000
	s_mov_b32 s7, -1
	s_mov_b32 s5, 0xf7f00000
	v_lshl_add_u64 v[36:37], v[34:35], 0, s[6:7]
	v_add_co_u32_e32 v34, vcc, s5, v34
	s_cmp_lt_i32 s4, 0x10000
	s_nop 0
	v_addc_co_u32_e32 v35, vcc, -1, v35, vcc
	global_load_dwordx4 v[60:63], v[34:35], off
	global_load_dwordx4 v[46:49], v[36:37], off offset:1024
	v_readlane_b32 s5, v253, 62
	s_cselect_b32 s5, s5, 0
	s_add_i32 s6, s5, s10
	s_ashr_i32 s7, s6, 31
	s_mov_b64 s[8:9], s[46:47]
	s_lshl_b64 s[6:7], s[6:7], 11
	s_add_u32 s6, s8, s6
	s_addc_u32 s7, s9, s7
	v_lshl_add_u64 v[34:35], s[6:7], 0, v[44:45]
	s_mov_b64 s[6:7], 0x100000
	s_mov_b32 s5, 0x100000
	v_lshl_add_u64 v[38:39], v[34:35], 0, s[6:7]
	v_add_co_u32_e32 v34, vcc, s5, v34
	s_mov_b64 s[6:7], s[46:47]
	s_nop 0
	v_addc_co_u32_e32 v35, vcc, 0, v35, vcc
	global_load_dwordx4 v[34:37], v[34:35], off
	s_nop 0
	global_load_dwordx4 v[38:41], v[38:39], off offset:1024
	s_add_u32 s8, s6, s2
	s_addc_u32 s9, s7, s3
	s_cmp_gt_i32 s4, 0xffff
	s_waitcnt vmcnt(0)
	v_lshlrev_b32_e32 v59, 16, v61
	v_lshlrev_b32_e32 v58, 16, v60
	v_and_b32_e32 v65, 0xffff0000, v61
	v_and_b32_e32 v64, 0xffff0000, v60
	v_pk_add_f32 v[60:61], v[58:59], v[64:65]
	v_lshlrev_b32_e32 v54, 16, v46
	v_add_f32_e32 v1, v60, v61
	v_lshlrev_b32_e32 v61, 16, v63
	v_lshlrev_b32_e32 v60, 16, v62
	v_and_b32_e32 v63, 0xffff0000, v63
	v_and_b32_e32 v62, 0xffff0000, v62
	v_and_b32_e32 v55, 0xffff0000, v46
	v_lshlrev_b32_e32 v56, 16, v47
	v_and_b32_e32 v57, 0xffff0000, v47
	v_pk_add_f32 v[66:67], v[60:61], v[62:63]
	v_lshlrev_b32_e32 v50, 16, v48
	v_and_b32_e32 v52, 0xffff0000, v48
	v_lshlrev_b32_e32 v46, 16, v49
	v_and_b32_e32 v48, 0xffff0000, v49
	v_add_f32_e32 v49, 0, v1
	v_pk_add_f32 v[66:67], v[66:67], v[66:67] op_sel_hi:[0,1]
	v_add_f32_e32 v51, v54, v55
	v_add_f32_e32 v53, v56, v57
	v_and_b32_e32 v1, 64, v239
	v_pk_add_f32 v[68:69], v[50:51], v[52:53]
	v_mov_b32_e32 v47, v67
	v_add_u32_e32 v51, 64, v1
	v_xor_b32_e32 v1, 1, v239
	v_pk_add_f32 v[66:67], v[46:47], v[48:49]
	v_cmp_lt_i32_e32 vcc, v1, v51
	v_pk_add_f32 v[66:67], v[68:69], v[66:67]
	s_nop 0
	v_cndmask_b32_e32 v1, v239, v1, vcc
	v_add_f32_e32 v47, v66, v67
	v_lshlrev_b32_e32 v1, 2, v1
	ds_bpermute_b32 v49, v1, v47
	s_waitcnt lgkmcnt(0)
	v_add_f32_e32 v47, v47, v49
	v_xor_b32_e32 v49, 2, v239
	v_cmp_lt_i32_e32 vcc, v49, v51
	s_nop 1
	v_cndmask_b32_e32 v49, v239, v49, vcc
	v_lshlrev_b32_e32 v49, 2, v49
	ds_bpermute_b32 v53, v49, v47
	s_waitcnt lgkmcnt(0)
	v_add_f32_e32 v47, v47, v53
	v_xor_b32_e32 v53, 4, v239
	v_cmp_lt_i32_e32 vcc, v53, v51
	s_nop 1
	v_cndmask_b32_e32 v53, v239, v53, vcc
	v_lshlrev_b32_e32 v53, 2, v53
	ds_bpermute_b32 v66, v53, v47
	s_waitcnt lgkmcnt(0)
	v_add_f32_e32 v47, v47, v66
	v_xor_b32_e32 v66, 8, v239
	v_cmp_lt_i32_e32 vcc, v66, v51
	s_nop 1
	v_cndmask_b32_e32 v66, v239, v66, vcc
	v_lshlrev_b32_e32 v70, 2, v66
	ds_bpermute_b32 v66, v70, v47
	s_waitcnt lgkmcnt(0)
	v_add_f32_e32 v47, v47, v66
	v_xor_b32_e32 v66, 16, v239
	v_cmp_lt_i32_e32 vcc, v66, v51
	s_nop 1
	v_cndmask_b32_e32 v66, v239, v66, vcc
	v_lshlrev_b32_e32 v71, 2, v66
	ds_bpermute_b32 v66, v71, v47
	s_waitcnt lgkmcnt(0)
	v_add_f32_e32 v47, v47, v66
	v_xor_b32_e32 v66, 32, v239
	v_cmp_lt_i32_e32 vcc, v66, v51
	s_nop 1
	v_cndmask_b32_e32 v51, v239, v66, vcc
	v_lshlrev_b32_e32 v72, 2, v51
	ds_bpermute_b32 v51, v72, v47
	s_waitcnt lgkmcnt(0)
	v_add_f32_e32 v47, v47, v51
	v_fmac_f32_e32 v64, 0xba800000, v47
	v_fmac_f32_e32 v65, 0xba800000, v47
	v_fmac_f32_e32 v59, 0xba800000, v47
	v_fmac_f32_e32 v58, 0xba800000, v47
	v_mov_b32_e32 v66, v59
	v_mov_b32_e32 v67, v65
	v_mov_b32_e32 v59, v64
	v_pk_mul_f32 v[68:69], v[66:67], v[66:67]
	v_pk_mul_f32 v[64:65], v[58:59], v[58:59]
	v_fmac_f32_e32 v62, 0xba800000, v47
	v_pk_mov_b32 v[74:75], v[64:65], v[68:69] op_sel:[1,0]
	v_mov_b32_e32 v65, v69
	v_pk_add_f32 v[64:65], v[74:75], v[64:65]
	v_fmac_f32_e32 v63, 0xba800000, v47
	v_fmac_f32_e32 v61, 0xba800000, v47
	v_pk_add_f32 v[68:69], v[64:65], v[64:65] op_sel_hi:[0,1]
	v_fmac_f32_e32 v60, 0xba800000, v47
	v_mov_b32_e32 v64, v61
	v_mov_b32_e32 v65, v63
	v_mov_b32_e32 v61, v62
	v_pk_mul_f32 v[74:75], v[64:65], v[64:65]
	v_pk_mul_f32 v[62:63], v[60:61], v[60:61]
	v_fmac_f32_e32 v54, 0xba800000, v47
	v_pk_mov_b32 v[76:77], v[62:63], v[74:75] op_sel:[1,0]
	v_mov_b32_e32 v63, v75
	v_pk_add_f32 v[62:63], v[76:77], v[62:63]
	v_fmac_f32_e32 v55, 0xba800000, v47
	v_pk_add_f32 v[62:63], v[62:63], v[62:63] op_sel_hi:[0,1]
	v_fmac_f32_e32 v56, 0xba800000, v47
	v_mul_f32_e32 v62, v54, v54
	v_fmac_f32_e32 v57, 0xba800000, v47
	v_pk_fma_f32 v[74:75], v[54:55], v[54:55], v[62:63] op_sel_hi:[1,1,0]
	v_mul_f32_e32 v62, v56, v56
	v_pk_fma_f32 v[76:77], v[56:57], v[56:57], v[62:63] op_sel_hi:[1,1,0]
	v_fmac_f32_e32 v48, 0xba800000, v47
	v_fmac_f32_e32 v46, 0xba800000, v47
	v_fmac_f32_e32 v52, 0xba800000, v47
	v_fmac_f32_e32 v50, 0xba800000, v47
	v_mul_f32_e32 v74, v50, v50
	v_mul_f32_e32 v76, v52, v52
	v_mul_f32_e32 v68, v46, v46
	v_mul_f32_e32 v62, v48, v48
	v_pk_add_f32 v[74:75], v[74:75], v[76:77]
	v_pk_add_f32 v[62:63], v[68:69], v[62:63]
	s_nop 0
	v_pk_add_f32 v[62:63], v[74:75], v[62:63]
	s_nop 0
	v_add_f32_e32 v47, v62, v63
	ds_bpermute_b32 v51, v1, v47
	s_waitcnt lgkmcnt(0)
	v_add_f32_e32 v47, v47, v51
	ds_bpermute_b32 v51, v49, v47
	s_waitcnt lgkmcnt(0)
	v_add_f32_e32 v47, v47, v51
	ds_bpermute_b32 v51, v53, v47
	s_waitcnt lgkmcnt(0)
	v_add_f32_e32 v47, v47, v51
	ds_bpermute_b32 v51, v70, v47
	s_waitcnt lgkmcnt(0)
; #define GAS __attribute__((address_space(1)))
; __device__ __forceinline__ unsigned pk2(float lo, float hi) { return f2bf(lo) | (f2bf(hi) << 16); }
; #define WSB(F, off) ((bf16*)(wsq((F).ws) + (off)))
; __device__ __forceinline__ void ln_rows(const Frame& F, int idx, bool final_out, int row_lo, int row_hi, int gw0, int NGW, bool comb = false) {
;     ...
;         const float mean = wave_sum(s) * (1.f / D); float s2 = 0.f;
; #pragma unroll
;         for (int j = 0; j < 4; ++j) { v[j] = v[j] - mean; s2 += (v[j].x * v[j].x + v[j].y * v[j].y) + (v[j].z * v[j].z + v[j].w * v[j].w); }
;         const float rstd = 1.f / sqrtf(wave_sum(s2) * (1.f / D) + LN_EPS);
; #pragma unroll
;         for (int j = 0; j < 4; ++j) v[j] = v[j] * rstd * gv[j] + bv[j];
;         if (!final_out) { GAS v4u* o = (GAS v4u*)(WSB(F, WS_HB) + (size_t)m * D) + tc.lane;
; #pragma unroll
;             for (int j = 0; j < 2; ++j) o[64 * j] = (v4u){pk2(v[2 * j].x, v[2 * j].y), pk2(v[2 * j].z, v[2 * j].w), pk2(v[2 * j + 1].x, v[2 * j + 1].y), pk2(v[2 * j + 1].z, v[2 * j + 1].w)}; }
	v_add_f32_e32 v47, v47, v51
	ds_bpermute_b32 v51, v71, v47
	s_waitcnt lgkmcnt(0)
	v_add_f32_e32 v47, v47, v51
	ds_bpermute_b32 v51, v72, v47
	s_waitcnt lgkmcnt(0)
	v_add_f32_e32 v47, v47, v51
	v_fmamk_f32 v47, v47, 0x3a800000, v235
	v_cmp_gt_f32_e32 vcc, s89, v47
	v_mul_f32_e32 v51, 0x4f800000, v47
	s_nop 0
	v_cndmask_b32_e32 v47, v47, v51, vcc
	v_sqrt_f32_e32 v51, v47
	s_nop 0
	v_add_u32_e32 v62, -1, v51
	v_fma_f32 v63, -v62, v51, v47
	v_cmp_ge_f32_e64 s[6:7], 0, v63
	v_add_u32_e32 v63, 1, v51
	s_nop 0
	v_cndmask_b32_e64 v62, v51, v62, s[6:7]
	v_fma_f32 v51, -v63, v51, v47
	v_cmp_lt_f32_e64 s[6:7], 0, v51
	s_nop 1
	v_cndmask_b32_e64 v51, v62, v63, s[6:7]
	v_mul_f32_e32 v62, 0x37800000, v51
	v_cndmask_b32_e32 v51, v51, v62, vcc
	v_cmp_class_f32_e32 vcc, v47, v236
	s_nop 1
	v_cndmask_b32_e32 v47, v51, v47, vcc
	v_div_scale_f32 v51, s[6:7], v47, v47, 1.0
	v_rcp_f32_e32 v62, v51
	s_nop 0
	v_fma_f32 v63, -v51, v62, 1.0
	v_fmac_f32_e32 v62, v63, v62
	v_div_scale_f32 v63, vcc, 1.0, v47, 1.0
	v_mul_f32_e32 v68, v63, v62
	v_fma_f32 v69, -v51, v68, v63
	v_fmac_f32_e32 v68, v69, v62
	v_fma_f32 v51, -v51, v68, v63
	v_div_fmas_f32 v51, v51, v62, v68
	v_div_fixup_f32 v68, v51, v47, 1.0
	v_pk_mul_f32 v[58:59], v[58:59], v[68:69] op_sel_hi:[1,0]
	v_mov_b32_e32 v47, v48
	v_pk_mul_f32 v[62:63], v[66:67], v[68:69] op_sel_hi:[1,0]
	v_pk_mul_f32 v[60:61], v[60:61], v[68:69] op_sel_hi:[1,0]
	v_pk_mul_f32 v[46:47], v[46:47], v[68:69] op_sel_hi:[1,0]
	v_pk_fma_f32 v[58:59], v[6:7], v[58:59], v[14:15]
	v_pk_fma_f32 v[66:67], v[20:21], v[46:47], v[28:29]
	v_pk_fma_f32 v[46:47], v[2:3], v[60:61], v[10:11]
	v_pk_fma_f32 v[60:61], v[8:9], v[62:63], v[16:17]
	v_lshl_add_u64 v[62:63], s[8:9], 0, v[44:45]
	v_cvt_pk_bf16_f32 v44, v58, v59
	v_cvt_pk_bf16_f32 v45, v60, v61
	v_pk_mul_f32 v[64:65], v[64:65], v[68:69] op_sel_hi:[1,0]
	v_pk_fma_f32 v[64:65], v[4:5], v[64:65], v[12:13]
	v_cvt_pk_bf16_f32 v46, v46, v47
	v_pk_mul_f32 v[54:55], v[54:55], v[68:69] op_sel_hi:[1,0]
	v_pk_fma_f32 v[54:55], v[22:23], v[54:55], v[30:31]
	v_cvt_pk_bf16_f32 v47, v64, v65
	global_store_dwordx4 v[62:63], v[44:47], off
	v_pk_mul_f32 v[56:57], v[56:57], v[68:69] op_sel_hi:[1,0]
	v_mov_b32_e32 v51, v52
	v_pk_fma_f32 v[56:57], v[24:25], v[56:57], v[32:33]
	v_cvt_pk_bf16_f32 v44, v54, v55
	v_pk_mul_f32 v[50:51], v[50:51], v[68:69] op_sel_hi:[1,0]
	v_pk_fma_f32 v[50:51], v[18:19], v[50:51], v[26:27]
	v_cvt_pk_bf16_f32 v45, v56, v57
	v_cvt_pk_bf16_f32 v46, v50, v51
	v_cvt_pk_bf16_f32 v47, v66, v67
	global_store_dwordx4 v[62:63], v[44:47], off offset:1024
	s_cbranch_scc1 .LBB0_1881
; #define GAS __attribute__((address_space(1)))
; __device__ __forceinline__ unsigned pk2(float lo, float hi) { return f2bf(lo) | (f2bf(hi) << 16); }
; #define WSB(F, off) ((bf16*)(wsq((F).ws) + (off)))
; __device__ __forceinline__ void ln_rows(const Frame& F, int idx, bool final_out, int row_lo, int row_hi, int gw0, int NGW, bool comb = false) {
;     ...
;         for (int r = 0; r < 2; ++r) { const int m = m0 + r * NGW; if (r == 1 && !two) break;
;         f32x4 v[4]; float s = 0.f;
; #pragma unroll
;         for (int j = 0; j < 2; ++j) { const v4u x = w[r][j]; v[2 * j] = (f32x4){bflo(x.x), bfhi(x.x), bflo(x.y), bfhi(x.y)}; v[2 * j + 1] = (f32x4){bflo(x.z), bfhi(x.z), bflo(x.w), bfhi(x.w)}; }
;         if (comb) {
;             const GAS f32x4* pa = (const GAS f32x4*)((const float*)WSB(F, WS_ACT) + (size_t)(m - MP) * D) + 2 * tc.lane; const GAS f32x4* pb = pa + (size_t)512 * D / 4;
; #pragma unroll
;             for (int j = 0; j < 2; ++j) { v[2 * j] = v[2 * j] * ALPHA + (pa[128 * j] + pb[128 * j]) * 0.5f; v[2 * j + 1] = v[2 * j + 1] * ALPHA + (pa[128 * j + 1] + pb[128 * j + 1]) * 0.5f; } }
; #pragma unroll
;         for (int j = 0; j < 4; ++j) s += (v[j].x + v[j].y) + (v[j].z + v[j].w);
;         const float mean = wave_sum(s) * (1.f / D); float s2 = 0.f;
; #pragma unroll
;         for (int j = 0; j < 4; ++j) { v[j] = v[j] - mean; s2 += (v[j].x * v[j].x + v[j].y * v[j].y) + (v[j].z * v[j].z + v[j].w * v[j].w); }
;         const float rstd = 1.f / sqrtf(wave_sum(s2) * (1.f / D) + LN_EPS);
; #pragma unroll
;         for (int j = 0; j < 4; ++j) v[j] = v[j] * rstd * gv[j] + bv[j];
;         if (!final_out) { GAS v4u* o = (GAS v4u*)(WSB(F, WS_HB) + (size_t)m * D) + tc.lane;
; #pragma unroll
;             for (int j = 0; j < 2; ++j) o[64 * j] = (v4u){pk2(v[2 * j].x, v[2 * j].y), pk2(v[2 * j].z, v[2 * j].w), pk2(v[2 * j + 1].x, v[2 * j + 1].y), pk2(v[2 * j + 1].z, v[2 * j + 1].w)}; }
	v_lshlrev_b32_e32 v57, 16, v35
	v_lshlrev_b32_e32 v56, 16, v34
	v_and_b32_e32 v35, 0xffff0000, v35
	v_and_b32_e32 v34, 0xffff0000, v34
	v_pk_add_f32 v[58:59], v[56:57], v[34:35]
	v_lshlrev_b32_e32 v50, 16, v41
	v_and_b32_e32 v54, 0xffff0000, v41
	v_add_f32_e32 v41, v58, v59
	v_lshlrev_b32_e32 v59, 16, v37
	v_lshlrev_b32_e32 v58, 16, v36
	v_and_b32_e32 v37, 0xffff0000, v37
	v_and_b32_e32 v36, 0xffff0000, v36
	v_pk_add_f32 v[60:61], v[58:59], v[36:37]
	v_lshlrev_b32_e32 v44, 16, v38
	v_and_b32_e32 v45, 0xffff0000, v38
	v_lshlrev_b32_e32 v38, 16, v39
	v_and_b32_e32 v39, 0xffff0000, v39
	v_pk_add_f32 v[60:61], v[60:61], v[60:61] op_sel_hi:[0,1]
	v_lshlrev_b32_e32 v46, 16, v40
	v_and_b32_e32 v40, 0xffff0000, v40
	v_add_f32_e32 v55, 0, v41
	v_add_f32_e32 v47, v44, v45
	v_add_f32_e32 v41, v38, v39
	v_mov_b32_e32 v51, v61
	v_pk_add_f32 v[62:63], v[46:47], v[40:41]
	v_pk_add_f32 v[60:61], v[50:51], v[54:55]
	s_ashr_i32 s5, s4, 31
	v_pk_add_f32 v[60:61], v[62:63], v[60:61]
	s_lshl_b64 s[4:5], s[4:5], 11
	v_add_f32_e32 v41, v60, v61
	ds_bpermute_b32 v47, v1, v41
	s_waitcnt lgkmcnt(0)
	v_add_f32_e32 v41, v41, v47
	ds_bpermute_b32 v47, v49, v41
	s_waitcnt lgkmcnt(0)
	v_add_f32_e32 v41, v41, v47
	ds_bpermute_b32 v47, v53, v41
	s_waitcnt lgkmcnt(0)
	v_add_f32_e32 v41, v41, v47
	ds_bpermute_b32 v47, v70, v41
	s_waitcnt lgkmcnt(0)
	v_add_f32_e32 v41, v41, v47
	ds_bpermute_b32 v47, v71, v41
	s_waitcnt lgkmcnt(0)
	v_add_f32_e32 v41, v41, v47
	ds_bpermute_b32 v47, v72, v41
	s_waitcnt lgkmcnt(0)
	v_add_f32_e32 v41, v41, v47
	v_fmac_f32_e32 v34, 0xba800000, v41
	v_fmac_f32_e32 v35, 0xba800000, v41
	v_fmac_f32_e32 v57, 0xba800000, v41
	v_fmac_f32_e32 v56, 0xba800000, v41
	v_mov_b32_e32 v60, v57
	v_mov_b32_e32 v61, v35
	v_mov_b32_e32 v57, v34
	v_pk_mul_f32 v[62:63], v[60:61], v[60:61]
	v_pk_mul_f32 v[34:35], v[56:57], v[56:57]
	v_fmac_f32_e32 v36, 0xba800000, v41
	v_pk_mov_b32 v[64:65], v[34:35], v[62:63] op_sel:[1,0]
	v_mov_b32_e32 v35, v63
	v_fmac_f32_e32 v37, 0xba800000, v41
	v_fmac_f32_e32 v59, 0xba800000, v41
	v_pk_add_f32 v[34:35], v[64:65], v[34:35]
	v_fmac_f32_e32 v58, 0xba800000, v41
	v_mov_b32_e32 v62, v59
	v_mov_b32_e32 v63, v37
	v_mov_b32_e32 v59, v36
	v_pk_add_f32 v[34:35], v[34:35], v[34:35] op_sel_hi:[0,1]
	v_pk_mul_f32 v[64:65], v[62:63], v[62:63]
	v_pk_mul_f32 v[36:37], v[58:59], v[58:59]
	v_fmac_f32_e32 v44, 0xba800000, v41
	v_pk_mov_b32 v[66:67], v[36:37], v[64:65] op_sel:[1,0]
	v_mov_b32_e32 v37, v65
	v_fmac_f32_e32 v45, 0xba800000, v41
	v_fmac_f32_e32 v38, 0xba800000, v41
	v_mul_f32_e32 v34, v44, v44
	v_pk_add_f32 v[36:37], v[66:67], v[36:37]
	v_fmac_f32_e32 v39, 0xba800000, v41
	v_pk_fma_f32 v[64:65], v[44:45], v[44:45], v[34:35] op_sel_hi:[1,1,0]
	v_mul_f32_e32 v34, v38, v38
	v_pk_add_f32 v[36:37], v[36:37], v[36:37] op_sel_hi:[0,1]
	v_pk_fma_f32 v[66:67], v[38:39], v[38:39], v[34:35] op_sel_hi:[1,1,0]
	v_fmac_f32_e32 v54, 0xba800000, v41
	v_fmac_f32_e32 v50, 0xba800000, v41
	v_fmac_f32_e32 v40, 0xba800000, v41
	v_fmac_f32_e32 v46, 0xba800000, v41
	v_mul_f32_e32 v64, v46, v46
	v_mul_f32_e32 v66, v40, v40
	v_mul_f32_e32 v34, v50, v50
	v_mul_f32_e32 v36, v54, v54
	v_pk_add_f32 v[64:65], v[64:65], v[66:67]
	v_pk_add_f32 v[34:35], v[34:35], v[36:37]
	v_mov_b32_e32 v47, v40
	v_pk_add_f32 v[34:35], v[64:65], v[34:35]
	v_mov_b32_e32 v51, v54
	v_add_f32_e32 v34, v34, v35
	ds_bpermute_b32 v1, v1, v34
	s_waitcnt lgkmcnt(0)
	v_add_f32_e32 v1, v34, v1
	ds_bpermute_b32 v34, v49, v1
	s_waitcnt lgkmcnt(0)
	v_add_f32_e32 v1, v1, v34
	ds_bpermute_b32 v34, v53, v1
	s_waitcnt lgkmcnt(0)
	v_add_f32_e32 v1, v1, v34
	ds_bpermute_b32 v34, v70, v1
	s_waitcnt lgkmcnt(0)
	v_add_f32_e32 v1, v1, v34
	ds_bpermute_b32 v34, v71, v1
	s_waitcnt lgkmcnt(0)
	v_add_f32_e32 v1, v1, v34
	ds_bpermute_b32 v34, v72, v1
	s_waitcnt lgkmcnt(0)
	v_add_f32_e32 v1, v1, v34
	v_fmamk_f32 v1, v1, 0x3a800000, v235
	v_mul_f32_e32 v34, 0x4f800000, v1
	v_cmp_gt_f32_e32 vcc, s89, v1
	s_nop 1
	v_cndmask_b32_e32 v1, v1, v34, vcc
	v_sqrt_f32_e32 v34, v1
	s_nop 0
	v_add_u32_e32 v35, -1, v34
	v_fma_f32 v36, -v35, v34, v1
	v_cmp_ge_f32_e64 s[6:7], 0, v36
	v_add_u32_e32 v36, 1, v34
	s_nop 0
	v_cndmask_b32_e64 v35, v34, v35, s[6:7]
	v_fma_f32 v34, -v36, v34, v1
	v_cmp_lt_f32_e64 s[6:7], 0, v34
	s_nop 1
	v_cndmask_b32_e64 v34, v35, v36, s[6:7]
	v_mul_f32_e32 v35, 0x37800000, v34
	v_cndmask_b32_e32 v34, v34, v35, vcc
	v_cmp_class_f32_e32 vcc, v1, v236
	s_nop 1
	v_cndmask_b32_e32 v1, v34, v1, vcc
	v_div_scale_f32 v34, s[6:7], v1, v1, 1.0
	v_rcp_f32_e32 v35, v34
	s_mov_b64 s[6:7], s[46:47]
	s_add_u32 s4, s6, s4
	v_fma_f32 v36, -v34, v35, 1.0
	v_fmac_f32_e32 v35, v36, v35
	v_div_scale_f32 v36, vcc, 1.0, v1, 1.0
	v_mul_f32_e32 v37, v36, v35
	v_fma_f32 v41, -v34, v37, v36
	v_fmac_f32_e32 v37, v41, v35
	v_fma_f32 v34, -v34, v37, v36
	v_div_fmas_f32 v34, v34, v35, v37
	v_div_fixup_f32 v34, v34, v1, 1.0
	v_pk_mul_f32 v[36:37], v[56:57], v[34:35] op_sel_hi:[1,0]
	v_pk_mul_f32 v[48:49], v[60:61], v[34:35] op_sel_hi:[1,0]
	v_pk_mul_f32 v[52:53], v[58:59], v[34:35] op_sel_hi:[1,0]
	v_pk_mul_f32 v[56:57], v[62:63], v[34:35] op_sel_hi:[1,0]
	v_pk_mul_f32 v[44:45], v[44:45], v[34:35] op_sel_hi:[1,0]
	v_pk_mul_f32 v[38:39], v[38:39], v[34:35] op_sel_hi:[1,0]
	v_pk_mul_f32 v[40:41], v[46:47], v[34:35] op_sel_hi:[1,0]
	v_pk_mul_f32 v[34:35], v[50:51], v[34:35] op_sel_hi:[1,0]
	v_pk_fma_f32 v[48:49], v[8:9], v[48:49], v[16:17]
	v_pk_fma_f32 v[46:47], v[20:21], v[34:35], v[28:29]
	v_pk_fma_f32 v[34:35], v[6:7], v[36:37], v[14:15]
	v_pk_fma_f32 v[52:53], v[2:3], v[52:53], v[10:11]
	v_cvt_pk_bf16_f32 v34, v34, v35
	v_cvt_pk_bf16_f32 v35, v48, v49
	v_pk_fma_f32 v[50:51], v[4:5], v[56:57], v[12:13]
	s_addc_u32 s5, s7, s5
	v_lshl_add_u64 v[54:55], v[42:43], 4, s[4:5]
	s_mov_b64 s[4:5], 0x8200000
	v_cvt_pk_bf16_f32 v36, v52, v53
	v_lshl_add_u64 v[56:57], v[54:55], 0, s[4:5]
	s_mov_b32 s4, 0x8200000
	v_pk_fma_f32 v[44:45], v[22:23], v[44:45], v[30:31]
	v_add_co_u32_e32 v48, vcc, s4, v54
	v_cvt_pk_bf16_f32 v37, v50, v51
	s_nop 0
	v_addc_co_u32_e32 v49, vcc, 0, v55, vcc
	v_bfe_u32 v1, v44, 16, 1
	global_store_dwordx4 v[48:49], v[34:37], off
	v_add3_u32 v1, v44, v1, s72
	v_pk_fma_f32 v[38:39], v[24:25], v[38:39], v[32:33]
	v_bfe_u32 v34, v45, 16, 1
	v_lshrrev_b32_e32 v1, 16, v1
	v_add3_u32 v34, v45, v34, s72
	v_and_or_b32 v34, v34, s88, v1
	v_pk_fma_f32 v[40:41], v[18:19], v[40:41], v[26:27]
	v_cvt_pk_bf16_f32 v35, v38, v39
	v_cvt_pk_bf16_f32 v36, v40, v41
	v_cvt_pk_bf16_f32 v37, v46, v47
	global_store_dwordx4 v[56:57], v[34:37], off offset:1024
	s_branch .LBB0_1881

; #define GAS __attribute__((address_space(1)))
; __device__ __forceinline__ unsigned pk2(float lo, float hi) { return f2bf(lo) | (f2bf(hi) << 16); }
; #define WSB(F, off) ((bf16*)(wsq((F).ws) + (off)))
; __device__ __forceinline__ void ln_rows(const Frame& F, int idx, bool final_out, int row_lo, int row_hi, int gw0, int NGW, bool comb = false) {
;     ...
;         if (!final_out) { GAS v4u* o = (GAS v4u*)(WSB(F, WS_HB) + (size_t)m * D) + tc.lane;
; #pragma unroll
;             for (int j = 0; j < 2; ++j) o[64 * j] = (v4u){pk2(v[2 * j].x, v[2 * j].y), pk2(v[2 * j].z, v[2 * j].w), pk2(v[2 * j + 1].x, v[2 * j + 1].y), pk2(v[2 * j + 1].z, v[2 * j + 1].w)}; }
.LBB0_2097:
	v_cvt_pk_bf16_f32 v54, v54, v55
	v_cvt_pk_bf16_f32 v55, v56, v57
	v_cvt_pk_bf16_f32 v56, v50, v51
	v_cvt_pk_bf16_f32 v57, v52, v53
	v_cvt_pk_bf16_f32 v42, v42, v43
	v_cvt_pk_bf16_f32 v43, v44, v45
	s_mov_b64 s[6:7], s[46:47]
	v_cvt_pk_bf16_f32 v44, v46, v47
	s_add_u32 s6, s6, s2
	s_addc_u32 s7, s7, s3
	v_lshl_add_u64 v[64:65], v[58:59], 4, s[6:7]
	v_cvt_pk_bf16_f32 v45, v48, v49
	global_store_dwordx4 v[64:65], v[54:57], off
	global_store_dwordx4 v[64:65], v[42:45], off offset:1024
	s_andn2_b64 vcc, exec, s[8:9]
	s_cbranch_vccnz .LBB0_2090

; #define GAS __attribute__((address_space(1)))
; __device__ __forceinline__ unsigned pk2(float lo, float hi) { return f2bf(lo) | (f2bf(hi) << 16); }
; #define WSB(F, off) ((bf16*)(wsq((F).ws) + (off)))
; __device__ __forceinline__ void ln_rows(const Frame& F, int idx, bool final_out, int row_lo, int row_hi, int gw0, int NGW, bool comb = false) {
;     ...
;         if (!final_out) { GAS v4u* o = (GAS v4u*)(WSB(F, WS_HB) + (size_t)m * D) + tc.lane;
; #pragma unroll
;             for (int j = 0; j < 2; ++j) o[64 * j] = (v4u){pk2(v[2 * j].x, v[2 * j].y), pk2(v[2 * j].z, v[2 * j].w), pk2(v[2 * j + 1].x, v[2 * j + 1].y), pk2(v[2 * j + 1].z, v[2 * j + 1].w)}; }
.LBB0_2102:
	s_andn2_b64 vcc, exec, s[6:7]
	s_cbranch_vccnz .LBB0_2090
	v_cvt_pk_bf16_f32 v46, v46, v47
	v_cvt_pk_bf16_f32 v47, v48, v49
	v_cvt_pk_bf16_f32 v48, v42, v43
	v_cvt_pk_bf16_f32 v49, v44, v45
	v_cvt_pk_bf16_f32 v34, v34, v35
	s_ashr_i32 s5, s4, 31
	s_mov_b64 s[6:7], s[46:47]
	s_lshl_b64 s[4:5], s[4:5], 11
	v_cvt_pk_bf16_f32 v35, v36, v37
	s_add_u32 s4, s6, s4
	s_addc_u32 s5, s7, s5
	v_lshl_add_u64 v[50:51], v[58:59], 4, s[4:5]
	s_mov_b64 s[4:5], 0x8200000
	v_cvt_pk_bf16_f32 v36, v38, v39
	v_lshl_add_u64 v[52:53], v[50:51], 0, s[4:5]
	s_mov_b32 s4, 0x8200000
	v_add_co_u32_e32 v42, vcc, s4, v50
	v_addc_co_u32_e32 v43, vcc, 0, v51, vcc
	v_cvt_pk_bf16_f32 v37, v40, v41
	global_store_dwordx4 v[42:43], v[46:49], off
	global_store_dwordx4 v[52:53], v[34:37], off offset:1024
	s_branch .LBB0_2090

; #define GAS __attribute__((address_space(1)))
; #define WSB(F, off) ((bf16*)(wsq((F).ws) + (off)))
; __device__ __forceinline__ void ln_rows(const Frame& F, int idx, bool final_out, int row_lo, int row_hi, int gw0, int NGW, bool comb = false) {
;     ...
;     for (int m0 = row_lo + gw; m0 < row_hi; m0 += 2 * NGW) {
;         v4u w[2][2]; const bool two = m0 + NGW < row_hi;
; #pragma unroll
;         for (int r = 0; r < 2; ++r) { const int m = (r == 0 || two) ? m0 + r * NGW : m0; const GAS v4u* yr = (const GAS v4u*)(WSB(F, comb ? WS_HB : WS_YB) + (size_t)m * D) + tc.lane; w[r][0] = yr[0]; w[r][1] = yr[64]; }
; #pragma unroll
;         for (int r = 0; r < 2; ++r) { const int m = m0 + r * NGW; if (r == 1 && !two) break;
;         f32x4 v[4]; float s = 0.f;
; #pragma unroll
;         for (int j = 0; j < 2; ++j) { const v4u x = w[r][j]; v[2 * j] = (f32x4){bflo(x.x), bfhi(x.x), bflo(x.y), bfhi(x.y)}; v[2 * j + 1] = (f32x4){bflo(x.z), bfhi(x.z), bflo(x.w), bfhi(x.w)}; }
;         if (comb) {
;             const GAS f32x4* pa = (const GAS f32x4*)((const float*)WSB(F, WS_ACT) + (size_t)(m - MP) * D) + 2 * tc.lane; const GAS f32x4* pb = pa + (size_t)512 * D / 4;
; #pragma unroll
;             for (int j = 0; j < 2; ++j) { v[2 * j] = v[2 * j] * ALPHA + (pa[128 * j] + pb[128 * j]) * 0.5f; v[2 * j + 1] = v[2 * j + 1] * ALPHA + (pa[128 * j + 1] + pb[128 * j + 1]) * 0.5f; } }
; #pragma unroll
;         for (int j = 0; j < 4; ++j) s += (v[j].x + v[j].y) + (v[j].z + v[j].w);
;         const float mean = wave_sum(s) * (1.f / D); float s2 = 0.f;
.LBB0_2169:
	v_readlane_b32 s11, v253, 7
	s_mov_b64 s[4:5], s[46:47]
	s_add_i32 s10, s11, s16
	s_add_u32 s4, s4, s2
	s_addc_u32 s5, s5, s3
	v_lshlrev_b64 v[34:35], 4, v[58:59]
	v_lshl_add_u64 v[36:37], s[4:5], 0, v[34:35]
	global_load_dwordx4 v[42:45], v[36:37], off
	global_load_dwordx4 v[46:49], v[36:37], off offset:1024
	s_cmp_lt_i32 s10, 0x10200
	s_cselect_b64 s[6:7], -1, 0
	s_and_b64 s[4:5], s[6:7], exec
	s_cselect_b32 s4, s11, 0
	s_add_i32 s4, s4, s16
	s_ashr_i32 s5, s4, 31
	s_mov_b64 s[12:13], s[46:47]
	s_lshl_b64 s[4:5], s[4:5], 11
	s_add_u32 s4, s12, s4
	s_addc_u32 s5, s13, s5
	v_lshl_add_u64 v[34:35], s[4:5], 0, v[34:35]
	s_mov_b64 s[4:5], 0x8200000
	v_lshl_add_u64 v[36:37], v[34:35], 0, s[4:5]
	s_mov_b32 s4, 0x8200000
	v_add_co_u32_e32 v34, vcc, s4, v34
	s_add_i32 s12, s16, 0xffff0000
	s_nop 0
	v_addc_co_u32_e32 v35, vcc, 0, v35, vcc
	s_mov_b64 s[4:5], s[46:47]
	s_ashr_i32 s13, s12, 31
	global_load_dwordx4 v[38:41], v[34:35], off
	s_nop 0
	global_load_dwordx4 v[34:37], v[36:37], off offset:1024
	s_lshl_b64 s[14:15], s[12:13], 12
	s_add_u32 s4, s4, s14
	s_addc_u32 s5, s5, s15
	v_lshl_add_u64 v[78:79], v[60:61], 4, s[4:5]
	s_mov_b64 s[4:5], 0x10300000
	v_lshl_add_u64 v[80:81], v[78:79], 0, s[4:5]
	s_mov_b64 s[4:5], 0x10500000
	v_lshl_add_u64 v[62:63], v[78:79], 0, s[4:5]
	s_mov_b32 s4, 0x10300000
	v_readlane_b32 s18, v252, 6
	v_readlane_b32 s19, v252, 7
	s_mov_b64 s[14:15], -1
	s_waitcnt vmcnt(0)
	v_lshlrev_b32_e32 v66, 16, v42
	v_and_b32_e32 v67, 0xffff0000, v42
	v_add_co_u32_e32 v42, vcc, s4, v78
	v_lshlrev_b32_e32 v68, 16, v43
	v_and_b32_e32 v69, 0xffff0000, v43
	v_addc_co_u32_e32 v43, vcc, 0, v79, vcc
	s_mov_b32 s4, 0x10500000
	v_add_co_u32_e32 v82, vcc, s4, v78
	v_lshlrev_b32_e32 v70, 16, v44
	s_nop 0
	v_addc_co_u32_e32 v83, vcc, 0, v79, vcc
	v_and_b32_e32 v71, 0xffff0000, v44
	v_lshlrev_b32_e32 v72, 16, v45
	v_and_b32_e32 v73, 0xffff0000, v45
	v_lshlrev_b32_e32 v74, 16, v46
	v_and_b32_e32 v75, 0xffff0000, v46
	v_lshlrev_b32_e32 v76, 16, v47
	v_and_b32_e32 v77, 0xffff0000, v47
	v_lshlrev_b32_e32 v54, 16, v48
	v_and_b32_e32 v55, 0xffff0000, v48
	v_lshlrev_b32_e32 v56, 16, v49
	v_and_b32_e32 v57, 0xffff0000, v49
	global_load_dwordx4 v[42:45], v[42:43], off
	s_nop 0
	global_load_dwordx4 v[46:49], v[80:81], off offset:16
	global_load_dwordx4 v[50:53], v[82:83], off
	s_nop 0
	global_load_dwordx4 v[62:65], v[62:63], off offset:16
	s_mov_b64 s[4:5], 0x10500800
	s_waitcnt vmcnt(1)
	v_pk_add_f32 v[44:45], v[44:45], v[52:53]
	s_waitcnt vmcnt(0)
	v_pk_add_f32 v[46:47], v[46:47], v[62:63]
	v_pk_add_f32 v[42:43], v[42:43], v[50:51]
	v_pk_add_f32 v[48:49], v[48:49], v[64:65]
	v_pk_mul_f32 v[46:47], v[46:47], 0.5 op_sel_hi:[1,0]
	v_pk_mul_f32 v[44:45], v[44:45], 0.5 op_sel_hi:[1,0]
	v_pk_mul_f32 v[50:51], v[42:43], 0.5 op_sel_hi:[1,0]
	v_pk_mul_f32 v[48:49], v[48:49], 0.5 op_sel_hi:[1,0]
	v_pk_fma_f32 v[46:47], v[70:71], s[96:97], v[46:47] op_sel_hi:[1,0,1]
	v_lshl_add_u64 v[70:71], v[78:79], 0, s[4:5]
	v_pk_fma_f32 v[42:43], v[68:69], s[96:97], v[44:45] op_sel_hi:[1,0,1]
	v_pk_fma_f32 v[44:45], v[66:67], s[96:97], v[50:51] op_sel_hi:[1,0,1]
	v_pk_fma_f32 v[48:49], v[72:73], s[96:97], v[48:49] op_sel_hi:[1,0,1]
	global_load_dwordx4 v[62:65], v[80:81], off offset:2064
	global_load_dwordx4 v[50:53], v[80:81], off offset:2048
	global_load_dwordx4 v[66:69], v[82:83], off offset:2048
	s_nop 0
	global_load_dwordx4 v[70:73], v[70:71], off offset:16
	s_waitcnt vmcnt(1)
	v_pk_add_f32 v[52:53], v[52:53], v[68:69]
	s_waitcnt vmcnt(0)
	v_pk_add_f32 v[64:65], v[64:65], v[72:73]
	v_pk_add_f32 v[62:63], v[62:63], v[70:71]
	v_pk_add_f32 v[50:51], v[50:51], v[66:67]
	v_pk_mul_f32 v[64:65], v[64:65], 0.5 op_sel_hi:[1,0]
	v_pk_mul_f32 v[62:63], v[62:63], 0.5 op_sel_hi:[1,0]
	v_pk_mul_f32 v[52:53], v[52:53], 0.5 op_sel_hi:[1,0]
	v_pk_mul_f32 v[66:67], v[50:51], 0.5 op_sel_hi:[1,0]
	v_pk_fma_f32 v[56:57], v[56:57], s[96:97], v[64:65] op_sel_hi:[1,0,1]
	v_pk_fma_f32 v[54:55], v[54:55], s[96:97], v[62:63] op_sel_hi:[1,0,1]
	v_pk_mov_b32 v[62:63], v[44:45], v[42:43] op_sel:[1,0]
	v_mov_b32_e32 v64, v44
	v_mov_b32_e32 v65, v43
	v_pk_fma_f32 v[50:51], v[76:77], s[96:97], v[52:53] op_sel_hi:[1,0,1]
	v_pk_fma_f32 v[52:53], v[74:75], s[96:97], v[66:67] op_sel_hi:[1,0,1]
	v_pk_add_f32 v[62:63], v[62:63], v[64:65]
	v_pk_mov_b32 v[64:65], v[46:47], v[48:49] op_sel:[1,0]
	v_mov_b32_e32 v66, v46
	v_mov_b32_e32 v67, v49
	v_pk_add_f32 v[64:65], v[64:65], v[66:67]
	v_add_f32_e32 v1, v62, v63
	v_pk_add_f32 v[64:65], v[64:65], v[64:65] op_sel:[0,1] op_sel_hi:[1,0]
	v_add_f32_e32 v62, 0, v1
	v_add_f32_e32 v66, v52, v53
	v_add_f32_e32 v68, v50, v51
	v_mov_b32_e32 v63, v54
	v_mov_b32_e32 v65, v55
	v_mov_b32_e32 v67, v56
	v_mov_b32_e32 v69, v57
	v_and_b32_e32 v1, 64, v239
	v_pk_add_f32 v[62:63], v[62:63], v[64:65]
	v_pk_add_f32 v[64:65], v[66:67], v[68:69]
	v_add_u32_e32 v66, 64, v1
	v_xor_b32_e32 v1, 1, v239
	v_cmp_lt_i32_e32 vcc, v1, v66
	v_pk_add_f32 v[62:63], v[62:63], v[64:65]
	s_nop 0
	v_cndmask_b32_e32 v1, v239, v1, vcc
	v_add_f32_e32 v62, v62, v63
	v_lshlrev_b32_e32 v1, 2, v1
	ds_bpermute_b32 v63, v1, v62
	s_waitcnt lgkmcnt(0)
	v_add_f32_e32 v63, v62, v63
	v_xor_b32_e32 v62, 2, v239
	v_cmp_lt_i32_e32 vcc, v62, v66
	s_nop 1
	v_cndmask_b32_e32 v62, v239, v62, vcc
	v_lshlrev_b32_e32 v62, 2, v62
	ds_bpermute_b32 v64, v62, v63
	s_waitcnt lgkmcnt(0)
	v_add_f32_e32 v64, v63, v64
	v_xor_b32_e32 v63, 4, v239
	v_cmp_lt_i32_e32 vcc, v63, v66
	s_nop 1
	v_cndmask_b32_e32 v63, v239, v63, vcc
	v_lshlrev_b32_e32 v63, 2, v63
	ds_bpermute_b32 v65, v63, v64
	s_waitcnt lgkmcnt(0)
; #define GAS __attribute__((address_space(1)))
; __device__ __forceinline__ unsigned pk2(float lo, float hi) { return f2bf(lo) | (f2bf(hi) << 16); }
; #define WSB(F, off) ((bf16*)(wsq((F).ws) + (off)))
; __device__ __forceinline__ void ln_rows(const Frame& F, int idx, bool final_out, int row_lo, int row_hi, int gw0, int NGW, bool comb = false) {
;     ...
;         const float mean = wave_sum(s) * (1.f / D); float s2 = 0.f;
; #pragma unroll
;         for (int j = 0; j < 4; ++j) { v[j] = v[j] - mean; s2 += (v[j].x * v[j].x + v[j].y * v[j].y) + (v[j].z * v[j].z + v[j].w * v[j].w); }
;         const float rstd = 1.f / sqrtf(wave_sum(s2) * (1.f / D) + LN_EPS);
; #pragma unroll
;         for (int j = 0; j < 4; ++j) v[j] = v[j] * rstd * gv[j] + bv[j];
;         if (!final_out) { GAS v4u* o = (GAS v4u*)(WSB(F, WS_HB) + (size_t)m * D) + tc.lane;
; #pragma unroll
;             for (int j = 0; j < 2; ++j) o[64 * j] = (v4u){pk2(v[2 * j].x, v[2 * j].y), pk2(v[2 * j].z, v[2 * j].w), pk2(v[2 * j + 1].x, v[2 * j + 1].y), pk2(v[2 * j + 1].z, v[2 * j + 1].w)}; }
	v_add_f32_e32 v65, v64, v65
	v_xor_b32_e32 v64, 8, v239
	v_cmp_lt_i32_e32 vcc, v64, v66
	s_nop 1
	v_cndmask_b32_e32 v64, v239, v64, vcc
	v_lshlrev_b32_e32 v64, 2, v64
	ds_bpermute_b32 v67, v64, v65
	s_waitcnt lgkmcnt(0)
	v_add_f32_e32 v67, v65, v67
	v_xor_b32_e32 v65, 16, v239
	v_cmp_lt_i32_e32 vcc, v65, v66
	s_nop 1
	v_cndmask_b32_e32 v65, v239, v65, vcc
	v_lshlrev_b32_e32 v65, 2, v65
	ds_bpermute_b32 v68, v65, v67
	s_waitcnt lgkmcnt(0)
	v_add_f32_e32 v67, v67, v68
	v_xor_b32_e32 v68, 32, v239
	v_cmp_lt_i32_e32 vcc, v68, v66
	s_nop 1
	v_cndmask_b32_e32 v66, v239, v68, vcc
	v_lshlrev_b32_e32 v66, 2, v66
	ds_bpermute_b32 v68, v66, v67
	s_waitcnt lgkmcnt(0)
	v_add_f32_e32 v67, v67, v68
	v_fmamk_f32 v45, v67, 0xba800000, v45
	v_fmac_f32_e32 v44, 0xba800000, v67
	v_fmamk_f32 v43, v67, 0xba800000, v43
	v_fmac_f32_e32 v42, 0xba800000, v67
	v_pk_mul_f32 v[68:69], v[42:43], v[42:43]
	v_pk_mul_f32 v[70:71], v[44:45], v[44:45]
	v_fmamk_f32 v47, v67, 0xba800000, v47
	v_pk_mov_b32 v[72:73], v[70:71], v[68:69] op_sel:[1,0]
	v_mov_b32_e32 v71, v69
	v_pk_add_f32 v[68:69], v[72:73], v[70:71]
	v_fmac_f32_e32 v46, 0xba800000, v67
	v_fmamk_f32 v49, v67, 0xba800000, v49
	v_fmac_f32_e32 v48, 0xba800000, v67
	v_pk_add_f32 v[68:69], v[68:69], v[68:69] op_sel_hi:[0,1]
	v_pk_mul_f32 v[70:71], v[48:49], v[48:49]
	v_pk_mul_f32 v[72:73], v[46:47], v[46:47]
	v_fmac_f32_e32 v52, 0xba800000, v67
	v_pk_mov_b32 v[74:75], v[72:73], v[70:71] op_sel:[1,0]
	v_mov_b32_e32 v73, v71
	v_fmamk_f32 v53, v67, 0xba800000, v53
	v_fmac_f32_e32 v50, 0xba800000, v67
	v_mul_f32_e32 v68, v52, v52
	v_pk_add_f32 v[70:71], v[74:75], v[72:73]
	v_fmamk_f32 v51, v67, 0xba800000, v51
	v_pk_fma_f32 v[72:73], v[52:53], v[52:53], v[68:69] op_sel_hi:[1,1,0]
	v_mul_f32_e32 v68, v50, v50
	v_pk_add_f32 v[70:71], v[70:71], v[70:71] op_sel_hi:[0,1]
	v_pk_fma_f32 v[74:75], v[50:51], v[50:51], v[68:69] op_sel_hi:[1,1,0]
	v_fmamk_f32 v57, v67, 0xba800000, v57
	v_fmac_f32_e32 v56, 0xba800000, v67
	v_fmamk_f32 v55, v67, 0xba800000, v55
	v_fmac_f32_e32 v54, 0xba800000, v67
	v_mul_f32_e32 v72, v54, v54
	v_mul_f32_e32 v74, v55, v55
	v_mul_f32_e32 v68, v56, v56
	v_mul_f32_e32 v70, v57, v57
	v_pk_add_f32 v[72:73], v[72:73], v[74:75]
	v_pk_add_f32 v[68:69], v[68:69], v[70:71]
	s_nop 0
	v_pk_add_f32 v[68:69], v[72:73], v[68:69]
	s_nop 0
	v_add_f32_e32 v67, v68, v69
	ds_bpermute_b32 v68, v1, v67
	s_waitcnt lgkmcnt(0)
	v_add_f32_e32 v67, v67, v68
	ds_bpermute_b32 v68, v62, v67
	s_waitcnt lgkmcnt(0)
	v_add_f32_e32 v67, v67, v68
	ds_bpermute_b32 v68, v63, v67
	s_waitcnt lgkmcnt(0)
	v_add_f32_e32 v67, v67, v68
	ds_bpermute_b32 v68, v64, v67
	s_waitcnt lgkmcnt(0)
	v_add_f32_e32 v67, v67, v68
	ds_bpermute_b32 v68, v65, v67
	s_waitcnt lgkmcnt(0)
	v_add_f32_e32 v67, v67, v68
	ds_bpermute_b32 v68, v66, v67
	s_waitcnt lgkmcnt(0)
	v_add_f32_e32 v67, v67, v68
	v_fmamk_f32 v67, v67, 0x3a800000, v235
	v_cmp_gt_f32_e32 vcc, s89, v67
	v_mul_f32_e32 v68, 0x4f800000, v67
	s_nop 0
	v_cndmask_b32_e32 v67, v67, v68, vcc
	v_sqrt_f32_e32 v68, v67
	s_nop 0
	v_add_u32_e32 v69, -1, v68
	v_fma_f32 v70, -v69, v68, v67
	v_cmp_ge_f32_e64 s[4:5], 0, v70
	v_add_u32_e32 v70, 1, v68
	s_nop 0
	v_cndmask_b32_e64 v69, v68, v69, s[4:5]
	v_fma_f32 v68, -v70, v68, v67
	v_cmp_lt_f32_e64 s[4:5], 0, v68
	s_nop 1
	v_cndmask_b32_e64 v68, v69, v70, s[4:5]
	v_mul_f32_e32 v69, 0x37800000, v68
	v_cndmask_b32_e32 v68, v68, v69, vcc
	v_cmp_class_f32_e32 vcc, v67, v236
	s_nop 1
	v_cndmask_b32_e32 v67, v68, v67, vcc
	v_div_scale_f32 v68, s[4:5], v67, v67, 1.0
	v_rcp_f32_e32 v69, v68
	s_nop 0
	v_fma_f32 v70, -v68, v69, 1.0
	v_fmac_f32_e32 v69, v70, v69
	v_div_scale_f32 v70, vcc, 1.0, v67, 1.0
	v_mul_f32_e32 v71, v70, v69
	v_fma_f32 v72, -v68, v71, v70
	v_fmac_f32_e32 v71, v72, v69
	v_fma_f32 v68, -v68, v71, v70
	v_div_fmas_f32 v68, v68, v69, v71
	v_div_fixup_f32 v68, v68, v67, 1.0
	v_pk_mul_f32 v[70:71], v[44:45], v[68:69] op_sel_hi:[1,0]
	v_pk_mul_f32 v[42:43], v[42:43], v[68:69] op_sel_hi:[1,0]
	v_pk_mul_f32 v[46:47], v[46:47], v[68:69] op_sel_hi:[1,0]
	v_pk_fma_f32 v[44:45], v[8:9], v[42:43], v[16:17]
	v_pk_fma_f32 v[42:43], v[6:7], v[70:71], v[14:15]
	v_pk_mul_f32 v[48:49], v[48:49], v[68:69] op_sel_hi:[1,0]
	v_pk_mul_f32 v[70:71], v[52:53], v[68:69] op_sel_hi:[1,0]
	v_pk_mul_f32 v[50:51], v[50:51], v[68:69] op_sel_hi:[1,0]
	v_pk_mul_f32 v[54:55], v[54:55], v[68:69] op_sel_hi:[1,0]
	v_pk_mul_f32 v[56:57], v[56:57], v[68:69] op_sel_hi:[1,0]
	v_cndmask_b32_e64 v67, 0, 1, s[18:19]
	v_pk_fma_f32 v[48:49], v[4:5], v[48:49], v[12:13]
	v_pk_fma_f32 v[46:47], v[2:3], v[46:47], v[10:11]
	v_pk_fma_f32 v[52:53], v[24:25], v[50:51], v[32:33]
	v_pk_fma_f32 v[50:51], v[22:23], v[70:71], v[30:31]
	v_pk_fma_f32 v[56:57], v[20:21], v[56:57], v[28:29]
	v_pk_fma_f32 v[54:55], v[18:19], v[54:55], v[26:27]
	v_cmp_ne_u32_e64 s[4:5], 1, v67
	s_andn2_b64 vcc, exec, s[18:19]
	s_cbranch_vccnz .LBB0_2171
	v_cvt_pk_bf16_f32 v68, v42, v43
	v_cvt_pk_bf16_f32 v69, v44, v45
	s_mov_b64 s[14:15], s[46:47]
	v_cvt_pk_bf16_f32 v70, v46, v47
	s_add_u32 s14, s14, s2
	s_addc_u32 s15, s15, s3
	v_lshl_add_u64 v[72:73], v[58:59], 4, s[14:15]
	v_cvt_pk_bf16_f32 v71, v48, v49
	v_bfe_u32 v67, v50, 16, 1
	global_store_dwordx4 v[72:73], v[68:71], off
	v_add3_u32 v67, v50, v67, s72
	v_lshrrev_b32_e32 v67, 16, v67
	v_bfe_u32 v68, v51, 16, 1
	v_add3_u32 v68, v51, v68, s72
	v_and_or_b32 v68, v68, s88, v67
	v_cvt_pk_bf16_f32 v69, v52, v53
	v_cvt_pk_bf16_f32 v70, v54, v55
	v_cvt_pk_bf16_f32 v71, v56, v57
	s_mov_b64 s[14:15], 0
	global_store_dwordx4 v[72:73], v[68:71], off offset:1024

; #define GAS __attribute__((address_space(1)))
; #define WSB(F, off) ((bf16*)(wsq((F).ws) + (off)))
; __device__ __forceinline__ void ln_rows(const Frame& F, int idx, bool final_out, int row_lo, int row_hi, int gw0, int NGW, bool comb = false) {
;     ...
;         for (int r = 0; r < 2; ++r) { const int m = (r == 0 || two) ? m0 + r * NGW : m0; const GAS v4u* yr = (const GAS v4u*)(WSB(F, comb ? WS_HB : WS_YB) + (size_t)m * D) + tc.lane; w[r][0] = yr[0]; w[r][1] = yr[64]; }
; #pragma unroll
;         for (int r = 0; r < 2; ++r) { const int m = m0 + r * NGW; if (r == 1 && !two) break;
;         f32x4 v[4]; float s = 0.f;
; #pragma unroll
;         for (int j = 0; j < 2; ++j) { const v4u x = w[r][j]; v[2 * j] = (f32x4){bflo(x.x), bfhi(x.x), bflo(x.y), bfhi(x.y)}; v[2 * j + 1] = (f32x4){bflo(x.z), bfhi(x.z), bflo(x.w), bfhi(x.w)}; }
;         if (comb) {
;             const GAS f32x4* pa = (const GAS f32x4*)((const float*)WSB(F, WS_ACT) + (size_t)(m - MP) * D) + 2 * tc.lane; const GAS f32x4* pb = pa + (size_t)512 * D / 4;
; #pragma unroll
;             for (int j = 0; j < 2; ++j) { v[2 * j] = v[2 * j] * ALPHA + (pa[128 * j] + pb[128 * j]) * 0.5f; v[2 * j + 1] = v[2 * j + 1] * ALPHA + (pa[128 * j + 1] + pb[128 * j + 1]) * 0.5f; } }
; #pragma unroll
;         for (int j = 0; j < 4; ++j) s += (v[j].x + v[j].y) + (v[j].z + v[j].w);
;         const float mean = wave_sum(s) * (1.f / D); float s2 = 0.f;
.LBB0_2176:
	s_andn2_b64 vcc, exec, s[6:7]
	s_cbranch_vccnz .LBB0_2168
	s_add_i32 s12, s10, 0xffff0000
	s_mov_b64 s[6:7], s[46:47]
	s_ashr_i32 s13, s12, 31
	s_lshl_b64 s[14:15], s[12:13], 12
	s_add_u32 s6, s6, s14
	s_addc_u32 s7, s7, s15
	v_lshl_add_u64 v[76:77], v[60:61], 4, s[6:7]
	s_mov_b64 s[6:7], 0x10300000
	v_lshl_add_u64 v[78:79], v[76:77], 0, s[6:7]
	s_mov_b64 s[6:7], 0x10500000
	v_lshl_add_u64 v[50:51], v[76:77], 0, s[6:7]
	s_mov_b32 s6, 0x10300000
	v_lshlrev_b32_e32 v72, 16, v34
	v_and_b32_e32 v73, 0xffff0000, v34
	v_add_co_u32_e32 v34, vcc, s6, v76
	v_lshlrev_b32_e32 v74, 16, v35
	v_and_b32_e32 v75, 0xffff0000, v35
	v_addc_co_u32_e32 v35, vcc, 0, v77, vcc
	s_mov_b32 s6, 0x10500000
	v_add_co_u32_e32 v80, vcc, s6, v76
	v_lshlrev_b32_e32 v54, 16, v38
	s_nop 0
	v_addc_co_u32_e32 v81, vcc, 0, v77, vcc
	v_and_b32_e32 v55, 0xffff0000, v38
	v_lshlrev_b32_e32 v56, 16, v39
	v_and_b32_e32 v57, 0xffff0000, v39
	v_lshlrev_b32_e32 v68, 16, v40
	v_and_b32_e32 v69, 0xffff0000, v40
	v_lshlrev_b32_e32 v70, 16, v41
	v_and_b32_e32 v71, 0xffff0000, v41
	v_lshlrev_b32_e32 v48, 16, v36
	v_and_b32_e32 v49, 0xffff0000, v36
	v_lshlrev_b32_e32 v46, 16, v37
	v_and_b32_e32 v47, 0xffff0000, v37
	global_load_dwordx4 v[34:37], v[34:35], off
	s_nop 0
	global_load_dwordx4 v[38:41], v[78:79], off offset:16
	global_load_dwordx4 v[42:45], v[80:81], off
	s_nop 0
	global_load_dwordx4 v[50:53], v[50:51], off offset:16
	s_mov_b64 s[6:7], 0x10500800
	s_waitcnt vmcnt(1)
	v_pk_add_f32 v[36:37], v[36:37], v[44:45]
	v_pk_add_f32 v[34:35], v[34:35], v[42:43]
	v_pk_mul_f32 v[36:37], v[36:37], 0.5 op_sel_hi:[1,0]
	v_pk_mul_f32 v[42:43], v[34:35], 0.5 op_sel_hi:[1,0]
	s_waitcnt vmcnt(0)
	v_pk_add_f32 v[40:41], v[40:41], v[52:53]
	v_pk_add_f32 v[38:39], v[38:39], v[50:51]
	v_pk_fma_f32 v[34:35], v[56:57], s[96:97], v[36:37] op_sel_hi:[1,0,1]
	v_pk_fma_f32 v[36:37], v[54:55], s[96:97], v[42:43] op_sel_hi:[1,0,1]
	v_pk_mul_f32 v[40:41], v[40:41], 0.5 op_sel_hi:[1,0]
	v_pk_mul_f32 v[42:43], v[38:39], 0.5 op_sel_hi:[1,0]
	v_pk_fma_f32 v[38:39], v[70:71], s[96:97], v[40:41] op_sel_hi:[1,0,1]
	v_pk_fma_f32 v[40:41], v[68:69], s[96:97], v[42:43] op_sel_hi:[1,0,1]
	v_lshl_add_u64 v[68:69], v[76:77], 0, s[6:7]
	global_load_dwordx4 v[50:53], v[78:79], off offset:2064
	global_load_dwordx4 v[42:45], v[78:79], off offset:2048
	global_load_dwordx4 v[54:57], v[80:81], off offset:2048
	s_nop 0
	global_load_dwordx4 v[68:71], v[68:69], off offset:16
	s_waitcnt vmcnt(1)
	v_pk_add_f32 v[44:45], v[44:45], v[56:57]
	s_waitcnt vmcnt(0)
	v_pk_add_f32 v[52:53], v[52:53], v[70:71]
	v_pk_add_f32 v[50:51], v[50:51], v[68:69]
	v_pk_add_f32 v[42:43], v[42:43], v[54:55]
	v_pk_mul_f32 v[52:53], v[52:53], 0.5 op_sel_hi:[1,0]
	v_pk_mul_f32 v[50:51], v[50:51], 0.5 op_sel_hi:[1,0]
	v_pk_mul_f32 v[44:45], v[44:45], 0.5 op_sel_hi:[1,0]
	v_pk_mul_f32 v[54:55], v[42:43], 0.5 op_sel_hi:[1,0]
	v_pk_fma_f32 v[46:47], v[46:47], s[96:97], v[52:53] op_sel_hi:[1,0,1]
	v_pk_fma_f32 v[48:49], v[48:49], s[96:97], v[50:51] op_sel_hi:[1,0,1]
	v_pk_mov_b32 v[50:51], v[36:37], v[34:35] op_sel:[1,0]
	v_mov_b32_e32 v52, v36
	v_mov_b32_e32 v53, v35
	v_pk_fma_f32 v[42:43], v[74:75], s[96:97], v[44:45] op_sel_hi:[1,0,1]
	v_pk_fma_f32 v[44:45], v[72:73], s[96:97], v[54:55] op_sel_hi:[1,0,1]
	v_pk_add_f32 v[50:51], v[50:51], v[52:53]
	v_pk_mov_b32 v[52:53], v[40:41], v[38:39] op_sel:[1,0]
	v_mov_b32_e32 v54, v40
	v_mov_b32_e32 v55, v39
	v_pk_add_f32 v[52:53], v[52:53], v[54:55]
	v_add_f32_e32 v50, v50, v51
	v_pk_add_f32 v[52:53], v[52:53], v[52:53] op_sel:[0,1] op_sel_hi:[1,0]
	v_add_f32_e32 v50, 0, v50
	v_add_f32_e32 v54, v44, v45
	v_add_f32_e32 v56, v42, v43
	v_mov_b32_e32 v51, v48
	v_mov_b32_e32 v53, v49
	v_mov_b32_e32 v55, v46
	v_mov_b32_e32 v57, v47
	v_pk_add_f32 v[50:51], v[50:51], v[52:53]
	v_pk_add_f32 v[52:53], v[54:55], v[56:57]
	s_nop 0
	v_pk_add_f32 v[50:51], v[50:51], v[52:53]
	s_nop 0
	v_add_f32_e32 v50, v50, v51
	ds_bpermute_b32 v51, v1, v50
	s_waitcnt lgkmcnt(0)
	v_add_f32_e32 v50, v50, v51
	ds_bpermute_b32 v51, v62, v50
	s_waitcnt lgkmcnt(0)
	v_add_f32_e32 v50, v50, v51
	ds_bpermute_b32 v51, v63, v50
	s_waitcnt lgkmcnt(0)
	v_add_f32_e32 v50, v50, v51
	ds_bpermute_b32 v51, v64, v50
	s_waitcnt lgkmcnt(0)
	v_add_f32_e32 v50, v50, v51
	ds_bpermute_b32 v51, v65, v50
	s_waitcnt lgkmcnt(0)
	v_add_f32_e32 v50, v50, v51
	ds_bpermute_b32 v51, v66, v50
	s_waitcnt lgkmcnt(0)
; #define GAS __attribute__((address_space(1)))
; __device__ __forceinline__ unsigned pk2(float lo, float hi) { return f2bf(lo) | (f2bf(hi) << 16); }
; #define WSB(F, off) ((bf16*)(wsq((F).ws) + (off)))
; __device__ __forceinline__ void ln_rows(const Frame& F, int idx, bool final_out, int row_lo, int row_hi, int gw0, int NGW, bool comb = false) {
;     ...
;         const float mean = wave_sum(s) * (1.f / D); float s2 = 0.f;
; #pragma unroll
;         for (int j = 0; j < 4; ++j) { v[j] = v[j] - mean; s2 += (v[j].x * v[j].x + v[j].y * v[j].y) + (v[j].z * v[j].z + v[j].w * v[j].w); }
;         const float rstd = 1.f / sqrtf(wave_sum(s2) * (1.f / D) + LN_EPS);
; #pragma unroll
;         for (int j = 0; j < 4; ++j) v[j] = v[j] * rstd * gv[j] + bv[j];
;         if (!final_out) { GAS v4u* o = (GAS v4u*)(WSB(F, WS_HB) + (size_t)m * D) + tc.lane;
; #pragma unroll
;             for (int j = 0; j < 2; ++j) o[64 * j] = (v4u){pk2(v[2 * j].x, v[2 * j].y), pk2(v[2 * j].z, v[2 * j].w), pk2(v[2 * j + 1].x, v[2 * j + 1].y), pk2(v[2 * j + 1].z, v[2 * j + 1].w)}; }
	v_add_f32_e32 v67, v50, v51
	v_fmamk_f32 v37, v67, 0xba800000, v37
	v_fmac_f32_e32 v36, 0xba800000, v67
	v_fmamk_f32 v35, v67, 0xba800000, v35
	v_fmac_f32_e32 v34, 0xba800000, v67
	v_pk_mul_f32 v[50:51], v[34:35], v[34:35]
	v_pk_mul_f32 v[52:53], v[36:37], v[36:37]
	v_fmamk_f32 v41, v67, 0xba800000, v41
	v_pk_mov_b32 v[54:55], v[52:53], v[50:51] op_sel:[1,0]
	v_mov_b32_e32 v53, v51
	v_pk_add_f32 v[50:51], v[54:55], v[52:53]
	v_fmac_f32_e32 v40, 0xba800000, v67
	v_fmamk_f32 v39, v67, 0xba800000, v39
	v_fmac_f32_e32 v38, 0xba800000, v67
	v_pk_add_f32 v[50:51], v[50:51], v[50:51] op_sel_hi:[0,1]
	v_pk_mul_f32 v[52:53], v[38:39], v[38:39]
	v_pk_mul_f32 v[54:55], v[40:41], v[40:41]
	v_fmac_f32_e32 v44, 0xba800000, v67
	v_pk_mov_b32 v[56:57], v[54:55], v[52:53] op_sel:[1,0]
	v_mov_b32_e32 v55, v53
	v_fmamk_f32 v45, v67, 0xba800000, v45
	v_fmac_f32_e32 v42, 0xba800000, v67
	v_mul_f32_e32 v50, v44, v44
	v_pk_add_f32 v[52:53], v[56:57], v[54:55]
	v_fmamk_f32 v43, v67, 0xba800000, v43
	v_pk_fma_f32 v[54:55], v[44:45], v[44:45], v[50:51] op_sel_hi:[1,1,0]
	v_mul_f32_e32 v50, v42, v42
	v_pk_add_f32 v[52:53], v[52:53], v[52:53] op_sel_hi:[0,1]
	v_pk_fma_f32 v[56:57], v[42:43], v[42:43], v[50:51] op_sel_hi:[1,1,0]
	v_fmamk_f32 v47, v67, 0xba800000, v47
	v_fmac_f32_e32 v46, 0xba800000, v67
	v_fmamk_f32 v49, v67, 0xba800000, v49
	v_fmac_f32_e32 v48, 0xba800000, v67
	v_mul_f32_e32 v54, v48, v48
	v_mul_f32_e32 v56, v49, v49
	v_mul_f32_e32 v50, v46, v46
	v_mul_f32_e32 v52, v47, v47
	v_pk_add_f32 v[54:55], v[54:55], v[56:57]
	v_pk_add_f32 v[50:51], v[50:51], v[52:53]
	s_nop 0
	v_pk_add_f32 v[50:51], v[54:55], v[50:51]
	s_nop 0
	v_add_f32_e32 v50, v50, v51
	ds_bpermute_b32 v1, v1, v50
	s_waitcnt lgkmcnt(0)
	v_add_f32_e32 v1, v50, v1
	ds_bpermute_b32 v50, v62, v1
	s_waitcnt lgkmcnt(0)
	v_add_f32_e32 v1, v1, v50
	ds_bpermute_b32 v50, v63, v1
	s_waitcnt lgkmcnt(0)
	v_add_f32_e32 v1, v1, v50
	ds_bpermute_b32 v50, v64, v1
	s_waitcnt lgkmcnt(0)
	v_add_f32_e32 v1, v1, v50
	ds_bpermute_b32 v50, v65, v1
	s_waitcnt lgkmcnt(0)
	v_add_f32_e32 v1, v1, v50
	ds_bpermute_b32 v50, v66, v1
	s_waitcnt lgkmcnt(0)
	v_add_f32_e32 v1, v1, v50
	v_fmamk_f32 v1, v1, 0x3a800000, v235
	v_cmp_gt_f32_e32 vcc, s89, v1
	v_mul_f32_e32 v50, 0x4f800000, v1
	s_nop 0
	v_cndmask_b32_e32 v1, v1, v50, vcc
	v_sqrt_f32_e32 v50, v1
	s_nop 0
	v_add_u32_e32 v51, -1, v50
	v_fma_f32 v52, -v51, v50, v1
	v_cmp_ge_f32_e64 s[6:7], 0, v52
	v_add_u32_e32 v52, 1, v50
	s_nop 0
	v_cndmask_b32_e64 v51, v50, v51, s[6:7]
	v_fma_f32 v50, -v52, v50, v1
	v_cmp_lt_f32_e64 s[6:7], 0, v50
	s_nop 1
	v_cndmask_b32_e64 v50, v51, v52, s[6:7]
	v_mul_f32_e32 v51, 0x37800000, v50
	v_cndmask_b32_e32 v50, v50, v51, vcc
	v_cmp_class_f32_e32 vcc, v1, v236
	s_nop 1
	v_cndmask_b32_e32 v1, v50, v1, vcc
	v_div_scale_f32 v50, s[6:7], v1, v1, 1.0
	v_rcp_f32_e32 v51, v50
	s_mov_b64 s[6:7], -1
	v_fma_f32 v52, -v50, v51, 1.0
	v_fmac_f32_e32 v51, v52, v51
	v_div_scale_f32 v52, vcc, 1.0, v1, 1.0
	v_mul_f32_e32 v53, v52, v51
	v_fma_f32 v54, -v50, v53, v52
	v_fmac_f32_e32 v53, v54, v51
	v_fma_f32 v50, -v50, v53, v52
	v_div_fmas_f32 v50, v50, v51, v53
	v_div_fixup_f32 v50, v50, v1, 1.0
	v_pk_mul_f32 v[52:53], v[36:37], v[50:51] op_sel_hi:[1,0]
	v_pk_mul_f32 v[34:35], v[34:35], v[50:51] op_sel_hi:[1,0]
	v_pk_mul_f32 v[38:39], v[38:39], v[50:51] op_sel_hi:[1,0]
	v_pk_fma_f32 v[36:37], v[8:9], v[34:35], v[16:17]
	v_pk_fma_f32 v[34:35], v[6:7], v[52:53], v[14:15]
	v_pk_mul_f32 v[52:53], v[40:41], v[50:51] op_sel_hi:[1,0]
	v_pk_fma_f32 v[40:41], v[4:5], v[38:39], v[12:13]
	v_pk_fma_f32 v[38:39], v[2:3], v[52:53], v[10:11]
	v_pk_mul_f32 v[52:53], v[44:45], v[50:51] op_sel_hi:[1,0]
	v_pk_mul_f32 v[42:43], v[42:43], v[50:51] op_sel_hi:[1,0]
	v_pk_mul_f32 v[46:47], v[46:47], v[50:51] op_sel_hi:[1,0]
	v_pk_fma_f32 v[44:45], v[24:25], v[42:43], v[32:33]
	v_pk_fma_f32 v[42:43], v[22:23], v[52:53], v[30:31]
	v_pk_mul_f32 v[52:53], v[48:49], v[50:51] op_sel_hi:[1,0]
	v_pk_fma_f32 v[48:49], v[20:21], v[46:47], v[28:29]
	v_pk_fma_f32 v[46:47], v[18:19], v[52:53], v[26:27]
	s_and_b64 vcc, exec, s[4:5]
	s_cbranch_vccnz .LBB0_2179
	v_cvt_pk_bf16_f32 v50, v34, v35
	s_mov_b64 s[4:5], s[46:47]
	s_ashr_i32 s11, s10, 31
	s_lshl_b64 s[6:7], s[10:11], 11
	v_cvt_pk_bf16_f32 v51, v36, v37
	s_add_u32 s4, s4, s6
	s_addc_u32 s5, s5, s7
	v_lshl_add_u64 v[54:55], v[58:59], 4, s[4:5]
	s_mov_b64 s[4:5], 0x8200000
	v_cvt_pk_bf16_f32 v52, v38, v39
	v_lshl_add_u64 v[56:57], v[54:55], 0, s[4:5]
	s_mov_b32 s4, 0x8200000
	v_add_co_u32_e32 v54, vcc, s4, v54
	v_cvt_pk_bf16_f32 v53, v40, v41
	s_nop 0
	v_addc_co_u32_e32 v55, vcc, 0, v55, vcc
	v_bfe_u32 v1, v42, 16, 1
	global_store_dwordx4 v[54:55], v[50:53], off
	v_add3_u32 v1, v42, v1, s72
	v_lshrrev_b32_e32 v1, 16, v1
	v_bfe_u32 v50, v43, 16, 1
	v_add3_u32 v50, v43, v50, s72
	v_and_or_b32 v50, v50, s88, v1
	v_cvt_pk_bf16_f32 v51, v44, v45
	v_cvt_pk_bf16_f32 v52, v46, v47
	v_cvt_pk_bf16_f32 v53, v48, v49
	s_mov_b64 s[6:7], 0
	global_store_dwordx4 v[56:57], v[50:53], off offset:1024
